# stack of small edits: vt-loop load pipelining, attention Q-wait hoist + 6-deep MLA LDS reads, GEMM phase-3 B0 LDS reads, batched LDS reads in weight transposes, DPP/permlane reductions
# speedup vs baseline: 1.0068x; 1.0068x over previous
; #define LAS __attribute__((address_space(3)))
; __device__ __forceinline__ void transpose_item(const float* W, int K, int N, bf16_t* WT, LAS float* scr, int item, int lane, const float* gk) {
;     const int nblk = N / 64, kb = item / nblk, nb = item % nblk, k0 = 64 * kb, n0 = 64 * nb;
;     f32x4 v[16];
; #pragma unroll
;     for (int i = 0; i < 16; ++i) { const int kk = 4 * i + (lane >> 4); v[i] = *(const f32x4*)(W + (size_t)(k0 + kk) * N + n0 + 4 * (lane & 15)); }
;     if (gk) {
; #pragma unroll
;         for (int i = 0; i < 16; ++i) v[i] *= gk[k0 + 4 * i + (lane >> 4)]; }
; #pragma unroll
;     for (int i = 0; i < 16; ++i) { LAS float* d = scr + (4 * i + (lane >> 4)) * 65 + 4 * (lane & 15); d[0] = v[i][0]; d[1] = v[i][1]; d[2] = v[i][2]; d[3] = v[i][3]; }
.LBB0_19:
	s_mul_hi_i32 s4, s19, 0x4325c53f
	s_lshr_b32 s5, s4, 31
	s_ashr_i32 s4, s4, 4
	s_add_i32 s4, s4, s5
	s_lshl_b32 s12, s4, 6
	s_mulk_i32 s4, 0xf0c0
	s_add_i32 s4, s16, s4
	v_or_b32_e32 v48, s12, v13
	s_ashr_i32 s5, s4, 31
	v_or_b32_e32 v49, 4, v48
	v_or_b32_e32 v50, 8, v48
	v_or_b32_e32 v51, 12, v48
	v_or_b32_e32 v52, 16, v48
	v_or_b32_e32 v53, 20, v48
	v_or_b32_e32 v54, 24, v48
	v_or_b32_e32 v55, 28, v48
	v_or_b32_e32 v56, 32, v48
	v_or_b32_e32 v57, 36, v48
	v_or_b32_e32 v58, 40, v48
	v_or_b32_e32 v59, 44, v48
	v_lshl_add_u64 v[46:47], s[4:5], 2, v[6:7]
	v_or_b32_e32 v60, 48, v48
	v_or_b32_e32 v61, 52, v48
	v_or_b32_e32 v62, 56, v48
	v_or_b32_e32 v63, 60, v48
	v_add_u32_e32 v10, s4, v15
	v_mad_i64_i32 v[86:87], s[4:5], v48, s18, v[46:47]
	v_mad_i64_i32 v[88:89], s[4:5], v49, s18, v[46:47]
	v_mad_i64_i32 v[90:91], s[4:5], v50, s18, v[46:47]
	v_mad_i64_i32 v[92:93], s[4:5], v51, s18, v[46:47]
	v_mad_i64_i32 v[94:95], s[4:5], v52, s18, v[46:47]
	v_mad_i64_i32 v[96:97], s[4:5], v53, s18, v[46:47]
	v_mad_i64_i32 v[98:99], s[4:5], v54, s18, v[46:47]
	v_mad_i64_i32 v[100:101], s[4:5], v55, s18, v[46:47]
	v_mad_i64_i32 v[102:103], s[4:5], v56, s18, v[46:47]
	v_mad_i64_i32 v[104:105], s[4:5], v57, s18, v[46:47]
	v_mad_i64_i32 v[106:107], s[4:5], v58, s18, v[46:47]
	v_mad_i64_i32 v[108:109], s[4:5], v59, s18, v[46:47]
	v_mad_i64_i32 v[122:123], s[4:5], v60, s18, v[46:47]
	v_mad_i64_i32 v[124:125], s[4:5], v61, s18, v[46:47]
	v_mad_i64_i32 v[126:127], s[4:5], v62, s18, v[46:47]
	v_mad_i64_i32 v[128:129], s[4:5], v63, s18, v[46:47]
	global_load_dwordx4 v[46:49], v[86:87], off
	global_load_dwordx4 v[50:53], v[88:89], off
	global_load_dwordx4 v[54:57], v[90:91], off
	global_load_dwordx4 v[58:61], v[92:93], off
	global_load_dwordx4 v[62:65], v[94:95], off
	global_load_dwordx4 v[66:69], v[96:97], off
	global_load_dwordx4 v[70:73], v[98:99], off
	global_load_dwordx4 v[74:77], v[100:101], off
	global_load_dwordx4 v[78:81], v[102:103], off
	global_load_dwordx4 v[82:85], v[104:105], off
	global_load_dwordx4 v[86:89], v[106:107], off
	global_load_dwordx4 v[90:93], v[108:109], off
	global_load_dwordx4 v[94:97], v[122:123], off
	global_load_dwordx4 v[98:101], v[124:125], off
	s_nop 0
	global_load_dwordx4 v[102:105], v[126:127], off
	global_load_dwordx4 v[106:109], v[128:129], off
	s_ashr_i32 s13, s12, 31
	v_ashrrev_i32_e32 v11, 31, v10
	v_lshl_add_u64 v[8:9], s[12:13], 1, v[4:5]
	v_lshlrev_b64 v[130:131], 12, v[10:11]
	v_add_u32_e32 v110, 8, v10
	v_lshl_add_u64 v[122:123], v[8:9], 0, v[130:131]
	v_ashrrev_i32_e32 v111, 31, v110
	v_lshlrev_b64 v[110:111], 12, v[110:111]
	v_add_u32_e32 v112, 16, v10
	v_lshl_add_u64 v[110:111], v[8:9], 0, v[110:111]
	v_ashrrev_i32_e32 v113, 31, v112
	v_lshlrev_b64 v[112:113], 12, v[112:113]
	v_add_u32_e32 v114, 24, v10
	v_lshl_add_u64 v[112:113], v[8:9], 0, v[112:113]
	v_ashrrev_i32_e32 v115, 31, v114
	v_lshlrev_b64 v[114:115], 12, v[114:115]
	v_add_u32_e32 v116, 32, v10
	v_lshl_add_u64 v[114:115], v[8:9], 0, v[114:115]
	v_ashrrev_i32_e32 v117, 31, v116
	v_lshlrev_b64 v[116:117], 12, v[116:117]
	v_add_u32_e32 v118, 40, v10
	v_lshl_add_u64 v[116:117], v[8:9], 0, v[116:117]
	v_ashrrev_i32_e32 v119, 31, v118
	v_lshlrev_b64 v[118:119], 12, v[118:119]
	v_add_u32_e32 v120, 48, v10
	v_lshl_add_u64 v[118:119], v[8:9], 0, v[118:119]
	v_ashrrev_i32_e32 v121, 31, v120
	v_lshlrev_b64 v[120:121], 12, v[120:121]
	v_add_u32_e32 v10, 56, v10
	s_waitcnt vmcnt(15)
	ds_write2_b32 v14, v46, v47 offset1:1
	ds_write2_b32 v14, v48, v49 offset0:2 offset1:3
	s_waitcnt vmcnt(14)
	ds_write2_b32 v1, v50, v51 offset1:1
	ds_write2_b32 v3, v52, v53 offset1:1
	s_waitcnt vmcnt(13)
	ds_write2_b32 v17, v54, v55 offset1:1
	ds_write2_b32 v18, v56, v57 offset1:1
	s_waitcnt vmcnt(12)
	ds_write2_b32 v19, v58, v59 offset1:1
	ds_write2_b32 v20, v60, v61 offset1:1
	s_waitcnt vmcnt(11)
	ds_write2_b32 v21, v62, v63 offset1:1
	ds_write2_b32 v22, v64, v65 offset1:1
	s_waitcnt vmcnt(10)
	ds_write2_b32 v23, v66, v67 offset1:1
	ds_write2_b32 v24, v68, v69 offset1:1
	s_waitcnt vmcnt(9)
	ds_write2_b32 v25, v70, v71 offset1:1
	ds_write2_b32 v26, v72, v73 offset1:1
	s_waitcnt vmcnt(8)
	ds_write2_b32 v27, v74, v75 offset1:1
	ds_write2_b32 v28, v76, v77 offset1:1
	s_waitcnt vmcnt(7)
	ds_write2_b32 v29, v78, v79 offset1:1
	ds_write2_b32 v30, v80, v81 offset1:1
	s_waitcnt vmcnt(6)
	ds_write2_b32 v31, v82, v83 offset1:1
	ds_write2_b32 v32, v84, v85 offset1:1
	s_waitcnt vmcnt(5)
	ds_write2_b32 v33, v86, v87 offset1:1
	ds_write2_b32 v34, v88, v89 offset1:1
	s_waitcnt vmcnt(4)
	ds_write2_b32 v35, v90, v91 offset1:1
	ds_write2_b32 v36, v92, v93 offset1:1
	s_waitcnt vmcnt(3)
; #define LAS __attribute__((address_space(3)))
; __device__ __forceinline__ unsigned cvt_pk_bf16(float lo, float hi) { unsigned r; asm volatile("v_cvt_pk_bf16_f32 %0, %1, %2" : "=v"(r) : "v"(lo), "v"(hi)); return r; }
; __device__ __forceinline__ void transpose_item(const float* W, int K, int N, bf16_t* WT, LAS float* scr, int item, int lane, const float* gk) {
;     ...
;     for (int j = 0; j < 8; ++j) { const int n = (lane >> 3) + 8 * j; const LAS float* s = scr + (8 * c) * 65 + n;
;         u32x4 o; o.x = cvt_pk_bf16(s[0 * 65], s[1 * 65]); o.y = cvt_pk_bf16(s[2 * 65], s[3 * 65]); o.z = cvt_pk_bf16(s[4 * 65], s[5 * 65]); o.w = cvt_pk_bf16(s[6 * 65], s[7 * 65]);
;         *(u32x4*)(WT + (size_t)(n0 + n) * K + k0 + 8 * c) = o; }
	ds_write2_b32 v37, v94, v95 offset1:1
	ds_write2_b32 v38, v96, v97 offset1:1
	s_waitcnt vmcnt(2)
	ds_write2_b32 v39, v98, v99 offset1:1
	ds_write2_b32 v40, v100, v101 offset1:1
	s_waitcnt vmcnt(1)
	ds_write2_b32 v41, v102, v103 offset1:1
	ds_write2_b32 v42, v104, v105 offset1:1
	s_waitcnt vmcnt(0)
	ds_write2_b32 v43, v106, v107 offset1:1
	ds_write2_b32 v44, v108, v109 offset1:1
	s_waitcnt lgkmcnt(0)
	ds_read2_b32 v[52:53], v16 offset1:65
	ds_read2_b32 v[54:55], v16 offset0:130 offset1:195
	ds_read2_b32 v[56:57], v45 offset0:4 offset1:69
	ds_read2_b32 v[58:59], v45 offset0:134 offset1:199
	ds_read2_b32 v[60:61], v16 offset0:8 offset1:73
	ds_read2_b32 v[62:63], v16 offset0:138 offset1:203
	ds_read2_b32 v[64:65], v45 offset0:12 offset1:77
	ds_read2_b32 v[66:67], v45 offset0:142 offset1:207
	ds_read2_b32 v[68:69], v16 offset0:16 offset1:81
	ds_read2_b32 v[90:91], v16 offset0:146 offset1:211
	ds_read2_b32 v[100:101], v45 offset0:20 offset1:85
	ds_read2_b32 v[102:103], v45 offset0:150 offset1:215
	ds_read2_b32 v[104:105], v16 offset0:24 offset1:89
	ds_read2_b32 v[106:107], v16 offset0:154 offset1:219
	ds_read2_b32 v[108:109], v45 offset0:28 offset1:93
	ds_read2_b32 v[124:125], v45 offset0:158 offset1:223
	ds_read2_b32 v[126:127], v16 offset0:32 offset1:97
	ds_read2_b32 v[128:129], v16 offset0:162 offset1:227
	ds_read2_b32 v[130:131], v45 offset0:36 offset1:101
	ds_read2_b32 v[132:133], v45 offset0:166 offset1:231
	ds_read2_b32 v[134:135], v16 offset0:40 offset1:105
	ds_read2_b32 v[136:137], v16 offset0:170 offset1:235
	ds_read2_b32 v[138:139], v45 offset0:44 offset1:109
	ds_read2_b32 v[140:141], v45 offset0:174 offset1:239
	ds_read2_b32 v[142:143], v16 offset0:48 offset1:113
	ds_read2_b32 v[144:145], v16 offset0:178 offset1:243
	ds_read2_b32 v[146:147], v45 offset0:52 offset1:117
	ds_read2_b32 v[148:149], v45 offset0:182 offset1:247
	ds_read2_b32 v[150:151], v16 offset0:56 offset1:121
	ds_read2_b32 v[152:153], v16 offset0:186 offset1:251
	ds_read2_b32 v[154:155], v45 offset0:60 offset1:125
	ds_read2_b32 v[156:157], v45 offset0:190 offset1:255
	s_waitcnt lgkmcnt(15)
	v_cvt_pk_bf16_f32 v46, v52, v53
	s_waitcnt lgkmcnt(15)
	v_cvt_pk_bf16_f32 v47, v54, v55
	s_waitcnt lgkmcnt(15)
	v_cvt_pk_bf16_f32 v48, v56, v57
	s_waitcnt lgkmcnt(15)
	v_cvt_pk_bf16_f32 v49, v58, v59
	global_store_dwordx4 v[122:123], v[46:49], off
	v_lshl_add_u64 v[120:121], v[8:9], 0, v[120:121]
	v_ashrrev_i32_e32 v11, 31, v10
	s_waitcnt lgkmcnt(15)
	v_cvt_pk_bf16_f32 v46, v60, v61
	s_waitcnt lgkmcnt(15)
	v_cvt_pk_bf16_f32 v47, v62, v63
	s_waitcnt lgkmcnt(15)
	v_cvt_pk_bf16_f32 v48, v64, v65
	s_waitcnt lgkmcnt(15)
	v_cvt_pk_bf16_f32 v49, v66, v67
	global_store_dwordx4 v[110:111], v[46:49], off
	v_lshlrev_b64 v[10:11], 12, v[10:11]
	v_lshl_add_u64 v[8:9], v[8:9], 0, v[10:11]
	s_waitcnt lgkmcnt(15)
	v_cvt_pk_bf16_f32 v46, v68, v69
	s_waitcnt lgkmcnt(15)
	v_cvt_pk_bf16_f32 v47, v90, v91
	s_waitcnt lgkmcnt(15)
	v_cvt_pk_bf16_f32 v48, v100, v101
	s_waitcnt lgkmcnt(15)
	v_cvt_pk_bf16_f32 v49, v102, v103
	global_store_dwordx4 v[112:113], v[46:49], off
	s_add_i32 s19, s19, s26
	s_add_i32 s16, s16, s17
	s_waitcnt lgkmcnt(15)
	v_cvt_pk_bf16_f32 v46, v104, v105
	s_waitcnt lgkmcnt(15)
	v_cvt_pk_bf16_f32 v47, v106, v107
	s_waitcnt lgkmcnt(15)
	v_cvt_pk_bf16_f32 v48, v108, v109
	s_waitcnt lgkmcnt(15)
	v_cvt_pk_bf16_f32 v49, v124, v125
	global_store_dwordx4 v[114:115], v[46:49], off
	s_cmpk_lt_i32 s19, 0x7a0
	s_waitcnt lgkmcnt(15)
	v_cvt_pk_bf16_f32 v46, v126, v127
	s_waitcnt lgkmcnt(14)
	v_cvt_pk_bf16_f32 v47, v128, v129
	s_waitcnt lgkmcnt(13)
	v_cvt_pk_bf16_f32 v48, v130, v131
	s_waitcnt lgkmcnt(12)
	v_cvt_pk_bf16_f32 v49, v132, v133
	global_store_dwordx4 v[116:117], v[46:49], off
	s_waitcnt lgkmcnt(11)
	s_nop 0
	v_cvt_pk_bf16_f32 v46, v134, v135
	s_waitcnt lgkmcnt(10)
	v_cvt_pk_bf16_f32 v47, v136, v137
	s_waitcnt lgkmcnt(9)
	v_cvt_pk_bf16_f32 v48, v138, v139
	s_waitcnt lgkmcnt(8)
	v_cvt_pk_bf16_f32 v49, v140, v141
	global_store_dwordx4 v[118:119], v[46:49], off
	s_waitcnt lgkmcnt(7)
	s_nop 0
	v_cvt_pk_bf16_f32 v46, v142, v143
	s_waitcnt lgkmcnt(6)
	v_cvt_pk_bf16_f32 v47, v144, v145
	s_waitcnt lgkmcnt(5)
	v_cvt_pk_bf16_f32 v48, v146, v147
	s_waitcnt lgkmcnt(4)
	v_cvt_pk_bf16_f32 v49, v148, v149
	global_store_dwordx4 v[120:121], v[46:49], off
	s_waitcnt lgkmcnt(3)
	s_nop 0
	v_cvt_pk_bf16_f32 v46, v150, v151
	s_waitcnt lgkmcnt(2)
	v_cvt_pk_bf16_f32 v47, v152, v153
	s_waitcnt lgkmcnt(1)
	v_cvt_pk_bf16_f32 v48, v154, v155
	s_waitcnt lgkmcnt(0)
	v_cvt_pk_bf16_f32 v49, v156, v157
	global_store_dwordx4 v[8:9], v[46:49], off
	s_waitcnt lgkmcnt(0)
	s_cbranch_scc1 .LBB0_19

; #define LAS __attribute__((address_space(3)))
; __device__ __forceinline__ void transpose_item(const float* W, int K, int N, bf16_t* WT, LAS float* scr, int item, int lane, const float* gk) {
;     const int nblk = N / 64, kb = item / nblk, nb = item % nblk, k0 = 64 * kb, n0 = 64 * nb;
;     f32x4 v[16];
; #pragma unroll
;     for (int i = 0; i < 16; ++i) { const int kk = 4 * i + (lane >> 4); v[i] = *(const f32x4*)(W + (size_t)(k0 + kk) * N + n0 + 4 * (lane & 15)); }
;     if (gk) {
; #pragma unroll
;         for (int i = 0; i < 16; ++i) v[i] *= gk[k0 + 4 * i + (lane >> 4)]; }
; #pragma unroll
;     for (int i = 0; i < 16; ++i) { LAS float* d = scr + (4 * i + (lane >> 4)) * 65 + 4 * (lane & 15); d[0] = v[i][0]; d[1] = v[i][1]; d[2] = v[i][2]; d[3] = v[i][3]; }
.LBB0_22:
	s_mul_hi_i32 s4, s19, 0x2aaaaaab
	s_lshr_b32 s5, s4, 31
	s_ashr_i32 s4, s4, 2
	s_add_i32 s4, s4, s5
	s_lshl_b32 s12, s4, 6
	s_mulk_i32 s4, 0xfa00
	s_add_i32 s4, s16, s4
	v_or_b32_e32 v48, s12, v13
	s_ashr_i32 s5, s4, 31
	v_or_b32_e32 v49, 4, v48
	v_or_b32_e32 v50, 8, v48
	v_or_b32_e32 v51, 12, v48
	v_or_b32_e32 v52, 16, v48
	v_or_b32_e32 v53, 20, v48
	v_or_b32_e32 v54, 24, v48
	v_or_b32_e32 v55, 28, v48
	v_or_b32_e32 v56, 32, v48
	v_or_b32_e32 v57, 36, v48
	v_or_b32_e32 v58, 40, v48
	v_or_b32_e32 v59, 44, v48
	v_lshl_add_u64 v[46:47], s[4:5], 2, v[6:7]
	v_or_b32_e32 v60, 48, v48
	v_or_b32_e32 v61, 52, v48
	v_or_b32_e32 v62, 56, v48
	v_or_b32_e32 v63, 60, v48
	v_add_u32_e32 v10, s4, v15
	v_mad_i64_i32 v[86:87], s[4:5], v48, s18, v[46:47]
	v_mad_i64_i32 v[88:89], s[4:5], v49, s18, v[46:47]
	v_mad_i64_i32 v[90:91], s[4:5], v50, s18, v[46:47]
	v_mad_i64_i32 v[92:93], s[4:5], v51, s18, v[46:47]
	v_mad_i64_i32 v[94:95], s[4:5], v52, s18, v[46:47]
	v_mad_i64_i32 v[96:97], s[4:5], v53, s18, v[46:47]
	v_mad_i64_i32 v[98:99], s[4:5], v54, s18, v[46:47]
	v_mad_i64_i32 v[100:101], s[4:5], v55, s18, v[46:47]
	v_mad_i64_i32 v[102:103], s[4:5], v56, s18, v[46:47]
	v_mad_i64_i32 v[104:105], s[4:5], v57, s18, v[46:47]
	v_mad_i64_i32 v[106:107], s[4:5], v58, s18, v[46:47]
	v_mad_i64_i32 v[108:109], s[4:5], v59, s18, v[46:47]
	v_mad_i64_i32 v[122:123], s[4:5], v60, s18, v[46:47]
	v_mad_i64_i32 v[124:125], s[4:5], v61, s18, v[46:47]
	v_mad_i64_i32 v[126:127], s[4:5], v62, s18, v[46:47]
	v_mad_i64_i32 v[128:129], s[4:5], v63, s18, v[46:47]
	global_load_dwordx4 v[46:49], v[86:87], off
	global_load_dwordx4 v[50:53], v[88:89], off
	global_load_dwordx4 v[54:57], v[90:91], off
	global_load_dwordx4 v[58:61], v[92:93], off
	global_load_dwordx4 v[62:65], v[94:95], off
	global_load_dwordx4 v[66:69], v[96:97], off
	global_load_dwordx4 v[70:73], v[98:99], off
	global_load_dwordx4 v[74:77], v[100:101], off
	global_load_dwordx4 v[78:81], v[102:103], off
	global_load_dwordx4 v[82:85], v[104:105], off
	global_load_dwordx4 v[86:89], v[106:107], off
	global_load_dwordx4 v[90:93], v[108:109], off
	global_load_dwordx4 v[94:97], v[122:123], off
	global_load_dwordx4 v[98:101], v[124:125], off
	s_nop 0
	global_load_dwordx4 v[102:105], v[126:127], off
	global_load_dwordx4 v[106:109], v[128:129], off
	s_ashr_i32 s13, s12, 31
	v_ashrrev_i32_e32 v11, 31, v10
	v_lshl_add_u64 v[8:9], s[12:13], 1, v[4:5]
	v_lshlrev_b64 v[130:131], 10, v[10:11]
	v_add_u32_e32 v110, 8, v10
	v_lshl_add_u64 v[122:123], v[8:9], 0, v[130:131]
	v_ashrrev_i32_e32 v111, 31, v110
	v_lshlrev_b64 v[110:111], 10, v[110:111]
	v_add_u32_e32 v112, 16, v10
	v_lshl_add_u64 v[110:111], v[8:9], 0, v[110:111]
	v_ashrrev_i32_e32 v113, 31, v112
	v_lshlrev_b64 v[112:113], 10, v[112:113]
	v_add_u32_e32 v114, 24, v10
	v_lshl_add_u64 v[112:113], v[8:9], 0, v[112:113]
	v_ashrrev_i32_e32 v115, 31, v114
	v_lshlrev_b64 v[114:115], 10, v[114:115]
	v_add_u32_e32 v116, 32, v10
	v_lshl_add_u64 v[114:115], v[8:9], 0, v[114:115]
	v_ashrrev_i32_e32 v117, 31, v116
	v_lshlrev_b64 v[116:117], 10, v[116:117]
	v_add_u32_e32 v118, 40, v10
	v_lshl_add_u64 v[116:117], v[8:9], 0, v[116:117]
	v_ashrrev_i32_e32 v119, 31, v118
	v_lshlrev_b64 v[118:119], 10, v[118:119]
	v_add_u32_e32 v120, 48, v10
	v_lshl_add_u64 v[118:119], v[8:9], 0, v[118:119]
	v_ashrrev_i32_e32 v121, 31, v120
	v_lshlrev_b64 v[120:121], 10, v[120:121]
	v_add_u32_e32 v10, 56, v10
	s_waitcnt vmcnt(15)
	ds_write2_b32 v14, v46, v47 offset1:1
	ds_write2_b32 v14, v48, v49 offset0:2 offset1:3
	s_waitcnt vmcnt(14)
	ds_write2_b32 v1, v50, v51 offset1:1
	ds_write2_b32 v3, v52, v53 offset1:1
	s_waitcnt vmcnt(13)
	ds_write2_b32 v17, v54, v55 offset1:1
	ds_write2_b32 v18, v56, v57 offset1:1
	s_waitcnt vmcnt(12)
	ds_write2_b32 v19, v58, v59 offset1:1
	ds_write2_b32 v20, v60, v61 offset1:1
	s_waitcnt vmcnt(11)
	ds_write2_b32 v21, v62, v63 offset1:1
	ds_write2_b32 v22, v64, v65 offset1:1
	s_waitcnt vmcnt(10)
	ds_write2_b32 v23, v66, v67 offset1:1
	ds_write2_b32 v24, v68, v69 offset1:1
	s_waitcnt vmcnt(9)
	ds_write2_b32 v25, v70, v71 offset1:1
	ds_write2_b32 v26, v72, v73 offset1:1
	s_waitcnt vmcnt(8)
	ds_write2_b32 v27, v74, v75 offset1:1
	ds_write2_b32 v28, v76, v77 offset1:1
	s_waitcnt vmcnt(7)
	ds_write2_b32 v29, v78, v79 offset1:1
	ds_write2_b32 v30, v80, v81 offset1:1
	s_waitcnt vmcnt(6)
	ds_write2_b32 v31, v82, v83 offset1:1
	ds_write2_b32 v32, v84, v85 offset1:1
	s_waitcnt vmcnt(5)
	ds_write2_b32 v33, v86, v87 offset1:1
	ds_write2_b32 v34, v88, v89 offset1:1
	s_waitcnt vmcnt(4)
	ds_write2_b32 v35, v90, v91 offset1:1
	ds_write2_b32 v36, v92, v93 offset1:1
	s_waitcnt vmcnt(3)
; #define LAS __attribute__((address_space(3)))
; __device__ __forceinline__ unsigned cvt_pk_bf16(float lo, float hi) { unsigned r; asm volatile("v_cvt_pk_bf16_f32 %0, %1, %2" : "=v"(r) : "v"(lo), "v"(hi)); return r; }
; __device__ __forceinline__ void transpose_item(const float* W, int K, int N, bf16_t* WT, LAS float* scr, int item, int lane, const float* gk) {
;     ...
;     for (int j = 0; j < 8; ++j) { const int n = (lane >> 3) + 8 * j; const LAS float* s = scr + (8 * c) * 65 + n;
;         u32x4 o; o.x = cvt_pk_bf16(s[0 * 65], s[1 * 65]); o.y = cvt_pk_bf16(s[2 * 65], s[3 * 65]); o.z = cvt_pk_bf16(s[4 * 65], s[5 * 65]); o.w = cvt_pk_bf16(s[6 * 65], s[7 * 65]);
;         *(u32x4*)(WT + (size_t)(n0 + n) * K + k0 + 8 * c) = o; }
	ds_write2_b32 v37, v94, v95 offset1:1
	ds_write2_b32 v38, v96, v97 offset1:1
	s_waitcnt vmcnt(2)
	ds_write2_b32 v39, v98, v99 offset1:1
	ds_write2_b32 v40, v100, v101 offset1:1
	s_waitcnt vmcnt(1)
	ds_write2_b32 v41, v102, v103 offset1:1
	ds_write2_b32 v42, v104, v105 offset1:1
	s_waitcnt vmcnt(0)
	ds_write2_b32 v43, v106, v107 offset1:1
	ds_write2_b32 v44, v108, v109 offset1:1
	s_waitcnt lgkmcnt(0)
	ds_read2_b32 v[52:53], v16 offset1:65
	ds_read2_b32 v[54:55], v16 offset0:130 offset1:195
	ds_read2_b32 v[56:57], v45 offset0:4 offset1:69
	ds_read2_b32 v[58:59], v45 offset0:134 offset1:199
	ds_read2_b32 v[60:61], v16 offset0:8 offset1:73
	ds_read2_b32 v[62:63], v16 offset0:138 offset1:203
	ds_read2_b32 v[64:65], v45 offset0:12 offset1:77
	ds_read2_b32 v[66:67], v45 offset0:142 offset1:207
	ds_read2_b32 v[68:69], v16 offset0:16 offset1:81
	ds_read2_b32 v[90:91], v16 offset0:146 offset1:211
	ds_read2_b32 v[100:101], v45 offset0:20 offset1:85
	ds_read2_b32 v[102:103], v45 offset0:150 offset1:215
	ds_read2_b32 v[104:105], v16 offset0:24 offset1:89
	ds_read2_b32 v[106:107], v16 offset0:154 offset1:219
	ds_read2_b32 v[108:109], v45 offset0:28 offset1:93
	ds_read2_b32 v[124:125], v45 offset0:158 offset1:223
	ds_read2_b32 v[126:127], v16 offset0:32 offset1:97
	ds_read2_b32 v[128:129], v16 offset0:162 offset1:227
	ds_read2_b32 v[130:131], v45 offset0:36 offset1:101
	ds_read2_b32 v[132:133], v45 offset0:166 offset1:231
	ds_read2_b32 v[134:135], v16 offset0:40 offset1:105
	ds_read2_b32 v[136:137], v16 offset0:170 offset1:235
	ds_read2_b32 v[138:139], v45 offset0:44 offset1:109
	ds_read2_b32 v[140:141], v45 offset0:174 offset1:239
	ds_read2_b32 v[142:143], v16 offset0:48 offset1:113
	ds_read2_b32 v[144:145], v16 offset0:178 offset1:243
	ds_read2_b32 v[146:147], v45 offset0:52 offset1:117
	ds_read2_b32 v[148:149], v45 offset0:182 offset1:247
	ds_read2_b32 v[150:151], v16 offset0:56 offset1:121
	ds_read2_b32 v[152:153], v16 offset0:186 offset1:251
	ds_read2_b32 v[154:155], v45 offset0:60 offset1:125
	ds_read2_b32 v[156:157], v45 offset0:190 offset1:255
	s_waitcnt lgkmcnt(15)
	v_cvt_pk_bf16_f32 v46, v52, v53
	s_waitcnt lgkmcnt(15)
	v_cvt_pk_bf16_f32 v47, v54, v55
	s_waitcnt lgkmcnt(15)
	v_cvt_pk_bf16_f32 v48, v56, v57
	s_waitcnt lgkmcnt(15)
	v_cvt_pk_bf16_f32 v49, v58, v59
	global_store_dwordx4 v[122:123], v[46:49], off
	v_lshl_add_u64 v[120:121], v[8:9], 0, v[120:121]
	v_ashrrev_i32_e32 v11, 31, v10
	s_waitcnt lgkmcnt(15)
	v_cvt_pk_bf16_f32 v46, v60, v61
	s_waitcnt lgkmcnt(15)
	v_cvt_pk_bf16_f32 v47, v62, v63
	s_waitcnt lgkmcnt(15)
	v_cvt_pk_bf16_f32 v48, v64, v65
	s_waitcnt lgkmcnt(15)
	v_cvt_pk_bf16_f32 v49, v66, v67
	global_store_dwordx4 v[110:111], v[46:49], off
	v_lshlrev_b64 v[10:11], 10, v[10:11]
	v_lshl_add_u64 v[8:9], v[8:9], 0, v[10:11]
	s_waitcnt lgkmcnt(15)
	v_cvt_pk_bf16_f32 v46, v68, v69
	s_waitcnt lgkmcnt(15)
	v_cvt_pk_bf16_f32 v47, v90, v91
	s_waitcnt lgkmcnt(15)
	v_cvt_pk_bf16_f32 v48, v100, v101
	s_waitcnt lgkmcnt(15)
	v_cvt_pk_bf16_f32 v49, v102, v103
	global_store_dwordx4 v[112:113], v[46:49], off
	s_add_i32 s19, s19, s26
	s_add_i32 s16, s16, s17
	s_waitcnt lgkmcnt(15)
	v_cvt_pk_bf16_f32 v46, v104, v105
	s_waitcnt lgkmcnt(15)
	v_cvt_pk_bf16_f32 v47, v106, v107
	s_waitcnt lgkmcnt(15)
	v_cvt_pk_bf16_f32 v48, v108, v109
	s_waitcnt lgkmcnt(15)
	v_cvt_pk_bf16_f32 v49, v124, v125
	global_store_dwordx4 v[114:115], v[46:49], off
	s_cmpk_lt_i32 s19, 0xc0
	s_waitcnt lgkmcnt(15)
	v_cvt_pk_bf16_f32 v46, v126, v127
	s_waitcnt lgkmcnt(14)
	v_cvt_pk_bf16_f32 v47, v128, v129
	s_waitcnt lgkmcnt(13)
	v_cvt_pk_bf16_f32 v48, v130, v131
	s_waitcnt lgkmcnt(12)
	v_cvt_pk_bf16_f32 v49, v132, v133
	global_store_dwordx4 v[116:117], v[46:49], off
	s_waitcnt lgkmcnt(11)
	s_nop 0
	v_cvt_pk_bf16_f32 v46, v134, v135
	s_waitcnt lgkmcnt(10)
	v_cvt_pk_bf16_f32 v47, v136, v137
	s_waitcnt lgkmcnt(9)
	v_cvt_pk_bf16_f32 v48, v138, v139
	s_waitcnt lgkmcnt(8)
	v_cvt_pk_bf16_f32 v49, v140, v141
	global_store_dwordx4 v[118:119], v[46:49], off
	s_waitcnt lgkmcnt(7)
	s_nop 0
	v_cvt_pk_bf16_f32 v46, v142, v143
	s_waitcnt lgkmcnt(6)
	v_cvt_pk_bf16_f32 v47, v144, v145
	s_waitcnt lgkmcnt(5)
	v_cvt_pk_bf16_f32 v48, v146, v147
	s_waitcnt lgkmcnt(4)
	v_cvt_pk_bf16_f32 v49, v148, v149
	global_store_dwordx4 v[120:121], v[46:49], off
	s_waitcnt lgkmcnt(3)
	s_nop 0
	v_cvt_pk_bf16_f32 v46, v150, v151
	s_waitcnt lgkmcnt(2)
	v_cvt_pk_bf16_f32 v47, v152, v153
	s_waitcnt lgkmcnt(1)
	v_cvt_pk_bf16_f32 v48, v154, v155
	s_waitcnt lgkmcnt(0)
	v_cvt_pk_bf16_f32 v49, v156, v157
	global_store_dwordx4 v[8:9], v[46:49], off
	s_waitcnt lgkmcnt(0)
	s_cbranch_scc1 .LBB0_22

; #define LAS __attribute__((address_space(3)))
; __device__ __forceinline__ void transpose_item(const float* W, int K, int N, bf16_t* WT, LAS float* scr, int item, int lane, const float* gk) {
;     const int nblk = N / 64, kb = item / nblk, nb = item % nblk, k0 = 64 * kb, n0 = 64 * nb;
;     f32x4 v[16];
; #pragma unroll
;     for (int i = 0; i < 16; ++i) { const int kk = 4 * i + (lane >> 4); v[i] = *(const f32x4*)(W + (size_t)(k0 + kk) * N + n0 + 4 * (lane & 15)); }
;     if (gk) {
; #pragma unroll
;         for (int i = 0; i < 16; ++i) v[i] *= gk[k0 + 4 * i + (lane >> 4)]; }
; #pragma unroll
;     for (int i = 0; i < 16; ++i) { LAS float* d = scr + (4 * i + (lane >> 4)) * 65 + 4 * (lane & 15); d[0] = v[i][0]; d[1] = v[i][1]; d[2] = v[i][2]; d[3] = v[i][3]; }
.LBB0_25:
	s_ashr_i32 s4, s18, 31
	s_lshr_b32 s4, s4, 27
	s_add_i32 s4, s18, s4
	s_ashr_i32 s4, s4, 5
	s_lshl_b32 s12, s4, 6
	s_lshl_b32 s4, s4, 11
	s_sub_i32 s4, s16, s4
	v_or_b32_e32 v8, s12, v13
	s_ashr_i32 s5, s4, 31
	v_ashrrev_i32_e32 v9, 31, v8
	v_or_b32_e32 v46, 4, v8
	v_or_b32_e32 v48, 8, v8
	v_or_b32_e32 v50, 12, v8
	v_or_b32_e32 v52, 16, v8
	v_or_b32_e32 v54, 20, v8
	v_or_b32_e32 v56, 24, v8
	v_or_b32_e32 v58, 28, v8
	v_or_b32_e32 v60, 32, v8
	v_or_b32_e32 v62, 36, v8
	v_or_b32_e32 v64, 40, v8
	v_or_b32_e32 v66, 44, v8
	v_or_b32_e32 v68, 48, v8
	v_or_b32_e32 v70, 52, v8
	v_or_b32_e32 v72, 56, v8
	v_or_b32_e32 v74, 60, v8
	v_lshl_add_u64 v[76:77], s[4:5], 2, v[0:1]
	v_lshlrev_b64 v[8:9], 13, v[8:9]
	v_ashrrev_i32_e32 v47, 31, v46
	v_ashrrev_i32_e32 v49, 31, v48
	v_ashrrev_i32_e32 v51, 31, v50
	v_ashrrev_i32_e32 v53, 31, v52
	v_ashrrev_i32_e32 v55, 31, v54
	v_ashrrev_i32_e32 v57, 31, v56
	v_ashrrev_i32_e32 v59, 31, v58
	v_ashrrev_i32_e32 v61, 31, v60
	v_ashrrev_i32_e32 v63, 31, v62
	v_ashrrev_i32_e32 v65, 31, v64
	v_ashrrev_i32_e32 v67, 31, v66
	v_ashrrev_i32_e32 v69, 31, v68
	v_ashrrev_i32_e32 v71, 31, v70
	v_ashrrev_i32_e32 v73, 31, v72
	v_ashrrev_i32_e32 v75, 31, v74
	v_lshl_add_u64 v[8:9], v[76:77], 0, v[8:9]
	v_lshlrev_b64 v[78:79], 13, v[46:47]
	v_lshlrev_b64 v[80:81], 13, v[48:49]
	v_lshlrev_b64 v[50:51], 13, v[50:51]
	v_lshlrev_b64 v[52:53], 13, v[52:53]
	v_lshlrev_b64 v[54:55], 13, v[54:55]
	v_lshlrev_b64 v[56:57], 13, v[56:57]
	v_lshlrev_b64 v[58:59], 13, v[58:59]
	v_lshlrev_b64 v[60:61], 13, v[60:61]
	v_lshlrev_b64 v[62:63], 13, v[62:63]
	v_lshlrev_b64 v[64:65], 13, v[64:65]
	v_lshlrev_b64 v[66:67], 13, v[66:67]
	v_lshlrev_b64 v[68:69], 13, v[68:69]
	v_lshlrev_b64 v[70:71], 13, v[70:71]
	v_lshlrev_b64 v[72:73], 13, v[72:73]
	v_lshlrev_b64 v[74:75], 13, v[74:75]
	global_load_dwordx4 v[46:49], v[8:9], off
	v_lshl_add_u64 v[8:9], v[76:77], 0, v[78:79]
	v_lshl_add_u64 v[90:91], v[76:77], 0, v[80:81]
	v_lshl_add_u64 v[92:93], v[76:77], 0, v[50:51]
	v_lshl_add_u64 v[94:95], v[76:77], 0, v[52:53]
	v_lshl_add_u64 v[96:97], v[76:77], 0, v[54:55]
	v_lshl_add_u64 v[98:99], v[76:77], 0, v[56:57]
	v_lshl_add_u64 v[100:101], v[76:77], 0, v[58:59]
	v_lshl_add_u64 v[102:103], v[76:77], 0, v[60:61]
	v_lshl_add_u64 v[104:105], v[76:77], 0, v[62:63]
	v_lshl_add_u64 v[106:107], v[76:77], 0, v[64:65]
	v_lshl_add_u64 v[124:125], v[76:77], 0, v[66:67]
	v_lshl_add_u64 v[126:127], v[76:77], 0, v[68:69]
	v_lshl_add_u64 v[128:129], v[76:77], 0, v[70:71]
	v_lshl_add_u64 v[130:131], v[76:77], 0, v[72:73]
	v_lshl_add_u64 v[132:133], v[76:77], 0, v[74:75]
	global_load_dwordx4 v[50:53], v[8:9], off
	global_load_dwordx4 v[54:57], v[90:91], off
	global_load_dwordx4 v[58:61], v[92:93], off
	global_load_dwordx4 v[62:65], v[94:95], off
	global_load_dwordx4 v[66:69], v[96:97], off
	global_load_dwordx4 v[70:73], v[98:99], off
	global_load_dwordx4 v[74:77], v[100:101], off
	global_load_dwordx4 v[78:81], v[102:103], off
	global_load_dwordx4 v[82:85], v[104:105], off
	global_load_dwordx4 v[86:89], v[106:107], off
	global_load_dwordx4 v[90:93], v[124:125], off
	global_load_dwordx4 v[94:97], v[126:127], off
	global_load_dwordx4 v[98:101], v[128:129], off
	s_nop 0
	global_load_dwordx4 v[102:105], v[130:131], off
	global_load_dwordx4 v[106:109], v[132:133], off
	v_add_u32_e32 v6, s4, v15
	s_ashr_i32 s13, s12, 31
	v_ashrrev_i32_e32 v7, 31, v6
	v_lshl_add_u64 v[2:3], s[12:13], 1, v[4:5]
	v_lshlrev_b64 v[122:123], 9, v[6:7]
	v_lshl_add_u64 v[8:9], v[2:3], 0, v[122:123]
	v_add_u32_e32 v110, 8, v6
	v_ashrrev_i32_e32 v111, 31, v110
	v_lshlrev_b64 v[110:111], 9, v[110:111]
	v_lshl_add_u64 v[110:111], v[2:3], 0, v[110:111]
	v_add_u32_e32 v112, 16, v6
	v_ashrrev_i32_e32 v113, 31, v112
	v_lshlrev_b64 v[112:113], 9, v[112:113]
	v_lshl_add_u64 v[112:113], v[2:3], 0, v[112:113]
	v_add_u32_e32 v114, 24, v6
	s_waitcnt vmcnt(15)
	ds_write2_b32 v14, v46, v47 offset1:1
	ds_write2_b32 v14, v48, v49 offset0:2 offset1:3
	s_waitcnt vmcnt(14)
	ds_write2_b32 v10, v50, v51 offset1:1
	ds_write2_b32 v11, v52, v53 offset1:1
	s_waitcnt vmcnt(13)
	ds_write2_b32 v17, v54, v55 offset1:1
	ds_write2_b32 v18, v56, v57 offset1:1
	s_waitcnt vmcnt(12)
	ds_write2_b32 v19, v58, v59 offset1:1
	ds_write2_b32 v20, v60, v61 offset1:1
	s_waitcnt vmcnt(11)
	ds_write2_b32 v21, v62, v63 offset1:1
	ds_write2_b32 v22, v64, v65 offset1:1
	s_waitcnt vmcnt(10)
	ds_write2_b32 v23, v66, v67 offset1:1
	ds_write2_b32 v24, v68, v69 offset1:1
	s_waitcnt vmcnt(9)
	ds_write2_b32 v25, v70, v71 offset1:1
	ds_write2_b32 v26, v72, v73 offset1:1
	s_waitcnt vmcnt(8)
	ds_write2_b32 v27, v74, v75 offset1:1
	ds_write2_b32 v28, v76, v77 offset1:1
	s_waitcnt vmcnt(7)
	ds_write2_b32 v29, v78, v79 offset1:1
	ds_write2_b32 v30, v80, v81 offset1:1
	s_waitcnt vmcnt(6)
	ds_write2_b32 v31, v82, v83 offset1:1
	ds_write2_b32 v32, v84, v85 offset1:1
	s_waitcnt vmcnt(5)
	ds_write2_b32 v33, v86, v87 offset1:1
	ds_write2_b32 v34, v88, v89 offset1:1
	s_waitcnt vmcnt(4)
	ds_write2_b32 v35, v90, v91 offset1:1
	ds_write2_b32 v36, v92, v93 offset1:1
	s_waitcnt vmcnt(3)
; #define LAS __attribute__((address_space(3)))
; __device__ __forceinline__ unsigned cvt_pk_bf16(float lo, float hi) { unsigned r; asm volatile("v_cvt_pk_bf16_f32 %0, %1, %2" : "=v"(r) : "v"(lo), "v"(hi)); return r; }
; __device__ __forceinline__ void transpose_item(const float* W, int K, int N, bf16_t* WT, LAS float* scr, int item, int lane, const float* gk) {
;     ...
;     for (int j = 0; j < 8; ++j) { const int n = (lane >> 3) + 8 * j; const LAS float* s = scr + (8 * c) * 65 + n;
;         u32x4 o; o.x = cvt_pk_bf16(s[0 * 65], s[1 * 65]); o.y = cvt_pk_bf16(s[2 * 65], s[3 * 65]); o.z = cvt_pk_bf16(s[4 * 65], s[5 * 65]); o.w = cvt_pk_bf16(s[6 * 65], s[7 * 65]);
;         *(u32x4*)(WT + (size_t)(n0 + n) * K + k0 + 8 * c) = o; }
	ds_write2_b32 v37, v94, v95 offset1:1
	ds_write2_b32 v38, v96, v97 offset1:1
	s_waitcnt vmcnt(2)
	ds_write2_b32 v39, v98, v99 offset1:1
	ds_write2_b32 v40, v100, v101 offset1:1
	s_waitcnt vmcnt(1)
	ds_write2_b32 v41, v102, v103 offset1:1
	ds_write2_b32 v42, v104, v105 offset1:1
	s_waitcnt vmcnt(0)
	ds_write2_b32 v43, v106, v107 offset1:1
	ds_write2_b32 v44, v108, v109 offset1:1
	s_waitcnt lgkmcnt(0)
	ds_read2_b32 v[52:53], v16 offset1:65
	ds_read2_b32 v[54:55], v16 offset0:130 offset1:195
	ds_read2_b32 v[56:57], v45 offset0:4 offset1:69
	ds_read2_b32 v[58:59], v45 offset0:134 offset1:199
	ds_read2_b32 v[60:61], v16 offset0:8 offset1:73
	ds_read2_b32 v[62:63], v16 offset0:138 offset1:203
	ds_read2_b32 v[64:65], v45 offset0:12 offset1:77
	ds_read2_b32 v[66:67], v45 offset0:142 offset1:207
	ds_read2_b32 v[68:69], v16 offset0:16 offset1:81
	ds_read2_b32 v[90:91], v16 offset0:146 offset1:211
	ds_read2_b32 v[100:101], v45 offset0:20 offset1:85
	ds_read2_b32 v[102:103], v45 offset0:150 offset1:215
	ds_read2_b32 v[104:105], v16 offset0:24 offset1:89
	ds_read2_b32 v[106:107], v16 offset0:154 offset1:219
	ds_read2_b32 v[108:109], v45 offset0:28 offset1:93
	ds_read2_b32 v[122:123], v45 offset0:158 offset1:223
	ds_read2_b32 v[124:125], v16 offset0:32 offset1:97
	ds_read2_b32 v[126:127], v16 offset0:162 offset1:227
	ds_read2_b32 v[128:129], v45 offset0:36 offset1:101
	ds_read2_b32 v[130:131], v45 offset0:166 offset1:231
	ds_read2_b32 v[132:133], v16 offset0:40 offset1:105
	ds_read2_b32 v[134:135], v16 offset0:170 offset1:235
	ds_read2_b32 v[136:137], v45 offset0:44 offset1:109
	ds_read2_b32 v[138:139], v45 offset0:174 offset1:239
	ds_read2_b32 v[140:141], v16 offset0:48 offset1:113
	ds_read2_b32 v[142:143], v16 offset0:178 offset1:243
	ds_read2_b32 v[144:145], v45 offset0:52 offset1:117
	ds_read2_b32 v[146:147], v45 offset0:182 offset1:247
	ds_read2_b32 v[148:149], v16 offset0:56 offset1:121
	ds_read2_b32 v[150:151], v16 offset0:186 offset1:251
	ds_read2_b32 v[152:153], v45 offset0:60 offset1:125
	ds_read2_b32 v[154:155], v45 offset0:190 offset1:255
	s_waitcnt lgkmcnt(15)
	v_cvt_pk_bf16_f32 v46, v52, v53
	s_waitcnt lgkmcnt(15)
	v_cvt_pk_bf16_f32 v47, v54, v55
	s_waitcnt lgkmcnt(15)
	v_cvt_pk_bf16_f32 v48, v56, v57
	s_waitcnt lgkmcnt(15)
	v_cvt_pk_bf16_f32 v49, v58, v59
	global_store_dwordx4 v[8:9], v[46:49], off
	v_ashrrev_i32_e32 v115, 31, v114
	v_lshlrev_b64 v[114:115], 9, v[114:115]
	s_waitcnt lgkmcnt(15)
	v_cvt_pk_bf16_f32 v46, v60, v61
	s_waitcnt lgkmcnt(15)
	v_cvt_pk_bf16_f32 v47, v62, v63
	s_waitcnt lgkmcnt(15)
	v_cvt_pk_bf16_f32 v48, v64, v65
	s_waitcnt lgkmcnt(15)
	v_cvt_pk_bf16_f32 v49, v66, v67
	global_store_dwordx4 v[110:111], v[46:49], off
	v_lshl_add_u64 v[114:115], v[2:3], 0, v[114:115]
	v_add_u32_e32 v116, 32, v6
	s_waitcnt lgkmcnt(15)
	v_cvt_pk_bf16_f32 v46, v68, v69
	s_waitcnt lgkmcnt(15)
	v_cvt_pk_bf16_f32 v47, v90, v91
	s_waitcnt lgkmcnt(15)
	v_cvt_pk_bf16_f32 v48, v100, v101
	s_waitcnt lgkmcnt(15)
	v_cvt_pk_bf16_f32 v49, v102, v103
	global_store_dwordx4 v[112:113], v[46:49], off
	v_ashrrev_i32_e32 v117, 31, v116
	v_lshlrev_b64 v[116:117], 9, v[116:117]
	s_waitcnt lgkmcnt(15)
	v_cvt_pk_bf16_f32 v46, v104, v105
	s_waitcnt lgkmcnt(15)
	v_cvt_pk_bf16_f32 v47, v106, v107
	s_waitcnt lgkmcnt(15)
	v_cvt_pk_bf16_f32 v48, v108, v109
	s_waitcnt lgkmcnt(15)
	v_cvt_pk_bf16_f32 v49, v122, v123
	global_store_dwordx4 v[114:115], v[46:49], off
	v_lshl_add_u64 v[116:117], v[2:3], 0, v[116:117]
	v_add_u32_e32 v118, 40, v6
	s_waitcnt lgkmcnt(15)
	v_cvt_pk_bf16_f32 v46, v124, v125
	s_waitcnt lgkmcnt(14)
	v_cvt_pk_bf16_f32 v47, v126, v127
	s_waitcnt lgkmcnt(13)
	v_cvt_pk_bf16_f32 v48, v128, v129
	s_waitcnt lgkmcnt(12)
	v_cvt_pk_bf16_f32 v49, v130, v131
	global_store_dwordx4 v[116:117], v[46:49], off
	v_ashrrev_i32_e32 v119, 31, v118
	v_lshlrev_b64 v[118:119], 9, v[118:119]
	s_waitcnt lgkmcnt(11)
	v_cvt_pk_bf16_f32 v46, v132, v133
	s_waitcnt lgkmcnt(10)
	v_cvt_pk_bf16_f32 v47, v134, v135
	s_waitcnt lgkmcnt(9)
	v_cvt_pk_bf16_f32 v48, v136, v137
	v_lshl_add_u64 v[118:119], v[2:3], 0, v[118:119]
	s_waitcnt lgkmcnt(8)
	v_cvt_pk_bf16_f32 v49, v138, v139
	v_add_u32_e32 v120, 48, v6
	global_store_dwordx4 v[118:119], v[46:49], off
	v_ashrrev_i32_e32 v121, 31, v120
	v_lshlrev_b64 v[120:121], 9, v[120:121]
	s_waitcnt lgkmcnt(7)
	v_cvt_pk_bf16_f32 v46, v140, v141
	s_waitcnt lgkmcnt(6)
	v_cvt_pk_bf16_f32 v47, v142, v143
	s_waitcnt lgkmcnt(5)
	v_cvt_pk_bf16_f32 v48, v144, v145
	v_add_u32_e32 v6, 56, v6
	v_lshl_add_u64 v[120:121], v[2:3], 0, v[120:121]
	s_waitcnt lgkmcnt(4)
	v_cvt_pk_bf16_f32 v49, v146, v147
	v_ashrrev_i32_e32 v7, 31, v6
	global_store_dwordx4 v[120:121], v[46:49], off
	v_lshlrev_b64 v[6:7], 9, v[6:7]
	v_lshl_add_u64 v[2:3], v[2:3], 0, v[6:7]
	s_waitcnt lgkmcnt(3)
	v_cvt_pk_bf16_f32 v46, v148, v149
	s_waitcnt lgkmcnt(2)
	v_cvt_pk_bf16_f32 v47, v150, v151
	s_waitcnt lgkmcnt(1)
	v_cvt_pk_bf16_f32 v48, v152, v153
	s_waitcnt lgkmcnt(0)
	v_cvt_pk_bf16_f32 v49, v154, v155
	global_store_dwordx4 v[2:3], v[46:49], off
	s_waitcnt lgkmcnt(0)
	s_add_i32 s18, s18, s26
	s_add_i32 s16, s16, s17
	s_cmpk_lt_i32 s18, 0x80
	s_cbranch_scc1 .LBB0_25

; #define PG8_STAGE(bufoff, gbase, voff) do { _Pragma("unroll") for (int _i = 0; _i < 2; ++_i) \
;         __builtin_amdgcn_global_load_lds((const unsigned*)((const char*)(gbase) + (voff)[_i]), (LAS unsigned*)(lds + (bufoff) + ldsw + _i * 8192), 16, 0, 0); } while (0)
; #define PG8_WAIT_V(n) asm volatile("s_waitcnt vmcnt(" #n ")" ::: "memory")
; #define PG8_BAR __builtin_amdgcn_s_barrier()
; template <class Epi>
; __device__ __forceinline__ void gemm_phase(LAS unsigned char* lds, const Gemm g, const StaticOrder& S, const Epi& E) {
;     ...
;     const int wid = __builtin_amdgcn_readfirstlane(tid >> 6), lane = tid & 63, wr = wid >> 2, wc = wid & 3, fr = lane & 15, fq = lane >> 4;
;     const int K = g.K, nt = K / BK;
;     unsigned voffA[2], voffB0[2], voffB1[2];
; #pragma unroll
;     for (int i = 0; i < 2; ++i) { int R, C; stage_rc(tid * 16 + i * 8192, R, C);
;         const int Rw = 64 * (R >> 5) + 16 * ((R >> 2) & 3) + 4 * ((R >> 4) & 1) + (R & 3);
;         const int Rf = 64 * (R >> 5) + 8 * ((R >> 2) & 3) + 4 * ((R >> 4) & 1) + (R & 3);
;         const int Rb0 = Epi::PERM ? (Epi::F32OUT ? Rf : Rw) : R, Rb1 = Epi::PERM ? (Epi::F32OUT ? Rf + 32 : Rw + 8) : R + HALF;
;         voffA[i] = (unsigned)(R * K + C) * 2u; voffB0[i] = (unsigned)(Rb0 * K + C) * 2u; voffB1[i] = (unsigned)(Rb1 * K + C) * 2u; }
;     const size_t kstep = (size_t)(BK * 2);
;     const size_t hstep = (size_t)HALF * K * 2;
;     const size_t tstep = 2 * hstep;
;     const unsigned ldsw = (unsigned)wid * 1024u;
;     const int aoff = lds_byte(wr * 64 + fr, fq * 8), boff = lds_byte(wc * 32 + fr, fq * 8);
;     ...
;     const char* cA = (const char*)g.A + (size_t)cur.pm * tstep; const char* cB = (const char*)g.Bt + (size_t)cur.pn * tstep;
;     PG8_STAGE(PG8_SB(0, 0), cB, voffB0); PG8_STAGE(PG8_SA(0, 0), cA, voffA); PG8_STAGE(PG8_SB(0, 1), cB, voffB1); PG8_STAGE(PG8_SA(0, 1), cA + hstep, voffA);
;     if (wr == 1) PG8_BAR;
;     PG8_WAIT_V(4); PG8_BAR;
;     PG8_STAGE(PG8_SB(1, 0), cB + kstep, voffB0); PG8_STAGE(PG8_SA(1, 0), cA + kstep, voffA); PG8_STAGE(PG8_SB(1, 1), cB + kstep, voffB1);
;     PG8_WAIT_V(6); PG8_BAR;
.LBB0_102:
	s_add_u32 s6, s4, 0xec00000
	s_mov_b64 s[8:9], 0x80
	s_addc_u32 s7, s5, 0
	s_add_i32 m0, s31, 0x18000
	v_lshl_add_u64 v[10:11], v[10:11], 0, s[8:9]
	s_waitcnt vmcnt(4)
	s_barrier
	global_load_lds_dwordx4 v[10:11], off
	v_lshl_add_u64 v[8:9], v[8:9], 0, s[8:9]
	s_add_i32 m0, s31, 0x1a000
	s_add_i32 s51, s31, 0x8000
	global_load_lds_dwordx4 v[8:9], off
	v_lshl_add_u64 v[6:7], v[6:7], 0, s[8:9]
	s_mov_b32 m0, s51
	s_add_i32 s52, s31, 0xa000
	global_load_lds_dwordx4 v[6:7], off
	v_lshl_add_u64 v[4:5], v[4:5], 0, s[8:9]
	s_mov_b32 m0, s52
	v_lshl_add_u64 v[0:1], v[0:1], 0, s[8:9]
	global_load_lds_dwordx4 v[4:5], off
	s_add_i32 m0, s31, 0x1c000
	v_and_b32_e32 v147, 15, v12
	global_load_lds_dwordx4 v[0:1], off
	v_lshl_add_u64 v[0:1], v[2:3], 0, s[8:9]
	s_add_i32 m0, s31, 0x1e000
	v_lshlrev_b32_e32 v2, 2, v12
	global_load_lds_dwordx4 v[0:1], off
	v_and_b32_e32 v0, 48, v12
	s_and_b32 s4, s12, 3
	s_lshl_b32 s5, s11, 13
	v_lshl_or_b32 v1, v147, 6, v0
	v_and_b32_e32 v2, 32, v2
	v_bitop3_b32 v3, v1, s5, v2 bitop3:0xde
	s_lshl_b32 s5, s4, 12
	s_sext_i32_i8 s58, s10
	v_bitop3_b32 v148, v1, s5, v2 bitop3:0xde
	s_lshl_b32 s10, s4, 6
	v_and_b32_e32 v1, 8, v12
	v_or3_b32 v157, s10, v1, v0
	v_lshlrev_b32_e32 v0, 15, v17
	v_and_b32_e32 v0, 0xffff0000, v0
	v_lshl_add_u32 v0, v16, 12, v0
	v_and_b32_e32 v1, 1, v17
	v_lshl_or_b32 v0, v1, 6, v0
	v_lshl_add_u32 v140, v18, 1, v0
	v_lshlrev_b32_e32 v0, 15, v13
	v_and_b32_e32 v0, 0xffff0000, v0
	s_waitcnt vmcnt(0)
	v_and_b32_e32 v149, 7, v12
	v_lshl_add_u32 v0, v14, 12, v0
	v_and_b32_e32 v1, 1, v13
	v_sub_u32_e32 v2, v149, v147
	v_lshl_or_b32 v0, v1, 6, v0
	s_add_i32 s56, 0, 0x10000
	s_add_i32 s57, 0, 0x14000
	s_lshl_b32 s53, s11, 6
	v_cmp_gt_u32_e64 s[4:5], 8, v147
	s_ashr_i32 s54, s20, 31
	s_mov_b32 s55, s20
	v_add_u32_e32 v150, 16, v2
	v_add_u32_e32 v151, 32, v2
	v_add_u32_e32 v152, 48, v2
	v_add_u32_e32 v153, 0x80, v2
	v_add_u32_e32 v154, 0x90, v2
	v_add_u32_e32 v155, 0xa0, v2
	v_add_u32_e32 v156, 0xb0, v2
	v_mov_b32_e32 v141, v135
	v_lshl_add_u32 v142, v15, 1, v0
	v_mov_b32_e32 v143, v135
	v_add_u32_e32 v158, s56, v148
	v_add_u32_e32 v159, 0, v3
	v_add_u32_e32 v160, s57, v148
	v_mov_b64_e32 v[144:145], 0x3ff
	s_barrier

; #define PG8_STAGE(bufoff, gbase, voff) do { _Pragma("unroll") for (int _i = 0; _i < 2; ++_i) \
;         __builtin_amdgcn_global_load_lds((const unsigned*)((const char*)(gbase) + (voff)[_i]), (LAS unsigned*)(lds + (bufoff) + ldsw + _i * 8192), 16, 0, 0); } while (0)
; #define PG8_LDA(dst, b, h) do { _Pragma("unroll") for (int m = 0; m < 4; ++m) _Pragma("unroll") for (int k = 0; k < 2; ++k) dst[m][k] = *(const LAS bf16x8*)(lds + PG8_SA(b, h) + aoff + m * 2048 + k * 1024); } while (0)
; #define PG8_LDB(dst, b, h) do { _Pragma("unroll") for (int n = 0; n < 2; ++n) _Pragma("unroll") for (int k = 0; k < 2; ++k) dst[n][k] = *(const LAS bf16x8*)(lds + PG8_SB(b, h) + boff + n * 2048 + k * 1024); } while (0)
; #define PG8_MMA(ai, bj, At, Bt) do { __builtin_amdgcn_s_setprio(1); _Pragma("unroll") for (int m = 0; m < 4; ++m) _Pragma("unroll") for (int n = 0; n < 2; ++n) _Pragma("unroll") for (int k = 0; k < 2; ++k) \
;         acc[ai][bj][m][n] = __builtin_amdgcn_mfma_f32_16x16x32_bf16(Bt[n][k], At[m][k], acc[ai][bj][m][n], 0, 0, 0); __builtin_amdgcn_s_setprio(0); } while (0)
; #define PG8_WAIT_L(n) asm volatile("s_waitcnt lgkmcnt(" #n ")" ::: "memory")
; #define PG8_BAR __builtin_amdgcn_s_barrier()
; #define PG8_SCHED __builtin_amdgcn_sched_barrier(0)
; template <class Epi>
; __device__ __forceinline__ void gemm_phase(LAS unsigned char* lds, const Gemm g, const StaticOrder& S, const Epi& E) {
;     ...
;         for (int t = 0; t < nt; t += 2) {
;             const bool last = (t == nt - 2);
;             const char* a1 = cA + (size_t)(t + 1) * kstep;
;             const char* a2 = last ? nA : cA + (size_t)(t + 2) * kstep; const char* b2 = last ? nB : cB + (size_t)(t + 2) * kstep;
;             const char* a3 = a2 + kstep; const char* b3 = b2 + kstep;
;             PG8_LDB(B0, 0, 0); PG8_SCHED; PG8_LDA(At, 0, 0); PG8_STAGE(PG8_SA(1, 1), a1 + hstep, voffA);
;             PG8_WAIT_L(8); PG8_BAR; PG8_WAIT_L(0); PG8_MMA(0, 0, At, B0); PG8_BAR; PG8_SCHED;
;             PG8_LDB(B1, 0, 1); PG8_STAGE(PG8_SB(0, 0), b2, voffB0);
;             PG8_BAR; PG8_WAIT_L(0); PG8_MMA(0, 1, At, B1); PG8_BAR;
;             PG8_LDA(At, 0, 1); PG8_STAGE(PG8_SA(0, 0), a2, voffA);
;             PG8_BAR; PG8_WAIT_L(0); PG8_MMA(1, 0, At, B0); PG8_BAR; PG8_SCHED;
.LBB0_107:
	ds_read_b128 v[162:165], v158
	ds_read_b128 v[166:169], v158 offset:1024
	ds_read_b128 v[170:173], v158 offset:2048
	ds_read_b128 v[174:177], v158 offset:3072
	s_add_u32 s33, s34, 0xfff80080
	s_addc_u32 s36, s35, -1
	s_cmp_eq_u32 s63, 28
	s_cselect_b32 s37, s13, s36
	s_cselect_b32 s36, s59, s33
	s_cselect_b32 s39, s11, s62
	s_cselect_b32 s38, s60, s61
	v_lshl_add_u64 v[212:213], s[34:35], 0, v[140:141]
	s_add_i32 m0, s31, 0xc000
	ds_read_b128 v[178:181], v159
	ds_read_b128 v[182:185], v159 offset:1024
	ds_read_b128 v[186:189], v159 offset:2048
	ds_read_b128 v[190:193], v159 offset:3072
	ds_read_b128 v[194:197], v159 offset:4096
	ds_read_b128 v[198:201], v159 offset:5120
	ds_read_b128 v[204:207], v159 offset:6144
	ds_read_b128 v[208:211], v159 offset:7168
	global_load_lds_dwordx4 v[212:213], off
	v_lshl_add_u64 v[212:213], s[34:35], 0, v[142:143]
	s_add_i32 m0, s31, 0xe000
	s_nop 0
	global_load_lds_dwordx4 v[212:213], off
	s_waitcnt lgkmcnt(8)
	s_barrier
	s_waitcnt lgkmcnt(0)
	v_mfma_f32_16x16x32_bf16 v[124:127], v[162:165], v[178:181], v[124:127]
	v_mfma_f32_16x16x32_bf16 v[120:123], v[170:173], v[178:181], v[120:123]
	v_mfma_f32_16x16x32_bf16 v[108:111], v[162:165], v[186:189], v[108:111]
	v_mfma_f32_16x16x32_bf16 v[104:107], v[170:173], v[186:189], v[104:107]
	v_mfma_f32_16x16x32_bf16 v[92:95], v[162:165], v[194:197], v[92:95]
	v_mfma_f32_16x16x32_bf16 v[88:91], v[170:173], v[194:197], v[88:91]
	v_mfma_f32_16x16x32_bf16 v[76:79], v[162:165], v[204:207], v[76:79]
	v_mfma_f32_16x16x32_bf16 v[72:75], v[170:173], v[204:207], v[72:75]
	v_mfma_f32_16x16x32_bf16 v[124:127], v[166:169], v[182:185], v[124:127]
	v_mfma_f32_16x16x32_bf16 v[120:123], v[174:177], v[182:185], v[120:123]
	v_mfma_f32_16x16x32_bf16 v[108:111], v[166:169], v[190:193], v[108:111]
	v_mfma_f32_16x16x32_bf16 v[104:107], v[174:177], v[190:193], v[104:107]
	v_mfma_f32_16x16x32_bf16 v[92:95], v[166:169], v[198:201], v[92:95]
	v_mfma_f32_16x16x32_bf16 v[88:91], v[174:177], v[198:201], v[88:91]
	v_mfma_f32_16x16x32_bf16 v[76:79], v[166:169], v[208:211], v[76:79]
	v_mfma_f32_16x16x32_bf16 v[72:75], v[174:177], v[208:211], v[72:75]
	s_barrier
	s_add_i32 s33, s56, s44
	v_lshl_add_u64 v[228:229], s[38:39], 0, v[134:135]
	s_mov_b32 m0, s33
	ds_read_b128 v[212:215], v160
	ds_read_b128 v[216:219], v160 offset:1024
	ds_read_b128 v[220:223], v160 offset:2048
	ds_read_b128 v[224:227], v160 offset:3072
	global_load_lds_dwordx4 v[228:229], off
	v_lshl_add_u64 v[230:231], s[38:39], 0, v[128:129]
	s_add_i32 m0, s33, 0x2000
	s_nop 0
	global_load_lds_dwordx4 v[230:231], off
	s_barrier
	s_waitcnt lgkmcnt(0)
	v_mfma_f32_16x16x32_bf16 v[116:119], v[212:215], v[178:181], v[116:119]
	v_mfma_f32_16x16x32_bf16 v[112:115], v[220:223], v[178:181], v[112:115]
	v_mfma_f32_16x16x32_bf16 v[100:103], v[212:215], v[186:189], v[100:103]
	v_mfma_f32_16x16x32_bf16 v[96:99], v[220:223], v[186:189], v[96:99]
	v_mfma_f32_16x16x32_bf16 v[84:87], v[212:215], v[194:197], v[84:87]
	v_mfma_f32_16x16x32_bf16 v[80:83], v[220:223], v[194:197], v[80:83]
	v_mfma_f32_16x16x32_bf16 v[68:71], v[212:215], v[204:207], v[68:71]
	v_mfma_f32_16x16x32_bf16 v[64:67], v[220:223], v[204:207], v[64:67]
	v_mfma_f32_16x16x32_bf16 v[116:119], v[216:219], v[182:185], v[116:119]
	v_mfma_f32_16x16x32_bf16 v[112:115], v[224:227], v[182:185], v[112:115]
	v_mfma_f32_16x16x32_bf16 v[100:103], v[216:219], v[190:193], v[100:103]
	v_mfma_f32_16x16x32_bf16 v[96:99], v[224:227], v[190:193], v[96:99]
	v_mfma_f32_16x16x32_bf16 v[84:87], v[216:219], v[198:201], v[84:87]
	v_mfma_f32_16x16x32_bf16 v[80:83], v[224:227], v[198:201], v[80:83]
	v_mfma_f32_16x16x32_bf16 v[68:71], v[216:219], v[208:211], v[68:71]
	v_mfma_f32_16x16x32_bf16 v[64:67], v[224:227], v[208:211], v[64:67]
	s_mov_b32 m0, s31
	v_lshl_add_u64 v[232:233], s[36:37], 0, v[138:139]
	s_barrier
	ds_read_b128 v[178:181], v159 offset:16384
	ds_read_b128 v[182:185], v159 offset:17408
	ds_read_b128 v[186:189], v159 offset:18432
	ds_read_b128 v[190:193], v159 offset:19456
	ds_read_b128 v[194:197], v159 offset:20480
	ds_read_b128 v[198:201], v159 offset:21504
	ds_read_b128 v[204:207], v159 offset:22528
	ds_read_b128 v[208:211], v159 offset:23552
	global_load_lds_dwordx4 v[232:233], off
	v_lshl_add_u64 v[234:235], s[36:37], 0, v[132:133]
	s_mov_b32 m0, s46
	s_nop 0
	global_load_lds_dwordx4 v[234:235], off
	s_barrier
	s_waitcnt lgkmcnt(0)
	v_mfma_f32_16x16x32_bf16 v[60:63], v[162:165], v[178:181], v[60:63]
	v_mfma_f32_16x16x32_bf16 v[56:59], v[170:173], v[178:181], v[56:59]
	v_mfma_f32_16x16x32_bf16 v[44:47], v[162:165], v[186:189], v[44:47]
	v_mfma_f32_16x16x32_bf16 v[40:43], v[170:173], v[186:189], v[40:43]
	v_mfma_f32_16x16x32_bf16 v[28:31], v[162:165], v[194:197], v[28:31]
	v_mfma_f32_16x16x32_bf16 v[24:27], v[170:173], v[194:197], v[24:27]
	v_mfma_f32_16x16x32_bf16 v[12:15], v[162:165], v[204:207], v[12:15]
	v_mfma_f32_16x16x32_bf16 v[8:11], v[170:173], v[204:207], v[8:11]
	v_mfma_f32_16x16x32_bf16 v[60:63], v[166:169], v[182:185], v[60:63]
	v_mfma_f32_16x16x32_bf16 v[56:59], v[174:177], v[182:185], v[56:59]
	v_mfma_f32_16x16x32_bf16 v[44:47], v[166:169], v[190:193], v[44:47]
	v_mfma_f32_16x16x32_bf16 v[40:43], v[174:177], v[190:193], v[40:43]
	v_mfma_f32_16x16x32_bf16 v[28:31], v[166:169], v[198:201], v[28:31]
	v_mfma_f32_16x16x32_bf16 v[24:27], v[174:177], v[198:201], v[24:27]
	v_mfma_f32_16x16x32_bf16 v[12:15], v[166:169], v[208:211], v[12:15]
	v_mfma_f32_16x16x32_bf16 v[8:11], v[174:177], v[208:211], v[8:11]
	s_barrier
; #define PG8_STAGE(bufoff, gbase, voff) do { _Pragma("unroll") for (int _i = 0; _i < 2; ++_i) \
;         __builtin_amdgcn_global_load_lds((const unsigned*)((const char*)(gbase) + (voff)[_i]), (LAS unsigned*)(lds + (bufoff) + ldsw + _i * 8192), 16, 0, 0); } while (0)
; #define PG8_LDA(dst, b, h) do { _Pragma("unroll") for (int m = 0; m < 4; ++m) _Pragma("unroll") for (int k = 0; k < 2; ++k) dst[m][k] = *(const LAS bf16x8*)(lds + PG8_SA(b, h) + aoff + m * 2048 + k * 1024); } while (0)
; #define PG8_LDB(dst, b, h) do { _Pragma("unroll") for (int n = 0; n < 2; ++n) _Pragma("unroll") for (int k = 0; k < 2; ++k) dst[n][k] = *(const LAS bf16x8*)(lds + PG8_SB(b, h) + boff + n * 2048 + k * 1024); } while (0)
; #define PG8_MMA(ai, bj, At, Bt) do { __builtin_amdgcn_s_setprio(1); _Pragma("unroll") for (int m = 0; m < 4; ++m) _Pragma("unroll") for (int n = 0; n < 2; ++n) _Pragma("unroll") for (int k = 0; k < 2; ++k) \
;         acc[ai][bj][m][n] = __builtin_amdgcn_mfma_f32_16x16x32_bf16(Bt[n][k], At[m][k], acc[ai][bj][m][n], 0, 0, 0); __builtin_amdgcn_s_setprio(0); } while (0)
; #define PG8_WAIT_V(n) asm volatile("s_waitcnt vmcnt(" #n ")" ::: "memory")
; #define PG8_WAIT_L(n) asm volatile("s_waitcnt lgkmcnt(" #n ")" ::: "memory")
; #define PG8_BAR __builtin_amdgcn_s_barrier()
; #define PG8_SCHED __builtin_amdgcn_sched_barrier(0)
; template <class Epi>
; __device__ __forceinline__ void gemm_phase(LAS unsigned char* lds, const Gemm g, const StaticOrder& S, const Epi& E) {
;     ...
;             PG8_STAGE(PG8_SB(0, 1), b2, voffB1);
;             PG8_WAIT_V(6); PG8_BAR; PG8_MMA(1, 1, At, B1); PG8_BAR;
;             PG8_LDB(B0, 1, 0); PG8_SCHED; PG8_LDA(At, 1, 0); PG8_STAGE(PG8_SA(0, 1), a2 + hstep, voffA);
;             PG8_WAIT_L(8); PG8_BAR; PG8_WAIT_L(0); PG8_MMA(0, 0, At, B0); PG8_BAR; PG8_SCHED;
;             PG8_LDB(B1, 1, 1); PG8_STAGE(PG8_SB(1, 0), b3, voffB0);
;             PG8_BAR; PG8_WAIT_L(0); PG8_MMA(0, 1, At, B1); PG8_BAR;
;             PG8_LDA(At, 1, 1); PG8_STAGE(PG8_SA(1, 0), a3, voffA);
;             PG8_BAR; PG8_WAIT_L(0); PG8_MMA(1, 0, At, B0); PG8_BAR; PG8_SCHED;
	s_add_i32 s33, s57, s44
	v_lshl_add_u64 v[236:237], s[38:39], 0, v[136:137]
	s_mov_b32 m0, s33
	v_lshl_add_u64 v[238:239], s[38:39], 0, v[130:131]
	global_load_lds_dwordx4 v[236:237], off
	s_add_i32 m0, s33, 0x2000
	s_nop 0
	global_load_lds_dwordx4 v[238:239], off
	s_add_i32 s33, 0, 0x18000
	v_add_u32_e32 v161, s33, v148
	ds_read_b128 v[162:165], v161
	ds_read_b128 v[166:169], v161 offset:1024
	ds_read_b128 v[170:173], v161 offset:2048
	ds_read_b128 v[174:177], v161 offset:3072
	s_waitcnt vmcnt(6)
	s_barrier
	v_mfma_f32_16x16x32_bf16 v[52:55], v[212:215], v[178:181], v[52:55]
	v_mfma_f32_16x16x32_bf16 v[48:51], v[220:223], v[178:181], v[48:51]
	v_mfma_f32_16x16x32_bf16 v[36:39], v[212:215], v[186:189], v[36:39]
	v_mfma_f32_16x16x32_bf16 v[32:35], v[220:223], v[186:189], v[32:35]
	v_mfma_f32_16x16x32_bf16 v[20:23], v[212:215], v[194:197], v[20:23]
	v_mfma_f32_16x16x32_bf16 v[16:19], v[220:223], v[194:197], v[16:19]
	v_mfma_f32_16x16x32_bf16 v[4:7], v[212:215], v[204:207], v[4:7]
	v_mfma_f32_16x16x32_bf16 v[0:3], v[220:223], v[204:207], v[0:3]
	v_mfma_f32_16x16x32_bf16 v[52:55], v[216:219], v[182:185], v[52:55]
	v_mfma_f32_16x16x32_bf16 v[48:51], v[224:227], v[182:185], v[48:51]
	v_mfma_f32_16x16x32_bf16 v[36:39], v[216:219], v[190:193], v[36:39]
	v_mfma_f32_16x16x32_bf16 v[32:35], v[224:227], v[190:193], v[32:35]
	v_mfma_f32_16x16x32_bf16 v[20:23], v[216:219], v[198:201], v[20:23]
	v_mfma_f32_16x16x32_bf16 v[16:19], v[224:227], v[198:201], v[16:19]
	v_mfma_f32_16x16x32_bf16 v[4:7], v[216:219], v[208:211], v[4:7]
	v_mfma_f32_16x16x32_bf16 v[0:3], v[224:227], v[208:211], v[0:3]
	s_barrier
	s_add_u32 s36, s36, 0x80000
	s_addc_u32 s37, s37, 0
	s_mov_b32 m0, s47
	v_lshl_add_u64 v[212:213], s[36:37], 0, v[138:139]
	ds_read_b128 v[178:181], v159 offset:32768
	ds_read_b128 v[182:185], v159 offset:33792
	ds_read_b128 v[186:189], v159 offset:34816
	ds_read_b128 v[190:193], v159 offset:35840
	ds_read_b128 v[194:197], v159 offset:36864
	ds_read_b128 v[198:201], v159 offset:37888
	ds_read_b128 v[204:207], v159 offset:38912
	ds_read_b128 v[208:211], v159 offset:39936
	global_load_lds_dwordx4 v[212:213], off
	v_lshl_add_u64 v[212:213], s[36:37], 0, v[132:133]
	s_mov_b32 m0, s48
	s_nop 0
	global_load_lds_dwordx4 v[212:213], off
	s_waitcnt lgkmcnt(8)
	s_barrier
	s_waitcnt lgkmcnt(0)
	v_mfma_f32_16x16x32_bf16 v[124:127], v[162:165], v[178:181], v[124:127]
	v_mfma_f32_16x16x32_bf16 v[120:123], v[170:173], v[178:181], v[120:123]
	v_mfma_f32_16x16x32_bf16 v[108:111], v[162:165], v[186:189], v[108:111]
	v_mfma_f32_16x16x32_bf16 v[104:107], v[170:173], v[186:189], v[104:107]
	v_mfma_f32_16x16x32_bf16 v[92:95], v[162:165], v[194:197], v[92:95]
	v_mfma_f32_16x16x32_bf16 v[88:91], v[170:173], v[194:197], v[88:91]
	v_mfma_f32_16x16x32_bf16 v[76:79], v[162:165], v[204:207], v[76:79]
	v_mfma_f32_16x16x32_bf16 v[72:75], v[170:173], v[204:207], v[72:75]
	v_mfma_f32_16x16x32_bf16 v[124:127], v[166:169], v[182:185], v[124:127]
	v_mfma_f32_16x16x32_bf16 v[120:123], v[174:177], v[182:185], v[120:123]
	v_mfma_f32_16x16x32_bf16 v[108:111], v[166:169], v[190:193], v[108:111]
	v_mfma_f32_16x16x32_bf16 v[104:107], v[174:177], v[190:193], v[104:107]
	v_mfma_f32_16x16x32_bf16 v[92:95], v[166:169], v[198:201], v[92:95]
	v_mfma_f32_16x16x32_bf16 v[88:91], v[174:177], v[198:201], v[88:91]
	v_mfma_f32_16x16x32_bf16 v[76:79], v[166:169], v[208:211], v[76:79]
	v_mfma_f32_16x16x32_bf16 v[72:75], v[174:177], v[208:211], v[72:75]
	s_barrier
	s_add_i32 s36, 0, 0x1c000
	s_add_i32 s33, s33, s44
	v_add_u32_e32 v161, s36, v148
	v_lshl_add_u64 v[228:229], v[228:229], 0, s[8:9]
	s_mov_b32 m0, s33
	ds_read_b128 v[212:215], v161
	ds_read_b128 v[216:219], v161 offset:1024
	ds_read_b128 v[220:223], v161 offset:2048
	ds_read_b128 v[224:227], v161 offset:3072
	global_load_lds_dwordx4 v[228:229], off
	v_lshl_add_u64 v[228:229], v[230:231], 0, s[8:9]
	s_add_i32 m0, s33, 0x2000
	s_nop 0
	global_load_lds_dwordx4 v[228:229], off
	s_barrier
	s_waitcnt lgkmcnt(0)
	v_mfma_f32_16x16x32_bf16 v[116:119], v[212:215], v[178:181], v[116:119]
	v_mfma_f32_16x16x32_bf16 v[112:115], v[220:223], v[178:181], v[112:115]
	v_mfma_f32_16x16x32_bf16 v[100:103], v[212:215], v[186:189], v[100:103]
	v_mfma_f32_16x16x32_bf16 v[96:99], v[220:223], v[186:189], v[96:99]
	v_mfma_f32_16x16x32_bf16 v[84:87], v[212:215], v[194:197], v[84:87]
	v_mfma_f32_16x16x32_bf16 v[80:83], v[220:223], v[194:197], v[80:83]
	v_mfma_f32_16x16x32_bf16 v[68:71], v[212:215], v[204:207], v[68:71]
	v_mfma_f32_16x16x32_bf16 v[64:67], v[220:223], v[204:207], v[64:67]
	v_mfma_f32_16x16x32_bf16 v[116:119], v[216:219], v[182:185], v[116:119]
	v_mfma_f32_16x16x32_bf16 v[112:115], v[224:227], v[182:185], v[112:115]
	v_mfma_f32_16x16x32_bf16 v[100:103], v[216:219], v[190:193], v[100:103]
	v_mfma_f32_16x16x32_bf16 v[96:99], v[224:227], v[190:193], v[96:99]
	v_mfma_f32_16x16x32_bf16 v[84:87], v[216:219], v[198:201], v[84:87]
	v_mfma_f32_16x16x32_bf16 v[80:83], v[224:227], v[198:201], v[80:83]
	v_mfma_f32_16x16x32_bf16 v[68:71], v[216:219], v[208:211], v[68:71]
	v_mfma_f32_16x16x32_bf16 v[64:67], v[224:227], v[208:211], v[64:67]
	s_mov_b32 m0, s51
	v_lshl_add_u64 v[228:229], v[232:233], 0, s[8:9]
	s_barrier
	ds_read_b128 v[178:181], v159 offset:49152
	ds_read_b128 v[182:185], v159 offset:50176
	ds_read_b128 v[186:189], v159 offset:51200
	ds_read_b128 v[190:193], v159 offset:52224
	ds_read_b128 v[194:197], v159 offset:53248
	ds_read_b128 v[198:201], v159 offset:54272
	ds_read_b128 v[204:207], v159 offset:55296
	ds_read_b128 v[208:211], v159 offset:56320
	global_load_lds_dwordx4 v[228:229], off
	v_lshl_add_u64 v[228:229], v[234:235], 0, s[8:9]
	s_mov_b32 m0, s52
	s_nop 0
	global_load_lds_dwordx4 v[228:229], off
	s_barrier
; __device__ __forceinline__ unsigned cvt_pk_bf16(float lo, float hi) { unsigned r; asm volatile("v_cvt_pk_bf16_f32 %0, %1, %2" : "=v"(r) : "v"(lo), "v"(hi)); return r; }
; #define PG8_STAGE(bufoff, gbase, voff) do { _Pragma("unroll") for (int _i = 0; _i < 2; ++_i) \
;         __builtin_amdgcn_global_load_lds((const unsigned*)((const char*)(gbase) + (voff)[_i]), (LAS unsigned*)(lds + (bufoff) + ldsw + _i * 8192), 16, 0, 0); } while (0)
; #define PG8_LDA(dst, b, h) do { _Pragma("unroll") for (int m = 0; m < 4; ++m) _Pragma("unroll") for (int k = 0; k < 2; ++k) dst[m][k] = *(const LAS bf16x8*)(lds + PG8_SA(b, h) + aoff + m * 2048 + k * 1024); } while (0)
; #define PG8_WAIT_V(n) asm volatile("s_waitcnt vmcnt(" #n ")" ::: "memory")
;     __device__ __forceinline__ void operator()(const f32x4 (&acc)[2][2][4][2], const Unit& u, int wr, int wc, int fr, int fq) const {
;     ...
;             for (int m = 0; m < 4; ++m) { const int row = row0 + ai * HALF + m * 16;
;                 const float rs = ssin ? __builtin_amdgcn_rsqf(ssin[row] * (1.f / D) + EPS) : 1.0f; float sq = 0.f; u32x4 w[2];
; #pragma unroll
;                 for (int bj = 0; bj < 2; ++bj) { f32x4 v0 = acc[ai][bj][m][0] * rs, v1 = acc[ai][bj][m][1] * rs;
;                     if (ACT == 1) {
; #pragma unroll
;                         for (int j = 0; j < 4; ++j) { const float a = fmaxf(v0[j], 0.f), b = fmaxf(v1[j], 0.f); v0[j] = a * a; v1[j] = b * b; } }
;                     sq += (v0[0] * v0[0] + v0[1] * v0[1]) + (v0[2] * v0[2] + v0[3] * v0[3]) + (v1[0] * v1[0] + v1[1] * v1[1]) + (v1[2] * v1[2] + v1[3] * v1[3]);
;                     w[bj].x = cvt_pk_bf16(v0[0], v0[1]); w[bj].y = cvt_pk_bf16(v0[2], v0[3]); w[bj].z = cvt_pk_bf16(v1[0], v1[1]); w[bj].w = cvt_pk_bf16(v1[2], v1[3]); }
;                 store_pair_lines(O, ldc, row, fr, col0, w[0], w[1]);
; template <class Epi>
; __device__ __forceinline__ void gemm_phase(LAS unsigned char* lds, const Gemm g, const StaticOrder& S, const Epi& E) {
;     ...
;             PG8_BAR; PG8_WAIT_L(0); PG8_MMA(0, 1, At, B1); PG8_BAR;
;             PG8_LDA(At, 1, 1); PG8_STAGE(PG8_SA(1, 0), a3, voffA);
;             PG8_BAR; PG8_WAIT_L(0); PG8_MMA(1, 0, At, B0); PG8_BAR; PG8_SCHED;
;             PG8_STAGE(PG8_SB(1, 1), b3, voffB1);
;             PG8_WAIT_V(6); PG8_BAR; PG8_MMA(1, 1, At, B1); PG8_BAR;
;         }
;         E(acc, cur, wr, wc, fr, fq);
	s_waitcnt lgkmcnt(0)
	v_mfma_f32_16x16x32_bf16 v[60:63], v[162:165], v[178:181], v[60:63]
	v_mfma_f32_16x16x32_bf16 v[56:59], v[170:173], v[178:181], v[56:59]
	v_mfma_f32_16x16x32_bf16 v[44:47], v[162:165], v[186:189], v[44:47]
	v_mfma_f32_16x16x32_bf16 v[40:43], v[170:173], v[186:189], v[40:43]
	v_mfma_f32_16x16x32_bf16 v[28:31], v[162:165], v[194:197], v[28:31]
	v_mfma_f32_16x16x32_bf16 v[24:27], v[170:173], v[194:197], v[24:27]
	v_mfma_f32_16x16x32_bf16 v[12:15], v[162:165], v[204:207], v[12:15]
	v_mfma_f32_16x16x32_bf16 v[8:11], v[170:173], v[204:207], v[8:11]
	v_mfma_f32_16x16x32_bf16 v[60:63], v[166:169], v[182:185], v[60:63]
	v_mfma_f32_16x16x32_bf16 v[56:59], v[174:177], v[182:185], v[56:59]
	v_mfma_f32_16x16x32_bf16 v[44:47], v[166:169], v[190:193], v[44:47]
	v_mfma_f32_16x16x32_bf16 v[40:43], v[174:177], v[190:193], v[40:43]
	v_mfma_f32_16x16x32_bf16 v[28:31], v[166:169], v[198:201], v[28:31]
	v_mfma_f32_16x16x32_bf16 v[24:27], v[174:177], v[198:201], v[24:27]
	v_mfma_f32_16x16x32_bf16 v[12:15], v[166:169], v[208:211], v[12:15]
	v_mfma_f32_16x16x32_bf16 v[8:11], v[174:177], v[208:211], v[8:11]
	s_barrier
	s_add_i32 s33, s36, s44
	v_lshl_add_u64 v[162:163], v[236:237], 0, s[8:9]
	s_mov_b32 m0, s33
	s_nop 0
	global_load_lds_dwordx4 v[162:163], off
	v_lshl_add_u64 v[162:163], v[238:239], 0, s[8:9]
	s_add_i32 m0, s33, 0x2000
	s_nop 0
	global_load_lds_dwordx4 v[162:163], off
	s_waitcnt vmcnt(6)
	s_barrier
	v_mfma_f32_16x16x32_bf16 v[52:55], v[212:215], v[178:181], v[52:55]
	v_mfma_f32_16x16x32_bf16 v[48:51], v[220:223], v[178:181], v[48:51]
	v_mfma_f32_16x16x32_bf16 v[36:39], v[212:215], v[186:189], v[36:39]
	v_mfma_f32_16x16x32_bf16 v[32:35], v[220:223], v[186:189], v[32:35]
	v_mfma_f32_16x16x32_bf16 v[20:23], v[212:215], v[194:197], v[20:23]
	v_mfma_f32_16x16x32_bf16 v[16:19], v[220:223], v[194:197], v[16:19]
	v_mfma_f32_16x16x32_bf16 v[4:7], v[212:215], v[204:207], v[4:7]
	v_mfma_f32_16x16x32_bf16 v[0:3], v[220:223], v[204:207], v[0:3]
	v_mfma_f32_16x16x32_bf16 v[52:55], v[216:219], v[182:185], v[52:55]
	v_mfma_f32_16x16x32_bf16 v[48:51], v[224:227], v[182:185], v[48:51]
	v_mfma_f32_16x16x32_bf16 v[36:39], v[216:219], v[190:193], v[36:39]
	v_mfma_f32_16x16x32_bf16 v[32:35], v[224:227], v[190:193], v[32:35]
	v_mfma_f32_16x16x32_bf16 v[20:23], v[216:219], v[198:201], v[20:23]
	v_mfma_f32_16x16x32_bf16 v[16:19], v[224:227], v[198:201], v[16:19]
	v_mfma_f32_16x16x32_bf16 v[4:7], v[216:219], v[208:211], v[4:7]
	v_mfma_f32_16x16x32_bf16 v[0:3], v[224:227], v[208:211], v[0:3]
	s_add_i32 s63, s63, 2
	s_add_u32 s34, s34, 0x100
	s_addc_u32 s35, s35, 0
	s_add_u32 s61, s61, 0x100
	s_addc_u32 s62, s62, 0
	s_cmp_gt_u32 s63, 29
	s_barrier
	s_cbranch_scc0 .LBB0_107
	s_lshl_b32 s11, s30, 8
	v_cvt_pk_bf16_f32 v124, v124, v125
	v_cvt_pk_bf16_f32 v125, v126, v127
	v_cvt_pk_bf16_f32 v120, v120, v121
	v_cvt_pk_bf16_f32 v121, v122, v123
	v_cvt_pk_bf16_f32 v122, v116, v117
	v_cvt_pk_bf16_f32 v119, v118, v119
	s_add_i32 s11, s11, s53
	v_cvt_pk_bf16_f32 v112, v112, v113
	v_cvt_pk_bf16_f32 v113, v114, v115
	v_mov_b32_dpp v118, v124 row_ror:8 row_mask:0xf bank_mask:0xf
	v_mov_b32_dpp v123, v125 row_ror:8 row_mask:0xf bank_mask:0xf
	v_mov_b32_dpp v114, v122 row_ror:8 row_mask:0xf bank_mask:0xf
	v_cndmask_b32_e64 v118, v122, v118, s[4:5]
	v_or_b32_e32 v122, s11, v149
	v_lshl_or_b32 v162, s58, 8, v157
	v_mov_b32_dpp v126, v120 row_ror:8 row_mask:0xf bank_mask:0xf
	v_mov_b32_dpp v127, v121 row_ror:8 row_mask:0xf bank_mask:0xf
	v_mov_b32_dpp v115, v119 row_ror:8 row_mask:0xf bank_mask:0xf
	v_mov_b32_dpp v116, v112 row_ror:8 row_mask:0xf bank_mask:0xf
	v_mov_b32_dpp v117, v113 row_ror:8 row_mask:0xf bank_mask:0xf
	v_cndmask_b32_e64 v119, v119, v123, s[4:5]
	v_ashrrev_i32_e32 v123, 31, v122
	v_ashrrev_i32_e32 v163, 31, v162
	v_cndmask_b32_e64 v116, v116, v120, s[4:5]
	v_cndmask_b32_e64 v117, v117, v121, s[4:5]
	v_cndmask_b32_e64 v120, v112, v126, s[4:5]
	v_cndmask_b32_e64 v121, v113, v127, s[4:5]
	v_lshlrev_b64 v[112:113], 13, v[122:123]
	v_cndmask_b32_e64 v114, v114, v124, s[4:5]
	v_cndmask_b32_e64 v115, v115, v125, s[4:5]
	v_lshl_add_u64 v[124:125], s[6:7], 0, v[112:113]
	v_lshlrev_b64 v[112:113], 1, v[162:163]
	v_lshl_add_u64 v[124:125], v[124:125], 0, v[112:113]
	global_store_dwordx4 v[124:125], v[114:117], off
	v_or_b32_e32 v161, s11, v147
	s_mov_b32 s58, s10
	v_or_b32_e32 v114, 8, v122
	v_ashrrev_i32_e32 v115, 31, v114
	v_lshlrev_b64 v[114:115], 13, v[114:115]
	v_lshl_add_u64 v[114:115], s[6:7], 0, v[114:115]
	v_lshl_add_u64 v[114:115], v[114:115], 0, v[112:113]
	global_store_dwordx4 v[114:115], v[118:121], off
	v_cvt_pk_bf16_f32 v108, v108, v109
	v_cvt_pk_bf16_f32 v109, v110, v111
	v_cvt_pk_bf16_f32 v104, v104, v105
	v_cvt_pk_bf16_f32 v105, v106, v107
	v_cvt_pk_bf16_f32 v100, v100, v101
	v_cvt_pk_bf16_f32 v101, v102, v103
	v_cvt_pk_bf16_f32 v102, v96, v97
	v_cvt_pk_bf16_f32 v103, v98, v99
	v_mov_b32_e32 v98, 0
	v_mov_b32_dpp v98, v102 row_ror:8 row_mask:0xf bank_mask:0xf
	v_mov_b32_dpp v110, v104 row_ror:8 row_mask:0xf bank_mask:0xf
	v_mov_b32_dpp v99, v103 row_ror:8 row_mask:0xf bank_mask:0xf
	v_cndmask_b32_e64 v98, v98, v104, s[4:5]
	v_add_u32_e32 v104, v150, v161
	v_mov_b32_dpp v111, v105 row_ror:8 row_mask:0xf bank_mask:0xf
	v_cndmask_b32_e64 v99, v99, v105, s[4:5]
	v_ashrrev_i32_e32 v105, 31, v104
	v_lshlrev_b64 v[104:105], 13, v[104:105]
	v_mov_b32_dpp v96, v100 row_ror:8 row_mask:0xf bank_mask:0xf
	v_mov_b32_dpp v97, v101 row_ror:8 row_mask:0xf bank_mask:0xf
	v_lshl_add_u64 v[104:105], s[6:7], 0, v[104:105]
	v_cndmask_b32_e64 v96, v96, v108, s[4:5]
	v_cndmask_b32_e64 v97, v97, v109, s[4:5]
	v_lshl_add_u64 v[104:105], v[104:105], 0, v[112:113]
; __device__ __forceinline__ unsigned cvt_pk_bf16(float lo, float hi) { unsigned r; asm volatile("v_cvt_pk_bf16_f32 %0, %1, %2" : "=v"(r) : "v"(lo), "v"(hi)); return r; }
; __device__ __forceinline__ unsigned dpp_ror8(unsigned x) { return (unsigned)__builtin_amdgcn_update_dpp(0, (int)x, 0x128, 0xf, 0xf, false); }
; __device__ __forceinline__ void store_pair_lines(bf16_t* O, int ldc, int row, int fr, int col0, u32x4 wA, u32x4 wB) {
;     const u32x4 sA = {dpp_ror8(wA.x), dpp_ror8(wA.y), dpp_ror8(wA.z), dpp_ror8(wA.w)}, sB = {dpp_ror8(wB.x), dpp_ror8(wB.y), dpp_ror8(wB.z), dpp_ror8(wB.w)};
;     const bool lo = fr < 8;
;     const u32x4 o1 = lo ? wA : sB, o2 = lo ? sA : wB;
;     const int r1 = row - fr + (fr & 7), cb = col0 + (lo ? 0 : 8);
;     *(u32x4*)(O + (size_t)r1 * ldc + cb) = o1;
;     *(u32x4*)(O + (size_t)(r1 + 8) * ldc + cb) = o2;
; }
;     __device__ __forceinline__ void operator()(const f32x4 (&acc)[2][2][4][2], const Unit& u, int wr, int wc, int fr, int fq) const {
;     ...
;             for (int m = 0; m < 4; ++m) { const int row = row0 + ai * HALF + m * 16;
;                 const float rs = ssin ? __builtin_amdgcn_rsqf(ssin[row] * (1.f / D) + EPS) : 1.0f; float sq = 0.f; u32x4 w[2];
; #pragma unroll
;                 for (int bj = 0; bj < 2; ++bj) { f32x4 v0 = acc[ai][bj][m][0] * rs, v1 = acc[ai][bj][m][1] * rs;
;                     if (ACT == 1) {
; #pragma unroll
;                         for (int j = 0; j < 4; ++j) { const float a = fmaxf(v0[j], 0.f), b = fmaxf(v1[j], 0.f); v0[j] = a * a; v1[j] = b * b; } }
;                     sq += (v0[0] * v0[0] + v0[1] * v0[1]) + (v0[2] * v0[2] + v0[3] * v0[3]) + (v1[0] * v1[0] + v1[1] * v1[1]) + (v1[2] * v1[2] + v1[3] * v1[3]);
;                     w[bj].x = cvt_pk_bf16(v0[0], v0[1]); w[bj].y = cvt_pk_bf16(v0[2], v0[3]); w[bj].z = cvt_pk_bf16(v1[0], v1[1]); w[bj].w = cvt_pk_bf16(v1[2], v1[3]); }
;                 store_pair_lines(O, ldc, row, fr, col0, w[0], w[1]);
	v_mov_b32_dpp v106, v108 row_ror:8 row_mask:0xf bank_mask:0xf
	v_mov_b32_dpp v107, v109 row_ror:8 row_mask:0xf bank_mask:0xf
	global_store_dwordx4 v[104:105], v[96:99], off
	v_cndmask_b32_e64 v100, v100, v106, s[4:5]
	v_cndmask_b32_e64 v101, v101, v107, s[4:5]
	v_add_co_u32_e32 v96, vcc, s49, v104
	v_cndmask_b32_e64 v102, v102, v110, s[4:5]
	v_cndmask_b32_e64 v103, v103, v111, s[4:5]
	v_addc_co_u32_e32 v97, vcc, 0, v105, vcc
	global_store_dwordx4 v[96:97], v[100:103], off
	v_cvt_pk_bf16_f32 v92, v92, v93
	v_cvt_pk_bf16_f32 v93, v94, v95
	v_cvt_pk_bf16_f32 v88, v88, v89
	v_cvt_pk_bf16_f32 v89, v90, v91
	v_cvt_pk_bf16_f32 v84, v84, v85
	v_cvt_pk_bf16_f32 v85, v86, v87
	v_cvt_pk_bf16_f32 v86, v80, v81
	v_cvt_pk_bf16_f32 v87, v82, v83
	v_mov_b32_e32 v82, 0
	v_mov_b32_dpp v82, v86 row_ror:8 row_mask:0xf bank_mask:0xf
	v_mov_b32_dpp v94, v88 row_ror:8 row_mask:0xf bank_mask:0xf
	v_mov_b32_dpp v83, v87 row_ror:8 row_mask:0xf bank_mask:0xf
	v_cndmask_b32_e64 v82, v82, v88, s[4:5]
	v_add_u32_e32 v88, v151, v161
	v_mov_b32_dpp v95, v89 row_ror:8 row_mask:0xf bank_mask:0xf
	v_cndmask_b32_e64 v83, v83, v89, s[4:5]
	v_ashrrev_i32_e32 v89, 31, v88
	v_lshlrev_b64 v[88:89], 13, v[88:89]
	v_mov_b32_dpp v80, v84 row_ror:8 row_mask:0xf bank_mask:0xf
	v_mov_b32_dpp v81, v85 row_ror:8 row_mask:0xf bank_mask:0xf
	v_lshl_add_u64 v[88:89], s[6:7], 0, v[88:89]
	v_cndmask_b32_e64 v80, v80, v92, s[4:5]
	v_cndmask_b32_e64 v81, v81, v93, s[4:5]
	v_lshl_add_u64 v[88:89], v[88:89], 0, v[112:113]
	v_mov_b32_dpp v90, v92 row_ror:8 row_mask:0xf bank_mask:0xf
	v_mov_b32_dpp v91, v93 row_ror:8 row_mask:0xf bank_mask:0xf
	global_store_dwordx4 v[88:89], v[80:83], off
	v_cndmask_b32_e64 v84, v84, v90, s[4:5]
	v_cndmask_b32_e64 v85, v85, v91, s[4:5]
	v_add_co_u32_e32 v80, vcc, s49, v88
	v_cndmask_b32_e64 v86, v86, v94, s[4:5]
	v_cndmask_b32_e64 v87, v87, v95, s[4:5]
	v_addc_co_u32_e32 v81, vcc, 0, v89, vcc
	global_store_dwordx4 v[80:81], v[84:87], off
	v_cvt_pk_bf16_f32 v76, v76, v77
	v_cvt_pk_bf16_f32 v77, v78, v79
	v_cvt_pk_bf16_f32 v72, v72, v73
	v_cvt_pk_bf16_f32 v73, v74, v75
	v_cvt_pk_bf16_f32 v68, v68, v69
	v_cvt_pk_bf16_f32 v69, v70, v71
	v_cvt_pk_bf16_f32 v70, v64, v65
	v_cvt_pk_bf16_f32 v71, v66, v67
	v_mov_b32_e32 v66, 0
	v_mov_b32_dpp v66, v70 row_ror:8 row_mask:0xf bank_mask:0xf
	v_mov_b32_dpp v78, v72 row_ror:8 row_mask:0xf bank_mask:0xf
	v_mov_b32_dpp v67, v71 row_ror:8 row_mask:0xf bank_mask:0xf
	v_cndmask_b32_e64 v66, v66, v72, s[4:5]
	v_add_u32_e32 v72, v152, v161
	v_mov_b32_dpp v79, v73 row_ror:8 row_mask:0xf bank_mask:0xf
	v_cndmask_b32_e64 v67, v67, v73, s[4:5]
	v_ashrrev_i32_e32 v73, 31, v72
	v_lshlrev_b64 v[72:73], 13, v[72:73]
	v_mov_b32_dpp v64, v68 row_ror:8 row_mask:0xf bank_mask:0xf
	v_mov_b32_dpp v65, v69 row_ror:8 row_mask:0xf bank_mask:0xf
	v_lshl_add_u64 v[72:73], s[6:7], 0, v[72:73]
	v_cndmask_b32_e64 v64, v64, v76, s[4:5]
	v_cndmask_b32_e64 v65, v65, v77, s[4:5]
	v_lshl_add_u64 v[72:73], v[72:73], 0, v[112:113]
	v_mov_b32_dpp v74, v76 row_ror:8 row_mask:0xf bank_mask:0xf
	v_mov_b32_dpp v75, v77 row_ror:8 row_mask:0xf bank_mask:0xf
	global_store_dwordx4 v[72:73], v[64:67], off
	v_cndmask_b32_e64 v68, v68, v74, s[4:5]
	v_cndmask_b32_e64 v69, v69, v75, s[4:5]
	v_add_co_u32_e32 v64, vcc, s49, v72
	v_cndmask_b32_e64 v70, v70, v78, s[4:5]
	v_cndmask_b32_e64 v71, v71, v79, s[4:5]
	v_addc_co_u32_e32 v65, vcc, 0, v73, vcc
	global_store_dwordx4 v[64:65], v[68:71], off
	v_cvt_pk_bf16_f32 v60, v60, v61
	v_cvt_pk_bf16_f32 v61, v62, v63
	v_cvt_pk_bf16_f32 v56, v56, v57
	v_cvt_pk_bf16_f32 v57, v58, v59
	v_cvt_pk_bf16_f32 v52, v52, v53
	v_cvt_pk_bf16_f32 v53, v54, v55
	v_cvt_pk_bf16_f32 v54, v48, v49
	v_cvt_pk_bf16_f32 v55, v50, v51
	v_mov_b32_e32 v50, 0
	v_mov_b32_dpp v50, v54 row_ror:8 row_mask:0xf bank_mask:0xf
	v_mov_b32_dpp v62, v56 row_ror:8 row_mask:0xf bank_mask:0xf
	v_mov_b32_dpp v51, v55 row_ror:8 row_mask:0xf bank_mask:0xf
	v_cndmask_b32_e64 v50, v50, v56, s[4:5]
	v_add_u32_e32 v56, v153, v161
	v_mov_b32_dpp v63, v57 row_ror:8 row_mask:0xf bank_mask:0xf
	v_cndmask_b32_e64 v51, v51, v57, s[4:5]
	v_ashrrev_i32_e32 v57, 31, v56
	v_lshlrev_b64 v[56:57], 13, v[56:57]
	v_mov_b32_dpp v48, v52 row_ror:8 row_mask:0xf bank_mask:0xf
	v_mov_b32_dpp v49, v53 row_ror:8 row_mask:0xf bank_mask:0xf
	v_lshl_add_u64 v[56:57], s[6:7], 0, v[56:57]
	v_cndmask_b32_e64 v48, v48, v60, s[4:5]
	v_cndmask_b32_e64 v49, v49, v61, s[4:5]
	v_lshl_add_u64 v[56:57], v[56:57], 0, v[112:113]
	v_mov_b32_dpp v58, v60 row_ror:8 row_mask:0xf bank_mask:0xf
	v_mov_b32_dpp v59, v61 row_ror:8 row_mask:0xf bank_mask:0xf
	global_store_dwordx4 v[56:57], v[48:51], off
	v_cndmask_b32_e64 v52, v52, v58, s[4:5]
	v_cndmask_b32_e64 v53, v53, v59, s[4:5]
	v_add_co_u32_e32 v48, vcc, s49, v56
; __device__ __forceinline__ unsigned cvt_pk_bf16(float lo, float hi) { unsigned r; asm volatile("v_cvt_pk_bf16_f32 %0, %1, %2" : "=v"(r) : "v"(lo), "v"(hi)); return r; }
; #define PG8_WAIT_V(n) asm volatile("s_waitcnt vmcnt(" #n ")" ::: "memory")
; #define PG8_BAR __builtin_amdgcn_s_barrier()
;     __device__ __forceinline__ void operator()(const f32x4 (&acc)[2][2][4][2], const Unit& u, int wr, int wc, int fr, int fq) const {
;     ...
;             for (int m = 0; m < 4; ++m) { const int row = row0 + ai * HALF + m * 16;
;                 const float rs = ssin ? __builtin_amdgcn_rsqf(ssin[row] * (1.f / D) + EPS) : 1.0f; float sq = 0.f; u32x4 w[2];
; #pragma unroll
;                 for (int bj = 0; bj < 2; ++bj) { f32x4 v0 = acc[ai][bj][m][0] * rs, v1 = acc[ai][bj][m][1] * rs;
;                     if (ACT == 1) {
; #pragma unroll
;                         for (int j = 0; j < 4; ++j) { const float a = fmaxf(v0[j], 0.f), b = fmaxf(v1[j], 0.f); v0[j] = a * a; v1[j] = b * b; } }
;                     sq += (v0[0] * v0[0] + v0[1] * v0[1]) + (v0[2] * v0[2] + v0[3] * v0[3]) + (v1[0] * v1[0] + v1[1] * v1[1]) + (v1[2] * v1[2] + v1[3] * v1[3]);
;                     w[bj].x = cvt_pk_bf16(v0[0], v0[1]); w[bj].y = cvt_pk_bf16(v0[2], v0[3]); w[bj].z = cvt_pk_bf16(v1[0], v1[1]); w[bj].w = cvt_pk_bf16(v1[2], v1[3]); }
;                 store_pair_lines(O, ldc, row, fr, col0, w[0], w[1]);
; template <class Epi>
; __device__ __forceinline__ void gemm_phase(LAS unsigned char* lds, const Gemm g, const StaticOrder& S, const Epi& E) {
;     ...
;         E(acc, cur, wr, wc, fr, fq);
;         if (!has_next) break;
; #pragma unroll
;         for (int a = 0; a < 2; ++a)
; #pragma unroll
;             for (int b = 0; b < 2; ++b)
; #pragma unroll
;                 for (int m = 0; m < 4; ++m)
; #pragma unroll
;                     for (int n = 0; n < 2; ++n) acc[a][b][m][n] = (f32x4){0.f, 0.f, 0.f, 0.f};
;         cur = nxt; cA = nA; cB = nB; ++ui;
;     }
;     PG8_WAIT_V(0);
;     if (wr == 0) PG8_BAR;
;     PG8_BAR;
	v_cndmask_b32_e64 v54, v54, v62, s[4:5]
	v_cndmask_b32_e64 v55, v55, v63, s[4:5]
	v_addc_co_u32_e32 v49, vcc, 0, v57, vcc
	global_store_dwordx4 v[48:49], v[52:55], off
	v_cvt_pk_bf16_f32 v44, v44, v45
	v_cvt_pk_bf16_f32 v45, v46, v47
	v_cvt_pk_bf16_f32 v40, v40, v41
	v_cvt_pk_bf16_f32 v41, v42, v43
	v_cvt_pk_bf16_f32 v36, v36, v37
	v_cvt_pk_bf16_f32 v37, v38, v39
	v_cvt_pk_bf16_f32 v38, v32, v33
	v_cvt_pk_bf16_f32 v39, v34, v35
	v_mov_b32_e32 v34, 0
	v_mov_b32_dpp v34, v38 row_ror:8 row_mask:0xf bank_mask:0xf
	v_mov_b32_dpp v46, v40 row_ror:8 row_mask:0xf bank_mask:0xf
	v_mov_b32_dpp v35, v39 row_ror:8 row_mask:0xf bank_mask:0xf
	v_cndmask_b32_e64 v34, v34, v40, s[4:5]
	v_add_u32_e32 v40, v154, v161
	v_mov_b32_dpp v47, v41 row_ror:8 row_mask:0xf bank_mask:0xf
	v_cndmask_b32_e64 v35, v35, v41, s[4:5]
	v_ashrrev_i32_e32 v41, 31, v40
	v_lshlrev_b64 v[40:41], 13, v[40:41]
	v_mov_b32_dpp v32, v36 row_ror:8 row_mask:0xf bank_mask:0xf
	v_mov_b32_dpp v33, v37 row_ror:8 row_mask:0xf bank_mask:0xf
	v_lshl_add_u64 v[40:41], s[6:7], 0, v[40:41]
	v_cndmask_b32_e64 v32, v32, v44, s[4:5]
	v_cndmask_b32_e64 v33, v33, v45, s[4:5]
	v_lshl_add_u64 v[40:41], v[40:41], 0, v[112:113]
	v_mov_b32_dpp v42, v44 row_ror:8 row_mask:0xf bank_mask:0xf
	v_mov_b32_dpp v43, v45 row_ror:8 row_mask:0xf bank_mask:0xf
	global_store_dwordx4 v[40:41], v[32:35], off
	v_cndmask_b32_e64 v36, v36, v42, s[4:5]
	v_cndmask_b32_e64 v37, v37, v43, s[4:5]
	v_add_co_u32_e32 v32, vcc, s49, v40
	v_cndmask_b32_e64 v38, v38, v46, s[4:5]
	v_cndmask_b32_e64 v39, v39, v47, s[4:5]
	v_addc_co_u32_e32 v33, vcc, 0, v41, vcc
	global_store_dwordx4 v[32:33], v[36:39], off
	v_cvt_pk_bf16_f32 v28, v28, v29
	v_cvt_pk_bf16_f32 v29, v30, v31
	v_cvt_pk_bf16_f32 v24, v24, v25
	v_cvt_pk_bf16_f32 v25, v26, v27
	v_cvt_pk_bf16_f32 v20, v20, v21
	v_cvt_pk_bf16_f32 v21, v22, v23
	v_cvt_pk_bf16_f32 v22, v16, v17
	v_cvt_pk_bf16_f32 v23, v18, v19
	v_mov_b32_e32 v18, 0
	v_mov_b32_dpp v18, v22 row_ror:8 row_mask:0xf bank_mask:0xf
	v_mov_b32_dpp v30, v24 row_ror:8 row_mask:0xf bank_mask:0xf
	v_mov_b32_dpp v19, v23 row_ror:8 row_mask:0xf bank_mask:0xf
	v_cndmask_b32_e64 v18, v18, v24, s[4:5]
	v_add_u32_e32 v24, v155, v161
	v_mov_b32_dpp v31, v25 row_ror:8 row_mask:0xf bank_mask:0xf
	v_cndmask_b32_e64 v19, v19, v25, s[4:5]
	v_ashrrev_i32_e32 v25, 31, v24
	v_lshlrev_b64 v[24:25], 13, v[24:25]
	v_mov_b32_dpp v16, v20 row_ror:8 row_mask:0xf bank_mask:0xf
	v_mov_b32_dpp v17, v21 row_ror:8 row_mask:0xf bank_mask:0xf
	v_lshl_add_u64 v[24:25], s[6:7], 0, v[24:25]
	v_cndmask_b32_e64 v16, v16, v28, s[4:5]
	v_cndmask_b32_e64 v17, v17, v29, s[4:5]
	v_lshl_add_u64 v[24:25], v[24:25], 0, v[112:113]
	v_mov_b32_dpp v26, v28 row_ror:8 row_mask:0xf bank_mask:0xf
	v_mov_b32_dpp v27, v29 row_ror:8 row_mask:0xf bank_mask:0xf
	global_store_dwordx4 v[24:25], v[16:19], off
	v_cndmask_b32_e64 v20, v20, v26, s[4:5]
	v_cndmask_b32_e64 v21, v21, v27, s[4:5]
	v_add_co_u32_e32 v16, vcc, s49, v24
	v_cndmask_b32_e64 v22, v22, v30, s[4:5]
	v_cndmask_b32_e64 v23, v23, v31, s[4:5]
	v_addc_co_u32_e32 v17, vcc, 0, v25, vcc
	global_store_dwordx4 v[16:17], v[20:23], off
	v_cvt_pk_bf16_f32 v12, v12, v13
	v_cvt_pk_bf16_f32 v13, v14, v15
	v_cvt_pk_bf16_f32 v8, v8, v9
	v_cvt_pk_bf16_f32 v9, v10, v11
	v_cvt_pk_bf16_f32 v4, v4, v5
	v_cvt_pk_bf16_f32 v5, v6, v7
	v_cvt_pk_bf16_f32 v6, v0, v1
	v_cvt_pk_bf16_f32 v7, v2, v3
	v_mov_b32_e32 v2, 0
	v_mov_b32_dpp v2, v6 row_ror:8 row_mask:0xf bank_mask:0xf
	v_mov_b32_dpp v14, v8 row_ror:8 row_mask:0xf bank_mask:0xf
	v_mov_b32_dpp v3, v7 row_ror:8 row_mask:0xf bank_mask:0xf
	v_cndmask_b32_e64 v2, v2, v8, s[4:5]
	v_add_u32_e32 v8, v156, v161
	v_mov_b32_dpp v15, v9 row_ror:8 row_mask:0xf bank_mask:0xf
	v_cndmask_b32_e64 v3, v3, v9, s[4:5]
	v_ashrrev_i32_e32 v9, 31, v8
	v_lshlrev_b64 v[8:9], 13, v[8:9]
	v_mov_b32_dpp v0, v4 row_ror:8 row_mask:0xf bank_mask:0xf
	v_mov_b32_dpp v1, v5 row_ror:8 row_mask:0xf bank_mask:0xf
	v_lshl_add_u64 v[8:9], s[6:7], 0, v[8:9]
	v_cndmask_b32_e64 v0, v0, v12, s[4:5]
	v_cndmask_b32_e64 v1, v1, v13, s[4:5]
	v_lshl_add_u64 v[8:9], v[8:9], 0, v[112:113]
	global_store_dwordx4 v[8:9], v[0:3], off
	v_mov_b32_dpp v10, v12 row_ror:8 row_mask:0xf bank_mask:0xf
	v_mov_b32_dpp v11, v13 row_ror:8 row_mask:0xf bank_mask:0xf
	v_add_co_u32_e32 v0, vcc, 0x10000, v8
	v_cndmask_b32_e64 v4, v4, v10, s[4:5]
	s_nop 0
	v_addc_co_u32_e32 v1, vcc, 0, v9, vcc
	v_cndmask_b32_e64 v5, v5, v11, s[4:5]
	v_cndmask_b32_e64 v6, v6, v14, s[4:5]
	v_cndmask_b32_e64 v7, v7, v15, s[4:5]
	s_and_b64 vcc, exec, s[18:19]
	s_mov_b32 s30, s12
	s_mov_b64 s[36:37], s[28:29]
	s_mov_b64 s[34:35], s[16:17]
	global_store_dwordx4 v[0:1], v[4:7], off
	s_cbranch_vccz .LBB0_103
	s_waitcnt vmcnt(0)
	s_cmpk_gt_u32 s27, 0xff
	s_cbranch_scc1 .LBB0_111
	s_barrier

; #define LAS __attribute__((address_space(3)))
; __device__ __forceinline__ void vt_item(LAS unsigned char* lds, const bf16_t* src, int sstride, bf16_t* vt_rows, int tok0) {
;     int tid = threadIdx.x; asm volatile("" : "+v"(tid));
;     constexpr int TROW = 272;
; #pragma unroll
;     for (int i = 0; i < 2; ++i) { const int cid = tid + i * 512, row = cid >> 4, cc = cid & 15;
;         const u32x4 v = *(const u32x4*)(src + (size_t)row * sstride + cc * 8);
;         *(LAS u32x4*)(lds + row * TROW + cc * 16) = v; }
;     __syncthreads();
; #pragma unroll
;     for (int i = 0; i < 2; ++i) { const int wid2 = tid + i * 512, d = wid2 >> 3, ck = wid2 & 7;
;         unsigned short e[8];
; #pragma unroll
;         for (int j = 0; j < 8; ++j) { const int quad = (ck & 1) * 2 + (j >> 2); const int q2 = (quad == 1) ? 2 : (quad == 2 ? 1 : quad); const int t = (ck >> 1) * 16 + q2 * 4 + (j & 3);
;             e[j] = *(const LAS unsigned short*)(lds + t * TROW + d * 2); }
;         u32x4 o; o.x = e[0] | ((unsigned)e[1] << 16); o.y = e[2] | ((unsigned)e[3] << 16); o.z = e[4] | ((unsigned)e[5] << 16); o.w = e[6] | ((unsigned)e[7] << 16);
;         *(u32x4*)(vt_rows + (size_t)d * M + tok0 + ck * 8) = o; }
;     __syncthreads();
; __global__ void __launch_bounds__(NTHREADS, 2) fwd_megakernel(Params P) {
;     ...
;         _Pragma("unroll 1") for (int rp_ = 0; rp_ < REP_PREP; ++rp_) for (int it = bid; it < 256 * 8; it += G) { const int tt = it >> 3, h = it & 7;
;             vt_item(lds, Z + (size_t)(tt * 64) * EV_INP + 2880 + h * 128, EV_INP, NVT + (size_t)(h * 128) * M, tt * 64); }
.LBB0_166:
	s_cmp_lg_u32 s6, s60
	s_mov_b64 s[6:7], -1
	s_cbranch_scc0 .LBB0_170
	s_andn2_b64 vcc, exec, s[40:41]
	s_mov_b32 s8, s61
	s_mov_b32 s9, s55
	s_mov_b32 s16, s54
	s_cbranch_vccnz .LBB0_169
	v_mov_b32_e32 v41, v1
	s_and_b32 s6, s9, 0xffffffc0
	s_ashr_i32 s7, s6, 31
	s_lshl_b64 s[18:19], s[6:7], 13
	s_add_u32 s17, s56, s18
	s_addc_u32 s19, s57, s19
	s_and_b32 s33, s8, 0x380
	v_mov_b32_e32 v43, v202
	s_lshl_b32 s18, s33, 1
	s_add_u32 s18, s17, s18
	v_lshlrev_b32_e32 v62, 4, v43
	v_add_u32_e32 v60, 0x200, v43
	v_ashrrev_i32_e32 v50, 4, v43
	v_and_b32_e32 v40, 0xf0, v62
	v_ashrrev_i32_e32 v52, 4, v60
	s_addc_u32 s19, s19, 0
	v_ashrrev_i32_e32 v51, 31, v50
	v_ashrrev_i32_e32 v53, 31, v52
	v_lshl_add_u64 v[48:49], s[18:19], 0, v[40:41]
	v_lshlrev_b64 v[44:45], 13, v[50:51]
	v_lshlrev_b64 v[46:47], 13, v[52:53]
	v_lshl_add_u64 v[48:49], v[48:49], 0, s[48:49]
	v_lshl_add_u64 v[44:45], v[48:49], 0, v[44:45]
	v_lshl_add_u64 v[48:49], v[48:49], 0, v[46:47]
	global_load_dwordx4 v[64:67], v[44:45], off
	global_load_dwordx4 v[100:103], v[48:49], off
	global_load_dword v39, v[44:45], off
	global_load_dword v68, v[48:49], off
.LBB0_168:
	s_and_b32 s6, s9, 0xffffffc0
	s_ashr_i32 s7, s6, 31
	s_lshl_b64 s[18:19], s[6:7], 13
	s_add_u32 s17, s56, s18
	s_addc_u32 s19, s57, s19
	s_and_b32 s33, s8, 0x380
	v_mov_b32_e32 v17, v202
	s_lshl_b32 s18, s33, 1
	s_add_u32 s18, s17, s18
	v_lshlrev_b32_e32 v34, 4, v17
	v_add_u32_e32 v32, 0x200, v17
	v_ashrrev_i32_e32 v26, 4, v17
	v_and_b32_e32 v0, 0xf0, v34
	v_ashrrev_i32_e32 v28, 4, v32
	s_addc_u32 s19, s19, 0
	v_ashrrev_i32_e32 v27, 31, v26
	v_ashrrev_i32_e32 v29, 31, v28
	v_lshl_add_u64 v[22:23], s[18:19], 0, v[0:1]
	v_lshlrev_b64 v[18:19], 13, v[26:27]
	v_lshlrev_b64 v[20:21], 13, v[28:29]
	v_lshl_add_u64 v[22:23], v[22:23], 0, s[48:49]
	v_lshl_add_u64 v[18:19], v[22:23], 0, v[18:19]
	v_lshl_add_u64 v[22:23], v[22:23], 0, v[20:21]
	s_nop 0
	s_nop 0
	s_nop 0
	v_lshlrev_b32_e32 v27, 1, v17
	v_lshlrev_b32_e32 v29, 3, v17
	v_ashrrev_i32_e32 v30, 3, v17
	v_and_b32_e32 v17, 2, v27
	v_add_u32_e32 v0, 0, v0
	s_lshl_b32 s17, s33, 15
	v_and_b32_e32 v35, 48, v29
	v_cmp_eq_u32_e32 vcc, 0, v17
	v_mad_u64_u32 v[26:27], s[18:19], v26, s35, v[0:1]
	v_mad_u64_u32 v[28:29], s[18:19], v28, s35, v[0:1]
	s_add_u32 s17, s58, s17
	v_ashrrev_i32_e32 v32, 3, v32
	v_lshl_or_b32 v37, v17, 1, v35
	v_cndmask_b32_e64 v17, 12, 8, vcc
	s_addc_u32 s18, s59, 0
	s_lshl_b64 s[6:7], s[6:7], 1
	v_lshl_add_u32 v36, v30, 1, 0
	v_lshl_add_u32 v38, v32, 1, 0
	v_or_b32_e32 v0, v17, v35
	s_add_u32 s6, s17, s6
	v_ashrrev_i32_e32 v31, 31, v30
	v_ashrrev_i32_e32 v33, 31, v32
	v_mad_u32_u24 v27, v37, s35, v36
	v_mad_u32_u24 v29, v0, s35, v36
	v_mad_u32_u24 v36, v0, s35, v38
	v_and_b32_e32 v0, 0x70, v34
	s_addc_u32 s7, s18, s7
	v_lshlrev_b64 v[30:31], 15, v[30:31]
	v_mad_u32_u24 v17, v37, s35, v38
	v_lshlrev_b64 v[32:33], 15, v[32:33]
	v_lshl_add_u64 v[34:35], s[6:7], 0, v[0:1]
	v_lshl_add_u64 v[30:31], v[34:35], 0, v[30:31]
	v_lshl_add_u64 v[32:33], v[34:35], 0, v[32:33]
	s_add_i32 s16, s16, s20
	s_add_i32 s9, s9, s26
	s_add_i32 s8, s8, s76
	s_cmpk_lt_i32 s16, 0x800
	s_waitcnt vmcnt(3)
	ds_write_b128 v26, v[64:67]
	s_waitcnt vmcnt(2)
	ds_write_b128 v28, v[100:103]
	s_waitcnt lgkmcnt(0)
	v_mov_b32_e32 v41, v1
	s_and_b32 s6, s9, 0xffffffc0
	s_ashr_i32 s7, s6, 31
	s_lshl_b64 s[18:19], s[6:7], 13
	s_add_u32 s17, s56, s18
	s_addc_u32 s19, s57, s19
	s_and_b32 s33, s8, 0x380
	v_mov_b32_e32 v43, v202
	s_lshl_b32 s18, s33, 1
	s_add_u32 s18, s17, s18
	v_lshlrev_b32_e32 v62, 4, v43
	v_add_u32_e32 v60, 0x200, v43
	v_ashrrev_i32_e32 v50, 4, v43
	v_and_b32_e32 v40, 0xf0, v62
	v_ashrrev_i32_e32 v52, 4, v60
	s_addc_u32 s19, s19, 0
	v_ashrrev_i32_e32 v51, 31, v50
	v_ashrrev_i32_e32 v53, 31, v52
	v_lshl_add_u64 v[48:49], s[18:19], 0, v[40:41]
	v_lshlrev_b64 v[44:45], 13, v[50:51]
	v_lshlrev_b64 v[46:47], 13, v[52:53]
	v_lshl_add_u64 v[48:49], v[48:49], 0, s[48:49]
	v_lshl_add_u64 v[44:45], v[48:49], 0, v[44:45]
	v_lshl_add_u64 v[48:49], v[48:49], 0, v[46:47]
	global_load_dwordx4 v[64:67], v[44:45], off
	global_load_dwordx4 v[100:103], v[48:49], off
	s_cmpk_lt_i32 s16, 0x800
	s_barrier
	ds_read_u16 v0, v27
	ds_read_u16 v18, v27 offset:272
	ds_read_u16 v19, v27 offset:544
	ds_read_u16 v22, v27 offset:816
	ds_read_u16 v20, v29
	ds_read_u16 v23, v29 offset:272
	ds_read_u16 v21, v29 offset:544
	ds_read_u16 v24, v29 offset:816
	ds_read_u16 v26, v17
	ds_read_u16 v27, v17 offset:272
	ds_read_u16 v28, v17 offset:544
	ds_read_u16 v17, v17 offset:816
	ds_read_u16 v29, v36
	ds_read_u16 v34, v36 offset:272
	ds_read_u16 v25, v36 offset:544
	ds_read_u16 v35, v36 offset:816
	s_waitcnt lgkmcnt(8)
	v_perm_b32 v21, v24, v21, s62
	v_perm_b32 v20, v23, v20, s62
	v_perm_b32 v19, v22, v19, s62
	v_perm_b32 v18, v18, v0, s62
	s_waitcnt lgkmcnt(0)
	v_perm_b32 v25, v35, v25, s62
	v_perm_b32 v24, v34, v29, s62
	v_perm_b32 v23, v17, v28, s62
	v_perm_b32 v22, v27, v26, s62
	global_store_dwordx4 v[30:31], v[18:21], off
	global_store_dwordx4 v[32:33], v[22:25], off
	s_barrier
	s_cbranch_scc1 .LBB0_168
	s_waitcnt vmcnt(0)

; #define PG8_STAGE(bufoff, gbase, voff) do { _Pragma("unroll") for (int _i = 0; _i < 2; ++_i) \
;         __builtin_amdgcn_global_load_lds((const unsigned*)((const char*)(gbase) + (voff)[_i]), (LAS unsigned*)(lds + (bufoff) + ldsw + _i * 8192), 16, 0, 0); } while (0)
; #define PG8_WAIT_V(n) asm volatile("s_waitcnt vmcnt(" #n ")" ::: "memory")
; #define PG8_BAR __builtin_amdgcn_s_barrier()
; template <class Epi>
; __device__ __forceinline__ void gemm_phase(LAS unsigned char* lds, const Gemm g, const StaticOrder& S, const Epi& E) {
;     ...
;     const int wid = __builtin_amdgcn_readfirstlane(tid >> 6), lane = tid & 63, wr = wid >> 2, wc = wid & 3, fr = lane & 15, fq = lane >> 4;
;     const int K = g.K, nt = K / BK;
;     unsigned voffA[2], voffB0[2], voffB1[2];
; #pragma unroll
;     for (int i = 0; i < 2; ++i) { int R, C; stage_rc(tid * 16 + i * 8192, R, C);
;         const int Rw = 64 * (R >> 5) + 16 * ((R >> 2) & 3) + 4 * ((R >> 4) & 1) + (R & 3);
;         const int Rf = 64 * (R >> 5) + 8 * ((R >> 2) & 3) + 4 * ((R >> 4) & 1) + (R & 3);
;         const int Rb0 = Epi::PERM ? (Epi::F32OUT ? Rf : Rw) : R, Rb1 = Epi::PERM ? (Epi::F32OUT ? Rf + 32 : Rw + 8) : R + HALF;
;         voffA[i] = (unsigned)(R * K + C) * 2u; voffB0[i] = (unsigned)(Rb0 * K + C) * 2u; voffB1[i] = (unsigned)(Rb1 * K + C) * 2u; }
;     const size_t kstep = (size_t)(BK * 2);
;     const size_t hstep = (size_t)HALF * K * 2;
;     const size_t tstep = 2 * hstep;
;     const unsigned ldsw = (unsigned)wid * 1024u;
;     const int aoff = lds_byte(wr * 64 + fr, fq * 8), boff = lds_byte(wc * 32 + fr, fq * 8);
;     ...
;     const char* cA = (const char*)g.A + (size_t)cur.pm * tstep; const char* cB = (const char*)g.Bt + (size_t)cur.pn * tstep;
;     PG8_STAGE(PG8_SB(0, 0), cB, voffB0); PG8_STAGE(PG8_SA(0, 0), cA, voffA); PG8_STAGE(PG8_SB(0, 1), cB, voffB1); PG8_STAGE(PG8_SA(0, 1), cA + hstep, voffA);
;     if (wr == 1) PG8_BAR;
;     PG8_WAIT_V(4); PG8_BAR;
;     PG8_STAGE(PG8_SB(1, 0), cB + kstep, voffB0); PG8_STAGE(PG8_SA(1, 0), cA + kstep, voffA); PG8_STAGE(PG8_SB(1, 1), cB + kstep, voffB1);
;     PG8_WAIT_V(6); PG8_BAR;
.LBB0_229:
	s_add_u32 s6, s4, 0xec00000
	s_mov_b64 s[8:9], 0x80
	s_addc_u32 s7, s5, 0
	s_add_i32 m0, s37, 0x18000
	v_lshl_add_u64 v[10:11], v[10:11], 0, s[8:9]
	s_waitcnt vmcnt(4)
	s_barrier
	global_load_lds_dwordx4 v[10:11], off
	v_lshl_add_u64 v[8:9], v[8:9], 0, s[8:9]
	s_add_i32 m0, s37, 0x1a000
	s_add_i32 s55, s37, 0x8000
	global_load_lds_dwordx4 v[8:9], off
	v_lshl_add_u64 v[6:7], v[6:7], 0, s[8:9]
	s_mov_b32 m0, s55
	s_add_i32 s56, s37, 0xa000
	global_load_lds_dwordx4 v[6:7], off
	v_lshl_add_u64 v[4:5], v[4:5], 0, s[8:9]
	s_mov_b32 m0, s56
	v_lshl_add_u64 v[0:1], v[0:1], 0, s[8:9]
	global_load_lds_dwordx4 v[4:5], off
	s_add_i32 m0, s37, 0x1c000
	v_and_b32_e32 v146, 15, v12
	global_load_lds_dwordx4 v[0:1], off
	v_lshl_add_u64 v[0:1], v[2:3], 0, s[8:9]
	s_add_i32 m0, s37, 0x1e000
	v_lshlrev_b32_e32 v2, 2, v12
	global_load_lds_dwordx4 v[0:1], off
	v_and_b32_e32 v0, 48, v12
	s_and_b32 s4, s16, 3
	s_lshl_b32 s5, s11, 13
	v_lshl_or_b32 v1, v146, 6, v0
	v_and_b32_e32 v2, 32, v2
	v_bitop3_b32 v3, v1, s5, v2 bitop3:0xde
	s_lshl_b32 s5, s4, 12
	s_sext_i32_i8 s63, s10
	v_bitop3_b32 v147, v1, s5, v2 bitop3:0xde
	s_lshl_b32 s10, s4, 6
	v_and_b32_e32 v1, 8, v12
	v_or3_b32 v156, s10, v1, v0
	v_lshlrev_b32_e32 v0, 13, v17
	v_and_b32_e32 v0, 0xffffc000, v0
	v_lshl_add_u32 v0, v16, 10, v0
	v_and_b32_e32 v1, 1, v17
	v_lshl_or_b32 v0, v1, 6, v0
	v_lshl_add_u32 v140, v18, 1, v0
	v_lshlrev_b32_e32 v0, 13, v13
	v_and_b32_e32 v0, 0xffffc000, v0
	s_waitcnt vmcnt(0)
	v_and_b32_e32 v148, 7, v12
	v_lshl_add_u32 v0, v14, 10, v0
	v_and_b32_e32 v1, 1, v13
	v_sub_u32_e32 v2, v148, v146
	v_lshl_or_b32 v0, v1, 6, v0
	s_add_i32 s60, 0, 0x10000
	s_add_i32 s61, 0, 0x14000
	s_lshl_b32 s57, s11, 6
	v_cmp_gt_u32_e64 s[4:5], 8, v146
	s_ashr_i32 s58, s20, 31
	s_mov_b32 s59, s20
	v_add_u32_e32 v149, 16, v2
	v_add_u32_e32 v150, 32, v2
	v_add_u32_e32 v151, 48, v2
	v_add_u32_e32 v152, 0x80, v2
	v_add_u32_e32 v153, 0x90, v2
	v_add_u32_e32 v154, 0xa0, v2
	v_add_u32_e32 v155, 0xb0, v2
	v_mov_b32_e32 v141, v135
	v_lshl_add_u32 v142, v15, 1, v0
	v_mov_b32_e32 v143, v135
	v_add_u32_e32 v157, s60, v147
	v_add_u32_e32 v158, 0, v3
	v_add_u32_e32 v159, s61, v147
	s_movk_i32 s62, 0xc00
	v_mov_b64_e32 v[144:145], 0x17f
	s_barrier

; #define PG8_STAGE(bufoff, gbase, voff) do { _Pragma("unroll") for (int _i = 0; _i < 2; ++_i) \
;         __builtin_amdgcn_global_load_lds((const unsigned*)((const char*)(gbase) + (voff)[_i]), (LAS unsigned*)(lds + (bufoff) + ldsw + _i * 8192), 16, 0, 0); } while (0)
; #define PG8_LDA(dst, b, h) do { _Pragma("unroll") for (int m = 0; m < 4; ++m) _Pragma("unroll") for (int k = 0; k < 2; ++k) dst[m][k] = *(const LAS bf16x8*)(lds + PG8_SA(b, h) + aoff + m * 2048 + k * 1024); } while (0)
; #define PG8_LDB(dst, b, h) do { _Pragma("unroll") for (int n = 0; n < 2; ++n) _Pragma("unroll") for (int k = 0; k < 2; ++k) dst[n][k] = *(const LAS bf16x8*)(lds + PG8_SB(b, h) + boff + n * 2048 + k * 1024); } while (0)
; #define PG8_MMA(ai, bj, At, Bt) do { __builtin_amdgcn_s_setprio(1); _Pragma("unroll") for (int m = 0; m < 4; ++m) _Pragma("unroll") for (int n = 0; n < 2; ++n) _Pragma("unroll") for (int k = 0; k < 2; ++k) \
;         acc[ai][bj][m][n] = __builtin_amdgcn_mfma_f32_16x16x32_bf16(Bt[n][k], At[m][k], acc[ai][bj][m][n], 0, 0, 0); __builtin_amdgcn_s_setprio(0); } while (0)
; #define PG8_WAIT_L(n) asm volatile("s_waitcnt lgkmcnt(" #n ")" ::: "memory")
; #define PG8_BAR __builtin_amdgcn_s_barrier()
; #define PG8_SCHED __builtin_amdgcn_sched_barrier(0)
; template <class Epi>
; __device__ __forceinline__ void gemm_phase(LAS unsigned char* lds, const Gemm g, const StaticOrder& S, const Epi& E) {
;     ...
;         for (int t = 0; t < nt; t += 2) {
;             const bool last = (t == nt - 2);
;             const char* a1 = cA + (size_t)(t + 1) * kstep;
;             const char* a2 = last ? nA : cA + (size_t)(t + 2) * kstep; const char* b2 = last ? nB : cB + (size_t)(t + 2) * kstep;
;             const char* a3 = a2 + kstep; const char* b3 = b2 + kstep;
;             PG8_LDB(B0, 0, 0); PG8_SCHED; PG8_LDA(At, 0, 0); PG8_STAGE(PG8_SA(1, 1), a1 + hstep, voffA);
;             PG8_WAIT_L(8); PG8_BAR; PG8_WAIT_L(0); PG8_MMA(0, 0, At, B0); PG8_BAR; PG8_SCHED;
;             PG8_LDB(B1, 0, 1); PG8_STAGE(PG8_SB(0, 0), b2, voffB0);
;             PG8_BAR; PG8_WAIT_L(0); PG8_MMA(0, 1, At, B1); PG8_BAR;
;             PG8_LDA(At, 0, 1); PG8_STAGE(PG8_SA(0, 0), a2, voffA);
;             PG8_BAR; PG8_WAIT_L(0); PG8_MMA(1, 0, At, B0); PG8_BAR; PG8_SCHED;
.LBB0_234:
	ds_read_b128 v[160:163], v157
	ds_read_b128 v[164:167], v157 offset:1024
	ds_read_b128 v[168:171], v157 offset:2048
	ds_read_b128 v[172:175], v157 offset:3072
	s_add_u32 s33, s38, 0xfffe0080
	s_addc_u32 s40, s39, -1
	s_cmp_eq_u32 s68, 4
	s_cselect_b32 s41, s17, s40
	s_cselect_b32 s40, s64, s33
	s_cselect_b32 s43, s11, s67
	s_cselect_b32 s42, s65, s66
	v_lshl_add_u64 v[200:201], s[38:39], 0, v[140:141]
	s_add_i32 m0, s37, 0xc000
	ds_read_b128 v[176:179], v158
	ds_read_b128 v[180:183], v158 offset:1024
	ds_read_b128 v[184:187], v158 offset:2048
	ds_read_b128 v[188:191], v158 offset:3072
	ds_read_b128 v[192:195], v158 offset:4096
	ds_read_b128 v[196:199], v158 offset:5120
	ds_read_b128 v[204:207], v158 offset:6144
	ds_read_b128 v[208:211], v158 offset:7168
	global_load_lds_dwordx4 v[200:201], off
	v_lshl_add_u64 v[200:201], s[38:39], 0, v[142:143]
	s_add_i32 m0, s37, 0xe000
	s_nop 0
	global_load_lds_dwordx4 v[200:201], off
	s_waitcnt lgkmcnt(8)
	s_barrier
	s_waitcnt lgkmcnt(0)
	v_mfma_f32_16x16x32_bf16 v[124:127], v[160:163], v[176:179], v[124:127]
	v_mfma_f32_16x16x32_bf16 v[120:123], v[168:171], v[176:179], v[120:123]
	v_mfma_f32_16x16x32_bf16 v[108:111], v[160:163], v[184:187], v[108:111]
	v_mfma_f32_16x16x32_bf16 v[104:107], v[168:171], v[184:187], v[104:107]
	v_mfma_f32_16x16x32_bf16 v[92:95], v[160:163], v[192:195], v[92:95]
	v_mfma_f32_16x16x32_bf16 v[88:91], v[168:171], v[192:195], v[88:91]
	v_mfma_f32_16x16x32_bf16 v[76:79], v[160:163], v[204:207], v[76:79]
	v_mfma_f32_16x16x32_bf16 v[72:75], v[168:171], v[204:207], v[72:75]
	v_mfma_f32_16x16x32_bf16 v[124:127], v[164:167], v[180:183], v[124:127]
	v_mfma_f32_16x16x32_bf16 v[120:123], v[172:175], v[180:183], v[120:123]
	v_mfma_f32_16x16x32_bf16 v[108:111], v[164:167], v[188:191], v[108:111]
	v_mfma_f32_16x16x32_bf16 v[104:107], v[172:175], v[188:191], v[104:107]
	v_mfma_f32_16x16x32_bf16 v[92:95], v[164:167], v[196:199], v[92:95]
	v_mfma_f32_16x16x32_bf16 v[88:91], v[172:175], v[196:199], v[88:91]
	v_mfma_f32_16x16x32_bf16 v[76:79], v[164:167], v[208:211], v[76:79]
	v_mfma_f32_16x16x32_bf16 v[72:75], v[172:175], v[208:211], v[72:75]
	s_barrier
	s_add_i32 s33, s60, s49
	v_lshl_add_u64 v[200:201], s[42:43], 0, v[134:135]
	s_mov_b32 m0, s33
	ds_read_b128 v[212:215], v159
	ds_read_b128 v[216:219], v159 offset:1024
	ds_read_b128 v[220:223], v159 offset:2048
	ds_read_b128 v[224:227], v159 offset:3072
	global_load_lds_dwordx4 v[200:201], off
	v_lshl_add_u64 v[228:229], s[42:43], 0, v[128:129]
	s_add_i32 m0, s33, 0x2000
	s_nop 0
	global_load_lds_dwordx4 v[228:229], off
	s_barrier
	s_waitcnt lgkmcnt(0)
	v_mfma_f32_16x16x32_bf16 v[116:119], v[212:215], v[176:179], v[116:119]
	v_mfma_f32_16x16x32_bf16 v[112:115], v[220:223], v[176:179], v[112:115]
	v_mfma_f32_16x16x32_bf16 v[100:103], v[212:215], v[184:187], v[100:103]
	v_mfma_f32_16x16x32_bf16 v[96:99], v[220:223], v[184:187], v[96:99]
	v_mfma_f32_16x16x32_bf16 v[84:87], v[212:215], v[192:195], v[84:87]
	v_mfma_f32_16x16x32_bf16 v[80:83], v[220:223], v[192:195], v[80:83]
	v_mfma_f32_16x16x32_bf16 v[68:71], v[212:215], v[204:207], v[68:71]
	v_mfma_f32_16x16x32_bf16 v[64:67], v[220:223], v[204:207], v[64:67]
	v_mfma_f32_16x16x32_bf16 v[116:119], v[216:219], v[180:183], v[116:119]
	v_mfma_f32_16x16x32_bf16 v[112:115], v[224:227], v[180:183], v[112:115]
	v_mfma_f32_16x16x32_bf16 v[100:103], v[216:219], v[188:191], v[100:103]
	v_mfma_f32_16x16x32_bf16 v[96:99], v[224:227], v[188:191], v[96:99]
	v_mfma_f32_16x16x32_bf16 v[84:87], v[216:219], v[196:199], v[84:87]
	v_mfma_f32_16x16x32_bf16 v[80:83], v[224:227], v[196:199], v[80:83]
	v_mfma_f32_16x16x32_bf16 v[68:71], v[216:219], v[208:211], v[68:71]
	v_mfma_f32_16x16x32_bf16 v[64:67], v[224:227], v[208:211], v[64:67]
	s_mov_b32 m0, s37
	v_lshl_add_u64 v[230:231], s[40:41], 0, v[138:139]
	s_barrier
	ds_read_b128 v[176:179], v158 offset:16384
	ds_read_b128 v[180:183], v158 offset:17408
	ds_read_b128 v[184:187], v158 offset:18432
	ds_read_b128 v[188:191], v158 offset:19456
	ds_read_b128 v[192:195], v158 offset:20480
	ds_read_b128 v[196:199], v158 offset:21504
	ds_read_b128 v[204:207], v158 offset:22528
	ds_read_b128 v[208:211], v158 offset:23552
	global_load_lds_dwordx4 v[230:231], off
	v_lshl_add_u64 v[232:233], s[40:41], 0, v[132:133]
	s_mov_b32 m0, s51
	s_nop 0
	global_load_lds_dwordx4 v[232:233], off
	s_barrier
	s_waitcnt lgkmcnt(0)
	v_mfma_f32_16x16x32_bf16 v[60:63], v[160:163], v[176:179], v[60:63]
	v_mfma_f32_16x16x32_bf16 v[56:59], v[168:171], v[176:179], v[56:59]
	v_mfma_f32_16x16x32_bf16 v[44:47], v[160:163], v[184:187], v[44:47]
	v_mfma_f32_16x16x32_bf16 v[40:43], v[168:171], v[184:187], v[40:43]
	v_mfma_f32_16x16x32_bf16 v[28:31], v[160:163], v[192:195], v[28:31]
	v_mfma_f32_16x16x32_bf16 v[24:27], v[168:171], v[192:195], v[24:27]
	v_mfma_f32_16x16x32_bf16 v[12:15], v[160:163], v[204:207], v[12:15]
	v_mfma_f32_16x16x32_bf16 v[8:11], v[168:171], v[204:207], v[8:11]
	v_mfma_f32_16x16x32_bf16 v[60:63], v[164:167], v[180:183], v[60:63]
	v_mfma_f32_16x16x32_bf16 v[56:59], v[172:175], v[180:183], v[56:59]
	v_mfma_f32_16x16x32_bf16 v[44:47], v[164:167], v[188:191], v[44:47]
	v_mfma_f32_16x16x32_bf16 v[40:43], v[172:175], v[188:191], v[40:43]
	v_mfma_f32_16x16x32_bf16 v[28:31], v[164:167], v[196:199], v[28:31]
	v_mfma_f32_16x16x32_bf16 v[24:27], v[172:175], v[196:199], v[24:27]
	v_mfma_f32_16x16x32_bf16 v[12:15], v[164:167], v[208:211], v[12:15]
	v_mfma_f32_16x16x32_bf16 v[8:11], v[172:175], v[208:211], v[8:11]
	s_barrier
; #define PG8_STAGE(bufoff, gbase, voff) do { _Pragma("unroll") for (int _i = 0; _i < 2; ++_i) \
;         __builtin_amdgcn_global_load_lds((const unsigned*)((const char*)(gbase) + (voff)[_i]), (LAS unsigned*)(lds + (bufoff) + ldsw + _i * 8192), 16, 0, 0); } while (0)
; #define PG8_LDA(dst, b, h) do { _Pragma("unroll") for (int m = 0; m < 4; ++m) _Pragma("unroll") for (int k = 0; k < 2; ++k) dst[m][k] = *(const LAS bf16x8*)(lds + PG8_SA(b, h) + aoff + m * 2048 + k * 1024); } while (0)
; #define PG8_LDB(dst, b, h) do { _Pragma("unroll") for (int n = 0; n < 2; ++n) _Pragma("unroll") for (int k = 0; k < 2; ++k) dst[n][k] = *(const LAS bf16x8*)(lds + PG8_SB(b, h) + boff + n * 2048 + k * 1024); } while (0)
; #define PG8_MMA(ai, bj, At, Bt) do { __builtin_amdgcn_s_setprio(1); _Pragma("unroll") for (int m = 0; m < 4; ++m) _Pragma("unroll") for (int n = 0; n < 2; ++n) _Pragma("unroll") for (int k = 0; k < 2; ++k) \
;         acc[ai][bj][m][n] = __builtin_amdgcn_mfma_f32_16x16x32_bf16(Bt[n][k], At[m][k], acc[ai][bj][m][n], 0, 0, 0); __builtin_amdgcn_s_setprio(0); } while (0)
; #define PG8_WAIT_V(n) asm volatile("s_waitcnt vmcnt(" #n ")" ::: "memory")
; #define PG8_WAIT_L(n) asm volatile("s_waitcnt lgkmcnt(" #n ")" ::: "memory")
; #define PG8_BAR __builtin_amdgcn_s_barrier()
; #define PG8_SCHED __builtin_amdgcn_sched_barrier(0)
; template <class Epi>
; __device__ __forceinline__ void gemm_phase(LAS unsigned char* lds, const Gemm g, const StaticOrder& S, const Epi& E) {
;     ...
;             PG8_STAGE(PG8_SB(0, 1), b2, voffB1);
;             PG8_WAIT_V(6); PG8_BAR; PG8_MMA(1, 1, At, B1); PG8_BAR;
;             PG8_LDB(B0, 1, 0); PG8_SCHED; PG8_LDA(At, 1, 0); PG8_STAGE(PG8_SA(0, 1), a2 + hstep, voffA);
;             PG8_WAIT_L(8); PG8_BAR; PG8_WAIT_L(0); PG8_MMA(0, 0, At, B0); PG8_BAR; PG8_SCHED;
;             PG8_LDB(B1, 1, 1); PG8_STAGE(PG8_SB(1, 0), b3, voffB0);
;             PG8_BAR; PG8_WAIT_L(0); PG8_MMA(0, 1, At, B1); PG8_BAR;
;             PG8_LDA(At, 1, 1); PG8_STAGE(PG8_SA(1, 0), a3, voffA);
;             PG8_BAR; PG8_WAIT_L(0); PG8_MMA(1, 0, At, B0); PG8_BAR; PG8_SCHED;
	s_add_i32 s33, s61, s49
	v_lshl_add_u64 v[234:235], s[42:43], 0, v[136:137]
	s_mov_b32 m0, s33
	v_lshl_add_u64 v[236:237], s[42:43], 0, v[130:131]
	global_load_lds_dwordx4 v[234:235], off
	s_add_i32 m0, s33, 0x2000
	s_nop 0
	global_load_lds_dwordx4 v[236:237], off
	s_add_i32 s33, 0, 0x18000
	v_add_u32_e32 v172, s33, v147
	ds_read_b128 v[160:163], v172
	ds_read_b128 v[164:167], v172 offset:1024
	ds_read_b128 v[168:171], v172 offset:2048
	ds_read_b128 v[172:175], v172 offset:3072
	s_waitcnt vmcnt(6)
	s_barrier
	v_mfma_f32_16x16x32_bf16 v[52:55], v[212:215], v[176:179], v[52:55]
	v_mfma_f32_16x16x32_bf16 v[48:51], v[220:223], v[176:179], v[48:51]
	v_mfma_f32_16x16x32_bf16 v[36:39], v[212:215], v[184:187], v[36:39]
	v_mfma_f32_16x16x32_bf16 v[32:35], v[220:223], v[184:187], v[32:35]
	v_mfma_f32_16x16x32_bf16 v[20:23], v[212:215], v[192:195], v[20:23]
	v_mfma_f32_16x16x32_bf16 v[16:19], v[220:223], v[192:195], v[16:19]
	v_mfma_f32_16x16x32_bf16 v[4:7], v[212:215], v[204:207], v[4:7]
	v_mfma_f32_16x16x32_bf16 v[0:3], v[220:223], v[204:207], v[0:3]
	v_mfma_f32_16x16x32_bf16 v[52:55], v[216:219], v[180:183], v[52:55]
	v_mfma_f32_16x16x32_bf16 v[48:51], v[224:227], v[180:183], v[48:51]
	v_mfma_f32_16x16x32_bf16 v[36:39], v[216:219], v[188:191], v[36:39]
	v_mfma_f32_16x16x32_bf16 v[32:35], v[224:227], v[188:191], v[32:35]
	v_mfma_f32_16x16x32_bf16 v[20:23], v[216:219], v[196:199], v[20:23]
	v_mfma_f32_16x16x32_bf16 v[16:19], v[224:227], v[196:199], v[16:19]
	v_mfma_f32_16x16x32_bf16 v[4:7], v[216:219], v[208:211], v[4:7]
	v_mfma_f32_16x16x32_bf16 v[0:3], v[224:227], v[208:211], v[0:3]
	s_barrier
	s_add_u32 s40, s40, 0x20000
	s_addc_u32 s41, s41, 0
	s_mov_b32 m0, s52
	v_lshl_add_u64 v[212:213], s[40:41], 0, v[138:139]
	ds_read_b128 v[176:179], v158 offset:32768
	ds_read_b128 v[180:183], v158 offset:33792
	ds_read_b128 v[184:187], v158 offset:34816
	ds_read_b128 v[188:191], v158 offset:35840
	ds_read_b128 v[192:195], v158 offset:36864
	ds_read_b128 v[196:199], v158 offset:37888
	ds_read_b128 v[204:207], v158 offset:38912
	ds_read_b128 v[208:211], v158 offset:39936
	global_load_lds_dwordx4 v[212:213], off
	v_lshl_add_u64 v[212:213], s[40:41], 0, v[132:133]
	s_mov_b32 m0, s53
	s_nop 0
	global_load_lds_dwordx4 v[212:213], off
	s_waitcnt lgkmcnt(8)
	s_barrier
	s_waitcnt lgkmcnt(0)
	v_mfma_f32_16x16x32_bf16 v[124:127], v[160:163], v[176:179], v[124:127]
	v_mfma_f32_16x16x32_bf16 v[120:123], v[168:171], v[176:179], v[120:123]
	v_mfma_f32_16x16x32_bf16 v[108:111], v[160:163], v[184:187], v[108:111]
	v_mfma_f32_16x16x32_bf16 v[104:107], v[168:171], v[184:187], v[104:107]
	v_mfma_f32_16x16x32_bf16 v[92:95], v[160:163], v[192:195], v[92:95]
	v_mfma_f32_16x16x32_bf16 v[88:91], v[168:171], v[192:195], v[88:91]
	v_mfma_f32_16x16x32_bf16 v[76:79], v[160:163], v[204:207], v[76:79]
	v_mfma_f32_16x16x32_bf16 v[72:75], v[168:171], v[204:207], v[72:75]
	v_mfma_f32_16x16x32_bf16 v[124:127], v[164:167], v[180:183], v[124:127]
	v_mfma_f32_16x16x32_bf16 v[120:123], v[172:175], v[180:183], v[120:123]
	v_mfma_f32_16x16x32_bf16 v[108:111], v[164:167], v[188:191], v[108:111]
	v_mfma_f32_16x16x32_bf16 v[104:107], v[172:175], v[188:191], v[104:107]
	v_mfma_f32_16x16x32_bf16 v[92:95], v[164:167], v[196:199], v[92:95]
	v_mfma_f32_16x16x32_bf16 v[88:91], v[172:175], v[196:199], v[88:91]
	v_mfma_f32_16x16x32_bf16 v[76:79], v[164:167], v[208:211], v[76:79]
	v_mfma_f32_16x16x32_bf16 v[72:75], v[172:175], v[208:211], v[72:75]
	s_barrier
	s_add_i32 s40, 0, 0x1c000
	s_add_i32 s33, s33, s49
	v_add_u32_e32 v224, s40, v147
	v_lshl_add_u64 v[200:201], v[200:201], 0, s[8:9]
	s_mov_b32 m0, s33
	ds_read_b128 v[212:215], v224
	ds_read_b128 v[216:219], v224 offset:1024
	ds_read_b128 v[220:223], v224 offset:2048
	ds_read_b128 v[224:227], v224 offset:3072
	global_load_lds_dwordx4 v[200:201], off
	v_lshl_add_u64 v[200:201], v[228:229], 0, s[8:9]
	s_add_i32 m0, s33, 0x2000
	s_nop 0
	global_load_lds_dwordx4 v[200:201], off
	s_barrier
	s_waitcnt lgkmcnt(0)
	v_mfma_f32_16x16x32_bf16 v[116:119], v[212:215], v[176:179], v[116:119]
	v_mfma_f32_16x16x32_bf16 v[112:115], v[220:223], v[176:179], v[112:115]
	v_mfma_f32_16x16x32_bf16 v[100:103], v[212:215], v[184:187], v[100:103]
	v_mfma_f32_16x16x32_bf16 v[96:99], v[220:223], v[184:187], v[96:99]
	v_mfma_f32_16x16x32_bf16 v[84:87], v[212:215], v[192:195], v[84:87]
	v_mfma_f32_16x16x32_bf16 v[80:83], v[220:223], v[192:195], v[80:83]
	v_mfma_f32_16x16x32_bf16 v[68:71], v[212:215], v[204:207], v[68:71]
	v_mfma_f32_16x16x32_bf16 v[64:67], v[220:223], v[204:207], v[64:67]
	v_mfma_f32_16x16x32_bf16 v[116:119], v[216:219], v[180:183], v[116:119]
	v_mfma_f32_16x16x32_bf16 v[112:115], v[224:227], v[180:183], v[112:115]
	v_mfma_f32_16x16x32_bf16 v[100:103], v[216:219], v[188:191], v[100:103]
	v_mfma_f32_16x16x32_bf16 v[96:99], v[224:227], v[188:191], v[96:99]
	v_mfma_f32_16x16x32_bf16 v[84:87], v[216:219], v[196:199], v[84:87]
	v_mfma_f32_16x16x32_bf16 v[80:83], v[224:227], v[196:199], v[80:83]
	v_mfma_f32_16x16x32_bf16 v[68:71], v[216:219], v[208:211], v[68:71]
	v_mfma_f32_16x16x32_bf16 v[64:67], v[224:227], v[208:211], v[64:67]
	s_mov_b32 m0, s55
	v_lshl_add_u64 v[200:201], v[230:231], 0, s[8:9]
	s_barrier
	ds_read_b128 v[176:179], v158 offset:49152
	ds_read_b128 v[180:183], v158 offset:50176
	ds_read_b128 v[184:187], v158 offset:51200
	ds_read_b128 v[188:191], v158 offset:52224
	ds_read_b128 v[192:195], v158 offset:53248
	ds_read_b128 v[196:199], v158 offset:54272
	ds_read_b128 v[204:207], v158 offset:55296
	ds_read_b128 v[208:211], v158 offset:56320
	global_load_lds_dwordx4 v[200:201], off
	v_lshl_add_u64 v[200:201], v[232:233], 0, s[8:9]
	s_mov_b32 m0, s56
	s_nop 0
	global_load_lds_dwordx4 v[200:201], off
	s_barrier
; __device__ __forceinline__ unsigned cvt_pk_bf16(float lo, float hi) { unsigned r; asm volatile("v_cvt_pk_bf16_f32 %0, %1, %2" : "=v"(r) : "v"(lo), "v"(hi)); return r; }
; #define PG8_STAGE(bufoff, gbase, voff) do { _Pragma("unroll") for (int _i = 0; _i < 2; ++_i) \
;         __builtin_amdgcn_global_load_lds((const unsigned*)((const char*)(gbase) + (voff)[_i]), (LAS unsigned*)(lds + (bufoff) + ldsw + _i * 8192), 16, 0, 0); } while (0)
; #define PG8_LDA(dst, b, h) do { _Pragma("unroll") for (int m = 0; m < 4; ++m) _Pragma("unroll") for (int k = 0; k < 2; ++k) dst[m][k] = *(const LAS bf16x8*)(lds + PG8_SA(b, h) + aoff + m * 2048 + k * 1024); } while (0)
; #define PG8_WAIT_V(n) asm volatile("s_waitcnt vmcnt(" #n ")" ::: "memory")
;     __device__ __forceinline__ void operator()(const f32x4 (&acc)[2][2][4][2], const Unit& u, int wr, int wc, int fr, int fq) const {
;     ...
;             for (int m = 0; m < 4; ++m) { const int row = row0 + ai * HALF + m * 16;
;                 const float rs = ssin ? __builtin_amdgcn_rsqf(ssin[row] * (1.f / D) + EPS) : 1.0f; float sq = 0.f; u32x4 w[2];
; #pragma unroll
;                 for (int bj = 0; bj < 2; ++bj) { f32x4 v0 = acc[ai][bj][m][0] * rs, v1 = acc[ai][bj][m][1] * rs;
;                     if (ACT == 1) {
; #pragma unroll
;                         for (int j = 0; j < 4; ++j) { const float a = fmaxf(v0[j], 0.f), b = fmaxf(v1[j], 0.f); v0[j] = a * a; v1[j] = b * b; } }
;                     sq += (v0[0] * v0[0] + v0[1] * v0[1]) + (v0[2] * v0[2] + v0[3] * v0[3]) + (v1[0] * v1[0] + v1[1] * v1[1]) + (v1[2] * v1[2] + v1[3] * v1[3]);
;                     w[bj].x = cvt_pk_bf16(v0[0], v0[1]); w[bj].y = cvt_pk_bf16(v0[2], v0[3]); w[bj].z = cvt_pk_bf16(v1[0], v1[1]); w[bj].w = cvt_pk_bf16(v1[2], v1[3]); }
;                 store_pair_lines(O, ldc, row, fr, col0, w[0], w[1]);
; template <class Epi>
; __device__ __forceinline__ void gemm_phase(LAS unsigned char* lds, const Gemm g, const StaticOrder& S, const Epi& E) {
;     ...
;             PG8_BAR; PG8_WAIT_L(0); PG8_MMA(0, 1, At, B1); PG8_BAR;
;             PG8_LDA(At, 1, 1); PG8_STAGE(PG8_SA(1, 0), a3, voffA);
;             PG8_BAR; PG8_WAIT_L(0); PG8_MMA(1, 0, At, B0); PG8_BAR; PG8_SCHED;
;             PG8_STAGE(PG8_SB(1, 1), b3, voffB1);
;             PG8_WAIT_V(6); PG8_BAR; PG8_MMA(1, 1, At, B1); PG8_BAR;
;         }
;         E(acc, cur, wr, wc, fr, fq);
	s_waitcnt lgkmcnt(0)
	v_mfma_f32_16x16x32_bf16 v[60:63], v[160:163], v[176:179], v[60:63]
	v_mfma_f32_16x16x32_bf16 v[56:59], v[168:171], v[176:179], v[56:59]
	v_mfma_f32_16x16x32_bf16 v[44:47], v[160:163], v[184:187], v[44:47]
	v_mfma_f32_16x16x32_bf16 v[40:43], v[168:171], v[184:187], v[40:43]
	v_mfma_f32_16x16x32_bf16 v[28:31], v[160:163], v[192:195], v[28:31]
	v_mfma_f32_16x16x32_bf16 v[24:27], v[168:171], v[192:195], v[24:27]
	v_mfma_f32_16x16x32_bf16 v[12:15], v[160:163], v[204:207], v[12:15]
	v_mfma_f32_16x16x32_bf16 v[8:11], v[168:171], v[204:207], v[8:11]
	v_mfma_f32_16x16x32_bf16 v[60:63], v[164:167], v[180:183], v[60:63]
	v_mfma_f32_16x16x32_bf16 v[56:59], v[172:175], v[180:183], v[56:59]
	v_mfma_f32_16x16x32_bf16 v[44:47], v[164:167], v[188:191], v[44:47]
	v_mfma_f32_16x16x32_bf16 v[40:43], v[172:175], v[188:191], v[40:43]
	v_mfma_f32_16x16x32_bf16 v[28:31], v[164:167], v[196:199], v[28:31]
	v_mfma_f32_16x16x32_bf16 v[24:27], v[172:175], v[196:199], v[24:27]
	v_mfma_f32_16x16x32_bf16 v[12:15], v[164:167], v[208:211], v[12:15]
	v_mfma_f32_16x16x32_bf16 v[8:11], v[172:175], v[208:211], v[8:11]
	s_barrier
	s_add_i32 s33, s40, s49
	v_lshl_add_u64 v[160:161], v[234:235], 0, s[8:9]
	s_mov_b32 m0, s33
	s_nop 0
	global_load_lds_dwordx4 v[160:161], off
	v_lshl_add_u64 v[160:161], v[236:237], 0, s[8:9]
	s_add_i32 m0, s33, 0x2000
	s_nop 0
	global_load_lds_dwordx4 v[160:161], off
	s_waitcnt vmcnt(6)
	s_barrier
	v_mfma_f32_16x16x32_bf16 v[52:55], v[212:215], v[176:179], v[52:55]
	v_mfma_f32_16x16x32_bf16 v[48:51], v[220:223], v[176:179], v[48:51]
	v_mfma_f32_16x16x32_bf16 v[36:39], v[212:215], v[184:187], v[36:39]
	v_mfma_f32_16x16x32_bf16 v[32:35], v[220:223], v[184:187], v[32:35]
	v_mfma_f32_16x16x32_bf16 v[20:23], v[212:215], v[192:195], v[20:23]
	v_mfma_f32_16x16x32_bf16 v[16:19], v[220:223], v[192:195], v[16:19]
	v_mfma_f32_16x16x32_bf16 v[4:7], v[212:215], v[204:207], v[4:7]
	v_mfma_f32_16x16x32_bf16 v[0:3], v[220:223], v[204:207], v[0:3]
	v_mfma_f32_16x16x32_bf16 v[52:55], v[216:219], v[180:183], v[52:55]
	v_mfma_f32_16x16x32_bf16 v[48:51], v[224:227], v[180:183], v[48:51]
	v_mfma_f32_16x16x32_bf16 v[36:39], v[216:219], v[188:191], v[36:39]
	v_mfma_f32_16x16x32_bf16 v[32:35], v[224:227], v[188:191], v[32:35]
	v_mfma_f32_16x16x32_bf16 v[20:23], v[216:219], v[196:199], v[20:23]
	v_mfma_f32_16x16x32_bf16 v[16:19], v[224:227], v[196:199], v[16:19]
	v_mfma_f32_16x16x32_bf16 v[4:7], v[216:219], v[208:211], v[4:7]
	v_mfma_f32_16x16x32_bf16 v[0:3], v[224:227], v[208:211], v[0:3]
	s_add_i32 s68, s68, 2
	s_add_u32 s38, s38, 0x100
	s_addc_u32 s39, s39, 0
	s_add_u32 s66, s66, 0x100
	s_addc_u32 s67, s67, 0
	s_cmp_gt_u32 s68, 5
	s_barrier
	s_cbranch_scc0 .LBB0_234
	s_lshl_b32 s11, s36, 8
	v_cvt_pk_bf16_f32 v124, v124, v125
	v_cvt_pk_bf16_f32 v125, v126, v127
	v_cvt_pk_bf16_f32 v120, v120, v121
	v_cvt_pk_bf16_f32 v121, v122, v123
	v_cvt_pk_bf16_f32 v122, v116, v117
	v_cvt_pk_bf16_f32 v123, v118, v119
	v_cvt_pk_bf16_f32 v112, v112, v113
	v_cvt_pk_bf16_f32 v113, v114, v115
	s_add_i32 s11, s11, s57
	v_lshl_or_b32 v162, s63, 8, v156
	v_mov_b32_dpp v114, v124 row_ror:8 row_mask:0xf bank_mask:0xf
	v_mov_b32_dpp v115, v125 row_ror:8 row_mask:0xf bank_mask:0xf
	v_mov_b32_dpp v126, v120 row_ror:8 row_mask:0xf bank_mask:0xf
	v_mov_b32_dpp v127, v121 row_ror:8 row_mask:0xf bank_mask:0xf
	v_mov_b32_dpp v118, v112 row_ror:8 row_mask:0xf bank_mask:0xf
	v_mov_b32_dpp v119, v113 row_ror:8 row_mask:0xf bank_mask:0xf
	v_ashrrev_i32_e32 v163, 31, v162
	v_mov_b32_dpp v116, v122 row_ror:8 row_mask:0xf bank_mask:0xf
	v_mov_b32_dpp v117, v123 row_ror:8 row_mask:0xf bank_mask:0xf
	v_cndmask_b32_e64 v118, v118, v120, s[4:5]
	v_cndmask_b32_e64 v119, v119, v121, s[4:5]
	v_cndmask_b32_e64 v120, v122, v114, s[4:5]
	v_cndmask_b32_e64 v121, v123, v115, s[4:5]
	v_cndmask_b32_e64 v122, v112, v126, s[4:5]
	v_cndmask_b32_e64 v123, v113, v127, s[4:5]
	v_or_b32_e32 v126, s11, v148
	v_mov_b64_e32 v[112:113], s[6:7]
	v_cndmask_b32_e64 v116, v116, v124, s[4:5]
	v_cndmask_b32_e64 v117, v117, v125, s[4:5]
	v_mad_i64_i32 v[124:125], s[38:39], v126, s62, v[112:113]
	v_lshlrev_b64 v[114:115], 1, v[162:163]
	v_lshl_add_u64 v[124:125], v[124:125], 0, v[114:115]
	global_store_dwordx4 v[124:125], v[116:119], off
	v_or_b32_e32 v160, s11, v146
	s_and_b64 vcc, exec, s[30:31]
	v_or_b32_e32 v116, 8, v126
	v_mad_i64_i32 v[116:117], s[38:39], v116, s62, v[112:113]
	v_lshl_add_u64 v[116:117], v[116:117], 0, v[114:115]
	global_store_dwordx4 v[116:117], v[120:123], off
	v_cvt_pk_bf16_f32 v108, v108, v109
	v_cvt_pk_bf16_f32 v109, v110, v111
	v_cvt_pk_bf16_f32 v104, v104, v105
	v_cvt_pk_bf16_f32 v105, v106, v107
	v_cvt_pk_bf16_f32 v100, v100, v101
	v_cvt_pk_bf16_f32 v101, v102, v103
	v_cvt_pk_bf16_f32 v102, v96, v97
	v_cvt_pk_bf16_f32 v103, v98, v99
	s_nop 0
	v_mov_b32_dpp v106, v108 row_ror:8 row_mask:0xf bank_mask:0xf
	v_mov_b32_dpp v96, v100 row_ror:8 row_mask:0xf bank_mask:0xf
	v_mov_b32_dpp v98, v102 row_ror:8 row_mask:0xf bank_mask:0xf
	v_mov_b32_dpp v99, v103 row_ror:8 row_mask:0xf bank_mask:0xf
	v_cndmask_b32_e64 v100, v100, v106, s[4:5]
	v_add_u32_e32 v106, v149, v160
	v_mov_b32_dpp v110, v104 row_ror:8 row_mask:0xf bank_mask:0xf
	v_mov_b32_dpp v111, v105 row_ror:8 row_mask:0xf bank_mask:0xf
	v_mov_b32_dpp v97, v101 row_ror:8 row_mask:0xf bank_mask:0xf
	v_cndmask_b32_e64 v98, v98, v104, s[4:5]
	v_cndmask_b32_e64 v99, v99, v105, s[4:5]
	v_mad_i64_i32 v[104:105], s[38:39], v106, s62, v[112:113]
	v_cndmask_b32_e64 v96, v96, v108, s[4:5]
	v_cndmask_b32_e64 v97, v97, v109, s[4:5]
	v_lshl_add_u64 v[104:105], v[104:105], 0, v[114:115]
	global_store_dwordx4 v[104:105], v[96:99], off
; __device__ __forceinline__ unsigned cvt_pk_bf16(float lo, float hi) { unsigned r; asm volatile("v_cvt_pk_bf16_f32 %0, %1, %2" : "=v"(r) : "v"(lo), "v"(hi)); return r; }
; __device__ __forceinline__ unsigned dpp_ror8(unsigned x) { return (unsigned)__builtin_amdgcn_update_dpp(0, (int)x, 0x128, 0xf, 0xf, false); }
; __device__ __forceinline__ void store_pair_lines(bf16_t* O, int ldc, int row, int fr, int col0, u32x4 wA, u32x4 wB) {
;     const u32x4 sA = {dpp_ror8(wA.x), dpp_ror8(wA.y), dpp_ror8(wA.z), dpp_ror8(wA.w)}, sB = {dpp_ror8(wB.x), dpp_ror8(wB.y), dpp_ror8(wB.z), dpp_ror8(wB.w)};
;     const bool lo = fr < 8;
;     const u32x4 o1 = lo ? wA : sB, o2 = lo ? sA : wB;
;     const int r1 = row - fr + (fr & 7), cb = col0 + (lo ? 0 : 8);
;     *(u32x4*)(O + (size_t)r1 * ldc + cb) = o1;
;     *(u32x4*)(O + (size_t)(r1 + 8) * ldc + cb) = o2;
; }
;     __device__ __forceinline__ void operator()(const f32x4 (&acc)[2][2][4][2], const Unit& u, int wr, int wc, int fr, int fq) const {
;     ...
;             for (int m = 0; m < 4; ++m) { const int row = row0 + ai * HALF + m * 16;
;                 const float rs = ssin ? __builtin_amdgcn_rsqf(ssin[row] * (1.f / D) + EPS) : 1.0f; float sq = 0.f; u32x4 w[2];
; #pragma unroll
;                 for (int bj = 0; bj < 2; ++bj) { f32x4 v0 = acc[ai][bj][m][0] * rs, v1 = acc[ai][bj][m][1] * rs;
;                     if (ACT == 1) {
; #pragma unroll
;                         for (int j = 0; j < 4; ++j) { const float a = fmaxf(v0[j], 0.f), b = fmaxf(v1[j], 0.f); v0[j] = a * a; v1[j] = b * b; } }
;                     sq += (v0[0] * v0[0] + v0[1] * v0[1]) + (v0[2] * v0[2] + v0[3] * v0[3]) + (v1[0] * v1[0] + v1[1] * v1[1]) + (v1[2] * v1[2] + v1[3] * v1[3]);
;                     w[bj].x = cvt_pk_bf16(v0[0], v0[1]); w[bj].y = cvt_pk_bf16(v0[2], v0[3]); w[bj].z = cvt_pk_bf16(v1[0], v1[1]); w[bj].w = cvt_pk_bf16(v1[2], v1[3]); }
;                 store_pair_lines(O, ldc, row, fr, col0, w[0], w[1]);
	v_cndmask_b32_e64 v102, v102, v110, s[4:5]
	v_mov_b32_dpp v107, v109 row_ror:8 row_mask:0xf bank_mask:0xf
	v_add_u32_e32 v96, 8, v106
	v_mad_i64_i32 v[96:97], s[38:39], v96, s62, v[112:113]
	v_cndmask_b32_e64 v101, v101, v107, s[4:5]
	v_cndmask_b32_e64 v103, v103, v111, s[4:5]
	v_lshl_add_u64 v[96:97], v[96:97], 0, v[114:115]
	global_store_dwordx4 v[96:97], v[100:103], off
	v_cvt_pk_bf16_f32 v92, v92, v93
	v_cvt_pk_bf16_f32 v93, v94, v95
	v_cvt_pk_bf16_f32 v88, v88, v89
	v_cvt_pk_bf16_f32 v89, v90, v91
	v_cvt_pk_bf16_f32 v84, v84, v85
	v_cvt_pk_bf16_f32 v85, v86, v87
	v_cvt_pk_bf16_f32 v86, v80, v81
	v_cvt_pk_bf16_f32 v87, v82, v83
	s_nop 0
	v_mov_b32_dpp v90, v92 row_ror:8 row_mask:0xf bank_mask:0xf
	v_mov_b32_dpp v80, v84 row_ror:8 row_mask:0xf bank_mask:0xf
	v_mov_b32_dpp v82, v86 row_ror:8 row_mask:0xf bank_mask:0xf
	v_mov_b32_dpp v83, v87 row_ror:8 row_mask:0xf bank_mask:0xf
	v_cndmask_b32_e64 v84, v84, v90, s[4:5]
	v_add_u32_e32 v90, v150, v160
	v_mov_b32_dpp v94, v88 row_ror:8 row_mask:0xf bank_mask:0xf
	v_mov_b32_dpp v95, v89 row_ror:8 row_mask:0xf bank_mask:0xf
	v_mov_b32_dpp v81, v85 row_ror:8 row_mask:0xf bank_mask:0xf
	v_cndmask_b32_e64 v82, v82, v88, s[4:5]
	v_cndmask_b32_e64 v83, v83, v89, s[4:5]
	v_mad_i64_i32 v[88:89], s[38:39], v90, s62, v[112:113]
	v_cndmask_b32_e64 v80, v80, v92, s[4:5]
	v_cndmask_b32_e64 v81, v81, v93, s[4:5]
	v_lshl_add_u64 v[88:89], v[88:89], 0, v[114:115]
	global_store_dwordx4 v[88:89], v[80:83], off
	v_cndmask_b32_e64 v86, v86, v94, s[4:5]
	v_mov_b32_dpp v91, v93 row_ror:8 row_mask:0xf bank_mask:0xf
	v_add_u32_e32 v80, 8, v90
	v_mad_i64_i32 v[80:81], s[38:39], v80, s62, v[112:113]
	v_cndmask_b32_e64 v85, v85, v91, s[4:5]
	v_cndmask_b32_e64 v87, v87, v95, s[4:5]
	v_lshl_add_u64 v[80:81], v[80:81], 0, v[114:115]
	global_store_dwordx4 v[80:81], v[84:87], off
	v_cvt_pk_bf16_f32 v76, v76, v77
	v_cvt_pk_bf16_f32 v77, v78, v79
	v_cvt_pk_bf16_f32 v72, v72, v73
	v_cvt_pk_bf16_f32 v73, v74, v75
	v_cvt_pk_bf16_f32 v68, v68, v69
	v_cvt_pk_bf16_f32 v69, v70, v71
	v_cvt_pk_bf16_f32 v70, v64, v65
	v_cvt_pk_bf16_f32 v71, v66, v67
	s_nop 0
	v_mov_b32_dpp v74, v76 row_ror:8 row_mask:0xf bank_mask:0xf
	v_mov_b32_dpp v64, v68 row_ror:8 row_mask:0xf bank_mask:0xf
	v_mov_b32_dpp v66, v70 row_ror:8 row_mask:0xf bank_mask:0xf
	v_mov_b32_dpp v67, v71 row_ror:8 row_mask:0xf bank_mask:0xf
	v_cndmask_b32_e64 v68, v68, v74, s[4:5]
	v_add_u32_e32 v74, v151, v160
	v_mov_b32_dpp v78, v72 row_ror:8 row_mask:0xf bank_mask:0xf
	v_mov_b32_dpp v79, v73 row_ror:8 row_mask:0xf bank_mask:0xf
	v_mov_b32_dpp v65, v69 row_ror:8 row_mask:0xf bank_mask:0xf
	v_cndmask_b32_e64 v66, v66, v72, s[4:5]
	v_cndmask_b32_e64 v67, v67, v73, s[4:5]
	v_mad_i64_i32 v[72:73], s[38:39], v74, s62, v[112:113]
	v_cndmask_b32_e64 v64, v64, v76, s[4:5]
	v_cndmask_b32_e64 v65, v65, v77, s[4:5]
	v_lshl_add_u64 v[72:73], v[72:73], 0, v[114:115]
	global_store_dwordx4 v[72:73], v[64:67], off
	v_cndmask_b32_e64 v70, v70, v78, s[4:5]
	v_mov_b32_dpp v75, v77 row_ror:8 row_mask:0xf bank_mask:0xf
	v_add_u32_e32 v64, 8, v74
	v_mad_i64_i32 v[64:65], s[38:39], v64, s62, v[112:113]
	v_cndmask_b32_e64 v69, v69, v75, s[4:5]
	v_cndmask_b32_e64 v71, v71, v79, s[4:5]
	v_lshl_add_u64 v[64:65], v[64:65], 0, v[114:115]
	global_store_dwordx4 v[64:65], v[68:71], off
	v_cvt_pk_bf16_f32 v60, v60, v61
	v_cvt_pk_bf16_f32 v61, v62, v63
	v_cvt_pk_bf16_f32 v56, v56, v57
	v_cvt_pk_bf16_f32 v57, v58, v59
	v_cvt_pk_bf16_f32 v52, v52, v53
	v_cvt_pk_bf16_f32 v53, v54, v55
	v_cvt_pk_bf16_f32 v54, v48, v49
	v_cvt_pk_bf16_f32 v55, v50, v51
	s_nop 0
	v_mov_b32_dpp v58, v60 row_ror:8 row_mask:0xf bank_mask:0xf
	v_mov_b32_dpp v48, v52 row_ror:8 row_mask:0xf bank_mask:0xf
	v_mov_b32_dpp v50, v54 row_ror:8 row_mask:0xf bank_mask:0xf
	v_mov_b32_dpp v51, v55 row_ror:8 row_mask:0xf bank_mask:0xf
	v_cndmask_b32_e64 v52, v52, v58, s[4:5]
	v_add_u32_e32 v58, v152, v160
	v_mov_b32_dpp v62, v56 row_ror:8 row_mask:0xf bank_mask:0xf
	v_mov_b32_dpp v63, v57 row_ror:8 row_mask:0xf bank_mask:0xf
	v_mov_b32_dpp v49, v53 row_ror:8 row_mask:0xf bank_mask:0xf
	v_cndmask_b32_e64 v50, v50, v56, s[4:5]
	v_cndmask_b32_e64 v51, v51, v57, s[4:5]
	v_mad_i64_i32 v[56:57], s[38:39], v58, s62, v[112:113]
	v_cndmask_b32_e64 v48, v48, v60, s[4:5]
	v_cndmask_b32_e64 v49, v49, v61, s[4:5]
	v_lshl_add_u64 v[56:57], v[56:57], 0, v[114:115]
	global_store_dwordx4 v[56:57], v[48:51], off
	v_cndmask_b32_e64 v54, v54, v62, s[4:5]
	v_mov_b32_dpp v59, v61 row_ror:8 row_mask:0xf bank_mask:0xf
	v_add_u32_e32 v48, 8, v58
	v_mad_i64_i32 v[48:49], s[38:39], v48, s62, v[112:113]
	v_cndmask_b32_e64 v53, v53, v59, s[4:5]
; __device__ __forceinline__ unsigned dpp_ror8(unsigned x) { return (unsigned)__builtin_amdgcn_update_dpp(0, (int)x, 0x128, 0xf, 0xf, false); }
; #define PG8_WAIT_V(n) asm volatile("s_waitcnt vmcnt(" #n ")" ::: "memory")
; #define PG8_BAR __builtin_amdgcn_s_barrier()
; __device__ __forceinline__ void store_pair_lines(bf16_t* O, int ldc, int row, int fr, int col0, u32x4 wA, u32x4 wB) {
;     const u32x4 sA = {dpp_ror8(wA.x), dpp_ror8(wA.y), dpp_ror8(wA.z), dpp_ror8(wA.w)}, sB = {dpp_ror8(wB.x), dpp_ror8(wB.y), dpp_ror8(wB.z), dpp_ror8(wB.w)};
;     const bool lo = fr < 8;
;     const u32x4 o1 = lo ? wA : sB, o2 = lo ? sA : wB;
;     const int r1 = row - fr + (fr & 7), cb = col0 + (lo ? 0 : 8);
;     *(u32x4*)(O + (size_t)r1 * ldc + cb) = o1;
;     *(u32x4*)(O + (size_t)(r1 + 8) * ldc + cb) = o2;
; }
; template <class Epi>
; __device__ __forceinline__ void gemm_phase(LAS unsigned char* lds, const Gemm g, const StaticOrder& S, const Epi& E) {
;     ...
;         E(acc, cur, wr, wc, fr, fq);
;         if (!has_next) break;
; #pragma unroll
;         for (int a = 0; a < 2; ++a)
; #pragma unroll
;             for (int b = 0; b < 2; ++b)
; #pragma unroll
;                 for (int m = 0; m < 4; ++m)
; #pragma unroll
;                     for (int n = 0; n < 2; ++n) acc[a][b][m][n] = (f32x4){0.f, 0.f, 0.f, 0.f};
;         cur = nxt; cA = nA; cB = nB; ++ui;
;     }
;     PG8_WAIT_V(0);
;     if (wr == 0) PG8_BAR;
;     PG8_BAR;
	v_cndmask_b32_e64 v55, v55, v63, s[4:5]
	v_lshl_add_u64 v[48:49], v[48:49], 0, v[114:115]
	global_store_dwordx4 v[48:49], v[52:55], off
	v_cvt_pk_bf16_f32 v44, v44, v45
	v_cvt_pk_bf16_f32 v45, v46, v47
	v_cvt_pk_bf16_f32 v40, v40, v41
	v_cvt_pk_bf16_f32 v41, v42, v43
	v_cvt_pk_bf16_f32 v36, v36, v37
	v_cvt_pk_bf16_f32 v37, v38, v39
	v_cvt_pk_bf16_f32 v38, v32, v33
	v_cvt_pk_bf16_f32 v39, v34, v35
	s_nop 0
	v_mov_b32_dpp v42, v44 row_ror:8 row_mask:0xf bank_mask:0xf
	v_mov_b32_dpp v32, v36 row_ror:8 row_mask:0xf bank_mask:0xf
	v_mov_b32_dpp v34, v38 row_ror:8 row_mask:0xf bank_mask:0xf
	v_mov_b32_dpp v35, v39 row_ror:8 row_mask:0xf bank_mask:0xf
	v_cndmask_b32_e64 v36, v36, v42, s[4:5]
	v_add_u32_e32 v42, v153, v160
	v_mov_b32_dpp v46, v40 row_ror:8 row_mask:0xf bank_mask:0xf
	v_mov_b32_dpp v47, v41 row_ror:8 row_mask:0xf bank_mask:0xf
	v_mov_b32_dpp v33, v37 row_ror:8 row_mask:0xf bank_mask:0xf
	v_cndmask_b32_e64 v34, v34, v40, s[4:5]
	v_cndmask_b32_e64 v35, v35, v41, s[4:5]
	v_mad_i64_i32 v[40:41], s[38:39], v42, s62, v[112:113]
	v_cndmask_b32_e64 v32, v32, v44, s[4:5]
	v_cndmask_b32_e64 v33, v33, v45, s[4:5]
	v_lshl_add_u64 v[40:41], v[40:41], 0, v[114:115]
	global_store_dwordx4 v[40:41], v[32:35], off
	v_cndmask_b32_e64 v38, v38, v46, s[4:5]
	v_mov_b32_dpp v43, v45 row_ror:8 row_mask:0xf bank_mask:0xf
	v_add_u32_e32 v32, 8, v42
	v_mad_i64_i32 v[32:33], s[38:39], v32, s62, v[112:113]
	v_cndmask_b32_e64 v37, v37, v43, s[4:5]
	v_cndmask_b32_e64 v39, v39, v47, s[4:5]
	v_lshl_add_u64 v[32:33], v[32:33], 0, v[114:115]
	global_store_dwordx4 v[32:33], v[36:39], off
	v_cvt_pk_bf16_f32 v28, v28, v29
	v_cvt_pk_bf16_f32 v29, v30, v31
	v_cvt_pk_bf16_f32 v24, v24, v25
	v_cvt_pk_bf16_f32 v25, v26, v27
	v_cvt_pk_bf16_f32 v20, v20, v21
	v_cvt_pk_bf16_f32 v21, v22, v23
	v_cvt_pk_bf16_f32 v22, v16, v17
	v_cvt_pk_bf16_f32 v23, v18, v19
	s_nop 0
	v_mov_b32_dpp v26, v28 row_ror:8 row_mask:0xf bank_mask:0xf
	v_mov_b32_dpp v16, v20 row_ror:8 row_mask:0xf bank_mask:0xf
	v_mov_b32_dpp v18, v22 row_ror:8 row_mask:0xf bank_mask:0xf
	v_mov_b32_dpp v19, v23 row_ror:8 row_mask:0xf bank_mask:0xf
	v_cndmask_b32_e64 v20, v20, v26, s[4:5]
	v_add_u32_e32 v26, v154, v160
	v_mov_b32_dpp v30, v24 row_ror:8 row_mask:0xf bank_mask:0xf
	v_mov_b32_dpp v31, v25 row_ror:8 row_mask:0xf bank_mask:0xf
	v_mov_b32_dpp v17, v21 row_ror:8 row_mask:0xf bank_mask:0xf
	v_cndmask_b32_e64 v18, v18, v24, s[4:5]
	v_cndmask_b32_e64 v19, v19, v25, s[4:5]
	v_mad_i64_i32 v[24:25], s[38:39], v26, s62, v[112:113]
	v_cndmask_b32_e64 v16, v16, v28, s[4:5]
	v_cndmask_b32_e64 v17, v17, v29, s[4:5]
	v_lshl_add_u64 v[24:25], v[24:25], 0, v[114:115]
	global_store_dwordx4 v[24:25], v[16:19], off
	v_cndmask_b32_e64 v22, v22, v30, s[4:5]
	v_mov_b32_dpp v27, v29 row_ror:8 row_mask:0xf bank_mask:0xf
	v_add_u32_e32 v16, 8, v26
	v_mad_i64_i32 v[16:17], s[38:39], v16, s62, v[112:113]
	v_cndmask_b32_e64 v21, v21, v27, s[4:5]
	v_cndmask_b32_e64 v23, v23, v31, s[4:5]
	v_lshl_add_u64 v[16:17], v[16:17], 0, v[114:115]
	global_store_dwordx4 v[16:17], v[20:23], off
	v_cvt_pk_bf16_f32 v12, v12, v13
	v_cvt_pk_bf16_f32 v13, v14, v15
	v_cvt_pk_bf16_f32 v8, v8, v9
	v_cvt_pk_bf16_f32 v9, v10, v11
	v_cvt_pk_bf16_f32 v4, v4, v5
	v_cvt_pk_bf16_f32 v5, v6, v7
	v_cvt_pk_bf16_f32 v6, v0, v1
	v_cvt_pk_bf16_f32 v7, v2, v3
	s_nop 0
	v_mov_b32_dpp v10, v12 row_ror:8 row_mask:0xf bank_mask:0xf
	v_mov_b32_dpp v0, v4 row_ror:8 row_mask:0xf bank_mask:0xf
	v_mov_b32_dpp v2, v6 row_ror:8 row_mask:0xf bank_mask:0xf
	v_mov_b32_dpp v3, v7 row_ror:8 row_mask:0xf bank_mask:0xf
	v_cndmask_b32_e64 v4, v4, v10, s[4:5]
	v_add_u32_e32 v10, v155, v160
	v_mov_b32_dpp v14, v8 row_ror:8 row_mask:0xf bank_mask:0xf
	v_mov_b32_dpp v15, v9 row_ror:8 row_mask:0xf bank_mask:0xf
	v_mov_b32_dpp v1, v5 row_ror:8 row_mask:0xf bank_mask:0xf
	v_cndmask_b32_e64 v2, v2, v8, s[4:5]
	v_cndmask_b32_e64 v3, v3, v9, s[4:5]
	v_mad_i64_i32 v[8:9], s[38:39], v10, s62, v[112:113]
	v_cndmask_b32_e64 v0, v0, v12, s[4:5]
	v_cndmask_b32_e64 v1, v1, v13, s[4:5]
	v_lshl_add_u64 v[8:9], v[8:9], 0, v[114:115]
	global_store_dwordx4 v[8:9], v[0:3], off
	v_cndmask_b32_e64 v6, v6, v14, s[4:5]
	v_mov_b32_dpp v11, v13 row_ror:8 row_mask:0xf bank_mask:0xf
	v_add_u32_e32 v0, 8, v10
	v_mad_i64_i32 v[0:1], s[38:39], v0, s62, v[112:113]
	v_cndmask_b32_e64 v5, v5, v11, s[4:5]
	v_cndmask_b32_e64 v7, v7, v15, s[4:5]
	v_lshl_add_u64 v[0:1], v[0:1], 0, v[114:115]
	s_mov_b32 s63, s10
	s_mov_b32 s36, s16
	s_mov_b64 s[40:41], s[34:35]
	s_mov_b64 s[38:39], s[18:19]
	global_store_dwordx4 v[0:1], v[4:7], off
	s_cbranch_vccz .LBB0_230
	s_waitcnt vmcnt(0)
	s_cmpk_gt_u32 s44, 0xff
	s_cbranch_scc1 .LBB0_238
	s_barrier

; #define LAS __attribute__((address_space(3)))
; __device__ __forceinline__ void vt_item(LAS unsigned char* lds, const bf16_t* src, int sstride, bf16_t* vt_rows, int tok0) {
;     int tid = threadIdx.x; asm volatile("" : "+v"(tid));
;     constexpr int TROW = 272;
; #pragma unroll
;     for (int i = 0; i < 2; ++i) { const int cid = tid + i * 512, row = cid >> 4, cc = cid & 15;
;         const u32x4 v = *(const u32x4*)(src + (size_t)row * sstride + cc * 8);
;         *(LAS u32x4*)(lds + row * TROW + cc * 16) = v; }
;     __syncthreads();
; #pragma unroll
;     for (int i = 0; i < 2; ++i) { const int wid2 = tid + i * 512, d = wid2 >> 3, ck = wid2 & 7;
;         unsigned short e[8];
; #pragma unroll
;         for (int j = 0; j < 8; ++j) { const int quad = (ck & 1) * 2 + (j >> 2); const int q2 = (quad == 1) ? 2 : (quad == 2 ? 1 : quad); const int t = (ck >> 1) * 16 + q2 * 4 + (j & 3);
;             e[j] = *(const LAS unsigned short*)(lds + t * TROW + d * 2); }
;         u32x4 o; o.x = e[0] | ((unsigned)e[1] << 16); o.y = e[2] | ((unsigned)e[3] << 16); o.z = e[4] | ((unsigned)e[5] << 16); o.w = e[6] | ((unsigned)e[7] << 16);
;         *(u32x4*)(vt_rows + (size_t)d * M + tok0 + ck * 8) = o; }
;     __syncthreads();
; __global__ void __launch_bounds__(NTHREADS, 2) fwd_megakernel(Params P) {
;     ...
;         _Pragma("unroll 1") for (int rp_ = 0; rp_ < REP_PREP; ++rp_) for (int it = bid; it < 256 * 8; it += G) { const int tt = it >> 3, h = it & 7;
;             vt_item(lds, KV1 + (size_t)(tt * 64) * 2048 + h * 256 + 128, 2048, VTM + (size_t)(h * 128) * M, tt * 64); }
.LBB0_307:
	s_cmp_lg_u32 s6, s56
	s_mov_b64 s[6:7], -1
	s_cbranch_scc0 .LBB0_311
	s_andn2_b64 vcc, exec, s[40:41]
	s_mov_b32 s8, s51
	s_mov_b32 s9, s50
	s_cbranch_vccnz .LBB0_310
	v_mov_b32_e32 v115, v57
	s_and_b32 s6, s8, 0xffffffc0
	s_ashr_i32 s7, s6, 31
	s_and_b32 s16, s9, 7
	s_lshl_b64 s[10:11], s[6:7], 12
	v_mov_b32_e32 v110, v202
	s_add_u32 s10, s52, s10
	s_addc_u32 s11, s53, s11
	v_add_u32_e32 v112, 0x200, v110
	s_lshl_b32 s17, s16, 9
	v_lshlrev_b32_e32 v116, 4, v110
	v_ashrrev_i32_e32 v106, 4, v110
	v_ashrrev_i32_e32 v108, 4, v112
	s_add_u32 s10, s10, s17
	v_and_b32_e32 v114, 0xf0, v116
	v_ashrrev_i32_e32 v107, 31, v106
	v_ashrrev_i32_e32 v109, 31, v108
	s_addc_u32 s11, s11, 0
	v_lshlrev_b64 v[100:101], 12, v[106:107]
	v_lshlrev_b64 v[102:103], 12, v[108:109]
	v_lshl_add_u64 v[104:105], s[10:11], 0, v[114:115]
	v_lshl_add_u64 v[100:101], v[104:105], 0, v[100:101]
	v_lshl_add_u64 v[104:105], v[104:105], 0, v[102:103]
	global_load_dwordx4 v[120:123], v[100:101], off offset:256
	global_load_dwordx4 v[124:127], v[104:105], off offset:256
	global_load_dword v76, v[100:101], off offset:256
	global_load_dword v78, v[104:105], off offset:256
.LBB0_309:
	s_and_b32 s6, s8, 0xffffffc0
	s_ashr_i32 s7, s6, 31
	s_and_b32 s16, s9, 7
	s_lshl_b64 s[10:11], s[6:7], 12
	v_mov_b32_e32 v52, v202
	s_add_u32 s10, s52, s10
	s_addc_u32 s11, s53, s11
	v_add_u32_e32 v54, 0x200, v52
	s_lshl_b32 s17, s16, 9
	v_lshlrev_b32_e32 v70, 4, v52
	v_ashrrev_i32_e32 v48, 4, v52
	v_ashrrev_i32_e32 v50, 4, v54
	s_add_u32 s10, s10, s17
	v_and_b32_e32 v56, 0xf0, v70
	v_ashrrev_i32_e32 v49, 31, v48
	v_ashrrev_i32_e32 v51, 31, v50
	s_addc_u32 s11, s11, 0
	v_lshlrev_b64 v[40:41], 12, v[48:49]
	v_lshlrev_b64 v[42:43], 12, v[50:51]
	v_lshl_add_u64 v[44:45], s[10:11], 0, v[56:57]
	v_lshl_add_u64 v[40:41], v[44:45], 0, v[40:41]
	v_lshl_add_u64 v[44:45], v[44:45], 0, v[42:43]
	s_nop 0
	s_nop 0
	s_nop 0
	v_lshlrev_b32_e32 v49, 1, v52
	v_lshlrev_b32_e32 v51, 3, v52
	v_and_b32_e32 v49, 2, v49
	v_and_b32_e32 v71, 48, v51
	v_add_u32_e32 v56, 0, v56
	v_lshl_or_b32 v73, v49, 1, v71
	v_cmp_eq_u32_e32 vcc, 0, v49
	v_mad_u64_u32 v[48:49], s[10:11], v48, s31, v[56:57]
	v_mad_u64_u32 v[50:51], s[10:11], v50, s31, v[56:57]
	s_lshl_b32 s10, s16, 22
	s_add_u32 s10, s54, s10
	s_addc_u32 s11, s55, 0
	s_lshl_b64 s[6:7], s[6:7], 1
	v_ashrrev_i32_e32 v52, 3, v52
	v_ashrrev_i32_e32 v54, 3, v54
	v_cndmask_b32_e64 v74, 12, 8, vcc
	s_add_u32 s6, s10, s6
	v_lshl_add_u32 v72, v52, 1, 0
	v_ashrrev_i32_e32 v53, 31, v52
	v_lshl_add_u32 v75, v54, 1, 0
	v_ashrrev_i32_e32 v55, 31, v54
	v_or_b32_e32 v51, v74, v71
	v_and_b32_e32 v56, 0x70, v70
	s_addc_u32 s7, s11, s7
	v_lshlrev_b64 v[52:53], 15, v[52:53]
	v_mad_u32_u24 v49, v73, s31, v72
	v_lshlrev_b64 v[54:55], 15, v[54:55]
	v_mad_u32_u24 v72, v51, s31, v72
	v_mad_u32_u24 v51, v51, s31, v75
	v_lshl_add_u64 v[70:71], s[6:7], 0, v[56:57]
	v_mad_u32_u24 v73, v73, s31, v75
	v_lshl_add_u64 v[52:53], v[70:71], 0, v[52:53]
	v_lshl_add_u64 v[54:55], v[70:71], 0, v[54:55]
	s_add_i32 s9, s9, s20
	s_add_i32 s8, s8, s26
	s_cmpk_lt_i32 s9, 0x800
	s_waitcnt vmcnt(3)
	ds_write_b128 v48, v[120:123]
	s_waitcnt vmcnt(2)
	ds_write_b128 v50, v[124:127]
	s_waitcnt lgkmcnt(0)
	v_mov_b32_e32 v115, v57
	s_and_b32 s6, s8, 0xffffffc0
	s_ashr_i32 s7, s6, 31
	s_and_b32 s16, s9, 7
	s_lshl_b64 s[10:11], s[6:7], 12
	v_mov_b32_e32 v110, v202
	s_add_u32 s10, s52, s10
	s_addc_u32 s11, s53, s11
	v_add_u32_e32 v112, 0x200, v110
	s_lshl_b32 s17, s16, 9
	v_lshlrev_b32_e32 v116, 4, v110
	v_ashrrev_i32_e32 v106, 4, v110
	v_ashrrev_i32_e32 v108, 4, v112
	s_add_u32 s10, s10, s17
	v_and_b32_e32 v114, 0xf0, v116
	v_ashrrev_i32_e32 v107, 31, v106
	v_ashrrev_i32_e32 v109, 31, v108
	s_addc_u32 s11, s11, 0
	v_lshlrev_b64 v[100:101], 12, v[106:107]
	v_lshlrev_b64 v[102:103], 12, v[108:109]
	v_lshl_add_u64 v[104:105], s[10:11], 0, v[114:115]
	v_lshl_add_u64 v[100:101], v[104:105], 0, v[100:101]
	v_lshl_add_u64 v[104:105], v[104:105], 0, v[102:103]
	global_load_dwordx4 v[120:123], v[100:101], off offset:256
	global_load_dwordx4 v[124:127], v[104:105], off offset:256
	s_cmpk_lt_i32 s9, 0x800
	s_barrier
	ds_read_u16 v40, v49
	ds_read_u16 v44, v49 offset:272
	ds_read_u16 v41, v49 offset:544
	ds_read_u16 v45, v49 offset:816
	ds_read_u16 v42, v72
	ds_read_u16 v46, v72 offset:272
	ds_read_u16 v43, v72 offset:544
	ds_read_u16 v47, v72 offset:816
	ds_read_u16 v48, v73
	ds_read_u16 v49, v73 offset:272
	ds_read_u16 v50, v73 offset:544
	ds_read_u16 v56, v73 offset:816
	ds_read_u16 v70, v51
	ds_read_u16 v71, v51 offset:272
	ds_read_u16 v72, v51 offset:544
	ds_read_u16 v51, v51 offset:816
	s_waitcnt lgkmcnt(8)
	v_perm_b32 v43, v47, v43, s57
	v_perm_b32 v42, v46, v42, s57
	v_perm_b32 v41, v45, v41, s57
	v_perm_b32 v40, v44, v40, s57
	s_waitcnt lgkmcnt(0)
	v_perm_b32 v47, v51, v72, s57
	v_perm_b32 v46, v71, v70, s57
	v_perm_b32 v45, v56, v50, s57
	v_perm_b32 v44, v49, v48, s57
	global_store_dwordx4 v[52:53], v[40:43], off
	global_store_dwordx4 v[54:55], v[44:47], off
	s_barrier
	s_cbranch_scc1 .LBB0_309
	s_waitcnt vmcnt(0)

; #define LAS __attribute__((address_space(3)))
; __device__ __forceinline__ unsigned cvt_pk_bf16(float lo, float hi) { unsigned r; asm volatile("v_cvt_pk_bf16_f32 %0, %1, %2" : "=v"(r) : "v"(lo), "v"(hi)); return r; }
; __device__ __forceinline__ void transpose_item(const float* W, int K, int N, bf16_t* WT, LAS float* scr, int item, int lane, const float* gk) {
;     ...
;     for (int i = 0; i < 16; ++i) { LAS float* d = scr + (4 * i + (lane >> 4)) * 65 + 4 * (lane & 15); d[0] = v[i][0]; d[1] = v[i][1]; d[2] = v[i][2]; d[3] = v[i][3]; }
;     asm volatile("s_waitcnt lgkmcnt(0)" ::: "memory");
;     const int c = lane & 7;
; #pragma unroll
;     for (int j = 0; j < 8; ++j) { const int n = (lane >> 3) + 8 * j; const LAS float* s = scr + (8 * c) * 65 + n;
;         u32x4 o; o.x = cvt_pk_bf16(s[0 * 65], s[1 * 65]); o.y = cvt_pk_bf16(s[2 * 65], s[3 * 65]); o.z = cvt_pk_bf16(s[4 * 65], s[5 * 65]); o.w = cvt_pk_bf16(s[6 * 65], s[7 * 65]);
;         *(u32x4*)(WT + (size_t)(n0 + n) * K + k0 + 8 * c) = o; }
.LBB0_392:
	v_add_u32_e32 v0, 0x410, v206
	s_waitcnt vmcnt(15)
	ds_write2_b32 v206, v6, v7 offset1:1
	ds_write2_b32 v206, v8, v9 offset0:2 offset1:3
	s_waitcnt vmcnt(14)
	ds_write2_b32 v0, v2, v3 offset1:1
	v_add_u32_e32 v0, 0x418, v206
	ds_write2_b32 v0, v4, v5 offset1:1
	v_add_u32_e32 v0, 0x820, v206
	s_waitcnt vmcnt(13)
	ds_write2_b32 v0, v14, v15 offset1:1
	v_add_u32_e32 v0, 0x828, v206
	ds_write2_b32 v0, v16, v17 offset1:1
	v_add_u32_e32 v0, 0xc30, v206
	s_waitcnt vmcnt(12)
	ds_write2_b32 v0, v10, v11 offset1:1
	v_add_u32_e32 v0, 0xc38, v206
	ds_write2_b32 v0, v12, v13 offset1:1
	v_add_u32_e32 v0, 0x1040, v206
	s_waitcnt vmcnt(11)
	ds_write2_b32 v0, v22, v23 offset1:1
	v_add_u32_e32 v0, 0x1048, v206
	ds_write2_b32 v0, v24, v25 offset1:1
	v_add_u32_e32 v0, 0x1450, v206
	s_waitcnt vmcnt(10)
	ds_write2_b32 v0, v18, v19 offset1:1
	v_add_u32_e32 v0, 0x1458, v206
	ds_write2_b32 v0, v20, v21 offset1:1
	v_add_u32_e32 v0, 0x1860, v206
	s_waitcnt vmcnt(9)
	ds_write2_b32 v0, v30, v31 offset1:1
	v_add_u32_e32 v0, 0x1868, v206
	ds_write2_b32 v0, v32, v33 offset1:1
	v_add_u32_e32 v0, 0x1c70, v206
	s_waitcnt vmcnt(8)
	ds_write2_b32 v0, v26, v27 offset1:1
	v_add_u32_e32 v0, 0x1c78, v206
	ds_write2_b32 v0, v28, v29 offset1:1
	v_add_u32_e32 v0, 0x2080, v206
	s_waitcnt vmcnt(7)
	ds_write2_b32 v0, v38, v39 offset1:1
	v_add_u32_e32 v0, 0x2088, v206
	ds_write2_b32 v0, v40, v41 offset1:1
	v_add_u32_e32 v0, 0x2490, v206
	s_waitcnt vmcnt(6)
	ds_write2_b32 v0, v34, v35 offset1:1
	v_add_u32_e32 v0, 0x2498, v206
	ds_write2_b32 v0, v36, v37 offset1:1
	v_add_u32_e32 v0, 0x28a0, v206
	s_waitcnt vmcnt(5)
	ds_write2_b32 v0, v46, v47 offset1:1
	v_add_u32_e32 v0, 0x28a8, v206
	ds_write2_b32 v0, v48, v49 offset1:1
	v_add_u32_e32 v0, 0x2cb0, v206
	s_waitcnt vmcnt(4)
	ds_write2_b32 v0, v42, v43 offset1:1
	v_add_u32_e32 v0, 0x2cb8, v206
	ds_write2_b32 v0, v44, v45 offset1:1
	v_add_u32_e32 v0, 0x30c0, v206
	s_waitcnt vmcnt(3)
	ds_write2_b32 v0, v54, v55 offset1:1
	v_add_u32_e32 v0, 0x30c8, v206
	ds_write2_b32 v0, v56, v57 offset1:1
	v_add_u32_e32 v0, 0x34d0, v206
	s_waitcnt vmcnt(2)
	ds_write2_b32 v0, v50, v51 offset1:1
	v_add_u32_e32 v0, 0x34d8, v206
	ds_write2_b32 v0, v52, v53 offset1:1
	v_add_u32_e32 v0, 0x38e0, v206
	s_waitcnt vmcnt(1)
	ds_write2_b32 v0, v62, v63 offset1:1
	v_add_u32_e32 v0, 0x38e8, v206
	ds_write2_b32 v0, v64, v65 offset1:1
	v_add_u32_e32 v0, 0x3cf0, v206
	s_waitcnt vmcnt(0)
	ds_write2_b32 v0, v58, v59 offset1:1
	v_add_u32_e32 v0, 0x3cf8, v206
	ds_write2_b32 v0, v60, v61 offset1:1
	s_waitcnt lgkmcnt(0)
	v_add_u32_e32 v14, 0x400, v208
	ds_read2_b32 v[16:17], v208 offset1:65
	ds_read2_b32 v[18:19], v208 offset0:130 offset1:195
	ds_read2_b32 v[20:21], v14 offset0:4 offset1:69
	ds_read2_b32 v[22:23], v14 offset0:134 offset1:199
	ds_read2_b32 v[24:25], v208 offset0:8 offset1:73
	ds_read2_b32 v[26:27], v208 offset0:138 offset1:203
	ds_read2_b32 v[28:29], v14 offset0:12 offset1:77
	ds_read2_b32 v[30:31], v14 offset0:142 offset1:207
	ds_read2_b32 v[32:33], v208 offset0:16 offset1:81
	ds_read2_b32 v[34:35], v208 offset0:146 offset1:211
	ds_read2_b32 v[36:37], v14 offset0:20 offset1:85
	ds_read2_b32 v[38:39], v14 offset0:150 offset1:215
	ds_read2_b32 v[40:41], v208 offset0:24 offset1:89
	ds_read2_b32 v[42:43], v208 offset0:154 offset1:219
	ds_read2_b32 v[44:45], v14 offset0:28 offset1:93
	ds_read2_b32 v[46:47], v14 offset0:158 offset1:223
	ds_read2_b32 v[48:49], v208 offset0:32 offset1:97
	ds_read2_b32 v[50:51], v208 offset0:162 offset1:227
	ds_read2_b32 v[52:53], v14 offset0:36 offset1:101
	ds_read2_b32 v[54:55], v14 offset0:166 offset1:231
	ds_read2_b32 v[56:57], v208 offset0:40 offset1:105
	ds_read2_b32 v[58:59], v208 offset0:170 offset1:235
	ds_read2_b32 v[60:61], v14 offset0:44 offset1:109
	ds_read2_b32 v[62:63], v14 offset0:174 offset1:239
	ds_read2_b32 v[64:65], v208 offset0:48 offset1:113
	ds_read2_b32 v[70:71], v208 offset0:178 offset1:243
	ds_read2_b32 v[100:101], v14 offset0:52 offset1:117
	ds_read2_b32 v[102:103], v14 offset0:182 offset1:247
	ds_read2_b32 v[104:105], v208 offset0:56 offset1:121
	ds_read2_b32 v[106:107], v208 offset0:186 offset1:251
	ds_read2_b32 v[108:109], v14 offset0:60 offset1:125
	ds_read2_b32 v[110:111], v14 offset0:190 offset1:255
	s_waitcnt lgkmcnt(15)
; #define LAS __attribute__((address_space(3)))
; __device__ __forceinline__ unsigned cvt_pk_bf16(float lo, float hi) { unsigned r; asm volatile("v_cvt_pk_bf16_f32 %0, %1, %2" : "=v"(r) : "v"(lo), "v"(hi)); return r; }
; __device__ __forceinline__ void transpose_item(const float* W, int K, int N, bf16_t* WT, LAS float* scr, int item, int lane, const float* gk) {
;     ...
;     for (int j = 0; j < 8; ++j) { const int n = (lane >> 3) + 8 * j; const LAS float* s = scr + (8 * c) * 65 + n;
;         u32x4 o; o.x = cvt_pk_bf16(s[0 * 65], s[1 * 65]); o.y = cvt_pk_bf16(s[2 * 65], s[3 * 65]); o.z = cvt_pk_bf16(s[4 * 65], s[5 * 65]); o.w = cvt_pk_bf16(s[6 * 65], s[7 * 65]);
;         *(u32x4*)(WT + (size_t)(n0 + n) * K + k0 + 8 * c) = o; }
	v_cvt_pk_bf16_f32 v4, v16, v17
	s_waitcnt lgkmcnt(15)
	v_cvt_pk_bf16_f32 v5, v18, v19
	s_waitcnt lgkmcnt(15)
	v_cvt_pk_bf16_f32 v6, v20, v21
	v_add_u32_e32 v15, s62, v207
	s_waitcnt lgkmcnt(15)
	v_cvt_pk_bf16_f32 v7, v22, v23
	v_mad_u64_u32 v[8:9], s[62:63], v15, s67, 0
	v_ashrrev_i32_e32 v12, 31, v15
	v_mov_b32_e32 v0, v9
	s_ashr_i32 s65, s64, 31
	v_mad_u64_u32 v[12:13], s[62:63], v12, s67, v[0:1]
	v_lshl_add_u64 v[2:3], s[64:65], 1, v[66:67]
	v_mov_b32_e32 v9, v12
	v_lshl_add_u64 v[8:9], v[8:9], 1, v[2:3]
	global_store_dwordx4 v[8:9], v[4:7], off
	v_add_u32_e32 v0, 8, v15
	v_ashrrev_i32_e32 v12, 31, v0
	s_waitcnt lgkmcnt(15)
	v_cvt_pk_bf16_f32 v4, v24, v25
	s_waitcnt lgkmcnt(15)
	v_cvt_pk_bf16_f32 v5, v26, v27
	s_waitcnt lgkmcnt(15)
	v_cvt_pk_bf16_f32 v6, v28, v29
	s_waitcnt lgkmcnt(15)
	v_cvt_pk_bf16_f32 v7, v30, v31
	v_mad_u64_u32 v[8:9], s[62:63], v0, s67, 0
	v_mov_b32_e32 v0, v9
	v_mad_u64_u32 v[12:13], s[62:63], v12, s67, v[0:1]
	v_mov_b32_e32 v9, v12
	v_lshl_add_u64 v[8:9], v[8:9], 1, v[2:3]
	global_store_dwordx4 v[8:9], v[4:7], off
	v_add_u32_e32 v0, 16, v15
	v_ashrrev_i32_e32 v12, 31, v0
	s_waitcnt lgkmcnt(15)
	v_cvt_pk_bf16_f32 v4, v32, v33
	s_waitcnt lgkmcnt(15)
	v_cvt_pk_bf16_f32 v5, v34, v35
	s_waitcnt lgkmcnt(15)
	v_cvt_pk_bf16_f32 v6, v36, v37
	s_waitcnt lgkmcnt(15)
	v_cvt_pk_bf16_f32 v7, v38, v39
	v_mad_u64_u32 v[8:9], s[62:63], v0, s67, 0
	v_mov_b32_e32 v0, v9
	v_mad_u64_u32 v[12:13], s[62:63], v12, s67, v[0:1]
	v_mov_b32_e32 v9, v12
	v_lshl_add_u64 v[8:9], v[8:9], 1, v[2:3]
	global_store_dwordx4 v[8:9], v[4:7], off
	v_add_u32_e32 v0, 24, v15
	v_ashrrev_i32_e32 v12, 31, v0
	s_waitcnt lgkmcnt(15)
	v_cvt_pk_bf16_f32 v4, v40, v41
	s_waitcnt lgkmcnt(15)
	v_cvt_pk_bf16_f32 v5, v42, v43
	s_waitcnt lgkmcnt(15)
	v_cvt_pk_bf16_f32 v6, v44, v45
	s_waitcnt lgkmcnt(15)
	v_cvt_pk_bf16_f32 v7, v46, v47
	v_mad_u64_u32 v[8:9], s[62:63], v0, s67, 0
	v_mov_b32_e32 v0, v9
	v_mad_u64_u32 v[12:13], s[62:63], v12, s67, v[0:1]
	v_mov_b32_e32 v9, v12
	v_lshl_add_u64 v[8:9], v[8:9], 1, v[2:3]
	global_store_dwordx4 v[8:9], v[4:7], off
	v_add_u32_e32 v0, 32, v15
	v_ashrrev_i32_e32 v12, 31, v0
	s_waitcnt lgkmcnt(15)
	v_cvt_pk_bf16_f32 v4, v48, v49
	s_waitcnt lgkmcnt(14)
	v_cvt_pk_bf16_f32 v5, v50, v51
	s_waitcnt lgkmcnt(13)
	v_cvt_pk_bf16_f32 v6, v52, v53
	s_waitcnt lgkmcnt(12)
	v_cvt_pk_bf16_f32 v7, v54, v55
	v_mad_u64_u32 v[8:9], s[62:63], v0, s67, 0
	v_mov_b32_e32 v0, v9
	v_mad_u64_u32 v[12:13], s[62:63], v12, s67, v[0:1]
	v_mov_b32_e32 v9, v12
	v_lshl_add_u64 v[8:9], v[8:9], 1, v[2:3]
	global_store_dwordx4 v[8:9], v[4:7], off
	v_add_u32_e32 v0, 40, v15
	v_ashrrev_i32_e32 v12, 31, v0
	s_waitcnt lgkmcnt(11)
	v_cvt_pk_bf16_f32 v4, v56, v57
	s_waitcnt lgkmcnt(10)
	v_cvt_pk_bf16_f32 v5, v58, v59
	s_waitcnt lgkmcnt(9)
	v_cvt_pk_bf16_f32 v6, v60, v61
	s_waitcnt lgkmcnt(8)
	v_cvt_pk_bf16_f32 v7, v62, v63
	v_mad_u64_u32 v[8:9], s[62:63], v0, s67, 0
	v_mov_b32_e32 v0, v9
	v_mad_u64_u32 v[12:13], s[62:63], v12, s67, v[0:1]
	v_mov_b32_e32 v9, v12
	v_lshl_add_u64 v[8:9], v[8:9], 1, v[2:3]
	global_store_dwordx4 v[8:9], v[4:7], off
	v_add_u32_e32 v0, 48, v15
	v_ashrrev_i32_e32 v12, 31, v0
	s_waitcnt lgkmcnt(7)
	v_cvt_pk_bf16_f32 v4, v64, v65
	s_waitcnt lgkmcnt(6)
	v_cvt_pk_bf16_f32 v5, v70, v71
	s_waitcnt lgkmcnt(5)
	v_cvt_pk_bf16_f32 v6, v100, v101
	s_waitcnt lgkmcnt(4)
	v_cvt_pk_bf16_f32 v7, v102, v103
	v_mad_u64_u32 v[8:9], s[62:63], v0, s67, 0
	v_mov_b32_e32 v0, v9
	v_mad_u64_u32 v[12:13], s[62:63], v12, s67, v[0:1]
	v_mov_b32_e32 v9, v12
	v_lshl_add_u64 v[8:9], v[8:9], 1, v[2:3]
	global_store_dwordx4 v[8:9], v[4:7], off
	v_add_u32_e32 v0, 56, v15
	s_add_i32 s90, s90, s26
	s_waitcnt lgkmcnt(3)
	v_cvt_pk_bf16_f32 v4, v104, v105
	s_waitcnt lgkmcnt(2)
	v_cvt_pk_bf16_f32 v5, v106, v107
	s_waitcnt lgkmcnt(1)
	v_cvt_pk_bf16_f32 v6, v108, v109
	s_waitcnt lgkmcnt(0)
	v_cvt_pk_bf16_f32 v7, v110, v111
	v_mad_u64_u32 v[8:9], s[62:63], v0, s67, 0
	v_ashrrev_i32_e32 v10, 31, v0
	v_mov_b32_e32 v0, v9
	v_mad_u64_u32 v[10:11], s[62:63], v10, s67, v[0:1]
	v_mov_b32_e32 v9, v10
	v_lshl_add_u64 v[2:3], v[8:9], 1, v[2:3]
	global_store_dwordx4 v[2:3], v[4:7], off
	s_waitcnt lgkmcnt(0)
	s_add_i32 s88, s88, s89
	s_cmp_lt_i32 s90, s69
	s_cbranch_scc0 .LBB0_372

; #define LAS __attribute__((address_space(3)))
; __device__ __forceinline__ unsigned cvt_pk_bf16(float lo, float hi) { unsigned r; asm volatile("v_cvt_pk_bf16_f32 %0, %1, %2" : "=v"(r) : "v"(lo), "v"(hi)); return r; }
; __device__ __forceinline__ void transpose_item(const float* W, int K, int N, bf16_t* WT, LAS float* scr, int item, int lane, const float* gk) {
;     ...
;     for (int i = 0; i < 16; ++i) { const int kk = 4 * i + (lane >> 4); v[i] = *(const f32x4*)(W + (size_t)(k0 + kk) * N + n0 + 4 * (lane & 15)); }
;     if (gk) {
; #pragma unroll
;         for (int i = 0; i < 16; ++i) v[i] *= gk[k0 + 4 * i + (lane >> 4)]; }
; #pragma unroll
;     for (int i = 0; i < 16; ++i) { LAS float* d = scr + (4 * i + (lane >> 4)) * 65 + 4 * (lane & 15); d[0] = v[i][0]; d[1] = v[i][1]; d[2] = v[i][2]; d[3] = v[i][3]; }
;     asm volatile("s_waitcnt lgkmcnt(0)" ::: "memory");
;     const int c = lane & 7;
; #pragma unroll
;     for (int j = 0; j < 8; ++j) { const int n = (lane >> 3) + 8 * j; const LAS float* s = scr + (8 * c) * 65 + n;
;         u32x4 o; o.x = cvt_pk_bf16(s[0 * 65], s[1 * 65]); o.y = cvt_pk_bf16(s[2 * 65], s[3 * 65]); o.z = cvt_pk_bf16(s[4 * 65], s[5 * 65]); o.w = cvt_pk_bf16(s[6 * 65], s[7 * 65]);
.LBB0_456:
	v_add_u32_e32 v0, 0x410, v206
	s_waitcnt vmcnt(15)
	ds_write2_b32 v206, v6, v7 offset1:1
	ds_write2_b32 v206, v8, v9 offset0:2 offset1:3
	s_waitcnt vmcnt(14)
	ds_write2_b32 v0, v2, v3 offset1:1
	v_add_u32_e32 v0, 0x418, v206
	ds_write2_b32 v0, v4, v5 offset1:1
	v_add_u32_e32 v0, 0x820, v206
	s_waitcnt vmcnt(13)
	ds_write2_b32 v0, v14, v15 offset1:1
	v_add_u32_e32 v0, 0x828, v206
	ds_write2_b32 v0, v16, v17 offset1:1
	v_add_u32_e32 v0, 0xc30, v206
	s_waitcnt vmcnt(12)
	ds_write2_b32 v0, v10, v11 offset1:1
	v_add_u32_e32 v0, 0xc38, v206
	ds_write2_b32 v0, v12, v13 offset1:1
	v_add_u32_e32 v0, 0x1040, v206
	s_waitcnt vmcnt(11)
	ds_write2_b32 v0, v22, v23 offset1:1
	v_add_u32_e32 v0, 0x1048, v206
	ds_write2_b32 v0, v24, v25 offset1:1
	v_add_u32_e32 v0, 0x1450, v206
	s_waitcnt vmcnt(10)
	ds_write2_b32 v0, v18, v19 offset1:1
	v_add_u32_e32 v0, 0x1458, v206
	ds_write2_b32 v0, v20, v21 offset1:1
	v_add_u32_e32 v0, 0x1860, v206
	s_waitcnt vmcnt(9)
	ds_write2_b32 v0, v30, v31 offset1:1
	v_add_u32_e32 v0, 0x1868, v206
	ds_write2_b32 v0, v32, v33 offset1:1
	v_add_u32_e32 v0, 0x1c70, v206
	s_waitcnt vmcnt(8)
	ds_write2_b32 v0, v26, v27 offset1:1
	v_add_u32_e32 v0, 0x1c78, v206
	ds_write2_b32 v0, v28, v29 offset1:1
	v_add_u32_e32 v0, 0x2080, v206
	s_waitcnt vmcnt(7)
	ds_write2_b32 v0, v54, v55 offset1:1
	v_add_u32_e32 v0, 0x2088, v206
	ds_write2_b32 v0, v56, v57 offset1:1
	v_add_u32_e32 v0, 0x2490, v206
	s_waitcnt vmcnt(6)
	ds_write2_b32 v0, v46, v47 offset1:1
	v_add_u32_e32 v0, 0x2498, v206
	ds_write2_b32 v0, v48, v49 offset1:1
	v_add_u32_e32 v0, 0x28a0, v206
	s_waitcnt vmcnt(5)
	ds_write2_b32 v0, v62, v63 offset1:1
	v_add_u32_e32 v0, 0x28a8, v206
	ds_write2_b32 v0, v64, v65 offset1:1
	v_add_u32_e32 v0, 0x2cb0, v206
	s_waitcnt vmcnt(4)
	ds_write2_b32 v0, v58, v59 offset1:1
	v_add_u32_e32 v0, 0x2cb8, v206
	ds_write2_b32 v0, v60, v61 offset1:1
	v_add_u32_e32 v0, 0x30c0, v206
	s_waitcnt vmcnt(3)
	ds_write2_b32 v0, v50, v51 offset1:1
	v_add_u32_e32 v0, 0x30c8, v206
	ds_write2_b32 v0, v52, v53 offset1:1
	v_add_u32_e32 v0, 0x34d0, v206
	s_waitcnt vmcnt(2)
	ds_write2_b32 v0, v42, v43 offset1:1
	v_add_u32_e32 v0, 0x34d8, v206
	ds_write2_b32 v0, v44, v45 offset1:1
	v_add_u32_e32 v0, 0x38e0, v206
	s_waitcnt vmcnt(1)
	ds_write2_b32 v0, v38, v39 offset1:1
	v_add_u32_e32 v0, 0x38e8, v206
	ds_write2_b32 v0, v40, v41 offset1:1
	v_add_u32_e32 v0, 0x3cf0, v206
	s_waitcnt vmcnt(0)
	ds_write2_b32 v0, v34, v35 offset1:1
	v_add_u32_e32 v0, 0x3cf8, v206
	ds_write2_b32 v0, v36, v37 offset1:1
	s_waitcnt lgkmcnt(0)
	v_add_u32_e32 v14, 0x400, v208
	ds_read2_b32 v[16:17], v208 offset1:65
	ds_read2_b32 v[18:19], v208 offset0:130 offset1:195
	ds_read2_b32 v[20:21], v14 offset0:4 offset1:69
	ds_read2_b32 v[22:23], v14 offset0:134 offset1:199
	ds_read2_b32 v[24:25], v208 offset0:8 offset1:73
	ds_read2_b32 v[26:27], v208 offset0:138 offset1:203
	ds_read2_b32 v[28:29], v14 offset0:12 offset1:77
	ds_read2_b32 v[30:31], v14 offset0:142 offset1:207
	ds_read2_b32 v[32:33], v208 offset0:16 offset1:81
	ds_read2_b32 v[34:35], v208 offset0:146 offset1:211
	ds_read2_b32 v[36:37], v14 offset0:20 offset1:85
	ds_read2_b32 v[38:39], v14 offset0:150 offset1:215
	ds_read2_b32 v[40:41], v208 offset0:24 offset1:89
	ds_read2_b32 v[42:43], v208 offset0:154 offset1:219
	ds_read2_b32 v[44:45], v14 offset0:28 offset1:93
	ds_read2_b32 v[46:47], v14 offset0:158 offset1:223
	ds_read2_b32 v[48:49], v208 offset0:32 offset1:97
	ds_read2_b32 v[50:51], v208 offset0:162 offset1:227
	ds_read2_b32 v[52:53], v14 offset0:36 offset1:101
	ds_read2_b32 v[54:55], v14 offset0:166 offset1:231
	ds_read2_b32 v[56:57], v208 offset0:40 offset1:105
	ds_read2_b32 v[58:59], v208 offset0:170 offset1:235
	ds_read2_b32 v[60:61], v14 offset0:44 offset1:109
	ds_read2_b32 v[62:63], v14 offset0:174 offset1:239
	ds_read2_b32 v[64:65], v208 offset0:48 offset1:113
	ds_read2_b32 v[70:71], v208 offset0:178 offset1:243
	ds_read2_b32 v[72:73], v14 offset0:52 offset1:117
	ds_read2_b32 v[100:101], v14 offset0:182 offset1:247
	ds_read2_b32 v[102:103], v208 offset0:56 offset1:121
	ds_read2_b32 v[104:105], v208 offset0:186 offset1:251
	ds_read2_b32 v[106:107], v14 offset0:60 offset1:125
	ds_read2_b32 v[108:109], v14 offset0:190 offset1:255
	s_waitcnt lgkmcnt(15)
; #define LAS __attribute__((address_space(3)))
; __device__ __forceinline__ unsigned cvt_pk_bf16(float lo, float hi) { unsigned r; asm volatile("v_cvt_pk_bf16_f32 %0, %1, %2" : "=v"(r) : "v"(lo), "v"(hi)); return r; }
; __device__ __forceinline__ void transpose_item(const float* W, int K, int N, bf16_t* WT, LAS float* scr, int item, int lane, const float* gk) {
;     ...
;     const int c = lane & 7;
; #pragma unroll
;     for (int j = 0; j < 8; ++j) { const int n = (lane >> 3) + 8 * j; const LAS float* s = scr + (8 * c) * 65 + n;
;         u32x4 o; o.x = cvt_pk_bf16(s[0 * 65], s[1 * 65]); o.y = cvt_pk_bf16(s[2 * 65], s[3 * 65]); o.z = cvt_pk_bf16(s[4 * 65], s[5 * 65]); o.w = cvt_pk_bf16(s[6 * 65], s[7 * 65]);
;         *(u32x4*)(WT + (size_t)(n0 + n) * K + k0 + 8 * c) = o; }
;     asm volatile("s_waitcnt lgkmcnt(0)" ::: "memory");
	v_cvt_pk_bf16_f32 v4, v16, v17
	s_waitcnt lgkmcnt(15)
	v_cvt_pk_bf16_f32 v5, v18, v19
	s_waitcnt lgkmcnt(15)
	v_cvt_pk_bf16_f32 v6, v20, v21
	v_add_u32_e32 v15, s66, v207
	s_waitcnt lgkmcnt(15)
	v_cvt_pk_bf16_f32 v7, v22, v23
	v_mad_u64_u32 v[8:9], s[66:67], v15, s71, 0
	v_ashrrev_i32_e32 v12, 31, v15
	v_mov_b32_e32 v0, v9
	s_ashr_i32 s69, s68, 31
	v_mad_u64_u32 v[12:13], s[66:67], v12, s71, v[0:1]
	v_lshl_add_u64 v[2:3], s[68:69], 1, v[66:67]
	v_mov_b32_e32 v9, v12
	v_lshl_add_u64 v[8:9], v[8:9], 1, v[2:3]
	global_store_dwordx4 v[8:9], v[4:7], off
	v_add_u32_e32 v0, 8, v15
	v_ashrrev_i32_e32 v12, 31, v0
	s_waitcnt lgkmcnt(15)
	v_cvt_pk_bf16_f32 v4, v24, v25
	s_waitcnt lgkmcnt(15)
	v_cvt_pk_bf16_f32 v5, v26, v27
	s_waitcnt lgkmcnt(15)
	v_cvt_pk_bf16_f32 v6, v28, v29
	s_waitcnt lgkmcnt(15)
	v_cvt_pk_bf16_f32 v7, v30, v31
	v_mad_u64_u32 v[8:9], s[66:67], v0, s71, 0
	v_mov_b32_e32 v0, v9
	v_mad_u64_u32 v[12:13], s[66:67], v12, s71, v[0:1]
	v_mov_b32_e32 v9, v12
	v_lshl_add_u64 v[8:9], v[8:9], 1, v[2:3]
	global_store_dwordx4 v[8:9], v[4:7], off
	v_add_u32_e32 v0, 16, v15
	v_ashrrev_i32_e32 v12, 31, v0
	s_waitcnt lgkmcnt(15)
	v_cvt_pk_bf16_f32 v4, v32, v33
	s_waitcnt lgkmcnt(15)
	v_cvt_pk_bf16_f32 v5, v34, v35
	s_waitcnt lgkmcnt(15)
	v_cvt_pk_bf16_f32 v6, v36, v37
	s_waitcnt lgkmcnt(15)
	v_cvt_pk_bf16_f32 v7, v38, v39
	v_mad_u64_u32 v[8:9], s[66:67], v0, s71, 0
	v_mov_b32_e32 v0, v9
	v_mad_u64_u32 v[12:13], s[66:67], v12, s71, v[0:1]
	v_mov_b32_e32 v9, v12
	v_lshl_add_u64 v[8:9], v[8:9], 1, v[2:3]
	global_store_dwordx4 v[8:9], v[4:7], off
	v_add_u32_e32 v0, 24, v15
	v_ashrrev_i32_e32 v12, 31, v0
	s_waitcnt lgkmcnt(15)
	v_cvt_pk_bf16_f32 v4, v40, v41
	s_waitcnt lgkmcnt(15)
	v_cvt_pk_bf16_f32 v5, v42, v43
	s_waitcnt lgkmcnt(15)
	v_cvt_pk_bf16_f32 v6, v44, v45
	s_waitcnt lgkmcnt(15)
	v_cvt_pk_bf16_f32 v7, v46, v47
	v_mad_u64_u32 v[8:9], s[66:67], v0, s71, 0
	v_mov_b32_e32 v0, v9
	v_mad_u64_u32 v[12:13], s[66:67], v12, s71, v[0:1]
	v_mov_b32_e32 v9, v12
	v_lshl_add_u64 v[8:9], v[8:9], 1, v[2:3]
	global_store_dwordx4 v[8:9], v[4:7], off
	v_add_u32_e32 v0, 32, v15
	v_ashrrev_i32_e32 v12, 31, v0
	s_waitcnt lgkmcnt(15)
	v_cvt_pk_bf16_f32 v4, v48, v49
	s_waitcnt lgkmcnt(14)
	v_cvt_pk_bf16_f32 v5, v50, v51
	s_waitcnt lgkmcnt(13)
	v_cvt_pk_bf16_f32 v6, v52, v53
	s_waitcnt lgkmcnt(12)
	v_cvt_pk_bf16_f32 v7, v54, v55
	v_mad_u64_u32 v[8:9], s[66:67], v0, s71, 0
	v_mov_b32_e32 v0, v9
	v_mad_u64_u32 v[12:13], s[66:67], v12, s71, v[0:1]
	v_mov_b32_e32 v9, v12
	v_lshl_add_u64 v[8:9], v[8:9], 1, v[2:3]
	global_store_dwordx4 v[8:9], v[4:7], off
	v_add_u32_e32 v0, 40, v15
	v_ashrrev_i32_e32 v12, 31, v0
	s_waitcnt lgkmcnt(11)
	v_cvt_pk_bf16_f32 v4, v56, v57
	s_waitcnt lgkmcnt(10)
	v_cvt_pk_bf16_f32 v5, v58, v59
	s_waitcnt lgkmcnt(9)
	v_cvt_pk_bf16_f32 v6, v60, v61
	s_waitcnt lgkmcnt(8)
	v_cvt_pk_bf16_f32 v7, v62, v63
	v_mad_u64_u32 v[8:9], s[66:67], v0, s71, 0
	v_mov_b32_e32 v0, v9
	v_mad_u64_u32 v[12:13], s[66:67], v12, s71, v[0:1]
	v_mov_b32_e32 v9, v12
	v_lshl_add_u64 v[8:9], v[8:9], 1, v[2:3]
	global_store_dwordx4 v[8:9], v[4:7], off
	v_add_u32_e32 v0, 48, v15
	v_ashrrev_i32_e32 v12, 31, v0
	s_waitcnt lgkmcnt(7)
	v_cvt_pk_bf16_f32 v4, v64, v65
	s_waitcnt lgkmcnt(6)
	v_cvt_pk_bf16_f32 v5, v70, v71
	s_waitcnt lgkmcnt(5)
	v_cvt_pk_bf16_f32 v6, v72, v73
	s_waitcnt lgkmcnt(4)
	v_cvt_pk_bf16_f32 v7, v100, v101
	v_mad_u64_u32 v[8:9], s[66:67], v0, s71, 0
	v_mov_b32_e32 v0, v9
	v_mad_u64_u32 v[12:13], s[66:67], v12, s71, v[0:1]
	v_mov_b32_e32 v9, v12
	v_lshl_add_u64 v[8:9], v[8:9], 1, v[2:3]
	global_store_dwordx4 v[8:9], v[4:7], off
	v_add_u32_e32 v0, 56, v15
	s_add_i32 s93, s93, s26
	s_waitcnt lgkmcnt(3)
	v_cvt_pk_bf16_f32 v4, v102, v103
	s_waitcnt lgkmcnt(2)
	v_cvt_pk_bf16_f32 v5, v104, v105
	s_waitcnt lgkmcnt(1)
	v_cvt_pk_bf16_f32 v6, v106, v107
	s_waitcnt lgkmcnt(0)
	v_cvt_pk_bf16_f32 v7, v108, v109
	v_mad_u64_u32 v[8:9], s[66:67], v0, s71, 0
	v_ashrrev_i32_e32 v10, 31, v0
	v_mov_b32_e32 v0, v9
	v_mad_u64_u32 v[10:11], s[66:67], v10, s71, v[0:1]
	v_mov_b32_e32 v9, v10
	v_lshl_add_u64 v[2:3], v[8:9], 1, v[2:3]
	global_store_dwordx4 v[2:3], v[4:7], off
	s_waitcnt lgkmcnt(0)
	s_add_i32 s91, s91, s92
	s_cmp_lt_i32 s93, s73
	s_cbranch_scc0 .LBB0_436

; #define LAS __attribute__((address_space(3)))
; __device__ __forceinline__ unsigned cvt_pk_bf16(float lo, float hi) { unsigned r; asm volatile("v_cvt_pk_bf16_f32 %0, %1, %2" : "=v"(r) : "v"(lo), "v"(hi)); return r; }
; __device__ __forceinline__ void transpose_item(const float* W, int K, int N, bf16_t* WT, LAS float* scr, int item, int lane, const float* gk) {
;     ...
;     for (int i = 0; i < 16; ++i) { const int kk = 4 * i + (lane >> 4); v[i] = *(const f32x4*)(W + (size_t)(k0 + kk) * N + n0 + 4 * (lane & 15)); }
;     if (gk) {
; #pragma unroll
;         for (int i = 0; i < 16; ++i) v[i] *= gk[k0 + 4 * i + (lane >> 4)]; }
; #pragma unroll
;     for (int i = 0; i < 16; ++i) { LAS float* d = scr + (4 * i + (lane >> 4)) * 65 + 4 * (lane & 15); d[0] = v[i][0]; d[1] = v[i][1]; d[2] = v[i][2]; d[3] = v[i][3]; }
;     asm volatile("s_waitcnt lgkmcnt(0)" ::: "memory");
;     const int c = lane & 7;
; #pragma unroll
;     for (int j = 0; j < 8; ++j) { const int n = (lane >> 3) + 8 * j; const LAS float* s = scr + (8 * c) * 65 + n;
;         u32x4 o; o.x = cvt_pk_bf16(s[0 * 65], s[1 * 65]); o.y = cvt_pk_bf16(s[2 * 65], s[3 * 65]); o.z = cvt_pk_bf16(s[4 * 65], s[5 * 65]); o.w = cvt_pk_bf16(s[6 * 65], s[7 * 65]);
.LBB0_530:
	s_waitcnt vmcnt(15)
	ds_write2_b32 v206, v4, v5 offset1:1
	ds_write2_b32 v206, v6, v7 offset0:2 offset1:3
	v_add_u32_e32 v4, 0x410, v206
	s_waitcnt vmcnt(14)
	ds_write2_b32 v4, v0, v1 offset1:1
	v_add_u32_e32 v0, 0x418, v206
	ds_write2_b32 v0, v2, v3 offset1:1
	v_add_u32_e32 v0, 0x820, v206
	s_waitcnt vmcnt(13)
	ds_write2_b32 v0, v12, v13 offset1:1
	v_add_u32_e32 v0, 0x828, v206
	ds_write2_b32 v0, v14, v15 offset1:1
	v_add_u32_e32 v0, 0xc30, v206
	s_waitcnt vmcnt(12)
	ds_write2_b32 v0, v8, v9 offset1:1
	v_add_u32_e32 v0, 0xc38, v206
	ds_write2_b32 v0, v10, v11 offset1:1
	v_add_u32_e32 v0, 0x1040, v206
	s_waitcnt vmcnt(11)
	ds_write2_b32 v0, v20, v21 offset1:1
	v_add_u32_e32 v0, 0x1048, v206
	ds_write2_b32 v0, v22, v23 offset1:1
	v_add_u32_e32 v0, 0x1450, v206
	s_waitcnt vmcnt(10)
	ds_write2_b32 v0, v16, v17 offset1:1
	v_add_u32_e32 v0, 0x1458, v206
	ds_write2_b32 v0, v18, v19 offset1:1
	v_add_u32_e32 v0, 0x1860, v206
	s_waitcnt vmcnt(9)
	ds_write2_b32 v0, v28, v29 offset1:1
	v_add_u32_e32 v0, 0x1868, v206
	ds_write2_b32 v0, v30, v31 offset1:1
	v_add_u32_e32 v0, 0x1c70, v206
	s_waitcnt vmcnt(8)
	ds_write2_b32 v0, v24, v25 offset1:1
	v_add_u32_e32 v0, 0x1c78, v206
	ds_write2_b32 v0, v26, v27 offset1:1
	v_add_u32_e32 v0, 0x2080, v206
	s_waitcnt vmcnt(7)
	ds_write2_b32 v0, v36, v37 offset1:1
	v_add_u32_e32 v0, 0x2088, v206
	ds_write2_b32 v0, v38, v39 offset1:1
	v_add_u32_e32 v0, 0x2490, v206
	s_waitcnt vmcnt(6)
	ds_write2_b32 v0, v32, v33 offset1:1
	v_add_u32_e32 v0, 0x2498, v206
	ds_write2_b32 v0, v34, v35 offset1:1
	v_add_u32_e32 v0, 0x28a0, v206
	s_waitcnt vmcnt(5)
	ds_write2_b32 v0, v44, v45 offset1:1
	v_add_u32_e32 v0, 0x28a8, v206
	ds_write2_b32 v0, v46, v47 offset1:1
	v_add_u32_e32 v0, 0x2cb0, v206
	s_waitcnt vmcnt(4)
	ds_write2_b32 v0, v40, v41 offset1:1
	v_add_u32_e32 v0, 0x2cb8, v206
	ds_write2_b32 v0, v42, v43 offset1:1
	v_add_u32_e32 v0, 0x30c0, v206
	s_waitcnt vmcnt(3)
	ds_write2_b32 v0, v52, v53 offset1:1
	v_add_u32_e32 v0, 0x30c8, v206
	ds_write2_b32 v0, v54, v55 offset1:1
	v_add_u32_e32 v0, 0x34d0, v206
	s_waitcnt vmcnt(2)
	ds_write2_b32 v0, v48, v49 offset1:1
	v_add_u32_e32 v0, 0x34d8, v206
	ds_write2_b32 v0, v50, v51 offset1:1
	v_add_u32_e32 v0, 0x38e0, v206
	s_waitcnt vmcnt(1)
	ds_write2_b32 v0, v60, v61 offset1:1
	v_add_u32_e32 v0, 0x38e8, v206
	ds_write2_b32 v0, v62, v63 offset1:1
	v_add_u32_e32 v0, 0x3cf0, v206
	s_waitcnt vmcnt(0)
	ds_write2_b32 v0, v56, v57 offset1:1
	v_add_u32_e32 v0, 0x3cf8, v206
	ds_write2_b32 v0, v58, v59 offset1:1
	s_waitcnt lgkmcnt(0)
	v_add_u32_e32 v12, 0x400, v208
	ds_read2_b32 v[14:15], v208 offset1:65
	ds_read2_b32 v[16:17], v208 offset0:130 offset1:195
	ds_read2_b32 v[18:19], v12 offset0:4 offset1:69
	ds_read2_b32 v[20:21], v12 offset0:134 offset1:199
	ds_read2_b32 v[22:23], v208 offset0:8 offset1:73
	ds_read2_b32 v[24:25], v208 offset0:138 offset1:203
	ds_read2_b32 v[26:27], v12 offset0:12 offset1:77
	ds_read2_b32 v[28:29], v12 offset0:142 offset1:207
	ds_read2_b32 v[30:31], v208 offset0:16 offset1:81
	ds_read2_b32 v[32:33], v208 offset0:146 offset1:211
	ds_read2_b32 v[34:35], v12 offset0:20 offset1:85
	ds_read2_b32 v[36:37], v12 offset0:150 offset1:215
	ds_read2_b32 v[38:39], v208 offset0:24 offset1:89
	ds_read2_b32 v[40:41], v208 offset0:154 offset1:219
	ds_read2_b32 v[42:43], v12 offset0:28 offset1:93
	ds_read2_b32 v[44:45], v12 offset0:158 offset1:223
	ds_read2_b32 v[46:47], v208 offset0:32 offset1:97
	ds_read2_b32 v[48:49], v208 offset0:162 offset1:227
	ds_read2_b32 v[50:51], v12 offset0:36 offset1:101
	ds_read2_b32 v[52:53], v12 offset0:166 offset1:231
	ds_read2_b32 v[54:55], v208 offset0:40 offset1:105
	ds_read2_b32 v[56:57], v208 offset0:170 offset1:235
	ds_read2_b32 v[58:59], v12 offset0:44 offset1:109
	ds_read2_b32 v[60:61], v12 offset0:174 offset1:239
	ds_read2_b32 v[62:63], v208 offset0:48 offset1:113
	ds_read2_b32 v[68:69], v208 offset0:178 offset1:243
	ds_read2_b32 v[100:101], v12 offset0:52 offset1:117
	ds_read2_b32 v[102:103], v12 offset0:182 offset1:247
	ds_read2_b32 v[104:105], v208 offset0:56 offset1:121
	ds_read2_b32 v[106:107], v208 offset0:186 offset1:251
	ds_read2_b32 v[108:109], v12 offset0:60 offset1:125
	ds_read2_b32 v[110:111], v12 offset0:190 offset1:255
	s_waitcnt lgkmcnt(15)
; #define LAS __attribute__((address_space(3)))
; __device__ __forceinline__ unsigned cvt_pk_bf16(float lo, float hi) { unsigned r; asm volatile("v_cvt_pk_bf16_f32 %0, %1, %2" : "=v"(r) : "v"(lo), "v"(hi)); return r; }
; __device__ __forceinline__ void transpose_item(const float* W, int K, int N, bf16_t* WT, LAS float* scr, int item, int lane, const float* gk) {
;     ...
;     const int c = lane & 7;
; #pragma unroll
;     for (int j = 0; j < 8; ++j) { const int n = (lane >> 3) + 8 * j; const LAS float* s = scr + (8 * c) * 65 + n;
;         u32x4 o; o.x = cvt_pk_bf16(s[0 * 65], s[1 * 65]); o.y = cvt_pk_bf16(s[2 * 65], s[3 * 65]); o.z = cvt_pk_bf16(s[4 * 65], s[5 * 65]); o.w = cvt_pk_bf16(s[6 * 65], s[7 * 65]);
;         *(u32x4*)(WT + (size_t)(n0 + n) * K + k0 + 8 * c) = o; }
;     asm volatile("s_waitcnt lgkmcnt(0)" ::: "memory");
	v_cvt_pk_bf16_f32 v2, v14, v15
	s_waitcnt lgkmcnt(15)
	v_cvt_pk_bf16_f32 v3, v16, v17
	s_waitcnt lgkmcnt(15)
	v_cvt_pk_bf16_f32 v4, v18, v19
	v_add_u32_e32 v13, s8, v207
	s_waitcnt lgkmcnt(15)
	v_cvt_pk_bf16_f32 v5, v20, v21
	v_mad_u64_u32 v[6:7], s[8:9], v13, s37, 0
	v_ashrrev_i32_e32 v9, 31, v13
	v_mov_b32_e32 v8, v7
	s_ashr_i32 s11, s10, 31
	v_mad_u64_u32 v[8:9], s[8:9], v9, s37, v[8:9]
	v_lshl_add_u64 v[0:1], s[10:11], 1, v[64:65]
	v_mov_b32_e32 v7, v8
	v_lshl_add_u64 v[6:7], v[6:7], 1, v[0:1]
	global_store_dwordx4 v[6:7], v[2:5], off
	s_add_i32 s58, s58, s26
	s_add_i32 s54, s54, s57
	s_waitcnt lgkmcnt(15)
	v_cvt_pk_bf16_f32 v2, v22, v23
	s_waitcnt lgkmcnt(15)
	v_cvt_pk_bf16_f32 v3, v24, v25
	s_waitcnt lgkmcnt(15)
	v_cvt_pk_bf16_f32 v4, v26, v27
	s_waitcnt lgkmcnt(15)
	v_cvt_pk_bf16_f32 v5, v28, v29
	v_add_u32_e32 v6, 8, v13
	v_ashrrev_i32_e32 v9, 31, v6
	v_mad_u64_u32 v[6:7], s[8:9], v6, s37, 0
	v_mov_b32_e32 v8, v7
	v_mad_u64_u32 v[8:9], s[8:9], v9, s37, v[8:9]
	v_mov_b32_e32 v7, v8
	v_lshl_add_u64 v[6:7], v[6:7], 1, v[0:1]
	global_store_dwordx4 v[6:7], v[2:5], off
	s_cmp_lt_i32 s58, s53
	s_waitcnt lgkmcnt(15)
	v_cvt_pk_bf16_f32 v2, v30, v31
	s_waitcnt lgkmcnt(15)
	v_cvt_pk_bf16_f32 v3, v32, v33
	s_waitcnt lgkmcnt(15)
	v_cvt_pk_bf16_f32 v4, v34, v35
	s_waitcnt lgkmcnt(15)
	v_cvt_pk_bf16_f32 v5, v36, v37
	v_add_u32_e32 v6, 16, v13
	v_ashrrev_i32_e32 v9, 31, v6
	v_mad_u64_u32 v[6:7], s[8:9], v6, s37, 0
	v_mov_b32_e32 v8, v7
	v_mad_u64_u32 v[8:9], s[8:9], v9, s37, v[8:9]
	v_mov_b32_e32 v7, v8
	v_lshl_add_u64 v[6:7], v[6:7], 1, v[0:1]
	global_store_dwordx4 v[6:7], v[2:5], off
	s_waitcnt lgkmcnt(15)
	s_nop 0
	v_cvt_pk_bf16_f32 v2, v38, v39
	s_waitcnt lgkmcnt(15)
	v_cvt_pk_bf16_f32 v3, v40, v41
	s_waitcnt lgkmcnt(15)
	v_cvt_pk_bf16_f32 v4, v42, v43
	s_waitcnt lgkmcnt(15)
	v_cvt_pk_bf16_f32 v5, v44, v45
	v_add_u32_e32 v6, 24, v13
	v_ashrrev_i32_e32 v9, 31, v6
	v_mad_u64_u32 v[6:7], s[8:9], v6, s37, 0
	v_mov_b32_e32 v8, v7
	v_mad_u64_u32 v[8:9], s[8:9], v9, s37, v[8:9]
	v_mov_b32_e32 v7, v8
	v_lshl_add_u64 v[6:7], v[6:7], 1, v[0:1]
	global_store_dwordx4 v[6:7], v[2:5], off
	s_waitcnt lgkmcnt(15)
	s_nop 0
	v_cvt_pk_bf16_f32 v2, v46, v47
	s_waitcnt lgkmcnt(14)
	v_cvt_pk_bf16_f32 v3, v48, v49
	s_waitcnt lgkmcnt(13)
	v_cvt_pk_bf16_f32 v4, v50, v51
	s_waitcnt lgkmcnt(12)
	v_cvt_pk_bf16_f32 v5, v52, v53
	v_add_u32_e32 v6, 32, v13
	v_ashrrev_i32_e32 v9, 31, v6
	v_mad_u64_u32 v[6:7], s[8:9], v6, s37, 0
	v_mov_b32_e32 v8, v7
	v_mad_u64_u32 v[8:9], s[8:9], v9, s37, v[8:9]
	v_mov_b32_e32 v7, v8
	v_lshl_add_u64 v[6:7], v[6:7], 1, v[0:1]
	global_store_dwordx4 v[6:7], v[2:5], off
	s_waitcnt lgkmcnt(11)
	s_nop 0
	v_cvt_pk_bf16_f32 v2, v54, v55
	s_waitcnt lgkmcnt(10)
	v_cvt_pk_bf16_f32 v3, v56, v57
	s_waitcnt lgkmcnt(9)
	v_cvt_pk_bf16_f32 v4, v58, v59
	s_waitcnt lgkmcnt(8)
	v_cvt_pk_bf16_f32 v5, v60, v61
	v_add_u32_e32 v6, 40, v13
	v_ashrrev_i32_e32 v9, 31, v6
	v_mad_u64_u32 v[6:7], s[8:9], v6, s37, 0
	v_mov_b32_e32 v8, v7
	v_mad_u64_u32 v[8:9], s[8:9], v9, s37, v[8:9]
	v_mov_b32_e32 v7, v8
	v_lshl_add_u64 v[6:7], v[6:7], 1, v[0:1]
	global_store_dwordx4 v[6:7], v[2:5], off
	s_waitcnt lgkmcnt(7)
	s_nop 0
	v_cvt_pk_bf16_f32 v2, v62, v63
	s_waitcnt lgkmcnt(6)
	v_cvt_pk_bf16_f32 v3, v68, v69
	s_waitcnt lgkmcnt(5)
	v_cvt_pk_bf16_f32 v4, v100, v101
	s_waitcnt lgkmcnt(4)
	v_cvt_pk_bf16_f32 v5, v102, v103
	v_add_u32_e32 v6, 48, v13
	v_ashrrev_i32_e32 v9, 31, v6
	v_mad_u64_u32 v[6:7], s[8:9], v6, s37, 0
	v_mov_b32_e32 v8, v7
	v_mad_u64_u32 v[8:9], s[8:9], v9, s37, v[8:9]
	v_mov_b32_e32 v7, v8
	v_lshl_add_u64 v[6:7], v[6:7], 1, v[0:1]
	global_store_dwordx4 v[6:7], v[2:5], off
	s_waitcnt lgkmcnt(3)
	s_nop 0
	v_cvt_pk_bf16_f32 v2, v104, v105
	s_waitcnt lgkmcnt(2)
	v_cvt_pk_bf16_f32 v3, v106, v107
	s_waitcnt lgkmcnt(1)
	v_cvt_pk_bf16_f32 v4, v108, v109
	s_waitcnt lgkmcnt(0)
	v_cvt_pk_bf16_f32 v5, v110, v111
	v_add_u32_e32 v6, 56, v13
	v_ashrrev_i32_e32 v9, 31, v6
	v_mad_u64_u32 v[6:7], s[8:9], v6, s37, 0
	v_mov_b32_e32 v8, v7
	v_mad_u64_u32 v[8:9], s[8:9], v9, s37, v[8:9]
	v_mov_b32_e32 v7, v8
	v_lshl_add_u64 v[0:1], v[6:7], 1, v[0:1]
	global_store_dwordx4 v[0:1], v[2:5], off
	s_waitcnt lgkmcnt(0)
	s_cbranch_scc0 .LBB0_510

; #define PG8_STAGE(bufoff, gbase, voff) do { _Pragma("unroll") for (int _i = 0; _i < 2; ++_i) \
;         __builtin_amdgcn_global_load_lds((const unsigned*)((const char*)(gbase) + (voff)[_i]), (LAS unsigned*)(lds + (bufoff) + ldsw + _i * 8192), 16, 0, 0); } while (0)
; #define PG8_WAIT_V(n) asm volatile("s_waitcnt vmcnt(" #n ")" ::: "memory")
; #define PG8_BAR __builtin_amdgcn_s_barrier()
; template <class Epi>
; __device__ __forceinline__ void gemm_phase(LAS unsigned char* lds, const Gemm g, const StaticOrder& S, const Epi& E) {
;     int tid = threadIdx.x; asm volatile("" : "+v"(tid));
;     const int wid = __builtin_amdgcn_readfirstlane(tid >> 6), lane = tid & 63, wr = wid >> 2, wc = wid & 3, fr = lane & 15, fq = lane >> 4;
;     const int K = g.K, nt = K / BK;
;     unsigned voffA[2], voffB0[2], voffB1[2];
; #pragma unroll
;     for (int i = 0; i < 2; ++i) { int R, C; stage_rc(tid * 16 + i * 8192, R, C);
;         const int Rw = 64 * (R >> 5) + 16 * ((R >> 2) & 3) + 4 * ((R >> 4) & 1) + (R & 3);
;         const int Rf = 64 * (R >> 5) + 8 * ((R >> 2) & 3) + 4 * ((R >> 4) & 1) + (R & 3);
;         const int Rb0 = Epi::PERM ? (Epi::F32OUT ? Rf : Rw) : R, Rb1 = Epi::PERM ? (Epi::F32OUT ? Rf + 32 : Rw + 8) : R + HALF;
;         voffA[i] = (unsigned)(R * K + C) * 2u; voffB0[i] = (unsigned)(Rb0 * K + C) * 2u; voffB1[i] = (unsigned)(Rb1 * K + C) * 2u; }
;     const size_t kstep = (size_t)(BK * 2);
;     const size_t hstep = (size_t)HALF * K * 2;
;     const size_t tstep = 2 * hstep;
;     const unsigned ldsw = (unsigned)wid * 1024u;
;     const int aoff = lds_byte(wr * 64 + fr, fq * 8), boff = lds_byte(wc * 32 + fr, fq * 8);
;     ...
;     PG8_STAGE(PG8_SB(0, 0), cB, voffB0); PG8_STAGE(PG8_SA(0, 0), cA, voffA); PG8_STAGE(PG8_SB(0, 1), cB, voffB1); PG8_STAGE(PG8_SA(0, 1), cA + hstep, voffA);
;     if (wr == 1) PG8_BAR;
;     PG8_WAIT_V(4); PG8_BAR;
;     PG8_STAGE(PG8_SB(1, 0), cB + kstep, voffB0); PG8_STAGE(PG8_SA(1, 0), cA + kstep, voffA); PG8_STAGE(PG8_SB(1, 1), cB + kstep, voffB1);
;     PG8_WAIT_V(6); PG8_BAR;
.LBB0_603:
	s_add_u32 s10, s6, 0x6400000
	s_addc_u32 s11, s7, 0
	s_add_u32 s12, s6, 0x1ec00000
	s_mov_b64 s[36:37], 0x80
	s_addc_u32 s13, s7, 0
	s_add_i32 m0, s53, 0x18000
	v_lshl_add_u64 v[10:11], v[10:11], 0, s[36:37]
	s_waitcnt vmcnt(4)
	s_barrier
	global_load_lds_dwordx4 v[10:11], off
	v_lshl_add_u64 v[8:9], v[8:9], 0, s[36:37]
	s_add_i32 m0, s53, 0x1a000
	s_add_i32 s72, s53, 0x8000
	global_load_lds_dwordx4 v[8:9], off
	v_lshl_add_u64 v[6:7], v[6:7], 0, s[36:37]
	s_mov_b32 m0, s72
	s_add_i32 s73, s53, 0xa000
	global_load_lds_dwordx4 v[6:7], off
	v_lshl_add_u64 v[4:5], v[4:5], 0, s[36:37]
	s_mov_b32 m0, s73
	v_lshl_add_u64 v[0:1], v[0:1], 0, s[36:37]
	global_load_lds_dwordx4 v[4:5], off
	s_add_i32 m0, s53, 0x1c000
	s_and_b32 s33, s8, 3
	global_load_lds_dwordx4 v[0:1], off
	v_lshl_add_u64 v[0:1], v[2:3], 0, s[36:37]
	s_add_i32 m0, s53, 0x1e000
	s_lshl_b32 s74, s9, 6
	global_load_lds_dwordx4 v[0:1], off
	v_bfe_u32 v0, v12, 4, 2
	v_lshlrev_b32_e32 v1, 4, v0
	s_lshl_b32 s6, s9, 13
	v_cmp_eq_u32_e64 s[8:9], 0, v0
	v_lshlrev_b32_e32 v0, 15, v13
	v_and_b32_e32 v150, 15, v12
	v_and_b32_e32 v0, 0xffff0000, v0
	v_lshl_or_b32 v2, v150, 6, v1
	v_lshl_or_b32 v154, s33, 6, v1
	v_lshl_add_u32 v0, v14, 12, v0
	v_and_b32_e32 v1, 1, v13
	v_lshl_or_b32 v0, v1, 6, v0
	v_lshlrev_b32_e32 v3, 2, v12
	v_lshl_add_u32 v140, v15, 1, v0
	v_lshlrev_b32_e32 v0, 15, v16
	v_and_b32_e32 v3, 32, v3
	v_and_b32_e32 v0, 0xffff0000, v0
	v_bitop3_b32 v4, v2, s6, v3 bitop3:0xde
	s_lshl_b32 s6, s33, 12
	s_waitcnt vmcnt(0)
	v_lshl_add_u32 v0, v17, 12, v0
	v_and_b32_e32 v1, 1, v16
	v_bitop3_b32 v151, v2, s6, v3 bitop3:0xde
	v_lshl_or_b32 v0, v1, 6, v0
	s_add_i32 s79, 0, 0x10000
	s_add_i32 s80, 0, 0x14000
	s_brev_b32 s38, 63
	v_cmp_gt_u32_e64 s[6:7], 8, v150
	v_and_b32_e32 v152, 7, v12
	v_and_b32_e32 v153, 8, v12
	s_ashr_i32 s75, s20, 31
	s_mov_b32 s77, s20
	s_ashr_i32 s78, s2, 31
	v_mov_b32_e32 v141, v131
	v_lshl_add_u32 v142, v18, 1, v0
	v_mov_b32_e32 v143, v131
	v_add_u32_e32 v155, s79, v151
	v_add_u32_e32 v156, 0, v4
	v_add_u32_e32 v157, s80, v151
	s_mov_b32 s39, -1
	s_movk_i32 s81, 0x1f80
	s_movk_i32 s82, 0x1f70
	s_movk_i32 s83, 0x1f60
	s_movk_i32 s84, 0x1f50
	v_mov_b64_e32 v[144:145], 0x1ff
	s_barrier
	s_branch .LBB0_605

; #define PG8_STAGE(bufoff, gbase, voff) do { _Pragma("unroll") for (int _i = 0; _i < 2; ++_i) \
;         __builtin_amdgcn_global_load_lds((const unsigned*)((const char*)(gbase) + (voff)[_i]), (LAS unsigned*)(lds + (bufoff) + ldsw + _i * 8192), 16, 0, 0); } while (0)
; #define PG8_LDA(dst, b, h) do { _Pragma("unroll") for (int m = 0; m < 4; ++m) _Pragma("unroll") for (int k = 0; k < 2; ++k) dst[m][k] = *(const LAS bf16x8*)(lds + PG8_SA(b, h) + aoff + m * 2048 + k * 1024); } while (0)
; #define PG8_LDB(dst, b, h) do { _Pragma("unroll") for (int n = 0; n < 2; ++n) _Pragma("unroll") for (int k = 0; k < 2; ++k) dst[n][k] = *(const LAS bf16x8*)(lds + PG8_SB(b, h) + boff + n * 2048 + k * 1024); } while (0)
; #define PG8_MMA(ai, bj, At, Bt) do { __builtin_amdgcn_s_setprio(1); _Pragma("unroll") for (int m = 0; m < 4; ++m) _Pragma("unroll") for (int n = 0; n < 2; ++n) _Pragma("unroll") for (int k = 0; k < 2; ++k) \
;         acc[ai][bj][m][n] = __builtin_amdgcn_mfma_f32_16x16x32_bf16(Bt[n][k], At[m][k], acc[ai][bj][m][n], 0, 0, 0); __builtin_amdgcn_s_setprio(0); } while (0)
; #define PG8_WAIT_L(n) asm volatile("s_waitcnt lgkmcnt(" #n ")" ::: "memory")
; #define PG8_BAR __builtin_amdgcn_s_barrier()
; #define PG8_SCHED __builtin_amdgcn_sched_barrier(0)
; template <class Epi>
; __device__ __forceinline__ void gemm_phase(LAS unsigned char* lds, const Gemm g, const StaticOrder& S, const Epi& E) {
;     ...
;             PG8_LDB(B0, 0, 0); PG8_SCHED; PG8_LDA(At, 0, 0); PG8_STAGE(PG8_SA(1, 1), a1 + hstep, voffA);
;             PG8_WAIT_L(8); PG8_BAR; PG8_WAIT_L(0); PG8_MMA(0, 0, At, B0); PG8_BAR; PG8_SCHED;
;             PG8_LDB(B1, 0, 1); PG8_STAGE(PG8_SB(0, 0), b2, voffB0);
;             PG8_BAR; PG8_WAIT_L(0); PG8_MMA(0, 1, At, B1); PG8_BAR;
;             PG8_LDA(At, 0, 1); PG8_STAGE(PG8_SA(0, 0), a2, voffA);
;             PG8_BAR; PG8_WAIT_L(0); PG8_MMA(1, 0, At, B0); PG8_BAR; PG8_SCHED;
;             PG8_STAGE(PG8_SB(0, 1), b2, voffB1);
.LBB0_613:
	ds_read_b128 v[146:149], v155
	ds_read_b128 v[158:161], v155 offset:1024
	ds_read_b128 v[162:165], v155 offset:2048
	ds_read_b128 v[166:169], v155 offset:3072
	s_add_u32 s33, s54, 0xfff80080
	s_addc_u32 s56, s55, -1
	s_cmp_eq_u32 s88, 28
	s_cselect_b32 s57, s43, s56
	s_cselect_b32 s56, s51, s33
	s_cselect_b32 s59, s41, s87
	s_cselect_b32 s58, s85, s86
	v_lshl_add_u64 v[204:205], s[54:55], 0, v[140:141]
	s_add_i32 m0, s53, 0xc000
	ds_read_b128 v[170:173], v156
	ds_read_b128 v[174:177], v156 offset:1024
	ds_read_b128 v[178:181], v156 offset:2048
	ds_read_b128 v[182:185], v156 offset:3072
	ds_read_b128 v[186:189], v156 offset:4096
	ds_read_b128 v[190:193], v156 offset:5120
	ds_read_b128 v[194:197], v156 offset:6144
	ds_read_b128 v[198:201], v156 offset:7168
	global_load_lds_dwordx4 v[204:205], off
	v_lshl_add_u64 v[204:205], s[54:55], 0, v[142:143]
	s_add_i32 m0, s53, 0xe000
	s_nop 0
	global_load_lds_dwordx4 v[204:205], off
	s_waitcnt lgkmcnt(8)
	s_barrier
	s_waitcnt lgkmcnt(0)
	v_mfma_f32_16x16x32_bf16 v[124:127], v[146:149], v[170:173], v[124:127]
	v_mfma_f32_16x16x32_bf16 v[120:123], v[162:165], v[170:173], v[120:123]
	v_mfma_f32_16x16x32_bf16 v[108:111], v[146:149], v[178:181], v[108:111]
	v_mfma_f32_16x16x32_bf16 v[104:107], v[162:165], v[178:181], v[104:107]
	v_mfma_f32_16x16x32_bf16 v[92:95], v[146:149], v[186:189], v[92:95]
	v_mfma_f32_16x16x32_bf16 v[88:91], v[162:165], v[186:189], v[88:91]
	v_mfma_f32_16x16x32_bf16 v[76:79], v[146:149], v[194:197], v[76:79]
	v_mfma_f32_16x16x32_bf16 v[72:75], v[162:165], v[194:197], v[72:75]
	v_mfma_f32_16x16x32_bf16 v[124:127], v[158:161], v[174:177], v[124:127]
	v_mfma_f32_16x16x32_bf16 v[120:123], v[166:169], v[174:177], v[120:123]
	v_mfma_f32_16x16x32_bf16 v[108:111], v[158:161], v[182:185], v[108:111]
	v_mfma_f32_16x16x32_bf16 v[104:107], v[166:169], v[182:185], v[104:107]
	v_mfma_f32_16x16x32_bf16 v[92:95], v[158:161], v[190:193], v[92:95]
	v_mfma_f32_16x16x32_bf16 v[88:91], v[166:169], v[190:193], v[88:91]
	v_mfma_f32_16x16x32_bf16 v[76:79], v[158:161], v[198:201], v[76:79]
	v_mfma_f32_16x16x32_bf16 v[72:75], v[166:169], v[198:201], v[72:75]
	s_barrier
	s_add_i32 s33, s79, s65
	v_lshl_add_u64 v[220:221], s[58:59], 0, v[130:131]
	s_mov_b32 m0, s33
	ds_read_b128 v[204:207], v157
	ds_read_b128 v[208:211], v157 offset:1024
	ds_read_b128 v[212:215], v157 offset:2048
	ds_read_b128 v[216:219], v157 offset:3072
	global_load_lds_dwordx4 v[220:221], off
	v_lshl_add_u64 v[222:223], s[58:59], 0, v[136:137]
	s_add_i32 m0, s33, 0x2000
	s_nop 0
	global_load_lds_dwordx4 v[222:223], off
	s_barrier
	s_waitcnt lgkmcnt(0)
	v_mfma_f32_16x16x32_bf16 v[116:119], v[204:207], v[170:173], v[116:119]
	v_mfma_f32_16x16x32_bf16 v[112:115], v[212:215], v[170:173], v[112:115]
	v_mfma_f32_16x16x32_bf16 v[100:103], v[204:207], v[178:181], v[100:103]
	v_mfma_f32_16x16x32_bf16 v[96:99], v[212:215], v[178:181], v[96:99]
	v_mfma_f32_16x16x32_bf16 v[84:87], v[204:207], v[186:189], v[84:87]
	v_mfma_f32_16x16x32_bf16 v[80:83], v[212:215], v[186:189], v[80:83]
	v_mfma_f32_16x16x32_bf16 v[68:71], v[204:207], v[194:197], v[68:71]
	v_mfma_f32_16x16x32_bf16 v[64:67], v[212:215], v[194:197], v[64:67]
	v_mfma_f32_16x16x32_bf16 v[116:119], v[208:211], v[174:177], v[116:119]
	v_mfma_f32_16x16x32_bf16 v[112:115], v[216:219], v[174:177], v[112:115]
	v_mfma_f32_16x16x32_bf16 v[100:103], v[208:211], v[182:185], v[100:103]
	v_mfma_f32_16x16x32_bf16 v[96:99], v[216:219], v[182:185], v[96:99]
	v_mfma_f32_16x16x32_bf16 v[84:87], v[208:211], v[190:193], v[84:87]
	v_mfma_f32_16x16x32_bf16 v[80:83], v[216:219], v[190:193], v[80:83]
	v_mfma_f32_16x16x32_bf16 v[68:71], v[208:211], v[198:201], v[68:71]
	v_mfma_f32_16x16x32_bf16 v[64:67], v[216:219], v[198:201], v[64:67]
	s_mov_b32 m0, s53
	v_lshl_add_u64 v[224:225], s[56:57], 0, v[128:129]
	s_barrier
	ds_read_b128 v[170:173], v156 offset:16384
	ds_read_b128 v[174:177], v156 offset:17408
	ds_read_b128 v[178:181], v156 offset:18432
	ds_read_b128 v[182:185], v156 offset:19456
	ds_read_b128 v[186:189], v156 offset:20480
	ds_read_b128 v[190:193], v156 offset:21504
	ds_read_b128 v[194:197], v156 offset:22528
	ds_read_b128 v[198:201], v156 offset:23552
	global_load_lds_dwordx4 v[224:225], off
	v_lshl_add_u64 v[226:227], s[56:57], 0, v[134:135]
	s_mov_b32 m0, s66
	s_nop 0
	global_load_lds_dwordx4 v[226:227], off
	s_barrier
	s_waitcnt lgkmcnt(0)
	v_mfma_f32_16x16x32_bf16 v[60:63], v[146:149], v[170:173], v[60:63]
	v_mfma_f32_16x16x32_bf16 v[56:59], v[162:165], v[170:173], v[56:59]
	v_mfma_f32_16x16x32_bf16 v[44:47], v[146:149], v[178:181], v[44:47]
	v_mfma_f32_16x16x32_bf16 v[40:43], v[162:165], v[178:181], v[40:43]
	v_mfma_f32_16x16x32_bf16 v[28:31], v[146:149], v[186:189], v[28:31]
	v_mfma_f32_16x16x32_bf16 v[24:27], v[162:165], v[186:189], v[24:27]
	v_mfma_f32_16x16x32_bf16 v[12:15], v[146:149], v[194:197], v[12:15]
	v_mfma_f32_16x16x32_bf16 v[8:11], v[162:165], v[194:197], v[8:11]
	v_mfma_f32_16x16x32_bf16 v[60:63], v[158:161], v[174:177], v[60:63]
	v_mfma_f32_16x16x32_bf16 v[56:59], v[166:169], v[174:177], v[56:59]
	v_mfma_f32_16x16x32_bf16 v[44:47], v[158:161], v[182:185], v[44:47]
	v_mfma_f32_16x16x32_bf16 v[40:43], v[166:169], v[182:185], v[40:43]
	v_mfma_f32_16x16x32_bf16 v[28:31], v[158:161], v[190:193], v[28:31]
	v_mfma_f32_16x16x32_bf16 v[24:27], v[166:169], v[190:193], v[24:27]
	v_mfma_f32_16x16x32_bf16 v[12:15], v[158:161], v[198:201], v[12:15]
	v_mfma_f32_16x16x32_bf16 v[8:11], v[166:169], v[198:201], v[8:11]
	s_barrier
; #define PG8_STAGE(bufoff, gbase, voff) do { _Pragma("unroll") for (int _i = 0; _i < 2; ++_i) \
;         __builtin_amdgcn_global_load_lds((const unsigned*)((const char*)(gbase) + (voff)[_i]), (LAS unsigned*)(lds + (bufoff) + ldsw + _i * 8192), 16, 0, 0); } while (0)
; #define PG8_LDA(dst, b, h) do { _Pragma("unroll") for (int m = 0; m < 4; ++m) _Pragma("unroll") for (int k = 0; k < 2; ++k) dst[m][k] = *(const LAS bf16x8*)(lds + PG8_SA(b, h) + aoff + m * 2048 + k * 1024); } while (0)
; #define PG8_LDB(dst, b, h) do { _Pragma("unroll") for (int n = 0; n < 2; ++n) _Pragma("unroll") for (int k = 0; k < 2; ++k) dst[n][k] = *(const LAS bf16x8*)(lds + PG8_SB(b, h) + boff + n * 2048 + k * 1024); } while (0)
; #define PG8_MMA(ai, bj, At, Bt) do { __builtin_amdgcn_s_setprio(1); _Pragma("unroll") for (int m = 0; m < 4; ++m) _Pragma("unroll") for (int n = 0; n < 2; ++n) _Pragma("unroll") for (int k = 0; k < 2; ++k) \
;         acc[ai][bj][m][n] = __builtin_amdgcn_mfma_f32_16x16x32_bf16(Bt[n][k], At[m][k], acc[ai][bj][m][n], 0, 0, 0); __builtin_amdgcn_s_setprio(0); } while (0)
; #define PG8_WAIT_V(n) asm volatile("s_waitcnt vmcnt(" #n ")" ::: "memory")
; #define PG8_WAIT_L(n) asm volatile("s_waitcnt lgkmcnt(" #n ")" ::: "memory")
; #define PG8_BAR __builtin_amdgcn_s_barrier()
; #define PG8_SCHED __builtin_amdgcn_sched_barrier(0)
; template <class Epi>
; __device__ __forceinline__ void gemm_phase(LAS unsigned char* lds, const Gemm g, const StaticOrder& S, const Epi& E) {
;     ...
;             PG8_STAGE(PG8_SB(0, 1), b2, voffB1);
;             PG8_WAIT_V(6); PG8_BAR; PG8_MMA(1, 1, At, B1); PG8_BAR;
;             PG8_LDB(B0, 1, 0); PG8_SCHED; PG8_LDA(At, 1, 0); PG8_STAGE(PG8_SA(0, 1), a2 + hstep, voffA);
;             PG8_WAIT_L(8); PG8_BAR; PG8_WAIT_L(0); PG8_MMA(0, 0, At, B0); PG8_BAR; PG8_SCHED;
;             PG8_LDB(B1, 1, 1); PG8_STAGE(PG8_SB(1, 0), b3, voffB0);
;             PG8_BAR; PG8_WAIT_L(0); PG8_MMA(0, 1, At, B1); PG8_BAR;
;             PG8_LDA(At, 1, 1); PG8_STAGE(PG8_SA(1, 0), a3, voffA);
	s_add_i32 s33, s80, s65
	v_lshl_add_u64 v[228:229], s[58:59], 0, v[132:133]
	s_mov_b32 m0, s33
	v_lshl_add_u64 v[230:231], s[58:59], 0, v[138:139]
	global_load_lds_dwordx4 v[228:229], off
	s_add_i32 m0, s33, 0x2000
	s_nop 0
	global_load_lds_dwordx4 v[230:231], off
	s_add_i32 s33, 0, 0x18000
	v_add_u32_e32 v166, s33, v151
	ds_read_b128 v[146:149], v166
	ds_read_b128 v[158:161], v166 offset:1024
	ds_read_b128 v[162:165], v166 offset:2048
	ds_read_b128 v[166:169], v166 offset:3072
	s_waitcnt vmcnt(6)
	s_barrier
	v_mfma_f32_16x16x32_bf16 v[52:55], v[204:207], v[170:173], v[52:55]
	v_mfma_f32_16x16x32_bf16 v[48:51], v[212:215], v[170:173], v[48:51]
	v_mfma_f32_16x16x32_bf16 v[36:39], v[204:207], v[178:181], v[36:39]
	v_mfma_f32_16x16x32_bf16 v[32:35], v[212:215], v[178:181], v[32:35]
	v_mfma_f32_16x16x32_bf16 v[20:23], v[204:207], v[186:189], v[20:23]
	v_mfma_f32_16x16x32_bf16 v[16:19], v[212:215], v[186:189], v[16:19]
	v_mfma_f32_16x16x32_bf16 v[4:7], v[204:207], v[194:197], v[4:7]
	v_mfma_f32_16x16x32_bf16 v[0:3], v[212:215], v[194:197], v[0:3]
	v_mfma_f32_16x16x32_bf16 v[52:55], v[208:211], v[174:177], v[52:55]
	v_mfma_f32_16x16x32_bf16 v[48:51], v[216:219], v[174:177], v[48:51]
	v_mfma_f32_16x16x32_bf16 v[36:39], v[208:211], v[182:185], v[36:39]
	v_mfma_f32_16x16x32_bf16 v[32:35], v[216:219], v[182:185], v[32:35]
	v_mfma_f32_16x16x32_bf16 v[20:23], v[208:211], v[190:193], v[20:23]
	v_mfma_f32_16x16x32_bf16 v[16:19], v[216:219], v[190:193], v[16:19]
	v_mfma_f32_16x16x32_bf16 v[4:7], v[208:211], v[198:201], v[4:7]
	v_mfma_f32_16x16x32_bf16 v[0:3], v[216:219], v[198:201], v[0:3]
	s_barrier
	s_add_u32 s56, s56, 0x80000
	s_addc_u32 s57, s57, 0
	s_mov_b32 m0, s67
	v_lshl_add_u64 v[204:205], s[56:57], 0, v[128:129]
	ds_read_b128 v[170:173], v156 offset:32768
	ds_read_b128 v[174:177], v156 offset:33792
	ds_read_b128 v[178:181], v156 offset:34816
	ds_read_b128 v[182:185], v156 offset:35840
	ds_read_b128 v[186:189], v156 offset:36864
	ds_read_b128 v[190:193], v156 offset:37888
	ds_read_b128 v[194:197], v156 offset:38912
	ds_read_b128 v[198:201], v156 offset:39936
	global_load_lds_dwordx4 v[204:205], off
	v_lshl_add_u64 v[204:205], s[56:57], 0, v[134:135]
	s_mov_b32 m0, s68
	s_nop 0
	global_load_lds_dwordx4 v[204:205], off
	s_waitcnt lgkmcnt(8)
	s_barrier
	s_waitcnt lgkmcnt(0)
	v_mfma_f32_16x16x32_bf16 v[124:127], v[146:149], v[170:173], v[124:127]
	v_mfma_f32_16x16x32_bf16 v[120:123], v[162:165], v[170:173], v[120:123]
	v_mfma_f32_16x16x32_bf16 v[108:111], v[146:149], v[178:181], v[108:111]
	v_mfma_f32_16x16x32_bf16 v[104:107], v[162:165], v[178:181], v[104:107]
	v_mfma_f32_16x16x32_bf16 v[92:95], v[146:149], v[186:189], v[92:95]
	v_mfma_f32_16x16x32_bf16 v[88:91], v[162:165], v[186:189], v[88:91]
	v_mfma_f32_16x16x32_bf16 v[76:79], v[146:149], v[194:197], v[76:79]
	v_mfma_f32_16x16x32_bf16 v[72:75], v[162:165], v[194:197], v[72:75]
	v_mfma_f32_16x16x32_bf16 v[124:127], v[158:161], v[174:177], v[124:127]
	v_mfma_f32_16x16x32_bf16 v[120:123], v[166:169], v[174:177], v[120:123]
	v_mfma_f32_16x16x32_bf16 v[108:111], v[158:161], v[182:185], v[108:111]
	v_mfma_f32_16x16x32_bf16 v[104:107], v[166:169], v[182:185], v[104:107]
	v_mfma_f32_16x16x32_bf16 v[92:95], v[158:161], v[190:193], v[92:95]
	v_mfma_f32_16x16x32_bf16 v[88:91], v[166:169], v[190:193], v[88:91]
	v_mfma_f32_16x16x32_bf16 v[76:79], v[158:161], v[198:201], v[76:79]
	v_mfma_f32_16x16x32_bf16 v[72:75], v[166:169], v[198:201], v[72:75]
	s_barrier
	s_add_i32 s56, 0, 0x1c000
	s_add_i32 s33, s33, s65
	v_add_u32_e32 v216, s56, v151
	v_lshl_add_u64 v[220:221], v[220:221], 0, s[36:37]
	s_mov_b32 m0, s33
	ds_read_b128 v[204:207], v216
	ds_read_b128 v[208:211], v216 offset:1024
	ds_read_b128 v[212:215], v216 offset:2048
	ds_read_b128 v[216:219], v216 offset:3072
	global_load_lds_dwordx4 v[220:221], off
	v_lshl_add_u64 v[220:221], v[222:223], 0, s[36:37]
	s_add_i32 m0, s33, 0x2000
	s_nop 0
	global_load_lds_dwordx4 v[220:221], off
	s_barrier
	s_waitcnt lgkmcnt(0)
	v_mfma_f32_16x16x32_bf16 v[116:119], v[204:207], v[170:173], v[116:119]
	v_mfma_f32_16x16x32_bf16 v[112:115], v[212:215], v[170:173], v[112:115]
	v_mfma_f32_16x16x32_bf16 v[100:103], v[204:207], v[178:181], v[100:103]
	v_mfma_f32_16x16x32_bf16 v[96:99], v[212:215], v[178:181], v[96:99]
	v_mfma_f32_16x16x32_bf16 v[84:87], v[204:207], v[186:189], v[84:87]
	v_mfma_f32_16x16x32_bf16 v[80:83], v[212:215], v[186:189], v[80:83]
	v_mfma_f32_16x16x32_bf16 v[68:71], v[204:207], v[194:197], v[68:71]
	v_mfma_f32_16x16x32_bf16 v[64:67], v[212:215], v[194:197], v[64:67]
	v_mfma_f32_16x16x32_bf16 v[116:119], v[208:211], v[174:177], v[116:119]
	v_mfma_f32_16x16x32_bf16 v[112:115], v[216:219], v[174:177], v[112:115]
	v_mfma_f32_16x16x32_bf16 v[100:103], v[208:211], v[182:185], v[100:103]
	v_mfma_f32_16x16x32_bf16 v[96:99], v[216:219], v[182:185], v[96:99]
	v_mfma_f32_16x16x32_bf16 v[84:87], v[208:211], v[190:193], v[84:87]
	v_mfma_f32_16x16x32_bf16 v[80:83], v[216:219], v[190:193], v[80:83]
	v_mfma_f32_16x16x32_bf16 v[68:71], v[208:211], v[198:201], v[68:71]
	v_mfma_f32_16x16x32_bf16 v[64:67], v[216:219], v[198:201], v[64:67]
	s_mov_b32 m0, s72
	v_lshl_add_u64 v[220:221], v[224:225], 0, s[36:37]
	s_barrier
	ds_read_b128 v[170:173], v156 offset:49152
	ds_read_b128 v[174:177], v156 offset:50176
	ds_read_b128 v[178:181], v156 offset:51200
	ds_read_b128 v[182:185], v156 offset:52224
	ds_read_b128 v[186:189], v156 offset:53248
	ds_read_b128 v[190:193], v156 offset:54272
	ds_read_b128 v[194:197], v156 offset:55296
	ds_read_b128 v[198:201], v156 offset:56320
	global_load_lds_dwordx4 v[220:221], off
	v_lshl_add_u64 v[220:221], v[226:227], 0, s[36:37]
	s_mov_b32 m0, s73
	s_nop 0
	global_load_lds_dwordx4 v[220:221], off
	s_barrier
; #define PG8_STAGE(bufoff, gbase, voff) do { _Pragma("unroll") for (int _i = 0; _i < 2; ++_i) \
;         __builtin_amdgcn_global_load_lds((const unsigned*)((const char*)(gbase) + (voff)[_i]), (LAS unsigned*)(lds + (bufoff) + ldsw + _i * 8192), 16, 0, 0); } while (0)
; #define PG8_LDA(dst, b, h) do { _Pragma("unroll") for (int m = 0; m < 4; ++m) _Pragma("unroll") for (int k = 0; k < 2; ++k) dst[m][k] = *(const LAS bf16x8*)(lds + PG8_SA(b, h) + aoff + m * 2048 + k * 1024); } while (0)
; #define PG8_MMA(ai, bj, At, Bt) do { __builtin_amdgcn_s_setprio(1); _Pragma("unroll") for (int m = 0; m < 4; ++m) _Pragma("unroll") for (int n = 0; n < 2; ++n) _Pragma("unroll") for (int k = 0; k < 2; ++k) \
;         acc[ai][bj][m][n] = __builtin_amdgcn_mfma_f32_16x16x32_bf16(Bt[n][k], At[m][k], acc[ai][bj][m][n], 0, 0, 0); __builtin_amdgcn_s_setprio(0); } while (0)
; #define PG8_WAIT_V(n) asm volatile("s_waitcnt vmcnt(" #n ")" ::: "memory")
; #define PG8_WAIT_L(n) asm volatile("s_waitcnt lgkmcnt(" #n ")" ::: "memory")
; #define PG8_BAR __builtin_amdgcn_s_barrier()
; #define PG8_SCHED __builtin_amdgcn_sched_barrier(0)
; template <class Epi>
; __device__ __forceinline__ void gemm_phase(LAS unsigned char* lds, const Gemm g, const StaticOrder& S, const Epi& E) {
;     ...
;             PG8_LDA(At, 1, 1); PG8_STAGE(PG8_SA(1, 0), a3, voffA);
;             PG8_BAR; PG8_WAIT_L(0); PG8_MMA(1, 0, At, B0); PG8_BAR; PG8_SCHED;
;             PG8_STAGE(PG8_SB(1, 1), b3, voffB1);
;             PG8_WAIT_V(6); PG8_BAR; PG8_MMA(1, 1, At, B1); PG8_BAR;
	s_waitcnt lgkmcnt(0)
	v_mfma_f32_16x16x32_bf16 v[60:63], v[146:149], v[170:173], v[60:63]
	v_mfma_f32_16x16x32_bf16 v[56:59], v[162:165], v[170:173], v[56:59]
	v_mfma_f32_16x16x32_bf16 v[44:47], v[146:149], v[178:181], v[44:47]
	v_mfma_f32_16x16x32_bf16 v[40:43], v[162:165], v[178:181], v[40:43]
	v_mfma_f32_16x16x32_bf16 v[28:31], v[146:149], v[186:189], v[28:31]
	v_mfma_f32_16x16x32_bf16 v[24:27], v[162:165], v[186:189], v[24:27]
	v_mfma_f32_16x16x32_bf16 v[12:15], v[146:149], v[194:197], v[12:15]
	v_mfma_f32_16x16x32_bf16 v[8:11], v[162:165], v[194:197], v[8:11]
	v_mfma_f32_16x16x32_bf16 v[60:63], v[158:161], v[174:177], v[60:63]
	v_mfma_f32_16x16x32_bf16 v[56:59], v[166:169], v[174:177], v[56:59]
	v_mfma_f32_16x16x32_bf16 v[44:47], v[158:161], v[182:185], v[44:47]
	v_mfma_f32_16x16x32_bf16 v[40:43], v[166:169], v[182:185], v[40:43]
	v_mfma_f32_16x16x32_bf16 v[28:31], v[158:161], v[190:193], v[28:31]
	v_mfma_f32_16x16x32_bf16 v[24:27], v[166:169], v[190:193], v[24:27]
	v_mfma_f32_16x16x32_bf16 v[12:15], v[158:161], v[198:201], v[12:15]
	v_mfma_f32_16x16x32_bf16 v[8:11], v[166:169], v[198:201], v[8:11]
	s_barrier
	s_add_i32 s33, s56, s65
	v_lshl_add_u64 v[146:147], v[228:229], 0, s[36:37]
	s_mov_b32 m0, s33
	s_nop 0
	global_load_lds_dwordx4 v[146:147], off
	v_lshl_add_u64 v[146:147], v[230:231], 0, s[36:37]
	s_add_i32 m0, s33, 0x2000
	s_nop 0
	global_load_lds_dwordx4 v[146:147], off
	s_waitcnt vmcnt(6)
	s_barrier
	v_mfma_f32_16x16x32_bf16 v[52:55], v[204:207], v[170:173], v[52:55]
	v_mfma_f32_16x16x32_bf16 v[48:51], v[212:215], v[170:173], v[48:51]
	v_mfma_f32_16x16x32_bf16 v[36:39], v[204:207], v[178:181], v[36:39]
	v_mfma_f32_16x16x32_bf16 v[32:35], v[212:215], v[178:181], v[32:35]
	v_mfma_f32_16x16x32_bf16 v[20:23], v[204:207], v[186:189], v[20:23]
	v_mfma_f32_16x16x32_bf16 v[16:19], v[212:215], v[186:189], v[16:19]
	v_mfma_f32_16x16x32_bf16 v[4:7], v[204:207], v[194:197], v[4:7]
	v_mfma_f32_16x16x32_bf16 v[0:3], v[212:215], v[194:197], v[0:3]
	v_mfma_f32_16x16x32_bf16 v[52:55], v[208:211], v[174:177], v[52:55]
	v_mfma_f32_16x16x32_bf16 v[48:51], v[216:219], v[174:177], v[48:51]
	v_mfma_f32_16x16x32_bf16 v[36:39], v[208:211], v[182:185], v[36:39]
	v_mfma_f32_16x16x32_bf16 v[32:35], v[216:219], v[182:185], v[32:35]
	v_mfma_f32_16x16x32_bf16 v[20:23], v[208:211], v[190:193], v[20:23]
	v_mfma_f32_16x16x32_bf16 v[16:19], v[216:219], v[190:193], v[16:19]
	v_mfma_f32_16x16x32_bf16 v[4:7], v[208:211], v[198:201], v[4:7]
	v_mfma_f32_16x16x32_bf16 v[0:3], v[216:219], v[198:201], v[0:3]
	s_add_i32 s88, s88, 2
	s_add_u32 s54, s54, 0x100
	s_addc_u32 s55, s55, 0
	s_add_u32 s86, s86, 0x100
	s_addc_u32 s87, s87, 0
	s_cmp_gt_u32 s88, 29
	s_barrier
	s_cbranch_scc0 .LBB0_613
; __device__ __forceinline__ unsigned cvt_pk_bf16(float lo, float hi) { unsigned r; asm volatile("v_cvt_pk_bf16_f32 %0, %1, %2" : "=v"(r) : "v"(lo), "v"(hi)); return r; }
; __device__ __forceinline__ float bflo(unsigned w) { return __uint_as_float(w << 16); }
; __device__ __forceinline__ void store_pair_lines(bf16_t* O, int ldc, int row, int fr, int col0, u32x4 wA, u32x4 wB) {
;     const u32x4 sA = {dpp_ror8(wA.x), dpp_ror8(wA.y), dpp_ror8(wA.z), dpp_ror8(wA.w)}, sB = {dpp_ror8(wB.x), dpp_ror8(wB.y), dpp_ror8(wB.z), dpp_ror8(wB.w)};
;     const bool lo = fr < 8;
;     const u32x4 o1 = lo ? wA : sB, o2 = lo ? sA : wB;
;     const int r1 = row - fr + (fr & 7), cb = col0 + (lo ? 0 : 8);
;     *(u32x4*)(O + (size_t)r1 * ldc + cb) = o1;
;     *(u32x4*)(O + (size_t)(r1 + 8) * ldc + cb) = o2;
; }
;     __device__ __forceinline__ void operator()(const f32x4 (&acc)[2][2][4][2], const Unit& u, int wr, int wc, int fr, int fq) const {
;     ...
;             for (int m = 0; m < 4; ++m) { const int row = row0 + ai * HALF + m * 16; const size_t off = (size_t)row * D + col0; float sq = 0.f; u32x4 w[2];
;                 const float sc = rsin ? __builtin_amdgcn_rcpf(rsin[row] * (1.f / D) + EPS) : 1.0f;
;                 u32x4 rr[2]; if (R) load_pair_lines(R, D, row, fr, col0, rr[0], rr[1]);
; #pragma unroll
;                 for (int bj = 0; bj < 2; ++bj) { f32x4 r0, r1;
;                     if (R) { const u32x4 rw = rr[bj]; r0 = (f32x4){bflo(rw.x), bfhi(rw.x), bflo(rw.y), bfhi(rw.y)}; r1 = (f32x4){bflo(rw.z), bfhi(rw.z), bflo(rw.w), bfhi(rw.w)}; }
;                     else { const float* rp = (row < 8192 ? src_p + off : src_s + (off - (size_t)8192 * D)) + 8 * bj; r0 = *(const f32x4*)rp; r1 = *(const f32x4*)(rp + 4); }
;                     const f32x4 o0 = r0 + acc[ai][bj][m][0] * sc, o1 = r1 + acc[ai][bj][m][1] * sc;
;                     sq += (o0[0] * o0[0] + o0[1] * o0[1]) + (o0[2] * o0[2] + o0[3] * o0[3]) + (o1[0] * o1[0] + o1[1] * o1[1]) + (o1[2] * o1[2] + o1[3] * o1[3]);
;                     w[bj].x = cvt_pk_bf16(o0[0], o0[1]); w[bj].y = cvt_pk_bf16(o0[2], o0[3]); w[bj].z = cvt_pk_bf16(o1[0], o1[1]); w[bj].w = cvt_pk_bf16(o1[2], o1[3]); }
;                 store_pair_lines(O, D, row, fr, col0, w[0], w[1]);
;                 if (ssout) { sq += __shfl_xor(sq, 16); sq += __shfl_xor(sq, 32); if (fq == 0) unsafeAtomicAdd(ssout + row, sq); } }
	s_lshl_b32 s33, s52, 8
	s_add_i32 s33, s33, s74
	v_or_b32_e32 v146, s33, v150
	v_lshl_or_b32 v148, s50, 8, v154
	v_ashrrev_i32_e32 v147, 31, v146
	v_ashrrev_i32_e32 v149, 31, v148
	v_lshlrev_b64 v[158:159], 11, v[146:147]
	v_lshl_add_u64 v[158:159], v[158:159], 0, v[148:149]
	v_lshlrev_b64 v[158:159], 2, v[158:159]
	v_lshl_add_u64 v[160:161], s[16:17], 0, v[158:159]
	v_lshl_add_u64 v[158:159], s[18:19], 0, v[158:159]
	v_lshl_add_u64 v[158:159], v[158:159], 0, s[38:39]
	v_cmp_gt_i32_e32 vcc, s70, v146
	v_mov_b32_e32 v183, 0
	v_mov_b32_e32 v184, 0
	v_cndmask_b32_e32 v167, v159, v161, vcc
	v_cndmask_b32_e32 v166, v158, v160, vcc
	global_load_dwordx4 v[158:161], v[166:167], off
	global_load_dwordx4 v[162:165], v[166:167], off offset:16
	v_or_b32_e32 v188, 16, v146
	v_ashrrev_i32_e32 v189, 31, v188
	v_lshlrev_b64 v[190:191], 11, v[188:189]
	v_lshl_add_u64 v[190:191], v[190:191], 0, v[148:149]
	v_lshlrev_b64 v[190:191], 2, v[190:191]
	v_lshl_add_u64 v[192:193], s[16:17], 0, v[190:191]
	v_lshl_add_u64 v[190:191], s[18:19], 0, v[190:191]
	v_lshl_add_u64 v[190:191], v[190:191], 0, s[38:39]
	v_cmp_gt_i32_e32 vcc, s70, v188
	s_nop 1
	v_cndmask_b32_e32 v195, v191, v193, vcc
	v_cndmask_b32_e32 v194, v190, v192, vcc
	global_load_dwordx4 v[196:199], v[194:195], off
	global_load_dwordx4 v[204:207], v[194:195], off offset:16
	global_load_dwordx4 v[208:211], v[194:195], off offset:32
	global_load_dwordx4 v[212:215], v[194:195], off offset:48
	v_or_b32_e32 v188, 32, v146
	v_ashrrev_i32_e32 v189, 31, v188
	v_lshlrev_b64 v[190:191], 11, v[188:189]
	v_lshl_add_u64 v[190:191], v[190:191], 0, v[148:149]
	v_lshlrev_b64 v[190:191], 2, v[190:191]
	v_lshl_add_u64 v[192:193], s[16:17], 0, v[190:191]
	v_lshl_add_u64 v[190:191], s[18:19], 0, v[190:191]
	v_lshl_add_u64 v[190:191], v[190:191], 0, s[38:39]
	v_cmp_gt_i32_e32 vcc, s70, v188
	s_nop 1
	v_cndmask_b32_e32 v195, v191, v193, vcc
	v_cndmask_b32_e32 v194, v190, v192, vcc
	global_load_dwordx4 v[216:219], v[194:195], off
	global_load_dwordx4 v[220:223], v[194:195], off offset:16
	global_load_dwordx4 v[224:227], v[194:195], off offset:32
	global_load_dwordx4 v[228:231], v[194:195], off offset:48
	v_or_b32_e32 v188, 48, v146
	v_ashrrev_i32_e32 v189, 31, v188
	v_lshlrev_b64 v[190:191], 11, v[188:189]
	v_lshl_add_u64 v[190:191], v[190:191], 0, v[148:149]
	v_lshlrev_b64 v[190:191], 2, v[190:191]
	v_lshl_add_u64 v[192:193], s[16:17], 0, v[190:191]
	v_lshl_add_u64 v[190:191], s[18:19], 0, v[190:191]
	v_lshl_add_u64 v[190:191], v[190:191], 0, s[38:39]
	v_cmp_gt_i32_e32 vcc, s70, v188
	s_nop 1
	v_cndmask_b32_e32 v195, v191, v193, vcc
	v_cndmask_b32_e32 v194, v190, v192, vcc
	global_load_dwordx4 v[232:235], v[194:195], off
	global_load_dwordx4 v[236:239], v[194:195], off offset:16
	global_load_dwordx4 v[240:243], v[194:195], off offset:32
	global_load_dwordx4 v[244:247], v[194:195], off offset:48
	s_waitcnt vmcnt(12)
	v_pk_add_f32 v[168:169], v[126:127], v[160:161]
	v_pk_add_f32 v[170:171], v[124:125], v[158:159]
	v_pk_add_f32 v[164:165], v[122:123], v[164:165]
	v_pk_add_f32 v[162:163], v[120:121], v[162:163]
	v_cvt_pk_bf16_f32 v123, v170, v171
	v_cvt_pk_bf16_f32 v176, v168, v169
	v_mul_f32_e32 v171, v171, v171
	v_cvt_pk_bf16_f32 v177, v162, v163
	v_cvt_pk_bf16_f32 v178, v164, v165
	global_load_dwordx4 v[124:127], v[166:167], off offset:32
	global_load_dwordx4 v[158:161], v[166:167], off offset:48
	v_mul_f32_e32 v169, v169, v169
	v_and_b32_e32 v121, 64, v203
	v_mul_f32_e32 v163, v163, v163
	v_fmac_f32_e32 v171, v170, v170
	v_fmac_f32_e32 v169, v168, v168
	v_xor_b32_e32 v122, 16, v203
	v_add_u32_e32 v172, 64, v121
	v_mul_f32_e32 v165, v165, v165
	v_fmac_f32_e32 v163, v162, v162
	v_add_f32_e32 v162, v171, v169
	v_cmp_lt_i32_e32 vcc, v122, v172
	v_fmac_f32_e32 v165, v164, v164
	v_add_f32_e32 v162, v163, v162
	v_cndmask_b32_e32 v122, v203, v122, vcc
	v_add_f32_e32 v162, v165, v162
	v_xor_b32_e32 v167, 32, v203
	v_lshlrev_b32_e32 v122, 2, v122
	v_or_b32_e32 v166, s33, v152
	v_cmp_lt_i32_e32 vcc, v167, v172
	v_or_b32_e32 v120, v148, v153
	v_ashrrev_i32_e32 v121, 31, v120
	v_cndmask_b32_e32 v187, v203, v167, vcc
	v_ashrrev_i32_e32 v167, 31, v166
	v_or_b32_e32 v174, 8, v166
	v_lshlrev_b64 v[166:167], 12, v[166:167]
	v_lshlrev_b64 v[172:173], 1, v[120:121]
	v_lshl_add_u64 v[166:167], s[10:11], 0, v[166:167]
	v_lshl_add_u64 v[166:167], v[166:167], 0, v[172:173]
	v_ashrrev_i32_e32 v175, 31, v174
	v_mov_b32_dpp v179, v123 row_ror:8 row_mask:0xf bank_mask:0xf
	v_mov_b32_dpp v180, v176 row_ror:8 row_mask:0xf bank_mask:0xf
	v_mov_b32_dpp v181, v177 row_ror:8 row_mask:0xf bank_mask:0xf
	v_mov_b32_dpp v182, v178 row_ror:8 row_mask:0xf bank_mask:0xf
	s_waitcnt vmcnt(0)
	v_pk_add_f32 v[126:127], v[118:119], v[126:127]
	v_pk_add_f32 v[124:125], v[116:117], v[124:125]
	v_pk_add_f32 v[112:113], v[112:113], v[158:159]
	v_cvt_pk_bf16_f32 v116, v124, v125
	v_cvt_pk_bf16_f32 v117, v126, v127
	v_mul_f32_e32 v125, v125, v125
	v_mul_f32_e32 v127, v127, v127
	v_pk_add_f32 v[114:115], v[114:115], v[160:161]
	v_mul_f32_e32 v158, v113, v113
	v_fmac_f32_e32 v125, v124, v124
	v_fmac_f32_e32 v127, v126, v126
	v_cvt_pk_bf16_f32 v118, v112, v113
	v_cvt_pk_bf16_f32 v119, v114, v115
	v_mul_f32_e32 v115, v115, v115
	v_fmac_f32_e32 v158, v112, v112
	v_add_f32_e32 v112, v125, v127
	v_fmac_f32_e32 v115, v114, v114
	v_add_f32_e32 v112, v158, v112
	v_add_f32_e32 v112, v115, v112
	v_add_f32_e32 v124, v162, v112
	v_mov_b32_e32 v125, v124
	s_nop 1
	v_permlane16_swap_b32_e32 v125, v124
	v_mov_b32_dpp v183, v116 row_ror:8 row_mask:0xf bank_mask:0xf
	v_mov_b32_dpp v184, v117 row_ror:8 row_mask:0xf bank_mask:0xf
	v_mov_b32_dpp v185, v118 row_ror:8 row_mask:0xf bank_mask:0xf
	v_mov_b32_dpp v186, v119 row_ror:8 row_mask:0xf bank_mask:0xf
	v_cndmask_b32_e64 v113, v184, v176, s[6:7]
	v_cndmask_b32_e64 v115, v186, v178, s[6:7]
	v_cndmask_b32_e64 v112, v183, v123, s[6:7]
	v_cndmask_b32_e64 v114, v185, v177, s[6:7]
	global_store_dwordx4 v[166:167], v[112:115], off
	v_cndmask_b32_e64 v117, v117, v180, s[6:7]
	v_cndmask_b32_e64 v119, v119, v182, s[6:7]
	s_waitcnt lgkmcnt(0)
	v_add_f32_e32 v112, v124, v125
	v_lshlrev_b32_e32 v114, 2, v187
	v_mov_b32_e32 v113, v112
	s_nop 1
	v_permlane32_swap_b32_e32 v113, v112
	v_lshlrev_b64 v[124:125], 12, v[174:175]
	v_lshl_add_u64 v[124:125], s[10:11], 0, v[124:125]
	v_cndmask_b32_e64 v116, v116, v179, s[6:7]
	v_cndmask_b32_e64 v118, v118, v181, s[6:7]
	v_lshl_add_u64 v[124:125], v[124:125], 0, v[172:173]
	global_store_dwordx4 v[124:125], v[116:119], off
	s_and_saveexec_b64 s[50:51], s[8:9]
	s_cbranch_execz .LBB0_616
	s_waitcnt lgkmcnt(0)
	v_add_f32_e32 v115, v112, v113
	v_lshl_add_u64 v[112:113], v[146:147], 2, s[12:13]
	global_atomic_add_f32 v[112:113], v115, off

; #define PG8_STAGE(bufoff, gbase, voff) do { _Pragma("unroll") for (int _i = 0; _i < 2; ++_i) \
;         __builtin_amdgcn_global_load_lds((const unsigned*)((const char*)(gbase) + (voff)[_i]), (LAS unsigned*)(lds + (bufoff) + ldsw + _i * 8192), 16, 0, 0); } while (0)
; #define PG8_WAIT_V(n) asm volatile("s_waitcnt vmcnt(" #n ")" ::: "memory")
; #define PG8_BAR __builtin_amdgcn_s_barrier()
; template <class Epi>
; __device__ __forceinline__ void gemm_phase(LAS unsigned char* lds, const Gemm g, const StaticOrder& S, const Epi& E) {
;     int tid = threadIdx.x; asm volatile("" : "+v"(tid));
;     const int wid = __builtin_amdgcn_readfirstlane(tid >> 6), lane = tid & 63, wr = wid >> 2, wc = wid & 3, fr = lane & 15, fq = lane >> 4;
;     const int K = g.K, nt = K / BK;
;     unsigned voffA[2], voffB0[2], voffB1[2];
; #pragma unroll
;     for (int i = 0; i < 2; ++i) { int R, C; stage_rc(tid * 16 + i * 8192, R, C);
;         const int Rw = 64 * (R >> 5) + 16 * ((R >> 2) & 3) + 4 * ((R >> 4) & 1) + (R & 3);
;         const int Rf = 64 * (R >> 5) + 8 * ((R >> 2) & 3) + 4 * ((R >> 4) & 1) + (R & 3);
;         const int Rb0 = Epi::PERM ? (Epi::F32OUT ? Rf : Rw) : R, Rb1 = Epi::PERM ? (Epi::F32OUT ? Rf + 32 : Rw + 8) : R + HALF;
;         voffA[i] = (unsigned)(R * K + C) * 2u; voffB0[i] = (unsigned)(Rb0 * K + C) * 2u; voffB1[i] = (unsigned)(Rb1 * K + C) * 2u; }
;     const size_t kstep = (size_t)(BK * 2);
;     const size_t hstep = (size_t)HALF * K * 2;
;     const size_t tstep = 2 * hstep;
;     const unsigned ldsw = (unsigned)wid * 1024u;
;     const int aoff = lds_byte(wr * 64 + fr, fq * 8), boff = lds_byte(wc * 32 + fr, fq * 8);
;     ...
;     PG8_STAGE(PG8_SB(0, 0), cB, voffB0); PG8_STAGE(PG8_SA(0, 0), cA, voffA); PG8_STAGE(PG8_SB(0, 1), cB, voffB1); PG8_STAGE(PG8_SA(0, 1), cA + hstep, voffA);
;     if (wr == 1) PG8_BAR;
;     PG8_WAIT_V(4); PG8_BAR;
;     PG8_STAGE(PG8_SB(1, 0), cB + kstep, voffB0); PG8_STAGE(PG8_SA(1, 0), cA + kstep, voffA); PG8_STAGE(PG8_SB(1, 1), cB + kstep, voffB1);
;     PG8_WAIT_V(6); PG8_BAR;
.LBB0_724:
	s_add_u32 s10, s8, 0xec00000
	s_mov_b64 s[16:17], 0x80
	s_addc_u32 s11, s9, 0
	s_add_i32 m0, s45, 0x18000
	v_lshl_add_u64 v[10:11], v[10:11], 0, s[16:17]
	s_waitcnt vmcnt(4)
	s_barrier
	global_load_lds_dwordx4 v[10:11], off
	v_lshl_add_u64 v[8:9], v[8:9], 0, s[16:17]
	s_add_i32 m0, s45, 0x1a000
	s_add_i32 s61, s45, 0x8000
	global_load_lds_dwordx4 v[8:9], off
	v_lshl_add_u64 v[6:7], v[6:7], 0, s[16:17]
	s_mov_b32 m0, s61
	s_add_i32 s62, s45, 0xa000
	global_load_lds_dwordx4 v[6:7], off
	v_lshl_add_u64 v[4:5], v[4:5], 0, s[16:17]
	s_mov_b32 m0, s62
	v_lshl_add_u64 v[0:1], v[0:1], 0, s[16:17]
	global_load_lds_dwordx4 v[4:5], off
	s_add_i32 m0, s45, 0x1c000
	v_and_b32_e32 v146, 15, v12
	global_load_lds_dwordx4 v[0:1], off
	v_lshl_add_u64 v[0:1], v[2:3], 0, s[16:17]
	s_add_i32 m0, s45, 0x1e000
	v_lshlrev_b32_e32 v2, 2, v12
	global_load_lds_dwordx4 v[0:1], off
	v_and_b32_e32 v0, 48, v12
	s_sext_i32_i16 s69, s6
	s_and_b32 s6, s7, 3
	s_lshl_b32 s7, s18, 13
	v_lshl_or_b32 v1, v146, 6, v0
	v_and_b32_e32 v2, 32, v2
	v_bitop3_b32 v3, v1, s7, v2 bitop3:0xde
	s_lshl_b32 s7, s6, 12
	s_lshl_b32 s63, s18, 6
	v_bitop3_b32 v147, v1, s7, v2 bitop3:0xde
	s_lshl_b32 s18, s6, 6
	v_and_b32_e32 v1, 8, v12
	v_or3_b32 v156, s18, v1, v0
	v_lshlrev_b32_e32 v0, 15, v13
	v_and_b32_e32 v0, 0xffff0000, v0
	v_lshl_add_u32 v0, v14, 12, v0
	v_and_b32_e32 v1, 1, v13
	v_lshl_or_b32 v0, v1, 6, v0
	v_lshl_add_u32 v140, v15, 1, v0
	v_lshlrev_b32_e32 v0, 15, v16
	v_and_b32_e32 v0, 0xffff0000, v0
	s_waitcnt vmcnt(0)
	v_and_b32_e32 v148, 7, v12
	v_lshl_add_u32 v0, v17, 12, v0
	v_and_b32_e32 v1, 1, v16
	v_sub_u32_e32 v2, v148, v146
	v_lshl_or_b32 v0, v1, 6, v0
	s_add_i32 s66, 0, 0x10000
	s_add_i32 s67, 0, 0x14000
	v_cmp_gt_u32_e64 s[6:7], 8, v146
	s_ashr_i32 s64, s20, 31
	s_mov_b32 s65, s20
	v_add_u32_e32 v149, 16, v2
	v_add_u32_e32 v150, 32, v2
	v_add_u32_e32 v151, 48, v2
	v_add_u32_e32 v152, 0x80, v2
	v_add_u32_e32 v153, 0x90, v2
	v_add_u32_e32 v154, 0xa0, v2
	v_add_u32_e32 v155, 0xb0, v2
	v_mov_b32_e32 v141, v131
	v_lshl_add_u32 v142, v18, 1, v0
	v_mov_b32_e32 v143, v131
	v_add_u32_e32 v157, s66, v147
	v_add_u32_e32 v158, 0, v3
	v_add_u32_e32 v159, s67, v147
	s_mov_b32 s68, 0x20000
	v_mov_b64_e32 v[144:145], 0x7ff
	s_barrier

; #define PG8_STAGE(bufoff, gbase, voff) do { _Pragma("unroll") for (int _i = 0; _i < 2; ++_i) \
;         __builtin_amdgcn_global_load_lds((const unsigned*)((const char*)(gbase) + (voff)[_i]), (LAS unsigned*)(lds + (bufoff) + ldsw + _i * 8192), 16, 0, 0); } while (0)
; #define PG8_LDA(dst, b, h) do { _Pragma("unroll") for (int m = 0; m < 4; ++m) _Pragma("unroll") for (int k = 0; k < 2; ++k) dst[m][k] = *(const LAS bf16x8*)(lds + PG8_SA(b, h) + aoff + m * 2048 + k * 1024); } while (0)
; #define PG8_LDB(dst, b, h) do { _Pragma("unroll") for (int n = 0; n < 2; ++n) _Pragma("unroll") for (int k = 0; k < 2; ++k) dst[n][k] = *(const LAS bf16x8*)(lds + PG8_SB(b, h) + boff + n * 2048 + k * 1024); } while (0)
; #define PG8_MMA(ai, bj, At, Bt) do { __builtin_amdgcn_s_setprio(1); _Pragma("unroll") for (int m = 0; m < 4; ++m) _Pragma("unroll") for (int n = 0; n < 2; ++n) _Pragma("unroll") for (int k = 0; k < 2; ++k) \
;         acc[ai][bj][m][n] = __builtin_amdgcn_mfma_f32_16x16x32_bf16(Bt[n][k], At[m][k], acc[ai][bj][m][n], 0, 0, 0); __builtin_amdgcn_s_setprio(0); } while (0)
; #define PG8_WAIT_L(n) asm volatile("s_waitcnt lgkmcnt(" #n ")" ::: "memory")
; #define PG8_BAR __builtin_amdgcn_s_barrier()
; #define PG8_SCHED __builtin_amdgcn_sched_barrier(0)
; template <class Epi>
; __device__ __forceinline__ void gemm_phase(LAS unsigned char* lds, const Gemm g, const StaticOrder& S, const Epi& E) {
;     ...
;             PG8_LDB(B0, 0, 0); PG8_SCHED; PG8_LDA(At, 0, 0); PG8_STAGE(PG8_SA(1, 1), a1 + hstep, voffA);
;             PG8_WAIT_L(8); PG8_BAR; PG8_WAIT_L(0); PG8_MMA(0, 0, At, B0); PG8_BAR; PG8_SCHED;
;             PG8_LDB(B1, 0, 1); PG8_STAGE(PG8_SB(0, 0), b2, voffB0);
;             PG8_BAR; PG8_WAIT_L(0); PG8_MMA(0, 1, At, B1); PG8_BAR;
;             PG8_LDA(At, 0, 1); PG8_STAGE(PG8_SA(0, 0), a2, voffA);
;             PG8_BAR; PG8_WAIT_L(0); PG8_MMA(1, 0, At, B0); PG8_BAR; PG8_SCHED;
;             PG8_STAGE(PG8_SB(0, 1), b2, voffB1);
.LBB0_733:
	ds_read_b128 v[160:163], v157
	ds_read_b128 v[164:167], v157 offset:1024
	ds_read_b128 v[168:171], v157 offset:2048
	ds_read_b128 v[172:175], v157 offset:3072
	s_add_u32 s33, s46, 0xfff80080
	s_addc_u32 s48, s47, -1
	s_cmp_eq_u32 s74, 28
	s_cselect_b32 s49, s37, s48
	s_cselect_b32 s48, s70, s33
	s_cselect_b32 s51, s19, s73
	s_cselect_b32 s50, s71, s72
	v_lshl_add_u64 v[200:201], s[46:47], 0, v[140:141]
	s_add_i32 m0, s45, 0xc000
	ds_read_b128 v[176:179], v158
	ds_read_b128 v[180:183], v158 offset:1024
	ds_read_b128 v[184:187], v158 offset:2048
	ds_read_b128 v[188:191], v158 offset:3072
	ds_read_b128 v[192:195], v158 offset:4096
	ds_read_b128 v[196:199], v158 offset:5120
	ds_read_b128 v[204:207], v158 offset:6144
	ds_read_b128 v[208:211], v158 offset:7168
	global_load_lds_dwordx4 v[200:201], off
	v_lshl_add_u64 v[200:201], s[46:47], 0, v[142:143]
	s_add_i32 m0, s45, 0xe000
	s_nop 0
	global_load_lds_dwordx4 v[200:201], off
	s_waitcnt lgkmcnt(8)
	s_barrier
	s_waitcnt lgkmcnt(0)
	v_mfma_f32_16x16x32_bf16 v[124:127], v[160:163], v[176:179], v[124:127]
	v_mfma_f32_16x16x32_bf16 v[120:123], v[168:171], v[176:179], v[120:123]
	v_mfma_f32_16x16x32_bf16 v[108:111], v[160:163], v[184:187], v[108:111]
	v_mfma_f32_16x16x32_bf16 v[104:107], v[168:171], v[184:187], v[104:107]
	v_mfma_f32_16x16x32_bf16 v[92:95], v[160:163], v[192:195], v[92:95]
	v_mfma_f32_16x16x32_bf16 v[88:91], v[168:171], v[192:195], v[88:91]
	v_mfma_f32_16x16x32_bf16 v[76:79], v[160:163], v[204:207], v[76:79]
	v_mfma_f32_16x16x32_bf16 v[72:75], v[168:171], v[204:207], v[72:75]
	v_mfma_f32_16x16x32_bf16 v[124:127], v[164:167], v[180:183], v[124:127]
	v_mfma_f32_16x16x32_bf16 v[120:123], v[172:175], v[180:183], v[120:123]
	v_mfma_f32_16x16x32_bf16 v[108:111], v[164:167], v[188:191], v[108:111]
	v_mfma_f32_16x16x32_bf16 v[104:107], v[172:175], v[188:191], v[104:107]
	v_mfma_f32_16x16x32_bf16 v[92:95], v[164:167], v[196:199], v[92:95]
	v_mfma_f32_16x16x32_bf16 v[88:91], v[172:175], v[196:199], v[88:91]
	v_mfma_f32_16x16x32_bf16 v[76:79], v[164:167], v[208:211], v[76:79]
	v_mfma_f32_16x16x32_bf16 v[72:75], v[172:175], v[208:211], v[72:75]
	s_barrier
	s_add_i32 s33, s66, s56
	v_lshl_add_u64 v[200:201], s[50:51], 0, v[130:131]
	s_mov_b32 m0, s33
	ds_read_b128 v[212:215], v159
	ds_read_b128 v[216:219], v159 offset:1024
	ds_read_b128 v[220:223], v159 offset:2048
	ds_read_b128 v[224:227], v159 offset:3072
	global_load_lds_dwordx4 v[200:201], off
	v_lshl_add_u64 v[228:229], s[50:51], 0, v[136:137]
	s_add_i32 m0, s33, 0x2000
	s_nop 0
	global_load_lds_dwordx4 v[228:229], off
	s_barrier
	s_waitcnt lgkmcnt(0)
	v_mfma_f32_16x16x32_bf16 v[116:119], v[212:215], v[176:179], v[116:119]
	v_mfma_f32_16x16x32_bf16 v[112:115], v[220:223], v[176:179], v[112:115]
	v_mfma_f32_16x16x32_bf16 v[100:103], v[212:215], v[184:187], v[100:103]
	v_mfma_f32_16x16x32_bf16 v[96:99], v[220:223], v[184:187], v[96:99]
	v_mfma_f32_16x16x32_bf16 v[84:87], v[212:215], v[192:195], v[84:87]
	v_mfma_f32_16x16x32_bf16 v[80:83], v[220:223], v[192:195], v[80:83]
	v_mfma_f32_16x16x32_bf16 v[68:71], v[212:215], v[204:207], v[68:71]
	v_mfma_f32_16x16x32_bf16 v[64:67], v[220:223], v[204:207], v[64:67]
	v_mfma_f32_16x16x32_bf16 v[116:119], v[216:219], v[180:183], v[116:119]
	v_mfma_f32_16x16x32_bf16 v[112:115], v[224:227], v[180:183], v[112:115]
	v_mfma_f32_16x16x32_bf16 v[100:103], v[216:219], v[188:191], v[100:103]
	v_mfma_f32_16x16x32_bf16 v[96:99], v[224:227], v[188:191], v[96:99]
	v_mfma_f32_16x16x32_bf16 v[84:87], v[216:219], v[196:199], v[84:87]
	v_mfma_f32_16x16x32_bf16 v[80:83], v[224:227], v[196:199], v[80:83]
	v_mfma_f32_16x16x32_bf16 v[68:71], v[216:219], v[208:211], v[68:71]
	v_mfma_f32_16x16x32_bf16 v[64:67], v[224:227], v[208:211], v[64:67]
	s_mov_b32 m0, s45
	v_lshl_add_u64 v[230:231], s[48:49], 0, v[128:129]
	s_barrier
	ds_read_b128 v[176:179], v158 offset:16384
	ds_read_b128 v[180:183], v158 offset:17408
	ds_read_b128 v[184:187], v158 offset:18432
	ds_read_b128 v[188:191], v158 offset:19456
	ds_read_b128 v[192:195], v158 offset:20480
	ds_read_b128 v[196:199], v158 offset:21504
	ds_read_b128 v[204:207], v158 offset:22528
	ds_read_b128 v[208:211], v158 offset:23552
	global_load_lds_dwordx4 v[230:231], off
	v_lshl_add_u64 v[232:233], s[48:49], 0, v[134:135]
	s_mov_b32 m0, s57
	s_nop 0
	global_load_lds_dwordx4 v[232:233], off
	s_barrier
	s_waitcnt lgkmcnt(0)
	v_mfma_f32_16x16x32_bf16 v[60:63], v[160:163], v[176:179], v[60:63]
	v_mfma_f32_16x16x32_bf16 v[56:59], v[168:171], v[176:179], v[56:59]
	v_mfma_f32_16x16x32_bf16 v[44:47], v[160:163], v[184:187], v[44:47]
	v_mfma_f32_16x16x32_bf16 v[40:43], v[168:171], v[184:187], v[40:43]
	v_mfma_f32_16x16x32_bf16 v[28:31], v[160:163], v[192:195], v[28:31]
	v_mfma_f32_16x16x32_bf16 v[24:27], v[168:171], v[192:195], v[24:27]
	v_mfma_f32_16x16x32_bf16 v[12:15], v[160:163], v[204:207], v[12:15]
	v_mfma_f32_16x16x32_bf16 v[8:11], v[168:171], v[204:207], v[8:11]
	v_mfma_f32_16x16x32_bf16 v[60:63], v[164:167], v[180:183], v[60:63]
	v_mfma_f32_16x16x32_bf16 v[56:59], v[172:175], v[180:183], v[56:59]
	v_mfma_f32_16x16x32_bf16 v[44:47], v[164:167], v[188:191], v[44:47]
	v_mfma_f32_16x16x32_bf16 v[40:43], v[172:175], v[188:191], v[40:43]
	v_mfma_f32_16x16x32_bf16 v[28:31], v[164:167], v[196:199], v[28:31]
	v_mfma_f32_16x16x32_bf16 v[24:27], v[172:175], v[196:199], v[24:27]
	v_mfma_f32_16x16x32_bf16 v[12:15], v[164:167], v[208:211], v[12:15]
	v_mfma_f32_16x16x32_bf16 v[8:11], v[172:175], v[208:211], v[8:11]
	s_barrier
; #define PG8_STAGE(bufoff, gbase, voff) do { _Pragma("unroll") for (int _i = 0; _i < 2; ++_i) \
;         __builtin_amdgcn_global_load_lds((const unsigned*)((const char*)(gbase) + (voff)[_i]), (LAS unsigned*)(lds + (bufoff) + ldsw + _i * 8192), 16, 0, 0); } while (0)
; #define PG8_LDA(dst, b, h) do { _Pragma("unroll") for (int m = 0; m < 4; ++m) _Pragma("unroll") for (int k = 0; k < 2; ++k) dst[m][k] = *(const LAS bf16x8*)(lds + PG8_SA(b, h) + aoff + m * 2048 + k * 1024); } while (0)
; #define PG8_LDB(dst, b, h) do { _Pragma("unroll") for (int n = 0; n < 2; ++n) _Pragma("unroll") for (int k = 0; k < 2; ++k) dst[n][k] = *(const LAS bf16x8*)(lds + PG8_SB(b, h) + boff + n * 2048 + k * 1024); } while (0)
; #define PG8_MMA(ai, bj, At, Bt) do { __builtin_amdgcn_s_setprio(1); _Pragma("unroll") for (int m = 0; m < 4; ++m) _Pragma("unroll") for (int n = 0; n < 2; ++n) _Pragma("unroll") for (int k = 0; k < 2; ++k) \
;         acc[ai][bj][m][n] = __builtin_amdgcn_mfma_f32_16x16x32_bf16(Bt[n][k], At[m][k], acc[ai][bj][m][n], 0, 0, 0); __builtin_amdgcn_s_setprio(0); } while (0)
; #define PG8_WAIT_V(n) asm volatile("s_waitcnt vmcnt(" #n ")" ::: "memory")
; #define PG8_WAIT_L(n) asm volatile("s_waitcnt lgkmcnt(" #n ")" ::: "memory")
; #define PG8_BAR __builtin_amdgcn_s_barrier()
; #define PG8_SCHED __builtin_amdgcn_sched_barrier(0)
; template <class Epi>
; __device__ __forceinline__ void gemm_phase(LAS unsigned char* lds, const Gemm g, const StaticOrder& S, const Epi& E) {
;     ...
;             PG8_STAGE(PG8_SB(0, 1), b2, voffB1);
;             PG8_WAIT_V(6); PG8_BAR; PG8_MMA(1, 1, At, B1); PG8_BAR;
;             PG8_LDB(B0, 1, 0); PG8_SCHED; PG8_LDA(At, 1, 0); PG8_STAGE(PG8_SA(0, 1), a2 + hstep, voffA);
;             PG8_WAIT_L(8); PG8_BAR; PG8_WAIT_L(0); PG8_MMA(0, 0, At, B0); PG8_BAR; PG8_SCHED;
;             PG8_LDB(B1, 1, 1); PG8_STAGE(PG8_SB(1, 0), b3, voffB0);
;             PG8_BAR; PG8_WAIT_L(0); PG8_MMA(0, 1, At, B1); PG8_BAR;
;             PG8_LDA(At, 1, 1); PG8_STAGE(PG8_SA(1, 0), a3, voffA);
	s_add_i32 s33, s67, s56
	v_lshl_add_u64 v[234:235], s[50:51], 0, v[132:133]
	s_mov_b32 m0, s33
	v_lshl_add_u64 v[236:237], s[50:51], 0, v[138:139]
	global_load_lds_dwordx4 v[234:235], off
	s_add_i32 m0, s33, 0x2000
	s_nop 0
	global_load_lds_dwordx4 v[236:237], off
	s_add_i32 s33, 0, 0x18000
	v_add_u32_e32 v172, s33, v147
	ds_read_b128 v[160:163], v172
	ds_read_b128 v[164:167], v172 offset:1024
	ds_read_b128 v[168:171], v172 offset:2048
	ds_read_b128 v[172:175], v172 offset:3072
	s_waitcnt vmcnt(6)
	s_barrier
	v_mfma_f32_16x16x32_bf16 v[52:55], v[212:215], v[176:179], v[52:55]
	v_mfma_f32_16x16x32_bf16 v[48:51], v[220:223], v[176:179], v[48:51]
	v_mfma_f32_16x16x32_bf16 v[36:39], v[212:215], v[184:187], v[36:39]
	v_mfma_f32_16x16x32_bf16 v[32:35], v[220:223], v[184:187], v[32:35]
	v_mfma_f32_16x16x32_bf16 v[20:23], v[212:215], v[192:195], v[20:23]
	v_mfma_f32_16x16x32_bf16 v[16:19], v[220:223], v[192:195], v[16:19]
	v_mfma_f32_16x16x32_bf16 v[4:7], v[212:215], v[204:207], v[4:7]
	v_mfma_f32_16x16x32_bf16 v[0:3], v[220:223], v[204:207], v[0:3]
	v_mfma_f32_16x16x32_bf16 v[52:55], v[216:219], v[180:183], v[52:55]
	v_mfma_f32_16x16x32_bf16 v[48:51], v[224:227], v[180:183], v[48:51]
	v_mfma_f32_16x16x32_bf16 v[36:39], v[216:219], v[188:191], v[36:39]
	v_mfma_f32_16x16x32_bf16 v[32:35], v[224:227], v[188:191], v[32:35]
	v_mfma_f32_16x16x32_bf16 v[20:23], v[216:219], v[196:199], v[20:23]
	v_mfma_f32_16x16x32_bf16 v[16:19], v[224:227], v[196:199], v[16:19]
	v_mfma_f32_16x16x32_bf16 v[4:7], v[216:219], v[208:211], v[4:7]
	v_mfma_f32_16x16x32_bf16 v[0:3], v[224:227], v[208:211], v[0:3]
	s_barrier
	s_add_u32 s48, s48, 0x80000
	s_addc_u32 s49, s49, 0
	s_mov_b32 m0, s58
	v_lshl_add_u64 v[212:213], s[48:49], 0, v[128:129]
	ds_read_b128 v[176:179], v158 offset:32768
	ds_read_b128 v[180:183], v158 offset:33792
	ds_read_b128 v[184:187], v158 offset:34816
	ds_read_b128 v[188:191], v158 offset:35840
	ds_read_b128 v[192:195], v158 offset:36864
	ds_read_b128 v[196:199], v158 offset:37888
	ds_read_b128 v[204:207], v158 offset:38912
	ds_read_b128 v[208:211], v158 offset:39936
	global_load_lds_dwordx4 v[212:213], off
	v_lshl_add_u64 v[212:213], s[48:49], 0, v[134:135]
	s_mov_b32 m0, s59
	s_nop 0
	global_load_lds_dwordx4 v[212:213], off
	s_waitcnt lgkmcnt(8)
	s_barrier
	s_waitcnt lgkmcnt(0)
	v_mfma_f32_16x16x32_bf16 v[124:127], v[160:163], v[176:179], v[124:127]
	v_mfma_f32_16x16x32_bf16 v[120:123], v[168:171], v[176:179], v[120:123]
	v_mfma_f32_16x16x32_bf16 v[108:111], v[160:163], v[184:187], v[108:111]
	v_mfma_f32_16x16x32_bf16 v[104:107], v[168:171], v[184:187], v[104:107]
	v_mfma_f32_16x16x32_bf16 v[92:95], v[160:163], v[192:195], v[92:95]
	v_mfma_f32_16x16x32_bf16 v[88:91], v[168:171], v[192:195], v[88:91]
	v_mfma_f32_16x16x32_bf16 v[76:79], v[160:163], v[204:207], v[76:79]
	v_mfma_f32_16x16x32_bf16 v[72:75], v[168:171], v[204:207], v[72:75]
	v_mfma_f32_16x16x32_bf16 v[124:127], v[164:167], v[180:183], v[124:127]
	v_mfma_f32_16x16x32_bf16 v[120:123], v[172:175], v[180:183], v[120:123]
	v_mfma_f32_16x16x32_bf16 v[108:111], v[164:167], v[188:191], v[108:111]
	v_mfma_f32_16x16x32_bf16 v[104:107], v[172:175], v[188:191], v[104:107]
	v_mfma_f32_16x16x32_bf16 v[92:95], v[164:167], v[196:199], v[92:95]
	v_mfma_f32_16x16x32_bf16 v[88:91], v[172:175], v[196:199], v[88:91]
	v_mfma_f32_16x16x32_bf16 v[76:79], v[164:167], v[208:211], v[76:79]
	v_mfma_f32_16x16x32_bf16 v[72:75], v[172:175], v[208:211], v[72:75]
	s_barrier
	s_add_i32 s48, 0, 0x1c000
	s_add_i32 s33, s33, s56
	v_add_u32_e32 v224, s48, v147
	v_lshl_add_u64 v[200:201], v[200:201], 0, s[16:17]
	s_mov_b32 m0, s33
	ds_read_b128 v[212:215], v224
	ds_read_b128 v[216:219], v224 offset:1024
	ds_read_b128 v[220:223], v224 offset:2048
	ds_read_b128 v[224:227], v224 offset:3072
	global_load_lds_dwordx4 v[200:201], off
	v_lshl_add_u64 v[200:201], v[228:229], 0, s[16:17]
	s_add_i32 m0, s33, 0x2000
	s_nop 0
	global_load_lds_dwordx4 v[200:201], off
	s_barrier
	s_waitcnt lgkmcnt(0)
	v_mfma_f32_16x16x32_bf16 v[116:119], v[212:215], v[176:179], v[116:119]
	v_mfma_f32_16x16x32_bf16 v[112:115], v[220:223], v[176:179], v[112:115]
	v_mfma_f32_16x16x32_bf16 v[100:103], v[212:215], v[184:187], v[100:103]
	v_mfma_f32_16x16x32_bf16 v[96:99], v[220:223], v[184:187], v[96:99]
	v_mfma_f32_16x16x32_bf16 v[84:87], v[212:215], v[192:195], v[84:87]
	v_mfma_f32_16x16x32_bf16 v[80:83], v[220:223], v[192:195], v[80:83]
	v_mfma_f32_16x16x32_bf16 v[68:71], v[212:215], v[204:207], v[68:71]
	v_mfma_f32_16x16x32_bf16 v[64:67], v[220:223], v[204:207], v[64:67]
	v_mfma_f32_16x16x32_bf16 v[116:119], v[216:219], v[180:183], v[116:119]
	v_mfma_f32_16x16x32_bf16 v[112:115], v[224:227], v[180:183], v[112:115]
	v_mfma_f32_16x16x32_bf16 v[100:103], v[216:219], v[188:191], v[100:103]
	v_mfma_f32_16x16x32_bf16 v[96:99], v[224:227], v[188:191], v[96:99]
	v_mfma_f32_16x16x32_bf16 v[84:87], v[216:219], v[196:199], v[84:87]
	v_mfma_f32_16x16x32_bf16 v[80:83], v[224:227], v[196:199], v[80:83]
	v_mfma_f32_16x16x32_bf16 v[68:71], v[216:219], v[208:211], v[68:71]
	v_mfma_f32_16x16x32_bf16 v[64:67], v[224:227], v[208:211], v[64:67]
	s_mov_b32 m0, s61
	v_lshl_add_u64 v[200:201], v[230:231], 0, s[16:17]
	s_barrier
	ds_read_b128 v[176:179], v158 offset:49152
	ds_read_b128 v[180:183], v158 offset:50176
	ds_read_b128 v[184:187], v158 offset:51200
	ds_read_b128 v[188:191], v158 offset:52224
	ds_read_b128 v[192:195], v158 offset:53248
	ds_read_b128 v[196:199], v158 offset:54272
	ds_read_b128 v[204:207], v158 offset:55296
	ds_read_b128 v[208:211], v158 offset:56320
	global_load_lds_dwordx4 v[200:201], off
	v_lshl_add_u64 v[200:201], v[232:233], 0, s[16:17]
	s_mov_b32 m0, s62
	s_nop 0
	global_load_lds_dwordx4 v[200:201], off
	s_barrier
; __device__ __forceinline__ unsigned cvt_pk_bf16(float lo, float hi) { unsigned r; asm volatile("v_cvt_pk_bf16_f32 %0, %1, %2" : "=v"(r) : "v"(lo), "v"(hi)); return r; }
; #define PG8_STAGE(bufoff, gbase, voff) do { _Pragma("unroll") for (int _i = 0; _i < 2; ++_i) \
;         __builtin_amdgcn_global_load_lds((const unsigned*)((const char*)(gbase) + (voff)[_i]), (LAS unsigned*)(lds + (bufoff) + ldsw + _i * 8192), 16, 0, 0); } while (0)
; #define PG8_LDA(dst, b, h) do { _Pragma("unroll") for (int m = 0; m < 4; ++m) _Pragma("unroll") for (int k = 0; k < 2; ++k) dst[m][k] = *(const LAS bf16x8*)(lds + PG8_SA(b, h) + aoff + m * 2048 + k * 1024); } while (0)
; #define PG8_WAIT_V(n) asm volatile("s_waitcnt vmcnt(" #n ")" ::: "memory")
; #define PG8_WAIT_L(n) asm volatile("s_waitcnt lgkmcnt(" #n ")" ::: "memory")
; #define PG8_BAR __builtin_amdgcn_s_barrier()
;     __device__ __forceinline__ void operator()(const f32x4 (&acc)[2][2][4][2], const Unit& u, int wr, int wc, int fr, int fq) const {
;     ...
;             for (int m = 0; m < 4; ++m) { const int row = row0 + ai * HALF + m * 16;
;                 const float rs = ssin ? __builtin_amdgcn_rsqf(ssin[row] * (1.f / D) + EPS) : 1.0f; float sq = 0.f; u32x4 w[2];
; #pragma unroll
;                 for (int bj = 0; bj < 2; ++bj) { f32x4 v0 = acc[ai][bj][m][0] * rs, v1 = acc[ai][bj][m][1] * rs;
;                     if (ACT == 1) {
; #pragma unroll
;                         for (int j = 0; j < 4; ++j) { const float a = fmaxf(v0[j], 0.f), b = fmaxf(v1[j], 0.f); v0[j] = a * a; v1[j] = b * b; } }
;                     sq += (v0[0] * v0[0] + v0[1] * v0[1]) + (v0[2] * v0[2] + v0[3] * v0[3]) + (v1[0] * v1[0] + v1[1] * v1[1]) + (v1[2] * v1[2] + v1[3] * v1[3]);
;                     w[bj].x = cvt_pk_bf16(v0[0], v0[1]); w[bj].y = cvt_pk_bf16(v0[2], v0[3]); w[bj].z = cvt_pk_bf16(v1[0], v1[1]); w[bj].w = cvt_pk_bf16(v1[2], v1[3]); }
;                 store_pair_lines(O, ldc, row, fr, col0, w[0], w[1]);
; template <class Epi>
; __device__ __forceinline__ void gemm_phase(LAS unsigned char* lds, const Gemm g, const StaticOrder& S, const Epi& E) {
;     ...
;             PG8_LDA(At, 1, 1); PG8_STAGE(PG8_SA(1, 0), a3, voffA);
;             PG8_BAR; PG8_WAIT_L(0); PG8_MMA(1, 0, At, B0); PG8_BAR; PG8_SCHED;
;             PG8_STAGE(PG8_SB(1, 1), b3, voffB1);
;             PG8_WAIT_V(6); PG8_BAR; PG8_MMA(1, 1, At, B1); PG8_BAR;
	s_waitcnt lgkmcnt(0)
	v_mfma_f32_16x16x32_bf16 v[60:63], v[160:163], v[176:179], v[60:63]
	v_mfma_f32_16x16x32_bf16 v[56:59], v[168:171], v[176:179], v[56:59]
	v_mfma_f32_16x16x32_bf16 v[44:47], v[160:163], v[184:187], v[44:47]
	v_mfma_f32_16x16x32_bf16 v[40:43], v[168:171], v[184:187], v[40:43]
	v_mfma_f32_16x16x32_bf16 v[28:31], v[160:163], v[192:195], v[28:31]
	v_mfma_f32_16x16x32_bf16 v[24:27], v[168:171], v[192:195], v[24:27]
	v_mfma_f32_16x16x32_bf16 v[12:15], v[160:163], v[204:207], v[12:15]
	v_mfma_f32_16x16x32_bf16 v[8:11], v[168:171], v[204:207], v[8:11]
	v_mfma_f32_16x16x32_bf16 v[60:63], v[164:167], v[180:183], v[60:63]
	v_mfma_f32_16x16x32_bf16 v[56:59], v[172:175], v[180:183], v[56:59]
	v_mfma_f32_16x16x32_bf16 v[44:47], v[164:167], v[188:191], v[44:47]
	v_mfma_f32_16x16x32_bf16 v[40:43], v[172:175], v[188:191], v[40:43]
	v_mfma_f32_16x16x32_bf16 v[28:31], v[164:167], v[196:199], v[28:31]
	v_mfma_f32_16x16x32_bf16 v[24:27], v[172:175], v[196:199], v[24:27]
	v_mfma_f32_16x16x32_bf16 v[12:15], v[164:167], v[208:211], v[12:15]
	v_mfma_f32_16x16x32_bf16 v[8:11], v[172:175], v[208:211], v[8:11]
	s_barrier
	s_add_i32 s33, s48, s56
	v_lshl_add_u64 v[160:161], v[234:235], 0, s[16:17]
	s_mov_b32 m0, s33
	s_nop 0
	global_load_lds_dwordx4 v[160:161], off
	v_lshl_add_u64 v[160:161], v[236:237], 0, s[16:17]
	s_add_i32 m0, s33, 0x2000
	s_nop 0
	global_load_lds_dwordx4 v[160:161], off
	s_waitcnt vmcnt(6)
	s_barrier
	v_mfma_f32_16x16x32_bf16 v[52:55], v[212:215], v[176:179], v[52:55]
	v_mfma_f32_16x16x32_bf16 v[48:51], v[220:223], v[176:179], v[48:51]
	v_mfma_f32_16x16x32_bf16 v[36:39], v[212:215], v[184:187], v[36:39]
	v_mfma_f32_16x16x32_bf16 v[32:35], v[220:223], v[184:187], v[32:35]
	v_mfma_f32_16x16x32_bf16 v[20:23], v[212:215], v[192:195], v[20:23]
	v_mfma_f32_16x16x32_bf16 v[16:19], v[220:223], v[192:195], v[16:19]
	v_mfma_f32_16x16x32_bf16 v[4:7], v[212:215], v[204:207], v[4:7]
	v_mfma_f32_16x16x32_bf16 v[0:3], v[220:223], v[204:207], v[0:3]
	v_mfma_f32_16x16x32_bf16 v[52:55], v[216:219], v[180:183], v[52:55]
	v_mfma_f32_16x16x32_bf16 v[48:51], v[224:227], v[180:183], v[48:51]
	v_mfma_f32_16x16x32_bf16 v[36:39], v[216:219], v[188:191], v[36:39]
	v_mfma_f32_16x16x32_bf16 v[32:35], v[224:227], v[188:191], v[32:35]
	v_mfma_f32_16x16x32_bf16 v[20:23], v[216:219], v[196:199], v[20:23]
	v_mfma_f32_16x16x32_bf16 v[16:19], v[224:227], v[196:199], v[16:19]
	v_mfma_f32_16x16x32_bf16 v[4:7], v[216:219], v[208:211], v[4:7]
	v_mfma_f32_16x16x32_bf16 v[0:3], v[224:227], v[208:211], v[0:3]
	s_add_i32 s74, s74, 2
	s_add_u32 s46, s46, 0x100
	s_addc_u32 s47, s47, 0
	s_add_u32 s72, s72, 0x100
	s_addc_u32 s73, s73, 0
	s_cmp_gt_u32 s74, 29
	s_barrier
	s_cbranch_scc0 .LBB0_733
	v_max_f32_e32 v124, 0, v124
	v_max_f32_e32 v120, 0, v120
	v_max_f32_e32 v125, 0, v125
	v_max_f32_e32 v121, 0, v121
	v_max_f32_e32 v122, 0, v122
	v_max_f32_e32 v118, 0, v118
	v_max_f32_e32 v119, 0, v119
	v_mul_f32_e32 v124, v124, v124
	v_mul_f32_e32 v120, v120, v120
	v_mul_f32_e32 v125, v125, v125
	v_mul_f32_e32 v121, v121, v121
	v_max_f32_e32 v126, 0, v126
	v_mul_f32_e32 v122, v122, v122
	v_max_f32_e32 v127, 0, v127
	v_max_f32_e32 v123, 0, v123
	v_max_f32_e32 v116, 0, v116
	v_max_f32_e32 v112, 0, v112
	v_max_f32_e32 v117, 0, v117
	v_max_f32_e32 v113, 0, v113
	v_max_f32_e32 v114, 0, v114
	v_mul_f32_e32 v118, v118, v118
	v_mul_f32_e32 v119, v119, v119
	s_lshl_b32 s19, s44, 8
	v_mul_f32_e32 v126, v126, v126
	v_mul_f32_e32 v127, v127, v127
	v_mul_f32_e32 v123, v123, v123
	v_cvt_pk_bf16_f32 v124, v124, v125
	v_cvt_pk_bf16_f32 v125, v126, v127
	v_cvt_pk_bf16_f32 v120, v120, v121
	v_cvt_pk_bf16_f32 v121, v122, v123
	v_mul_f32_e32 v116, v116, v116
	v_mul_f32_e32 v112, v112, v112
	v_mul_f32_e32 v117, v117, v117
	v_mul_f32_e32 v113, v113, v113
	v_mul_f32_e32 v114, v114, v114
	v_max_f32_e32 v115, 0, v115
	v_cvt_pk_bf16_f32 v122, v116, v117
	v_cvt_pk_bf16_f32 v119, v118, v119
	s_add_i32 s19, s19, s63
	v_mul_f32_e32 v115, v115, v115
	v_cvt_pk_bf16_f32 v112, v112, v113
	v_cvt_pk_bf16_f32 v113, v114, v115
	v_mov_b32_dpp v118, v124 row_ror:8 row_mask:0xf bank_mask:0xf
	v_mov_b32_dpp v123, v125 row_ror:8 row_mask:0xf bank_mask:0xf
	v_mov_b32_dpp v114, v122 row_ror:8 row_mask:0xf bank_mask:0xf
	v_cndmask_b32_e64 v118, v122, v118, s[6:7]
	v_or_b32_e32 v122, s19, v148
	v_lshl_or_b32 v162, s69, 8, v156
	v_mov_b32_dpp v126, v120 row_ror:8 row_mask:0xf bank_mask:0xf
	v_mov_b32_dpp v127, v121 row_ror:8 row_mask:0xf bank_mask:0xf
	v_mov_b32_dpp v115, v119 row_ror:8 row_mask:0xf bank_mask:0xf
	v_mov_b32_dpp v116, v112 row_ror:8 row_mask:0xf bank_mask:0xf
	v_mov_b32_dpp v117, v113 row_ror:8 row_mask:0xf bank_mask:0xf
	v_cndmask_b32_e64 v119, v119, v123, s[6:7]
	v_ashrrev_i32_e32 v123, 31, v122
	v_ashrrev_i32_e32 v163, 31, v162
	v_cndmask_b32_e64 v116, v116, v120, s[6:7]
	v_cndmask_b32_e64 v117, v117, v121, s[6:7]
	v_cndmask_b32_e64 v120, v112, v126, s[6:7]
	v_cndmask_b32_e64 v121, v113, v127, s[6:7]
	v_lshlrev_b64 v[112:113], 14, v[122:123]
	v_cndmask_b32_e64 v114, v114, v124, s[6:7]
	v_cndmask_b32_e64 v115, v115, v125, s[6:7]
	v_lshl_add_u64 v[124:125], s[10:11], 0, v[112:113]
	v_lshlrev_b64 v[112:113], 1, v[162:163]
	v_lshl_add_u64 v[124:125], v[124:125], 0, v[112:113]
	global_store_dwordx4 v[124:125], v[114:117], off
	v_max_f32_e32 v108, v108, v108
	v_max_f32_e32 v104, v104, v104
	v_or_b32_e32 v114, 8, v122
	v_ashrrev_i32_e32 v115, 31, v114
	v_lshlrev_b64 v[114:115], 14, v[114:115]
	v_lshl_add_u64 v[114:115], s[10:11], 0, v[114:115]
	v_max_f32_e32 v108, 0, v108
	v_max_f32_e32 v104, 0, v104
	v_max_f32_e32 v109, 0, v109
	v_max_f32_e32 v105, 0, v105
	v_max_f32_e32 v100, 0, v100
	v_max_f32_e32 v101, 0, v101
; __device__ __forceinline__ unsigned cvt_pk_bf16(float lo, float hi) { unsigned r; asm volatile("v_cvt_pk_bf16_f32 %0, %1, %2" : "=v"(r) : "v"(lo), "v"(hi)); return r; }
; __device__ __forceinline__ unsigned dpp_ror8(unsigned x) { return (unsigned)__builtin_amdgcn_update_dpp(0, (int)x, 0x128, 0xf, 0xf, false); }
; __device__ __forceinline__ void store_pair_lines(bf16_t* O, int ldc, int row, int fr, int col0, u32x4 wA, u32x4 wB) {
;     const u32x4 sA = {dpp_ror8(wA.x), dpp_ror8(wA.y), dpp_ror8(wA.z), dpp_ror8(wA.w)}, sB = {dpp_ror8(wB.x), dpp_ror8(wB.y), dpp_ror8(wB.z), dpp_ror8(wB.w)};
;     const bool lo = fr < 8;
;     const u32x4 o1 = lo ? wA : sB, o2 = lo ? sA : wB;
;     const int r1 = row - fr + (fr & 7), cb = col0 + (lo ? 0 : 8);
;     *(u32x4*)(O + (size_t)r1 * ldc + cb) = o1;
;     *(u32x4*)(O + (size_t)(r1 + 8) * ldc + cb) = o2;
; }
;     __device__ __forceinline__ void operator()(const f32x4 (&acc)[2][2][4][2], const Unit& u, int wr, int wc, int fr, int fq) const {
;     ...
;             for (int m = 0; m < 4; ++m) { const int row = row0 + ai * HALF + m * 16;
;                 const float rs = ssin ? __builtin_amdgcn_rsqf(ssin[row] * (1.f / D) + EPS) : 1.0f; float sq = 0.f; u32x4 w[2];
; #pragma unroll
;                 for (int bj = 0; bj < 2; ++bj) { f32x4 v0 = acc[ai][bj][m][0] * rs, v1 = acc[ai][bj][m][1] * rs;
;                     if (ACT == 1) {
; #pragma unroll
;                         for (int j = 0; j < 4; ++j) { const float a = fmaxf(v0[j], 0.f), b = fmaxf(v1[j], 0.f); v0[j] = a * a; v1[j] = b * b; } }
;                     sq += (v0[0] * v0[0] + v0[1] * v0[1]) + (v0[2] * v0[2] + v0[3] * v0[3]) + (v1[0] * v1[0] + v1[1] * v1[1]) + (v1[2] * v1[2] + v1[3] * v1[3]);
;                     w[bj].x = cvt_pk_bf16(v0[0], v0[1]); w[bj].y = cvt_pk_bf16(v0[2], v0[3]); w[bj].z = cvt_pk_bf16(v1[0], v1[1]); w[bj].w = cvt_pk_bf16(v1[2], v1[3]); }
;                 store_pair_lines(O, ldc, row, fr, col0, w[0], w[1]);
	v_max_f32_e32 v102, 0, v102
	v_max_f32_e32 v98, 0, v98
	v_max_f32_e32 v103, 0, v103
	v_lshl_add_u64 v[114:115], v[114:115], 0, v[112:113]
	v_mul_f32_e32 v108, v108, v108
	v_mul_f32_e32 v104, v104, v104
	v_mul_f32_e32 v109, v109, v109
	v_mul_f32_e32 v105, v105, v105
	v_max_f32_e32 v110, 0, v110
	v_max_f32_e32 v106, 0, v106
	v_max_f32_e32 v111, 0, v111
	v_max_f32_e32 v107, 0, v107
	v_max_f32_e32 v96, 0, v96
	v_mul_f32_e32 v100, v100, v100
	v_max_f32_e32 v97, 0, v97
	v_mul_f32_e32 v101, v101, v101
	v_mul_f32_e32 v102, v102, v102
	v_mul_f32_e32 v98, v98, v98
	v_max_f32_e32 v99, 0, v99
	v_mul_f32_e32 v103, v103, v103
	global_store_dwordx4 v[114:115], v[118:121], off
	v_mul_f32_e32 v110, v110, v110
	v_mul_f32_e32 v106, v106, v106
	v_mul_f32_e32 v111, v111, v111
	v_mul_f32_e32 v107, v107, v107
	v_cvt_pk_bf16_f32 v108, v108, v109
	v_cvt_pk_bf16_f32 v109, v110, v111
	v_cvt_pk_bf16_f32 v104, v104, v105
	v_cvt_pk_bf16_f32 v105, v106, v107
	v_mul_f32_e32 v96, v96, v96
	v_mul_f32_e32 v97, v97, v97
	v_mul_f32_e32 v99, v99, v99
	v_cvt_pk_bf16_f32 v100, v100, v101
	v_cvt_pk_bf16_f32 v101, v102, v103
	v_cvt_pk_bf16_f32 v102, v96, v97
	v_cvt_pk_bf16_f32 v103, v98, v99
	v_or_b32_e32 v160, s19, v146
	v_mov_b32_dpp v98, v102 row_ror:8 row_mask:0xf bank_mask:0xf
	v_mov_b32_dpp v110, v104 row_ror:8 row_mask:0xf bank_mask:0xf
	v_mov_b32_dpp v99, v103 row_ror:8 row_mask:0xf bank_mask:0xf
	v_cndmask_b32_e64 v98, v98, v104, s[6:7]
	v_add_u32_e32 v104, v149, v160
	v_mov_b32_dpp v111, v105 row_ror:8 row_mask:0xf bank_mask:0xf
	v_cndmask_b32_e64 v99, v99, v105, s[6:7]
	v_ashrrev_i32_e32 v105, 31, v104
	v_lshlrev_b64 v[104:105], 14, v[104:105]
	v_mov_b32_dpp v96, v100 row_ror:8 row_mask:0xf bank_mask:0xf
	v_mov_b32_dpp v97, v101 row_ror:8 row_mask:0xf bank_mask:0xf
	v_lshl_add_u64 v[104:105], s[10:11], 0, v[104:105]
	v_cndmask_b32_e64 v96, v96, v108, s[6:7]
	v_cndmask_b32_e64 v97, v97, v109, s[6:7]
	v_lshl_add_u64 v[104:105], v[104:105], 0, v[112:113]
	v_mov_b32_dpp v106, v108 row_ror:8 row_mask:0xf bank_mask:0xf
	v_mov_b32_dpp v107, v109 row_ror:8 row_mask:0xf bank_mask:0xf
	global_store_dwordx4 v[104:105], v[96:99], off
	v_max_f32_e32 v92, 0, v92
	v_max_f32_e32 v88, 0, v88
	v_add_co_u32_e32 v96, vcc, s68, v104
	v_max_f32_e32 v93, 0, v93
	v_max_f32_e32 v89, 0, v89
	v_max_f32_e32 v84, 0, v84
	v_max_f32_e32 v85, 0, v85
	v_max_f32_e32 v86, 0, v86
	v_max_f32_e32 v82, 0, v82
	v_max_f32_e32 v87, 0, v87
	v_cndmask_b32_e64 v100, v100, v106, s[6:7]
	v_cndmask_b32_e64 v101, v101, v107, s[6:7]
	v_cndmask_b32_e64 v102, v102, v110, s[6:7]
	v_cndmask_b32_e64 v103, v103, v111, s[6:7]
	v_addc_co_u32_e32 v97, vcc, 0, v105, vcc
	v_mul_f32_e32 v92, v92, v92
	v_mul_f32_e32 v88, v88, v88
	v_mul_f32_e32 v93, v93, v93
	v_mul_f32_e32 v89, v89, v89
	v_max_f32_e32 v94, 0, v94
	v_max_f32_e32 v90, 0, v90
	v_max_f32_e32 v95, 0, v95
	v_max_f32_e32 v91, 0, v91
	v_max_f32_e32 v80, 0, v80
	v_mul_f32_e32 v84, v84, v84
	v_max_f32_e32 v81, 0, v81
	v_mul_f32_e32 v85, v85, v85
	v_mul_f32_e32 v86, v86, v86
	v_mul_f32_e32 v82, v82, v82
	v_max_f32_e32 v83, 0, v83
	v_mul_f32_e32 v87, v87, v87
	global_store_dwordx4 v[96:97], v[100:103], off
	v_mul_f32_e32 v94, v94, v94
	v_mul_f32_e32 v90, v90, v90
	v_mul_f32_e32 v95, v95, v95
	v_mul_f32_e32 v91, v91, v91
	v_cvt_pk_bf16_f32 v92, v92, v93
	v_cvt_pk_bf16_f32 v93, v94, v95
	v_cvt_pk_bf16_f32 v88, v88, v89
	v_cvt_pk_bf16_f32 v89, v90, v91
	v_mul_f32_e32 v80, v80, v80
	v_mul_f32_e32 v81, v81, v81
	v_mul_f32_e32 v83, v83, v83
	v_cvt_pk_bf16_f32 v84, v84, v85
	v_cvt_pk_bf16_f32 v85, v86, v87
	v_cvt_pk_bf16_f32 v86, v80, v81
	v_cvt_pk_bf16_f32 v87, v82, v83
	v_mov_b32_e32 v82, 0
	v_mov_b32_dpp v82, v86 row_ror:8 row_mask:0xf bank_mask:0xf
	v_mov_b32_dpp v94, v88 row_ror:8 row_mask:0xf bank_mask:0xf
	v_mov_b32_dpp v83, v87 row_ror:8 row_mask:0xf bank_mask:0xf
	v_cndmask_b32_e64 v82, v82, v88, s[6:7]
	v_add_u32_e32 v88, v150, v160
	v_mov_b32_dpp v95, v89 row_ror:8 row_mask:0xf bank_mask:0xf
	v_cndmask_b32_e64 v83, v83, v89, s[6:7]
	v_ashrrev_i32_e32 v89, 31, v88
	v_lshlrev_b64 v[88:89], 14, v[88:89]
	v_mov_b32_dpp v80, v84 row_ror:8 row_mask:0xf bank_mask:0xf
	v_mov_b32_dpp v81, v85 row_ror:8 row_mask:0xf bank_mask:0xf
	v_lshl_add_u64 v[88:89], s[10:11], 0, v[88:89]
	v_cndmask_b32_e64 v80, v80, v92, s[6:7]
	v_cndmask_b32_e64 v81, v81, v93, s[6:7]
	v_lshl_add_u64 v[88:89], v[88:89], 0, v[112:113]
	v_mov_b32_dpp v90, v92 row_ror:8 row_mask:0xf bank_mask:0xf
	v_mov_b32_dpp v91, v93 row_ror:8 row_mask:0xf bank_mask:0xf
	global_store_dwordx4 v[88:89], v[80:83], off
	v_max_f32_e32 v76, 0, v76
	v_max_f32_e32 v72, 0, v72
	v_add_co_u32_e32 v80, vcc, s68, v88
	v_max_f32_e32 v77, 0, v77
	v_max_f32_e32 v73, 0, v73
	v_max_f32_e32 v68, 0, v68
	v_max_f32_e32 v69, 0, v69
	v_max_f32_e32 v70, 0, v70
	v_max_f32_e32 v66, 0, v66
	v_max_f32_e32 v71, 0, v71
	v_cndmask_b32_e64 v84, v84, v90, s[6:7]
	v_cndmask_b32_e64 v85, v85, v91, s[6:7]
	v_cndmask_b32_e64 v86, v86, v94, s[6:7]
	v_cndmask_b32_e64 v87, v87, v95, s[6:7]
	v_addc_co_u32_e32 v81, vcc, 0, v89, vcc
	v_mul_f32_e32 v76, v76, v76
	v_mul_f32_e32 v72, v72, v72
	v_mul_f32_e32 v77, v77, v77
	v_mul_f32_e32 v73, v73, v73
	v_max_f32_e32 v78, 0, v78
	v_max_f32_e32 v74, 0, v74
	v_max_f32_e32 v79, 0, v79
	v_max_f32_e32 v75, 0, v75
	v_max_f32_e32 v64, 0, v64
	v_mul_f32_e32 v68, v68, v68
	v_max_f32_e32 v65, 0, v65
	v_mul_f32_e32 v69, v69, v69
	v_mul_f32_e32 v70, v70, v70
	v_mul_f32_e32 v66, v66, v66
	v_max_f32_e32 v67, 0, v67
	v_mul_f32_e32 v71, v71, v71
	global_store_dwordx4 v[80:81], v[84:87], off
	v_mul_f32_e32 v78, v78, v78
	v_mul_f32_e32 v74, v74, v74
	v_mul_f32_e32 v79, v79, v79
	v_mul_f32_e32 v75, v75, v75
	v_cvt_pk_bf16_f32 v76, v76, v77
; __device__ __forceinline__ unsigned cvt_pk_bf16(float lo, float hi) { unsigned r; asm volatile("v_cvt_pk_bf16_f32 %0, %1, %2" : "=v"(r) : "v"(lo), "v"(hi)); return r; }
; __device__ __forceinline__ unsigned dpp_ror8(unsigned x) { return (unsigned)__builtin_amdgcn_update_dpp(0, (int)x, 0x128, 0xf, 0xf, false); }
; __device__ __forceinline__ void store_pair_lines(bf16_t* O, int ldc, int row, int fr, int col0, u32x4 wA, u32x4 wB) {
;     const u32x4 sA = {dpp_ror8(wA.x), dpp_ror8(wA.y), dpp_ror8(wA.z), dpp_ror8(wA.w)}, sB = {dpp_ror8(wB.x), dpp_ror8(wB.y), dpp_ror8(wB.z), dpp_ror8(wB.w)};
;     const bool lo = fr < 8;
;     const u32x4 o1 = lo ? wA : sB, o2 = lo ? sA : wB;
;     const int r1 = row - fr + (fr & 7), cb = col0 + (lo ? 0 : 8);
;     *(u32x4*)(O + (size_t)r1 * ldc + cb) = o1;
;     *(u32x4*)(O + (size_t)(r1 + 8) * ldc + cb) = o2;
; }
;     __device__ __forceinline__ void operator()(const f32x4 (&acc)[2][2][4][2], const Unit& u, int wr, int wc, int fr, int fq) const {
;     ...
;             for (int m = 0; m < 4; ++m) { const int row = row0 + ai * HALF + m * 16;
;                 const float rs = ssin ? __builtin_amdgcn_rsqf(ssin[row] * (1.f / D) + EPS) : 1.0f; float sq = 0.f; u32x4 w[2];
; #pragma unroll
;                 for (int bj = 0; bj < 2; ++bj) { f32x4 v0 = acc[ai][bj][m][0] * rs, v1 = acc[ai][bj][m][1] * rs;
;                     if (ACT == 1) {
; #pragma unroll
;                         for (int j = 0; j < 4; ++j) { const float a = fmaxf(v0[j], 0.f), b = fmaxf(v1[j], 0.f); v0[j] = a * a; v1[j] = b * b; } }
;                     sq += (v0[0] * v0[0] + v0[1] * v0[1]) + (v0[2] * v0[2] + v0[3] * v0[3]) + (v1[0] * v1[0] + v1[1] * v1[1]) + (v1[2] * v1[2] + v1[3] * v1[3]);
;                     w[bj].x = cvt_pk_bf16(v0[0], v0[1]); w[bj].y = cvt_pk_bf16(v0[2], v0[3]); w[bj].z = cvt_pk_bf16(v1[0], v1[1]); w[bj].w = cvt_pk_bf16(v1[2], v1[3]); }
;                 store_pair_lines(O, ldc, row, fr, col0, w[0], w[1]);
	v_cvt_pk_bf16_f32 v77, v78, v79
	v_cvt_pk_bf16_f32 v72, v72, v73
	v_cvt_pk_bf16_f32 v73, v74, v75
	v_mul_f32_e32 v64, v64, v64
	v_mul_f32_e32 v65, v65, v65
	v_mul_f32_e32 v67, v67, v67
	v_cvt_pk_bf16_f32 v68, v68, v69
	v_cvt_pk_bf16_f32 v69, v70, v71
	v_cvt_pk_bf16_f32 v70, v64, v65
	v_cvt_pk_bf16_f32 v71, v66, v67
	v_mov_b32_e32 v66, 0
	v_mov_b32_dpp v66, v70 row_ror:8 row_mask:0xf bank_mask:0xf
	v_mov_b32_dpp v78, v72 row_ror:8 row_mask:0xf bank_mask:0xf
	v_mov_b32_dpp v67, v71 row_ror:8 row_mask:0xf bank_mask:0xf
	v_cndmask_b32_e64 v66, v66, v72, s[6:7]
	v_add_u32_e32 v72, v151, v160
	v_mov_b32_dpp v79, v73 row_ror:8 row_mask:0xf bank_mask:0xf
	v_cndmask_b32_e64 v67, v67, v73, s[6:7]
	v_ashrrev_i32_e32 v73, 31, v72
	v_lshlrev_b64 v[72:73], 14, v[72:73]
	v_mov_b32_dpp v64, v68 row_ror:8 row_mask:0xf bank_mask:0xf
	v_mov_b32_dpp v65, v69 row_ror:8 row_mask:0xf bank_mask:0xf
	v_lshl_add_u64 v[72:73], s[10:11], 0, v[72:73]
	v_cndmask_b32_e64 v64, v64, v76, s[6:7]
	v_cndmask_b32_e64 v65, v65, v77, s[6:7]
	v_lshl_add_u64 v[72:73], v[72:73], 0, v[112:113]
	v_mov_b32_dpp v74, v76 row_ror:8 row_mask:0xf bank_mask:0xf
	v_mov_b32_dpp v75, v77 row_ror:8 row_mask:0xf bank_mask:0xf
	global_store_dwordx4 v[72:73], v[64:67], off
	v_max_f32_e32 v60, 0, v60
	v_max_f32_e32 v56, 0, v56
	v_add_co_u32_e32 v64, vcc, s68, v72
	v_max_f32_e32 v61, 0, v61
	v_max_f32_e32 v57, 0, v57
	v_max_f32_e32 v52, 0, v52
	v_max_f32_e32 v53, 0, v53
	v_max_f32_e32 v54, 0, v54
	v_max_f32_e32 v50, 0, v50
	v_max_f32_e32 v55, 0, v55
	v_cndmask_b32_e64 v68, v68, v74, s[6:7]
	v_cndmask_b32_e64 v69, v69, v75, s[6:7]
	v_cndmask_b32_e64 v70, v70, v78, s[6:7]
	v_cndmask_b32_e64 v71, v71, v79, s[6:7]
	v_addc_co_u32_e32 v65, vcc, 0, v73, vcc
	v_mul_f32_e32 v60, v60, v60
	v_mul_f32_e32 v56, v56, v56
	v_mul_f32_e32 v61, v61, v61
	v_mul_f32_e32 v57, v57, v57
	v_max_f32_e32 v62, 0, v62
	v_max_f32_e32 v58, 0, v58
	v_max_f32_e32 v63, 0, v63
	v_max_f32_e32 v59, 0, v59
	v_max_f32_e32 v48, 0, v48
	v_mul_f32_e32 v52, v52, v52
	v_max_f32_e32 v49, 0, v49
	v_mul_f32_e32 v53, v53, v53
	v_mul_f32_e32 v54, v54, v54
	v_mul_f32_e32 v50, v50, v50
	v_max_f32_e32 v51, 0, v51
	v_mul_f32_e32 v55, v55, v55
	global_store_dwordx4 v[64:65], v[68:71], off
	v_mul_f32_e32 v62, v62, v62
	v_mul_f32_e32 v58, v58, v58
	v_mul_f32_e32 v63, v63, v63
	v_mul_f32_e32 v59, v59, v59
	v_cvt_pk_bf16_f32 v60, v60, v61
	v_cvt_pk_bf16_f32 v61, v62, v63
	v_cvt_pk_bf16_f32 v56, v56, v57
	v_cvt_pk_bf16_f32 v57, v58, v59
	v_mul_f32_e32 v48, v48, v48
	v_mul_f32_e32 v49, v49, v49
	v_mul_f32_e32 v51, v51, v51
	v_cvt_pk_bf16_f32 v52, v52, v53
	v_cvt_pk_bf16_f32 v53, v54, v55
	v_cvt_pk_bf16_f32 v54, v48, v49
	v_cvt_pk_bf16_f32 v55, v50, v51
	v_mov_b32_e32 v50, 0
	v_mov_b32_dpp v50, v54 row_ror:8 row_mask:0xf bank_mask:0xf
	v_mov_b32_dpp v62, v56 row_ror:8 row_mask:0xf bank_mask:0xf
	v_mov_b32_dpp v51, v55 row_ror:8 row_mask:0xf bank_mask:0xf
	v_cndmask_b32_e64 v50, v50, v56, s[6:7]
	v_add_u32_e32 v56, v152, v160
	v_mov_b32_dpp v63, v57 row_ror:8 row_mask:0xf bank_mask:0xf
	v_cndmask_b32_e64 v51, v51, v57, s[6:7]
	v_ashrrev_i32_e32 v57, 31, v56
	v_lshlrev_b64 v[56:57], 14, v[56:57]
	v_mov_b32_dpp v48, v52 row_ror:8 row_mask:0xf bank_mask:0xf
	v_mov_b32_dpp v49, v53 row_ror:8 row_mask:0xf bank_mask:0xf
	v_lshl_add_u64 v[56:57], s[10:11], 0, v[56:57]
	v_cndmask_b32_e64 v48, v48, v60, s[6:7]
	v_cndmask_b32_e64 v49, v49, v61, s[6:7]
	v_lshl_add_u64 v[56:57], v[56:57], 0, v[112:113]
	v_mov_b32_dpp v58, v60 row_ror:8 row_mask:0xf bank_mask:0xf
	v_mov_b32_dpp v59, v61 row_ror:8 row_mask:0xf bank_mask:0xf
	global_store_dwordx4 v[56:57], v[48:51], off
	v_max_f32_e32 v44, 0, v44
	v_max_f32_e32 v40, 0, v40
	v_add_co_u32_e32 v48, vcc, s68, v56
	v_max_f32_e32 v45, 0, v45
	v_max_f32_e32 v41, 0, v41
	v_max_f32_e32 v36, 0, v36
	v_max_f32_e32 v37, 0, v37
	v_max_f32_e32 v38, 0, v38
	v_max_f32_e32 v34, 0, v34
	v_max_f32_e32 v39, 0, v39
	v_cndmask_b32_e64 v52, v52, v58, s[6:7]
	v_cndmask_b32_e64 v53, v53, v59, s[6:7]
	v_cndmask_b32_e64 v54, v54, v62, s[6:7]
	v_cndmask_b32_e64 v55, v55, v63, s[6:7]
	v_addc_co_u32_e32 v49, vcc, 0, v57, vcc
	v_mul_f32_e32 v44, v44, v44
	v_mul_f32_e32 v40, v40, v40
	v_mul_f32_e32 v45, v45, v45
	v_mul_f32_e32 v41, v41, v41
	v_max_f32_e32 v46, 0, v46
	v_max_f32_e32 v42, 0, v42
	v_max_f32_e32 v47, 0, v47
	v_max_f32_e32 v43, 0, v43
	v_max_f32_e32 v32, 0, v32
	v_mul_f32_e32 v36, v36, v36
	v_max_f32_e32 v33, 0, v33
	v_mul_f32_e32 v37, v37, v37
	v_mul_f32_e32 v38, v38, v38
	v_mul_f32_e32 v34, v34, v34
	v_max_f32_e32 v35, 0, v35
	v_mul_f32_e32 v39, v39, v39
	global_store_dwordx4 v[48:49], v[52:55], off
	v_mul_f32_e32 v46, v46, v46
	v_mul_f32_e32 v42, v42, v42
	v_mul_f32_e32 v47, v47, v47
	v_mul_f32_e32 v43, v43, v43
	v_cvt_pk_bf16_f32 v44, v44, v45
	v_cvt_pk_bf16_f32 v45, v46, v47
	v_cvt_pk_bf16_f32 v40, v40, v41
	v_cvt_pk_bf16_f32 v41, v42, v43
	v_mul_f32_e32 v32, v32, v32
	v_mul_f32_e32 v33, v33, v33
	v_mul_f32_e32 v35, v35, v35
	v_cvt_pk_bf16_f32 v36, v36, v37
	v_cvt_pk_bf16_f32 v37, v38, v39
	v_cvt_pk_bf16_f32 v38, v32, v33
	v_cvt_pk_bf16_f32 v39, v34, v35
	v_mov_b32_e32 v34, 0
	v_mov_b32_dpp v34, v38 row_ror:8 row_mask:0xf bank_mask:0xf
	v_mov_b32_dpp v46, v40 row_ror:8 row_mask:0xf bank_mask:0xf
	v_mov_b32_dpp v35, v39 row_ror:8 row_mask:0xf bank_mask:0xf
	v_cndmask_b32_e64 v34, v34, v40, s[6:7]
	v_add_u32_e32 v40, v153, v160
	v_mov_b32_dpp v47, v41 row_ror:8 row_mask:0xf bank_mask:0xf
	v_cndmask_b32_e64 v35, v35, v41, s[6:7]
	v_ashrrev_i32_e32 v41, 31, v40
	v_lshlrev_b64 v[40:41], 14, v[40:41]
	v_mov_b32_dpp v32, v36 row_ror:8 row_mask:0xf bank_mask:0xf
; __device__ __forceinline__ unsigned cvt_pk_bf16(float lo, float hi) { unsigned r; asm volatile("v_cvt_pk_bf16_f32 %0, %1, %2" : "=v"(r) : "v"(lo), "v"(hi)); return r; }
;     __device__ __forceinline__ void operator()(const f32x4 (&acc)[2][2][4][2], const Unit& u, int wr, int wc, int fr, int fq) const {
;     ...
;             for (int m = 0; m < 4; ++m) { const int row = row0 + ai * HALF + m * 16;
;                 const float rs = ssin ? __builtin_amdgcn_rsqf(ssin[row] * (1.f / D) + EPS) : 1.0f; float sq = 0.f; u32x4 w[2];
; #pragma unroll
;                 for (int bj = 0; bj < 2; ++bj) { f32x4 v0 = acc[ai][bj][m][0] * rs, v1 = acc[ai][bj][m][1] * rs;
;                     if (ACT == 1) {
; #pragma unroll
;                         for (int j = 0; j < 4; ++j) { const float a = fmaxf(v0[j], 0.f), b = fmaxf(v1[j], 0.f); v0[j] = a * a; v1[j] = b * b; } }
;                     sq += (v0[0] * v0[0] + v0[1] * v0[1]) + (v0[2] * v0[2] + v0[3] * v0[3]) + (v1[0] * v1[0] + v1[1] * v1[1]) + (v1[2] * v1[2] + v1[3] * v1[3]);
;                     w[bj].x = cvt_pk_bf16(v0[0], v0[1]); w[bj].y = cvt_pk_bf16(v0[2], v0[3]); w[bj].z = cvt_pk_bf16(v1[0], v1[1]); w[bj].w = cvt_pk_bf16(v1[2], v1[3]); }
;                 store_pair_lines(O, ldc, row, fr, col0, w[0], w[1]);
; template <class Epi>
; __device__ __forceinline__ void gemm_phase(LAS unsigned char* lds, const Gemm g, const StaticOrder& S, const Epi& E) {
;     ...
;         E(acc, cur, wr, wc, fr, fq);
;         if (!has_next) break;
; #pragma unroll
;         for (int a = 0; a < 2; ++a)
; #pragma unroll
;             for (int b = 0; b < 2; ++b)
; #pragma unroll
;                 for (int m = 0; m < 4; ++m)
; #pragma unroll
;                     for (int n = 0; n < 2; ++n) acc[a][b][m][n] = (f32x4){0.f, 0.f, 0.f, 0.f};
;         cur = nxt; cA = nA; cB = nB; ++ui;
	v_mov_b32_dpp v33, v37 row_ror:8 row_mask:0xf bank_mask:0xf
	v_lshl_add_u64 v[40:41], s[10:11], 0, v[40:41]
	v_cndmask_b32_e64 v32, v32, v44, s[6:7]
	v_cndmask_b32_e64 v33, v33, v45, s[6:7]
	v_lshl_add_u64 v[40:41], v[40:41], 0, v[112:113]
	v_mov_b32_dpp v42, v44 row_ror:8 row_mask:0xf bank_mask:0xf
	v_mov_b32_dpp v43, v45 row_ror:8 row_mask:0xf bank_mask:0xf
	global_store_dwordx4 v[40:41], v[32:35], off
	v_max_f32_e32 v28, 0, v28
	v_max_f32_e32 v24, 0, v24
	v_add_co_u32_e32 v32, vcc, s68, v40
	v_max_f32_e32 v29, 0, v29
	v_max_f32_e32 v25, 0, v25
	v_max_f32_e32 v20, 0, v20
	v_max_f32_e32 v21, 0, v21
	v_max_f32_e32 v22, 0, v22
	v_max_f32_e32 v18, 0, v18
	v_max_f32_e32 v23, 0, v23
	v_cndmask_b32_e64 v36, v36, v42, s[6:7]
	v_cndmask_b32_e64 v37, v37, v43, s[6:7]
	v_cndmask_b32_e64 v38, v38, v46, s[6:7]
	v_cndmask_b32_e64 v39, v39, v47, s[6:7]
	v_addc_co_u32_e32 v33, vcc, 0, v41, vcc
	v_mul_f32_e32 v28, v28, v28
	v_mul_f32_e32 v24, v24, v24
	v_mul_f32_e32 v29, v29, v29
	v_mul_f32_e32 v25, v25, v25
	v_max_f32_e32 v30, 0, v30
	v_max_f32_e32 v26, 0, v26
	v_max_f32_e32 v31, 0, v31
	v_max_f32_e32 v27, 0, v27
	v_max_f32_e32 v16, 0, v16
	v_mul_f32_e32 v20, v20, v20
	v_max_f32_e32 v17, 0, v17
	v_mul_f32_e32 v21, v21, v21
	v_mul_f32_e32 v22, v22, v22
	v_mul_f32_e32 v18, v18, v18
	v_max_f32_e32 v19, 0, v19
	v_mul_f32_e32 v23, v23, v23
	global_store_dwordx4 v[32:33], v[36:39], off
	v_mul_f32_e32 v30, v30, v30
	v_mul_f32_e32 v26, v26, v26
	v_mul_f32_e32 v31, v31, v31
	v_mul_f32_e32 v27, v27, v27
	v_cvt_pk_bf16_f32 v28, v28, v29
	v_cvt_pk_bf16_f32 v29, v30, v31
	v_cvt_pk_bf16_f32 v24, v24, v25
	v_cvt_pk_bf16_f32 v25, v26, v27
	v_mul_f32_e32 v16, v16, v16
	v_mul_f32_e32 v17, v17, v17
	v_mul_f32_e32 v19, v19, v19
	v_cvt_pk_bf16_f32 v20, v20, v21
	v_cvt_pk_bf16_f32 v21, v22, v23
	v_cvt_pk_bf16_f32 v22, v16, v17
	v_cvt_pk_bf16_f32 v23, v18, v19
	v_mov_b32_e32 v18, 0
	v_mov_b32_dpp v18, v22 row_ror:8 row_mask:0xf bank_mask:0xf
	v_mov_b32_dpp v30, v24 row_ror:8 row_mask:0xf bank_mask:0xf
	v_mov_b32_dpp v19, v23 row_ror:8 row_mask:0xf bank_mask:0xf
	v_cndmask_b32_e64 v18, v18, v24, s[6:7]
	v_add_u32_e32 v24, v154, v160
	v_mov_b32_dpp v31, v25 row_ror:8 row_mask:0xf bank_mask:0xf
	v_cndmask_b32_e64 v19, v19, v25, s[6:7]
	v_ashrrev_i32_e32 v25, 31, v24
	v_lshlrev_b64 v[24:25], 14, v[24:25]
	v_mov_b32_dpp v16, v20 row_ror:8 row_mask:0xf bank_mask:0xf
	v_mov_b32_dpp v17, v21 row_ror:8 row_mask:0xf bank_mask:0xf
	v_lshl_add_u64 v[24:25], s[10:11], 0, v[24:25]
	v_cndmask_b32_e64 v16, v16, v28, s[6:7]
	v_cndmask_b32_e64 v17, v17, v29, s[6:7]
	v_lshl_add_u64 v[24:25], v[24:25], 0, v[112:113]
	v_mov_b32_dpp v26, v28 row_ror:8 row_mask:0xf bank_mask:0xf
	v_mov_b32_dpp v27, v29 row_ror:8 row_mask:0xf bank_mask:0xf
	global_store_dwordx4 v[24:25], v[16:19], off
	v_max_f32_e32 v12, 0, v12
	v_max_f32_e32 v8, 0, v8
	v_add_co_u32_e32 v16, vcc, s68, v24
	v_max_f32_e32 v13, 0, v13
	v_max_f32_e32 v9, 0, v9
	v_max_f32_e32 v4, 0, v4
	v_max_f32_e32 v5, 0, v5
	v_max_f32_e32 v6, 0, v6
	v_max_f32_e32 v2, 0, v2
	v_max_f32_e32 v7, 0, v7
	v_cndmask_b32_e64 v20, v20, v26, s[6:7]
	v_cndmask_b32_e64 v21, v21, v27, s[6:7]
	v_cndmask_b32_e64 v22, v22, v30, s[6:7]
	v_cndmask_b32_e64 v23, v23, v31, s[6:7]
	v_addc_co_u32_e32 v17, vcc, 0, v25, vcc
	v_mul_f32_e32 v12, v12, v12
	v_mul_f32_e32 v8, v8, v8
	v_mul_f32_e32 v13, v13, v13
	v_mul_f32_e32 v9, v9, v9
	v_max_f32_e32 v14, 0, v14
	v_max_f32_e32 v10, 0, v10
	v_max_f32_e32 v15, 0, v15
	v_max_f32_e32 v11, 0, v11
	v_max_f32_e32 v0, 0, v0
	v_mul_f32_e32 v4, v4, v4
	v_max_f32_e32 v1, 0, v1
	v_mul_f32_e32 v5, v5, v5
	v_mul_f32_e32 v6, v6, v6
	v_mul_f32_e32 v2, v2, v2
	v_max_f32_e32 v3, 0, v3
	v_mul_f32_e32 v7, v7, v7
	global_store_dwordx4 v[16:17], v[20:23], off
	v_mul_f32_e32 v14, v14, v14
	v_mul_f32_e32 v10, v10, v10
	v_mul_f32_e32 v15, v15, v15
	v_mul_f32_e32 v11, v11, v11
	v_cvt_pk_bf16_f32 v12, v12, v13
	v_cvt_pk_bf16_f32 v13, v14, v15
	v_cvt_pk_bf16_f32 v8, v8, v9
	v_cvt_pk_bf16_f32 v9, v10, v11
	v_mul_f32_e32 v0, v0, v0
	v_mul_f32_e32 v1, v1, v1
	v_mul_f32_e32 v3, v3, v3
	v_cvt_pk_bf16_f32 v4, v4, v5
	v_cvt_pk_bf16_f32 v5, v6, v7
	v_cvt_pk_bf16_f32 v6, v0, v1
	v_cvt_pk_bf16_f32 v7, v2, v3
	v_mov_b32_e32 v2, 0
	v_mov_b32_dpp v2, v6 row_ror:8 row_mask:0xf bank_mask:0xf
	v_mov_b32_dpp v14, v8 row_ror:8 row_mask:0xf bank_mask:0xf
	v_mov_b32_dpp v3, v7 row_ror:8 row_mask:0xf bank_mask:0xf
	v_cndmask_b32_e64 v2, v2, v8, s[6:7]
	v_add_u32_e32 v8, v155, v160
	v_mov_b32_dpp v15, v9 row_ror:8 row_mask:0xf bank_mask:0xf
	v_cndmask_b32_e64 v3, v3, v9, s[6:7]
	v_ashrrev_i32_e32 v9, 31, v8
	v_lshlrev_b64 v[8:9], 14, v[8:9]
	v_mov_b32_dpp v0, v4 row_ror:8 row_mask:0xf bank_mask:0xf
	v_mov_b32_dpp v1, v5 row_ror:8 row_mask:0xf bank_mask:0xf
	v_lshl_add_u64 v[8:9], s[10:11], 0, v[8:9]
	v_cndmask_b32_e64 v0, v0, v12, s[6:7]
	v_cndmask_b32_e64 v1, v1, v13, s[6:7]
	v_lshl_add_u64 v[8:9], v[8:9], 0, v[112:113]
	global_store_dwordx4 v[8:9], v[0:3], off
	v_mov_b32_dpp v10, v12 row_ror:8 row_mask:0xf bank_mask:0xf
	v_mov_b32_dpp v11, v13 row_ror:8 row_mask:0xf bank_mask:0xf
	v_add_co_u32_e32 v0, vcc, 0x20000, v8
	v_cndmask_b32_e64 v4, v4, v10, s[6:7]
	s_nop 0
	v_addc_co_u32_e32 v1, vcc, 0, v9, vcc
	v_cndmask_b32_e64 v5, v5, v11, s[6:7]
	v_cndmask_b32_e64 v6, v6, v14, s[6:7]
	v_cndmask_b32_e64 v7, v7, v15, s[6:7]
	s_and_b64 vcc, exec, s[40:41]
	s_mov_b32 s69, s18
	s_mov_b32 s44, s36
	s_mov_b64 s[48:49], s[42:43]
	s_mov_b64 s[46:47], s[38:39]
	global_store_dwordx4 v[0:1], v[4:7], off
	s_cbranch_vccz .LBB0_725
	s_waitcnt vmcnt(0)
	s_cmpk_gt_u32 s52, 0xff
	s_cbranch_scc1 .LBB0_737
	s_barrier

; #define PG8_STAGE(bufoff, gbase, voff) do { _Pragma("unroll") for (int _i = 0; _i < 2; ++_i) \
;         __builtin_amdgcn_global_load_lds((const unsigned*)((const char*)(gbase) + (voff)[_i]), (LAS unsigned*)(lds + (bufoff) + ldsw + _i * 8192), 16, 0, 0); } while (0)
; #define PG8_WAIT_V(n) asm volatile("s_waitcnt vmcnt(" #n ")" ::: "memory")
; #define PG8_BAR __builtin_amdgcn_s_barrier()
; template <class Epi>
; __device__ __forceinline__ void gemm_phase(LAS unsigned char* lds, const Gemm g, const StaticOrder& S, const Epi& E) {
;     int tid = threadIdx.x; asm volatile("" : "+v"(tid));
;     const int wid = __builtin_amdgcn_readfirstlane(tid >> 6), lane = tid & 63, wr = wid >> 2, wc = wid & 3, fr = lane & 15, fq = lane >> 4;
;     const int K = g.K, nt = K / BK;
;     unsigned voffA[2], voffB0[2], voffB1[2];
; #pragma unroll
;     for (int i = 0; i < 2; ++i) { int R, C; stage_rc(tid * 16 + i * 8192, R, C);
;         const int Rw = 64 * (R >> 5) + 16 * ((R >> 2) & 3) + 4 * ((R >> 4) & 1) + (R & 3);
;         const int Rf = 64 * (R >> 5) + 8 * ((R >> 2) & 3) + 4 * ((R >> 4) & 1) + (R & 3);
;         const int Rb0 = Epi::PERM ? (Epi::F32OUT ? Rf : Rw) : R, Rb1 = Epi::PERM ? (Epi::F32OUT ? Rf + 32 : Rw + 8) : R + HALF;
;         voffA[i] = (unsigned)(R * K + C) * 2u; voffB0[i] = (unsigned)(Rb0 * K + C) * 2u; voffB1[i] = (unsigned)(Rb1 * K + C) * 2u; }
;     const size_t kstep = (size_t)(BK * 2);
;     const size_t hstep = (size_t)HALF * K * 2;
;     const size_t tstep = 2 * hstep;
;     const unsigned ldsw = (unsigned)wid * 1024u;
;     const int aoff = lds_byte(wr * 64 + fr, fq * 8), boff = lds_byte(wc * 32 + fr, fq * 8);
;     ...
;     PG8_STAGE(PG8_SB(0, 0), cB, voffB0); PG8_STAGE(PG8_SA(0, 0), cA, voffA); PG8_STAGE(PG8_SB(0, 1), cB, voffB1); PG8_STAGE(PG8_SA(0, 1), cA + hstep, voffA);
;     if (wr == 1) PG8_BAR;
;     PG8_WAIT_V(4); PG8_BAR;
;     PG8_STAGE(PG8_SB(1, 0), cB + kstep, voffB0); PG8_STAGE(PG8_SA(1, 0), cA + kstep, voffA); PG8_STAGE(PG8_SB(1, 1), cB + kstep, voffB1);
;     PG8_WAIT_V(6); PG8_BAR;
.LBB0_797:
	s_add_u32 s16, s10, 0x6400000
	s_addc_u32 s17, s11, 0
	s_add_u32 s10, s10, 0x1ec00000
	s_mov_b64 s[18:19], 0x80
	s_addc_u32 s11, s11, 0
	s_add_i32 m0, s49, 0x18000
	v_lshl_add_u64 v[10:11], v[10:11], 0, s[18:19]
	s_waitcnt vmcnt(4)
	s_barrier
	global_load_lds_dwordx4 v[10:11], off
	v_lshl_add_u64 v[8:9], v[8:9], 0, s[18:19]
	s_add_i32 m0, s49, 0x1a000
	s_add_i32 s67, s49, 0x8000
	global_load_lds_dwordx4 v[8:9], off
	v_lshl_add_u64 v[6:7], v[6:7], 0, s[18:19]
	s_mov_b32 m0, s67
	s_add_i32 s68, s49, 0xa000
	global_load_lds_dwordx4 v[6:7], off
	v_lshl_add_u64 v[4:5], v[4:5], 0, s[18:19]
	s_mov_b32 m0, s68
	v_lshl_add_u64 v[0:1], v[0:1], 0, s[18:19]
	global_load_lds_dwordx4 v[4:5], off
	s_add_i32 m0, s49, 0x1c000
	v_and_b32_e32 v152, 15, v12
	global_load_lds_dwordx4 v[0:1], off
	v_lshl_add_u64 v[0:1], v[2:3], 0, s[18:19]
	s_add_i32 m0, s49, 0x1e000
	v_lshlrev_b32_e32 v2, 2, v12
	global_load_lds_dwordx4 v[0:1], off
	v_and_b32_e32 v0, 48, v12
	s_sext_i32_i8 s74, s6
	s_and_b32 s6, s7, 3
	s_lshl_b32 s7, s36, 13
	v_lshl_or_b32 v1, v152, 6, v0
	v_and_b32_e32 v2, 32, v2
	v_bitop3_b32 v3, v1, s7, v2 bitop3:0xde
	s_lshl_b32 s7, s6, 12
	v_bitop3_b32 v153, v1, s7, v2 bitop3:0xde
	s_lshl_b32 s33, s6, 6
	v_and_b32_e32 v1, 8, v12
	v_or3_b32 v155, s33, v1, v0
	v_lshlrev_b32_e32 v0, 17, v13
	v_and_b32_e32 v0, 0xfffc0000, v0
	v_lshl_add_u32 v0, v14, 14, v0
	v_and_b32_e32 v1, 1, v13
	v_lshl_or_b32 v0, v1, 6, v0
	v_lshl_add_u32 v140, v15, 1, v0
	v_lshlrev_b32_e32 v0, 17, v16
	v_and_b32_e32 v0, 0xfffc0000, v0
	s_waitcnt vmcnt(0)
	v_lshl_add_u32 v0, v17, 14, v0
	v_and_b32_e32 v1, 1, v16
	v_lshl_or_b32 v0, v1, 6, v0
	s_add_i32 s72, 0, 0x10000
	s_add_i32 s73, 0, 0x14000
	s_lshl_b32 s69, s36, 6
	v_cmp_gt_u32_e64 s[6:7], 8, v152
	v_and_b32_e32 v154, 7, v12
	s_ashr_i32 s70, s20, 31
	s_mov_b32 s71, s20
	v_mov_b32_e32 v141, v131
	v_lshl_add_u32 v142, v18, 1, v0
	v_mov_b32_e32 v143, v131
	v_add_u32_e32 v156, s72, v153
	v_add_u32_e32 v157, 0, v3
	v_add_u32_e32 v158, s73, v153
	v_mov_b32_e32 v159, 0x358637bd
	s_mov_b64 s[36:37], 0x8000
	v_mov_b64_e32 v[144:145], 0x1ff
	s_barrier

; #define PG8_STAGE(bufoff, gbase, voff) do { _Pragma("unroll") for (int _i = 0; _i < 2; ++_i) \
;         __builtin_amdgcn_global_load_lds((const unsigned*)((const char*)(gbase) + (voff)[_i]), (LAS unsigned*)(lds + (bufoff) + ldsw + _i * 8192), 16, 0, 0); } while (0)
; #define PG8_LDA(dst, b, h) do { _Pragma("unroll") for (int m = 0; m < 4; ++m) _Pragma("unroll") for (int k = 0; k < 2; ++k) dst[m][k] = *(const LAS bf16x8*)(lds + PG8_SA(b, h) + aoff + m * 2048 + k * 1024); } while (0)
; #define PG8_LDB(dst, b, h) do { _Pragma("unroll") for (int n = 0; n < 2; ++n) _Pragma("unroll") for (int k = 0; k < 2; ++k) dst[n][k] = *(const LAS bf16x8*)(lds + PG8_SB(b, h) + boff + n * 2048 + k * 1024); } while (0)
; #define PG8_MMA(ai, bj, At, Bt) do { __builtin_amdgcn_s_setprio(1); _Pragma("unroll") for (int m = 0; m < 4; ++m) _Pragma("unroll") for (int n = 0; n < 2; ++n) _Pragma("unroll") for (int k = 0; k < 2; ++k) \
;         acc[ai][bj][m][n] = __builtin_amdgcn_mfma_f32_16x16x32_bf16(Bt[n][k], At[m][k], acc[ai][bj][m][n], 0, 0, 0); __builtin_amdgcn_s_setprio(0); } while (0)
; #define PG8_WAIT_L(n) asm volatile("s_waitcnt lgkmcnt(" #n ")" ::: "memory")
; #define PG8_BAR __builtin_amdgcn_s_barrier()
; #define PG8_SCHED __builtin_amdgcn_sched_barrier(0)
; template <class Epi>
; __device__ __forceinline__ void gemm_phase(LAS unsigned char* lds, const Gemm g, const StaticOrder& S, const Epi& E) {
;     ...
;             PG8_LDB(B0, 0, 0); PG8_SCHED; PG8_LDA(At, 0, 0); PG8_STAGE(PG8_SA(1, 1), a1 + hstep, voffA);
;             PG8_WAIT_L(8); PG8_BAR; PG8_WAIT_L(0); PG8_MMA(0, 0, At, B0); PG8_BAR; PG8_SCHED;
;             PG8_LDB(B1, 0, 1); PG8_STAGE(PG8_SB(0, 0), b2, voffB0);
;             PG8_BAR; PG8_WAIT_L(0); PG8_MMA(0, 1, At, B1); PG8_BAR;
;             PG8_LDA(At, 0, 1); PG8_STAGE(PG8_SA(0, 0), a2, voffA);
;             PG8_BAR; PG8_WAIT_L(0); PG8_MMA(1, 0, At, B0); PG8_BAR; PG8_SCHED;
;             PG8_STAGE(PG8_SB(0, 1), b2, voffB1);
.LBB0_806:
	ds_read_b128 v[146:149], v156
	ds_read_b128 v[160:163], v156 offset:1024
	ds_read_b128 v[164:167], v156 offset:2048
	ds_read_b128 v[168:171], v156 offset:3072
	s_add_u32 s33, s50, 0xffe00080
	s_addc_u32 s52, s51, -1
	s_cmpk_eq_i32 s80, 0x7c
	s_cselect_b32 s53, s41, s52
	s_cselect_b32 s52, s75, s33
	s_cselect_b32 s55, s39, s79
	s_cselect_b32 s54, s77, s78
	v_lshl_add_u64 v[150:151], s[50:51], 0, v[140:141]
	s_add_i32 m0, s49, 0xc000
	ds_read_b128 v[172:175], v157
	ds_read_b128 v[176:179], v157 offset:1024
	ds_read_b128 v[180:183], v157 offset:2048
	ds_read_b128 v[184:187], v157 offset:3072
	ds_read_b128 v[188:191], v157 offset:4096
	ds_read_b128 v[192:195], v157 offset:5120
	ds_read_b128 v[196:199], v157 offset:6144
	ds_read_b128 v[204:207], v157 offset:7168
	global_load_lds_dwordx4 v[150:151], off
	v_lshl_add_u64 v[150:151], s[50:51], 0, v[142:143]
	s_add_i32 m0, s49, 0xe000
	s_nop 0
	global_load_lds_dwordx4 v[150:151], off
	s_waitcnt lgkmcnt(8)
	s_barrier
	s_waitcnt lgkmcnt(0)
	v_mfma_f32_16x16x32_bf16 v[124:127], v[146:149], v[172:175], v[124:127]
	v_mfma_f32_16x16x32_bf16 v[120:123], v[164:167], v[172:175], v[120:123]
	v_mfma_f32_16x16x32_bf16 v[108:111], v[146:149], v[180:183], v[108:111]
	v_mfma_f32_16x16x32_bf16 v[104:107], v[164:167], v[180:183], v[104:107]
	v_mfma_f32_16x16x32_bf16 v[92:95], v[146:149], v[188:191], v[92:95]
	v_mfma_f32_16x16x32_bf16 v[88:91], v[164:167], v[188:191], v[88:91]
	v_mfma_f32_16x16x32_bf16 v[76:79], v[146:149], v[196:199], v[76:79]
	v_mfma_f32_16x16x32_bf16 v[72:75], v[164:167], v[196:199], v[72:75]
	v_mfma_f32_16x16x32_bf16 v[124:127], v[160:163], v[176:179], v[124:127]
	v_mfma_f32_16x16x32_bf16 v[120:123], v[168:171], v[176:179], v[120:123]
	v_mfma_f32_16x16x32_bf16 v[108:111], v[160:163], v[184:187], v[108:111]
	v_mfma_f32_16x16x32_bf16 v[104:107], v[168:171], v[184:187], v[104:107]
	v_mfma_f32_16x16x32_bf16 v[92:95], v[160:163], v[192:195], v[92:95]
	v_mfma_f32_16x16x32_bf16 v[88:91], v[168:171], v[192:195], v[88:91]
	v_mfma_f32_16x16x32_bf16 v[76:79], v[160:163], v[204:207], v[76:79]
	v_mfma_f32_16x16x32_bf16 v[72:75], v[168:171], v[204:207], v[72:75]
	s_barrier
	s_add_i32 s33, s72, s62
	v_lshl_add_u64 v[150:151], s[54:55], 0, v[130:131]
	s_mov_b32 m0, s33
	ds_read_b128 v[208:211], v158
	ds_read_b128 v[212:215], v158 offset:1024
	ds_read_b128 v[216:219], v158 offset:2048
	ds_read_b128 v[220:223], v158 offset:3072
	global_load_lds_dwordx4 v[150:151], off
	v_lshl_add_u64 v[200:201], s[54:55], 0, v[136:137]
	s_add_i32 m0, s33, 0x2000
	s_nop 0
	global_load_lds_dwordx4 v[200:201], off
	s_barrier
	s_waitcnt lgkmcnt(0)
	v_mfma_f32_16x16x32_bf16 v[116:119], v[208:211], v[172:175], v[116:119]
	v_mfma_f32_16x16x32_bf16 v[112:115], v[216:219], v[172:175], v[112:115]
	v_mfma_f32_16x16x32_bf16 v[100:103], v[208:211], v[180:183], v[100:103]
	v_mfma_f32_16x16x32_bf16 v[96:99], v[216:219], v[180:183], v[96:99]
	v_mfma_f32_16x16x32_bf16 v[84:87], v[208:211], v[188:191], v[84:87]
	v_mfma_f32_16x16x32_bf16 v[80:83], v[216:219], v[188:191], v[80:83]
	v_mfma_f32_16x16x32_bf16 v[68:71], v[208:211], v[196:199], v[68:71]
	v_mfma_f32_16x16x32_bf16 v[64:67], v[216:219], v[196:199], v[64:67]
	v_mfma_f32_16x16x32_bf16 v[116:119], v[212:215], v[176:179], v[116:119]
	v_mfma_f32_16x16x32_bf16 v[112:115], v[220:223], v[176:179], v[112:115]
	v_mfma_f32_16x16x32_bf16 v[100:103], v[212:215], v[184:187], v[100:103]
	v_mfma_f32_16x16x32_bf16 v[96:99], v[220:223], v[184:187], v[96:99]
	v_mfma_f32_16x16x32_bf16 v[84:87], v[212:215], v[192:195], v[84:87]
	v_mfma_f32_16x16x32_bf16 v[80:83], v[220:223], v[192:195], v[80:83]
	v_mfma_f32_16x16x32_bf16 v[68:71], v[212:215], v[204:207], v[68:71]
	v_mfma_f32_16x16x32_bf16 v[64:67], v[220:223], v[204:207], v[64:67]
	s_mov_b32 m0, s49
	v_lshl_add_u64 v[224:225], s[52:53], 0, v[128:129]
	s_barrier
	ds_read_b128 v[172:175], v157 offset:16384
	ds_read_b128 v[176:179], v157 offset:17408
	ds_read_b128 v[180:183], v157 offset:18432
	ds_read_b128 v[184:187], v157 offset:19456
	ds_read_b128 v[188:191], v157 offset:20480
	ds_read_b128 v[192:195], v157 offset:21504
	ds_read_b128 v[196:199], v157 offset:22528
	ds_read_b128 v[204:207], v157 offset:23552
	global_load_lds_dwordx4 v[224:225], off
	v_lshl_add_u64 v[226:227], s[52:53], 0, v[134:135]
	s_mov_b32 m0, s63
	s_nop 0
	global_load_lds_dwordx4 v[226:227], off
	s_barrier
	s_waitcnt lgkmcnt(0)
	v_mfma_f32_16x16x32_bf16 v[60:63], v[146:149], v[172:175], v[60:63]
	v_mfma_f32_16x16x32_bf16 v[56:59], v[164:167], v[172:175], v[56:59]
	v_mfma_f32_16x16x32_bf16 v[44:47], v[146:149], v[180:183], v[44:47]
	v_mfma_f32_16x16x32_bf16 v[40:43], v[164:167], v[180:183], v[40:43]
	v_mfma_f32_16x16x32_bf16 v[28:31], v[146:149], v[188:191], v[28:31]
	v_mfma_f32_16x16x32_bf16 v[24:27], v[164:167], v[188:191], v[24:27]
	v_mfma_f32_16x16x32_bf16 v[12:15], v[146:149], v[196:199], v[12:15]
	v_mfma_f32_16x16x32_bf16 v[8:11], v[164:167], v[196:199], v[8:11]
	v_mfma_f32_16x16x32_bf16 v[60:63], v[160:163], v[176:179], v[60:63]
	v_mfma_f32_16x16x32_bf16 v[56:59], v[168:171], v[176:179], v[56:59]
	v_mfma_f32_16x16x32_bf16 v[44:47], v[160:163], v[184:187], v[44:47]
	v_mfma_f32_16x16x32_bf16 v[40:43], v[168:171], v[184:187], v[40:43]
	v_mfma_f32_16x16x32_bf16 v[28:31], v[160:163], v[192:195], v[28:31]
	v_mfma_f32_16x16x32_bf16 v[24:27], v[168:171], v[192:195], v[24:27]
	v_mfma_f32_16x16x32_bf16 v[12:15], v[160:163], v[204:207], v[12:15]
	v_mfma_f32_16x16x32_bf16 v[8:11], v[168:171], v[204:207], v[8:11]
	s_barrier
; #define PG8_STAGE(bufoff, gbase, voff) do { _Pragma("unroll") for (int _i = 0; _i < 2; ++_i) \
;         __builtin_amdgcn_global_load_lds((const unsigned*)((const char*)(gbase) + (voff)[_i]), (LAS unsigned*)(lds + (bufoff) + ldsw + _i * 8192), 16, 0, 0); } while (0)
; #define PG8_LDA(dst, b, h) do { _Pragma("unroll") for (int m = 0; m < 4; ++m) _Pragma("unroll") for (int k = 0; k < 2; ++k) dst[m][k] = *(const LAS bf16x8*)(lds + PG8_SA(b, h) + aoff + m * 2048 + k * 1024); } while (0)
; #define PG8_LDB(dst, b, h) do { _Pragma("unroll") for (int n = 0; n < 2; ++n) _Pragma("unroll") for (int k = 0; k < 2; ++k) dst[n][k] = *(const LAS bf16x8*)(lds + PG8_SB(b, h) + boff + n * 2048 + k * 1024); } while (0)
; #define PG8_MMA(ai, bj, At, Bt) do { __builtin_amdgcn_s_setprio(1); _Pragma("unroll") for (int m = 0; m < 4; ++m) _Pragma("unroll") for (int n = 0; n < 2; ++n) _Pragma("unroll") for (int k = 0; k < 2; ++k) \
;         acc[ai][bj][m][n] = __builtin_amdgcn_mfma_f32_16x16x32_bf16(Bt[n][k], At[m][k], acc[ai][bj][m][n], 0, 0, 0); __builtin_amdgcn_s_setprio(0); } while (0)
; #define PG8_WAIT_V(n) asm volatile("s_waitcnt vmcnt(" #n ")" ::: "memory")
; #define PG8_WAIT_L(n) asm volatile("s_waitcnt lgkmcnt(" #n ")" ::: "memory")
; #define PG8_BAR __builtin_amdgcn_s_barrier()
; #define PG8_SCHED __builtin_amdgcn_sched_barrier(0)
; template <class Epi>
; __device__ __forceinline__ void gemm_phase(LAS unsigned char* lds, const Gemm g, const StaticOrder& S, const Epi& E) {
;     ...
;             PG8_STAGE(PG8_SB(0, 1), b2, voffB1);
;             PG8_WAIT_V(6); PG8_BAR; PG8_MMA(1, 1, At, B1); PG8_BAR;
;             PG8_LDB(B0, 1, 0); PG8_SCHED; PG8_LDA(At, 1, 0); PG8_STAGE(PG8_SA(0, 1), a2 + hstep, voffA);
;             PG8_WAIT_L(8); PG8_BAR; PG8_WAIT_L(0); PG8_MMA(0, 0, At, B0); PG8_BAR; PG8_SCHED;
;             PG8_LDB(B1, 1, 1); PG8_STAGE(PG8_SB(1, 0), b3, voffB0);
;             PG8_BAR; PG8_WAIT_L(0); PG8_MMA(0, 1, At, B1); PG8_BAR;
;             PG8_LDA(At, 1, 1); PG8_STAGE(PG8_SA(1, 0), a3, voffA);
	s_add_i32 s33, s73, s62
	v_lshl_add_u64 v[228:229], s[54:55], 0, v[132:133]
	s_mov_b32 m0, s33
	v_lshl_add_u64 v[230:231], s[54:55], 0, v[138:139]
	global_load_lds_dwordx4 v[228:229], off
	s_add_i32 m0, s33, 0x2000
	s_nop 0
	global_load_lds_dwordx4 v[230:231], off
	s_add_i32 s33, 0, 0x18000
	v_add_u32_e32 v168, s33, v153
	ds_read_b128 v[146:149], v168
	ds_read_b128 v[160:163], v168 offset:1024
	ds_read_b128 v[164:167], v168 offset:2048
	ds_read_b128 v[168:171], v168 offset:3072
	s_waitcnt vmcnt(6)
	s_barrier
	v_mfma_f32_16x16x32_bf16 v[52:55], v[208:211], v[172:175], v[52:55]
	v_mfma_f32_16x16x32_bf16 v[48:51], v[216:219], v[172:175], v[48:51]
	v_mfma_f32_16x16x32_bf16 v[36:39], v[208:211], v[180:183], v[36:39]
	v_mfma_f32_16x16x32_bf16 v[32:35], v[216:219], v[180:183], v[32:35]
	v_mfma_f32_16x16x32_bf16 v[20:23], v[208:211], v[188:191], v[20:23]
	v_mfma_f32_16x16x32_bf16 v[16:19], v[216:219], v[188:191], v[16:19]
	v_mfma_f32_16x16x32_bf16 v[4:7], v[208:211], v[196:199], v[4:7]
	v_mfma_f32_16x16x32_bf16 v[0:3], v[216:219], v[196:199], v[0:3]
	v_mfma_f32_16x16x32_bf16 v[52:55], v[212:215], v[176:179], v[52:55]
	v_mfma_f32_16x16x32_bf16 v[48:51], v[220:223], v[176:179], v[48:51]
	v_mfma_f32_16x16x32_bf16 v[36:39], v[212:215], v[184:187], v[36:39]
	v_mfma_f32_16x16x32_bf16 v[32:35], v[220:223], v[184:187], v[32:35]
	v_mfma_f32_16x16x32_bf16 v[20:23], v[212:215], v[192:195], v[20:23]
	v_mfma_f32_16x16x32_bf16 v[16:19], v[220:223], v[192:195], v[16:19]
	v_mfma_f32_16x16x32_bf16 v[4:7], v[212:215], v[204:207], v[4:7]
	v_mfma_f32_16x16x32_bf16 v[0:3], v[220:223], v[204:207], v[0:3]
	s_barrier
	s_add_u32 s52, s52, 0x200000
	s_addc_u32 s53, s53, 0
	s_mov_b32 m0, s64
	v_lshl_add_u64 v[208:209], s[52:53], 0, v[128:129]
	ds_read_b128 v[172:175], v157 offset:32768
	ds_read_b128 v[176:179], v157 offset:33792
	ds_read_b128 v[180:183], v157 offset:34816
	ds_read_b128 v[184:187], v157 offset:35840
	ds_read_b128 v[188:191], v157 offset:36864
	ds_read_b128 v[192:195], v157 offset:37888
	ds_read_b128 v[196:199], v157 offset:38912
	ds_read_b128 v[204:207], v157 offset:39936
	global_load_lds_dwordx4 v[208:209], off
	v_lshl_add_u64 v[208:209], s[52:53], 0, v[134:135]
	s_mov_b32 m0, s65
	s_nop 0
	global_load_lds_dwordx4 v[208:209], off
	s_waitcnt lgkmcnt(8)
	s_barrier
	s_waitcnt lgkmcnt(0)
	v_mfma_f32_16x16x32_bf16 v[124:127], v[146:149], v[172:175], v[124:127]
	v_mfma_f32_16x16x32_bf16 v[120:123], v[164:167], v[172:175], v[120:123]
	v_mfma_f32_16x16x32_bf16 v[108:111], v[146:149], v[180:183], v[108:111]
	v_mfma_f32_16x16x32_bf16 v[104:107], v[164:167], v[180:183], v[104:107]
	v_mfma_f32_16x16x32_bf16 v[92:95], v[146:149], v[188:191], v[92:95]
	v_mfma_f32_16x16x32_bf16 v[88:91], v[164:167], v[188:191], v[88:91]
	v_mfma_f32_16x16x32_bf16 v[76:79], v[146:149], v[196:199], v[76:79]
	v_mfma_f32_16x16x32_bf16 v[72:75], v[164:167], v[196:199], v[72:75]
	v_mfma_f32_16x16x32_bf16 v[124:127], v[160:163], v[176:179], v[124:127]
	v_mfma_f32_16x16x32_bf16 v[120:123], v[168:171], v[176:179], v[120:123]
	v_mfma_f32_16x16x32_bf16 v[108:111], v[160:163], v[184:187], v[108:111]
	v_mfma_f32_16x16x32_bf16 v[104:107], v[168:171], v[184:187], v[104:107]
	v_mfma_f32_16x16x32_bf16 v[92:95], v[160:163], v[192:195], v[92:95]
	v_mfma_f32_16x16x32_bf16 v[88:91], v[168:171], v[192:195], v[88:91]
	v_mfma_f32_16x16x32_bf16 v[76:79], v[160:163], v[204:207], v[76:79]
	v_mfma_f32_16x16x32_bf16 v[72:75], v[168:171], v[204:207], v[72:75]
	s_barrier
	s_add_i32 s52, 0, 0x1c000
	s_add_i32 s33, s33, s62
	v_add_u32_e32 v220, s52, v153
	v_lshl_add_u64 v[150:151], v[150:151], 0, s[18:19]
	s_mov_b32 m0, s33
	ds_read_b128 v[208:211], v220
	ds_read_b128 v[212:215], v220 offset:1024
	ds_read_b128 v[216:219], v220 offset:2048
	ds_read_b128 v[220:223], v220 offset:3072
	global_load_lds_dwordx4 v[150:151], off
	v_lshl_add_u64 v[150:151], v[200:201], 0, s[18:19]
	s_add_i32 m0, s33, 0x2000
	s_nop 0
	global_load_lds_dwordx4 v[150:151], off
	s_barrier
	s_waitcnt lgkmcnt(0)
	v_mfma_f32_16x16x32_bf16 v[116:119], v[208:211], v[172:175], v[116:119]
	v_mfma_f32_16x16x32_bf16 v[112:115], v[216:219], v[172:175], v[112:115]
	v_mfma_f32_16x16x32_bf16 v[100:103], v[208:211], v[180:183], v[100:103]
	v_mfma_f32_16x16x32_bf16 v[96:99], v[216:219], v[180:183], v[96:99]
	v_mfma_f32_16x16x32_bf16 v[84:87], v[208:211], v[188:191], v[84:87]
	v_mfma_f32_16x16x32_bf16 v[80:83], v[216:219], v[188:191], v[80:83]
	v_mfma_f32_16x16x32_bf16 v[68:71], v[208:211], v[196:199], v[68:71]
	v_mfma_f32_16x16x32_bf16 v[64:67], v[216:219], v[196:199], v[64:67]
	v_mfma_f32_16x16x32_bf16 v[116:119], v[212:215], v[176:179], v[116:119]
	v_mfma_f32_16x16x32_bf16 v[112:115], v[220:223], v[176:179], v[112:115]
	v_mfma_f32_16x16x32_bf16 v[100:103], v[212:215], v[184:187], v[100:103]
	v_mfma_f32_16x16x32_bf16 v[96:99], v[220:223], v[184:187], v[96:99]
	v_mfma_f32_16x16x32_bf16 v[84:87], v[212:215], v[192:195], v[84:87]
	v_mfma_f32_16x16x32_bf16 v[80:83], v[220:223], v[192:195], v[80:83]
	v_mfma_f32_16x16x32_bf16 v[68:71], v[212:215], v[204:207], v[68:71]
	v_mfma_f32_16x16x32_bf16 v[64:67], v[220:223], v[204:207], v[64:67]
	s_mov_b32 m0, s67
	v_lshl_add_u64 v[150:151], v[224:225], 0, s[18:19]
	s_barrier
	ds_read_b128 v[172:175], v157 offset:49152
	ds_read_b128 v[176:179], v157 offset:50176
	ds_read_b128 v[180:183], v157 offset:51200
	ds_read_b128 v[184:187], v157 offset:52224
	ds_read_b128 v[188:191], v157 offset:53248
	ds_read_b128 v[192:195], v157 offset:54272
	ds_read_b128 v[196:199], v157 offset:55296
	ds_read_b128 v[204:207], v157 offset:56320
	global_load_lds_dwordx4 v[150:151], off
	v_lshl_add_u64 v[150:151], v[226:227], 0, s[18:19]
	s_mov_b32 m0, s68
	s_nop 0
	global_load_lds_dwordx4 v[150:151], off
	s_barrier
; #define PG8_STAGE(bufoff, gbase, voff) do { _Pragma("unroll") for (int _i = 0; _i < 2; ++_i) \
;         __builtin_amdgcn_global_load_lds((const unsigned*)((const char*)(gbase) + (voff)[_i]), (LAS unsigned*)(lds + (bufoff) + ldsw + _i * 8192), 16, 0, 0); } while (0)
; #define PG8_MMA(ai, bj, At, Bt) do { __builtin_amdgcn_s_setprio(1); _Pragma("unroll") for (int m = 0; m < 4; ++m) _Pragma("unroll") for (int n = 0; n < 2; ++n) _Pragma("unroll") for (int k = 0; k < 2; ++k) \
;         acc[ai][bj][m][n] = __builtin_amdgcn_mfma_f32_16x16x32_bf16(Bt[n][k], At[m][k], acc[ai][bj][m][n], 0, 0, 0); __builtin_amdgcn_s_setprio(0); } while (0)
; #define PG8_WAIT_V(n) asm volatile("s_waitcnt vmcnt(" #n ")" ::: "memory")
; #define PG8_WAIT_L(n) asm volatile("s_waitcnt lgkmcnt(" #n ")" ::: "memory")
; #define PG8_BAR __builtin_amdgcn_s_barrier()
; #define PG8_SCHED __builtin_amdgcn_sched_barrier(0)
;     const bool lo = fr < 8;
;     const int r1 = row - fr + (fr & 7), cb = col0 + (lo ? 0 : boff);
;     const u32x4 l1 = *(const u32x4*)(P + (size_t)r1 * ld + cb), l2 = *(const u32x4*)(P + (size_t)(r1 + 8) * ld + cb);
;     __device__ __forceinline__ void operator()(const f32x4 (&acc)[2][2][4][2], const Unit& u, int wr, int wc, int fr, int fq) const {
;     ...
;             for (int m = 0; m < 4; ++m) { const int row = row0 + ai * HALF + m * 16; const size_t off = (size_t)row * D + col0; float sq = 0.f; u32x4 w[2];
;                 const float sc = rsin ? __builtin_amdgcn_rcpf(rsin[row] * (1.f / D) + EPS) : 1.0f;
;                 u32x4 rr[2]; if (R) load_pair_lines(R, D, row, fr, col0, rr[0], rr[1]);
; template <class Epi>
; __device__ __forceinline__ void gemm_phase(LAS unsigned char* lds, const Gemm g, const StaticOrder& S, const Epi& E) {
;     ...
;             PG8_BAR; PG8_WAIT_L(0); PG8_MMA(1, 0, At, B0); PG8_BAR; PG8_SCHED;
;             PG8_STAGE(PG8_SB(1, 1), b3, voffB1);
;             PG8_WAIT_V(6); PG8_BAR; PG8_MMA(1, 1, At, B1); PG8_BAR;
	s_waitcnt lgkmcnt(0)
	v_mfma_f32_16x16x32_bf16 v[60:63], v[146:149], v[172:175], v[60:63]
	v_mfma_f32_16x16x32_bf16 v[56:59], v[164:167], v[172:175], v[56:59]
	v_mfma_f32_16x16x32_bf16 v[44:47], v[146:149], v[180:183], v[44:47]
	v_mfma_f32_16x16x32_bf16 v[40:43], v[164:167], v[180:183], v[40:43]
	v_mfma_f32_16x16x32_bf16 v[28:31], v[146:149], v[188:191], v[28:31]
	v_mfma_f32_16x16x32_bf16 v[24:27], v[164:167], v[188:191], v[24:27]
	v_mfma_f32_16x16x32_bf16 v[12:15], v[146:149], v[196:199], v[12:15]
	v_mfma_f32_16x16x32_bf16 v[8:11], v[164:167], v[196:199], v[8:11]
	v_mfma_f32_16x16x32_bf16 v[60:63], v[160:163], v[176:179], v[60:63]
	v_mfma_f32_16x16x32_bf16 v[56:59], v[168:171], v[176:179], v[56:59]
	v_mfma_f32_16x16x32_bf16 v[44:47], v[160:163], v[184:187], v[44:47]
	v_mfma_f32_16x16x32_bf16 v[40:43], v[168:171], v[184:187], v[40:43]
	v_mfma_f32_16x16x32_bf16 v[28:31], v[160:163], v[192:195], v[28:31]
	v_mfma_f32_16x16x32_bf16 v[24:27], v[168:171], v[192:195], v[24:27]
	v_mfma_f32_16x16x32_bf16 v[12:15], v[160:163], v[204:207], v[12:15]
	v_mfma_f32_16x16x32_bf16 v[8:11], v[168:171], v[204:207], v[8:11]
	s_barrier
	s_add_i32 s33, s52, s62
	v_lshl_add_u64 v[146:147], v[228:229], 0, s[18:19]
	s_mov_b32 m0, s33
	s_nop 0
	global_load_lds_dwordx4 v[146:147], off
	v_lshl_add_u64 v[146:147], v[230:231], 0, s[18:19]
	s_add_i32 m0, s33, 0x2000
	s_nop 0
	global_load_lds_dwordx4 v[146:147], off
	s_waitcnt vmcnt(6)
	s_barrier
	v_mfma_f32_16x16x32_bf16 v[52:55], v[208:211], v[172:175], v[52:55]
	v_mfma_f32_16x16x32_bf16 v[48:51], v[216:219], v[172:175], v[48:51]
	v_mfma_f32_16x16x32_bf16 v[36:39], v[208:211], v[180:183], v[36:39]
	v_mfma_f32_16x16x32_bf16 v[32:35], v[216:219], v[180:183], v[32:35]
	v_mfma_f32_16x16x32_bf16 v[20:23], v[208:211], v[188:191], v[20:23]
	v_mfma_f32_16x16x32_bf16 v[16:19], v[216:219], v[188:191], v[16:19]
	v_mfma_f32_16x16x32_bf16 v[4:7], v[208:211], v[196:199], v[4:7]
	v_mfma_f32_16x16x32_bf16 v[0:3], v[216:219], v[196:199], v[0:3]
	v_mfma_f32_16x16x32_bf16 v[52:55], v[212:215], v[176:179], v[52:55]
	v_mfma_f32_16x16x32_bf16 v[48:51], v[220:223], v[176:179], v[48:51]
	v_mfma_f32_16x16x32_bf16 v[36:39], v[212:215], v[184:187], v[36:39]
	v_mfma_f32_16x16x32_bf16 v[32:35], v[220:223], v[184:187], v[32:35]
	v_mfma_f32_16x16x32_bf16 v[20:23], v[212:215], v[192:195], v[20:23]
	v_mfma_f32_16x16x32_bf16 v[16:19], v[220:223], v[192:195], v[16:19]
	v_mfma_f32_16x16x32_bf16 v[4:7], v[212:215], v[204:207], v[4:7]
	v_mfma_f32_16x16x32_bf16 v[0:3], v[220:223], v[204:207], v[0:3]
	s_add_i32 s80, s80, 2
	s_add_u32 s50, s50, 0x100
	s_addc_u32 s51, s51, 0
	s_add_u32 s78, s78, 0x100
	s_addc_u32 s79, s79, 0
	s_cmpk_gt_u32 s80, 0x7d
	s_barrier
	s_cbranch_scc0 .LBB0_806
	s_lshl_b32 s33, s48, 8
	s_add_i32 s33, s33, s69
	v_or_b32_e32 v164, s33, v154
	v_ashrrev_i32_e32 v165, 31, v164
	v_lshl_or_b32 v146, s74, 8, v155
	v_lshlrev_b64 v[168:169], 12, v[164:165]
	v_or_b32_e32 v164, 8, v164
	v_or_b32_e32 v150, s33, v152
	v_ashrrev_i32_e32 v147, 31, v146
	v_ashrrev_i32_e32 v165, 31, v164
	v_ashrrev_i32_e32 v151, 31, v150
	v_lshl_add_u64 v[160:161], s[16:17], 0, v[168:169]
	v_lshlrev_b64 v[146:147], 1, v[146:147]
	v_lshlrev_b64 v[170:171], 12, v[164:165]
	v_lshl_add_u64 v[148:149], v[150:151], 2, s[10:11]
	v_lshl_add_u64 v[160:161], v[160:161], 0, v[146:147]
	v_lshl_add_u64 v[164:165], s[16:17], 0, v[170:171]
	global_load_dword v151, v[148:149], off
	s_nop 0
	global_load_dwordx4 v[160:163], v[160:161], off
	v_lshl_add_u64 v[164:165], v[164:165], 0, v[146:147]
	global_load_dwordx4 v[164:167], v[164:165], off
	v_or_b32_e32 v190, 16, v150
	v_ashrrev_i32_e32 v191, 31, v190
	v_lshl_add_u64 v[192:193], v[190:191], 2, s[10:11]
	v_sub_u32_e32 v190, v190, v152
	v_add_u32_e32 v190, v190, v154
	v_ashrrev_i32_e32 v191, 31, v190
	v_lshlrev_b64 v[196:197], 12, v[190:191]
	v_lshl_add_u64 v[190:191], s[16:17], 0, v[196:197]
	v_lshl_add_u64 v[198:199], v[196:197], 0, s[36:37]
	v_lshl_add_u64 v[190:191], v[190:191], 0, v[146:147]
	v_lshl_add_u64 v[194:195], s[16:17], 0, v[198:199]
	global_load_dword v204, v[192:193], off
	global_load_dwordx4 v[208:211], v[190:191], off
	v_lshl_add_u64 v[194:195], v[194:195], 0, v[146:147]
	global_load_dwordx4 v[212:215], v[194:195], off
	v_or_b32_e32 v190, 32, v150
	v_ashrrev_i32_e32 v191, 31, v190
	v_lshl_add_u64 v[192:193], v[190:191], 2, s[10:11]
	v_sub_u32_e32 v190, v190, v152
	v_add_u32_e32 v190, v190, v154
	v_ashrrev_i32_e32 v191, 31, v190
	v_lshlrev_b64 v[196:197], 12, v[190:191]
	v_lshl_add_u64 v[190:191], s[16:17], 0, v[196:197]
	v_lshl_add_u64 v[198:199], v[196:197], 0, s[36:37]
	v_lshl_add_u64 v[190:191], v[190:191], 0, v[146:147]
	v_lshl_add_u64 v[194:195], s[16:17], 0, v[198:199]
	global_load_dword v205, v[192:193], off
	global_load_dwordx4 v[216:219], v[190:191], off
	v_lshl_add_u64 v[194:195], v[194:195], 0, v[146:147]
	global_load_dwordx4 v[220:223], v[194:195], off
	v_or_b32_e32 v190, 48, v150
	v_ashrrev_i32_e32 v191, 31, v190
	v_lshl_add_u64 v[192:193], v[190:191], 2, s[10:11]
	v_sub_u32_e32 v190, v190, v152
	v_add_u32_e32 v190, v190, v154
	v_ashrrev_i32_e32 v191, 31, v190
	v_lshlrev_b64 v[196:197], 12, v[190:191]
	v_lshl_add_u64 v[190:191], s[16:17], 0, v[196:197]
	v_lshl_add_u64 v[198:199], v[196:197], 0, s[36:37]
	v_lshl_add_u64 v[190:191], v[190:191], 0, v[146:147]
	v_lshl_add_u64 v[194:195], s[16:17], 0, v[198:199]
	global_load_dword v206, v[192:193], off
	global_load_dwordx4 v[224:227], v[190:191], off
	v_lshl_add_u64 v[194:195], v[194:195], 0, v[146:147]
	global_load_dwordx4 v[228:231], v[194:195], off
	v_sub_u32_e32 v190, v150, v152
	v_add_u32_e32 v199, v190, v154
	v_add_u32_e32 v190, 0x80, v199
	v_ashrrev_i32_e32 v191, 31, v190
	v_lshlrev_b64 v[194:195], 12, v[190:191]
	v_lshl_add_u64 v[190:191], s[16:17], 0, v[194:195]
	v_lshl_add_u64 v[196:197], v[194:195], 0, s[36:37]
	v_lshl_add_u64 v[190:191], v[190:191], 0, v[146:147]
	v_lshl_add_u64 v[192:193], s[16:17], 0, v[196:197]
	global_load_dword v207, v[148:149], off offset:512
	global_load_dwordx4 v[232:235], v[190:191], off
	v_lshl_add_u64 v[192:193], v[192:193], 0, v[146:147]
	global_load_dwordx4 v[236:239], v[192:193], off
	v_sub_u32_e32 v198, v150, v152
	v_add_u32_e32 v201, v198, v154
	v_add_u32_e32 v190, 0x90, v201
	v_ashrrev_i32_e32 v191, 31, v190
	v_lshlrev_b64 v[194:195], 12, v[190:191]
	v_lshl_add_u64 v[190:191], s[16:17], 0, v[194:195]
	v_lshl_add_u64 v[196:197], v[194:195], 0, s[36:37]
	v_lshl_add_u64 v[190:191], v[190:191], 0, v[146:147]
	v_lshl_add_u64 v[192:193], s[16:17], 0, v[196:197]
	global_load_dword v240, v[148:149], off offset:576
	global_load_dwordx4 v[244:247], v[190:191], off
	v_lshl_add_u64 v[192:193], v[192:193], 0, v[146:147]
	global_load_dwordx4 v[248:251], v[192:193], off
	s_and_b64 vcc, exec, s[44:45]
	s_mov_b32 s74, s38
	s_mov_b32 s48, s40
	s_mov_b64 s[52:53], s[46:47]
	s_mov_b64 s[50:51], s[42:43]
	s_waitcnt vmcnt(15)
; __device__ __forceinline__ unsigned cvt_pk_bf16(float lo, float hi) { unsigned r; asm volatile("v_cvt_pk_bf16_f32 %0, %1, %2" : "=v"(r) : "v"(lo), "v"(hi)); return r; }
; __device__ __forceinline__ float bflo(unsigned w) { return __uint_as_float(w << 16); }
; __device__ __forceinline__ float bfhi(unsigned w) { return __uint_as_float(w & 0xffff0000u); }
; __device__ __forceinline__ unsigned dpp_ror8(unsigned x) { return (unsigned)__builtin_amdgcn_update_dpp(0, (int)x, 0x128, 0xf, 0xf, false); }
;     ...
;     const u32x4 s1 = {dpp_ror8(l1.x), dpp_ror8(l1.y), dpp_ror8(l1.z), dpp_ror8(l1.w)}, s2 = {dpp_ror8(l2.x), dpp_ror8(l2.y), dpp_ror8(l2.z), dpp_ror8(l2.w)};
;     wA = lo ? l1 : s2; wB = lo ? s1 : l2;
;     __device__ __forceinline__ void operator()(const f32x4 (&acc)[2][2][4][2], const Unit& u, int wr, int wc, int fr, int fq) const {
;     ...
;                 const float sc = rsin ? __builtin_amdgcn_rcpf(rsin[row] * (1.f / D) + EPS) : 1.0f;
;                 u32x4 rr[2]; if (R) load_pair_lines(R, D, row, fr, col0, rr[0], rr[1]);
; #pragma unroll
;                 for (int bj = 0; bj < 2; ++bj) { f32x4 r0, r1;
;                     if (R) { const u32x4 rw = rr[bj]; r0 = (f32x4){bflo(rw.x), bfhi(rw.x), bflo(rw.y), bfhi(rw.y)}; r1 = (f32x4){bflo(rw.z), bfhi(rw.z), bflo(rw.w), bfhi(rw.w)}; }
;                     else { const float* rp = (row < 8192 ? src_p + off : src_s + (off - (size_t)8192 * D)) + 8 * bj; r0 = *(const f32x4*)rp; r1 = *(const f32x4*)(rp + 4); }
;                     const f32x4 o0 = r0 + acc[ai][bj][m][0] * sc, o1 = r1 + acc[ai][bj][m][1] * sc;
;                     sq += (o0[0] * o0[0] + o0[1] * o0[1]) + (o0[2] * o0[2] + o0[3] * o0[3]) + (o1[0] * o1[0] + o1[1] * o1[1]) + (o1[2] * o1[2] + o1[3] * o1[3]);
;                     w[bj].x = cvt_pk_bf16(o0[0], o0[1]); w[bj].y = cvt_pk_bf16(o0[2], o0[3]); w[bj].z = cvt_pk_bf16(o1[0], o1[1]); w[bj].w = cvt_pk_bf16(o1[2], o1[3]); }
;                 store_pair_lines(O, D, row, fr, col0, w[0], w[1]);
	v_fmamk_f32 v151, v151, 0x3a000000, v159
	v_rcp_f32_e32 v172, v151
	v_mov_b32_dpp v173, v160 row_ror:8 row_mask:0xf bank_mask:0xf
	v_mov_b32_dpp v174, v161 row_ror:8 row_mask:0xf bank_mask:0xf
	v_mov_b32_dpp v175, v162 row_ror:8 row_mask:0xf bank_mask:0xf
	v_mov_b32_dpp v177, v164 row_ror:8 row_mask:0xf bank_mask:0xf
	v_mov_b32_dpp v178, v165 row_ror:8 row_mask:0xf bank_mask:0xf
	v_mov_b32_dpp v179, v166 row_ror:8 row_mask:0xf bank_mask:0xf
	v_mov_b32_dpp v176, v163 row_ror:8 row_mask:0xf bank_mask:0xf
	v_mov_b32_dpp v180, v167 row_ror:8 row_mask:0xf bank_mask:0xf
	v_cndmask_b32_e64 v166, v166, v175, s[6:7]
	v_cndmask_b32_e64 v165, v165, v174, s[6:7]
	v_cndmask_b32_e64 v164, v164, v173, s[6:7]
	v_cndmask_b32_e64 v179, v179, v162, s[6:7]
	v_cndmask_b32_e64 v178, v178, v161, s[6:7]
	v_cndmask_b32_e64 v175, v177, v160, s[6:7]
	v_cndmask_b32_e64 v151, v167, v176, s[6:7]
	v_cndmask_b32_e64 v173, v180, v163, s[6:7]
	v_lshlrev_b32_e32 v160, 16, v164
	v_and_b32_e32 v161, 0xffff0000, v164
	v_lshlrev_b32_e32 v162, 16, v165
	v_and_b32_e32 v163, 0xffff0000, v165
	v_lshlrev_b32_e32 v174, 16, v175
	v_and_b32_e32 v175, 0xffff0000, v175
	v_lshlrev_b32_e32 v176, 16, v178
	v_and_b32_e32 v177, 0xffff0000, v178
	v_lshlrev_b32_e32 v178, 16, v179
	v_and_b32_e32 v179, 0xffff0000, v179
	v_lshlrev_b32_e32 v164, 16, v166
	v_and_b32_e32 v165, 0xffff0000, v166
	v_lshlrev_b32_e32 v166, 16, v151
	v_and_b32_e32 v167, 0xffff0000, v151
	v_lshlrev_b32_e32 v180, 16, v173
	v_and_b32_e32 v181, 0xffff0000, v173
	v_pk_fma_f32 v[118:119], v[118:119], v[172:173], v[162:163] op_sel_hi:[1,0,1]
	v_pk_fma_f32 v[116:117], v[116:117], v[172:173], v[160:161] op_sel_hi:[1,0,1]
	v_pk_fma_f32 v[124:125], v[124:125], v[172:173], v[174:175] op_sel_hi:[1,0,1]
	v_pk_fma_f32 v[120:121], v[120:121], v[172:173], v[178:179] op_sel_hi:[1,0,1]
	v_pk_fma_f32 v[114:115], v[114:115], v[172:173], v[166:167] op_sel_hi:[1,0,1]
	v_pk_fma_f32 v[112:113], v[112:113], v[172:173], v[164:165] op_sel_hi:[1,0,1]
	v_pk_fma_f32 v[126:127], v[126:127], v[172:173], v[176:177] op_sel_hi:[1,0,1]
	v_pk_fma_f32 v[122:123], v[122:123], v[172:173], v[180:181] op_sel_hi:[1,0,1]
	v_cvt_pk_bf16_f32 v124, v124, v125
	v_cvt_pk_bf16_f32 v125, v126, v127
	v_cvt_pk_bf16_f32 v120, v120, v121
	v_cvt_pk_bf16_f32 v121, v122, v123
	v_cvt_pk_bf16_f32 v116, v116, v117
	v_cvt_pk_bf16_f32 v117, v118, v119
	v_cvt_pk_bf16_f32 v118, v112, v113
	v_cvt_pk_bf16_f32 v119, v114, v115
	s_nop 0
	v_mov_b32_dpp v184, v120 row_ror:8 row_mask:0xf bank_mask:0xf
	v_mov_b32_dpp v185, v121 row_ror:8 row_mask:0xf bank_mask:0xf
	v_mov_b32_dpp v188, v118 row_ror:8 row_mask:0xf bank_mask:0xf
	v_mov_b32_dpp v189, v119 row_ror:8 row_mask:0xf bank_mask:0xf
	v_mov_b32_dpp v186, v116 row_ror:8 row_mask:0xf bank_mask:0xf
	v_mov_b32_dpp v187, v117 row_ror:8 row_mask:0xf bank_mask:0xf
	v_cndmask_b32_e64 v114, v188, v120, s[6:7]
	v_cndmask_b32_e64 v115, v189, v121, s[6:7]
	v_lshl_add_u64 v[120:121], s[8:9], 0, v[168:169]
	v_cndmask_b32_e64 v112, v186, v124, s[6:7]
	v_cndmask_b32_e64 v113, v187, v125, s[6:7]
	v_lshl_add_u64 v[120:121], v[120:121], 0, v[146:147]
	v_mov_b32_dpp v182, v124 row_ror:8 row_mask:0xf bank_mask:0xf
	v_mov_b32_dpp v183, v125 row_ror:8 row_mask:0xf bank_mask:0xf
	global_store_dwordx4 v[120:121], v[112:115], off
	v_cndmask_b32_e64 v116, v116, v182, s[6:7]
	v_cndmask_b32_e64 v117, v117, v183, s[6:7]
	v_lshl_add_u64 v[112:113], s[8:9], 0, v[170:171]
	v_cndmask_b32_e64 v118, v118, v184, s[6:7]
	v_cndmask_b32_e64 v119, v119, v185, s[6:7]
	v_lshl_add_u64 v[112:113], v[112:113], 0, v[146:147]
	global_store_dwordx4 v[112:113], v[116:119], off
	v_or_b32_e32 v112, 16, v150
	v_ashrrev_i32_e32 v113, 31, v112
	v_lshl_add_u64 v[114:115], v[112:113], 2, s[10:11]
	v_sub_u32_e32 v112, v112, v152
	v_add_u32_e32 v112, v112, v154
	v_ashrrev_i32_e32 v113, 31, v112
	v_lshlrev_b64 v[120:121], 12, v[112:113]
	v_lshl_add_u64 v[112:113], s[16:17], 0, v[120:121]
	v_lshl_add_u64 v[122:123], v[120:121], 0, s[36:37]
	v_lshl_add_u64 v[112:113], v[112:113], 0, v[146:147]
	v_lshl_add_u64 v[116:117], s[16:17], 0, v[122:123]
	s_waitcnt vmcnt(14)
	s_nop 0
	v_mov_b32_e32 v124, v204
	s_nop 0
	v_mov_b64_e32 v[112:113], v[208:209]
	v_mov_b64_e32 v[114:115], v[210:211]
	v_lshl_add_u64 v[116:117], v[116:117], 0, v[146:147]
	v_mov_b64_e32 v[116:117], v[212:213]
	v_mov_b64_e32 v[118:119], v[214:215]
	s_nop 1
	v_sub_u32_e32 v198, v150, v152
	v_add_u32_e32 v201, v198, v154
	v_add_u32_e32 v190, 0xa0, v201
	v_ashrrev_i32_e32 v191, 31, v190
	v_lshlrev_b64 v[194:195], 12, v[190:191]
	v_lshl_add_u64 v[196:197], v[194:195], 0, s[36:37]
	global_load_dword v204, v[148:149], off offset:640
	v_lshl_add_u64 v[190:191], s[16:17], 0, v[194:195]
	v_lshl_add_u64 v[192:193], s[16:17], 0, v[196:197]
	v_lshl_add_u64 v[190:191], v[190:191], 0, v[146:147]
	v_lshl_add_u64 v[192:193], v[192:193], 0, v[146:147]
	global_load_dwordx4 v[208:211], v[190:191], off
	global_load_dwordx4 v[212:215], v[192:193], off
	v_fmamk_f32 v124, v124, 0x3a000000, v159
	v_rcp_f32_e32 v124, v124
	v_mov_b32_dpp v125, v112 row_ror:8 row_mask:0xf bank_mask:0xf
	v_mov_b32_dpp v126, v113 row_ror:8 row_mask:0xf bank_mask:0xf
	v_mov_b32_dpp v127, v114 row_ror:8 row_mask:0xf bank_mask:0xf
	v_mov_b32_dpp v151, v115 row_ror:8 row_mask:0xf bank_mask:0xf
	v_mov_b32_dpp v160, v116 row_ror:8 row_mask:0xf bank_mask:0xf
	v_mov_b32_dpp v161, v117 row_ror:8 row_mask:0xf bank_mask:0xf
	v_mov_b32_dpp v162, v118 row_ror:8 row_mask:0xf bank_mask:0xf
	v_mov_b32_dpp v163, v119 row_ror:8 row_mask:0xf bank_mask:0xf
	v_cndmask_b32_e64 v163, v163, v115, s[6:7]
	v_cndmask_b32_e64 v162, v162, v114, s[6:7]
	v_cndmask_b32_e64 v115, v161, v113, s[6:7]
; __device__ __forceinline__ unsigned cvt_pk_bf16(float lo, float hi) { unsigned r; asm volatile("v_cvt_pk_bf16_f32 %0, %1, %2" : "=v"(r) : "v"(lo), "v"(hi)); return r; }
; __device__ __forceinline__ float bflo(unsigned w) { return __uint_as_float(w << 16); }
; __device__ __forceinline__ float bfhi(unsigned w) { return __uint_as_float(w & 0xffff0000u); }
; __device__ __forceinline__ unsigned dpp_ror8(unsigned x) { return (unsigned)__builtin_amdgcn_update_dpp(0, (int)x, 0x128, 0xf, 0xf, false); }
;     const bool lo = fr < 8;
;     const int r1 = row - fr + (fr & 7), cb = col0 + (lo ? 0 : boff);
;     const u32x4 l1 = *(const u32x4*)(P + (size_t)r1 * ld + cb), l2 = *(const u32x4*)(P + (size_t)(r1 + 8) * ld + cb);
;     const u32x4 s1 = {dpp_ror8(l1.x), dpp_ror8(l1.y), dpp_ror8(l1.z), dpp_ror8(l1.w)}, s2 = {dpp_ror8(l2.x), dpp_ror8(l2.y), dpp_ror8(l2.z), dpp_ror8(l2.w)};
;     wA = lo ? l1 : s2; wB = lo ? s1 : l2;
; }
;     __device__ __forceinline__ void operator()(const f32x4 (&acc)[2][2][4][2], const Unit& u, int wr, int wc, int fr, int fq) const {
;     ...
;                 const float sc = rsin ? __builtin_amdgcn_rcpf(rsin[row] * (1.f / D) + EPS) : 1.0f;
;                 u32x4 rr[2]; if (R) load_pair_lines(R, D, row, fr, col0, rr[0], rr[1]);
; #pragma unroll
;                 for (int bj = 0; bj < 2; ++bj) { f32x4 r0, r1;
;                     if (R) { const u32x4 rw = rr[bj]; r0 = (f32x4){bflo(rw.x), bfhi(rw.x), bflo(rw.y), bfhi(rw.y)}; r1 = (f32x4){bflo(rw.z), bfhi(rw.z), bflo(rw.w), bfhi(rw.w)}; }
;                     else { const float* rp = (row < 8192 ? src_p + off : src_s + (off - (size_t)8192 * D)) + 8 * bj; r0 = *(const f32x4*)rp; r1 = *(const f32x4*)(rp + 4); }
;                     const f32x4 o0 = r0 + acc[ai][bj][m][0] * sc, o1 = r1 + acc[ai][bj][m][1] * sc;
;                     sq += (o0[0] * o0[0] + o0[1] * o0[1]) + (o0[2] * o0[2] + o0[3] * o0[3]) + (o1[0] * o1[0] + o1[1] * o1[1]) + (o1[2] * o1[2] + o1[3] * o1[3]);
;                     w[bj].x = cvt_pk_bf16(o0[0], o0[1]); w[bj].y = cvt_pk_bf16(o0[2], o0[3]); w[bj].z = cvt_pk_bf16(o1[0], o1[1]); w[bj].w = cvt_pk_bf16(o1[2], o1[3]); }
;                 store_pair_lines(O, D, row, fr, col0, w[0], w[1]);
	v_cndmask_b32_e64 v113, v160, v112, s[6:7]
	v_cndmask_b32_e64 v151, v119, v151, s[6:7]
	v_cndmask_b32_e64 v164, v118, v127, s[6:7]
	v_cndmask_b32_e64 v161, v117, v126, s[6:7]
	v_cndmask_b32_e64 v125, v116, v125, s[6:7]
	v_lshlrev_b32_e32 v112, 16, v113
	v_and_b32_e32 v113, 0xffff0000, v113
	v_lshlrev_b32_e32 v116, 16, v162
	v_and_b32_e32 v117, 0xffff0000, v162
	v_lshlrev_b32_e32 v118, 16, v163
	v_and_b32_e32 v119, 0xffff0000, v163
	v_lshlrev_b32_e32 v126, 16, v125
	v_and_b32_e32 v127, 0xffff0000, v125
	v_lshlrev_b32_e32 v160, 16, v161
	v_and_b32_e32 v161, 0xffff0000, v161
	v_lshlrev_b32_e32 v162, 16, v164
	v_and_b32_e32 v163, 0xffff0000, v164
	v_lshlrev_b32_e32 v164, 16, v151
	v_and_b32_e32 v165, 0xffff0000, v151
	v_lshlrev_b32_e32 v114, 16, v115
	v_and_b32_e32 v115, 0xffff0000, v115
	v_pk_fma_f32 v[108:109], v[108:109], v[124:125], v[112:113] op_sel_hi:[1,0,1]
	v_pk_fma_f32 v[104:105], v[104:105], v[124:125], v[116:117] op_sel_hi:[1,0,1]
	v_pk_fma_f32 v[102:103], v[102:103], v[124:125], v[160:161] op_sel_hi:[1,0,1]
	v_pk_fma_f32 v[100:101], v[100:101], v[124:125], v[126:127] op_sel_hi:[1,0,1]
	v_pk_fma_f32 v[98:99], v[98:99], v[124:125], v[164:165] op_sel_hi:[1,0,1]
	v_pk_fma_f32 v[110:111], v[110:111], v[124:125], v[114:115] op_sel_hi:[1,0,1]
	v_pk_fma_f32 v[106:107], v[106:107], v[124:125], v[118:119] op_sel_hi:[1,0,1]
	v_pk_fma_f32 v[96:97], v[96:97], v[124:125], v[162:163] op_sel_hi:[1,0,1]
	v_cvt_pk_bf16_f32 v108, v108, v109
	v_cvt_pk_bf16_f32 v109, v110, v111
	v_cvt_pk_bf16_f32 v104, v104, v105
	v_cvt_pk_bf16_f32 v105, v106, v107
	v_cvt_pk_bf16_f32 v100, v100, v101
	v_cvt_pk_bf16_f32 v101, v102, v103
	s_nop 0
	v_cvt_pk_bf16_f32 v102, v96, v97
	v_cvt_pk_bf16_f32 v103, v98, v99
	v_mov_b32_e32 v98, 0
	v_mov_b32_dpp v98, v102 row_ror:8 row_mask:0xf bank_mask:0xf
	v_mov_b32_dpp v99, v103 row_ror:8 row_mask:0xf bank_mask:0xf
	v_mov_b32_dpp v107, v104 row_ror:8 row_mask:0xf bank_mask:0xf
	v_mov_b32_dpp v110, v105 row_ror:8 row_mask:0xf bank_mask:0xf
	v_mov_b32_dpp v96, v100 row_ror:8 row_mask:0xf bank_mask:0xf
	v_mov_b32_dpp v97, v101 row_ror:8 row_mask:0xf bank_mask:0xf
	v_cndmask_b32_e64 v98, v98, v104, s[6:7]
	v_cndmask_b32_e64 v99, v99, v105, s[6:7]
	v_lshl_add_u64 v[104:105], s[8:9], 0, v[120:121]
	v_cndmask_b32_e64 v96, v96, v108, s[6:7]
	v_cndmask_b32_e64 v97, v97, v109, s[6:7]
	v_lshl_add_u64 v[104:105], v[104:105], 0, v[146:147]
	v_mov_b32_dpp v166, v108 row_ror:8 row_mask:0xf bank_mask:0xf
	v_mov_b32_dpp v106, v109 row_ror:8 row_mask:0xf bank_mask:0xf
	global_store_dwordx4 v[104:105], v[96:99], off
	v_cndmask_b32_e64 v100, v100, v166, s[6:7]
	v_cndmask_b32_e64 v101, v101, v106, s[6:7]
	v_lshl_add_u64 v[96:97], s[8:9], 0, v[122:123]
	v_cndmask_b32_e64 v102, v102, v107, s[6:7]
	v_cndmask_b32_e64 v103, v103, v110, s[6:7]
	v_lshl_add_u64 v[96:97], v[96:97], 0, v[146:147]
	global_store_dwordx4 v[96:97], v[100:103], off
	v_or_b32_e32 v96, 32, v150
	v_ashrrev_i32_e32 v97, 31, v96
	v_lshl_add_u64 v[98:99], v[96:97], 2, s[10:11]
	v_sub_u32_e32 v96, v96, v152
	v_add_u32_e32 v96, v96, v154
	v_ashrrev_i32_e32 v97, 31, v96
	v_lshlrev_b64 v[104:105], 12, v[96:97]
	v_lshl_add_u64 v[96:97], s[16:17], 0, v[104:105]
	v_lshl_add_u64 v[106:107], v[104:105], 0, s[36:37]
	v_lshl_add_u64 v[96:97], v[96:97], 0, v[146:147]
	v_lshl_add_u64 v[100:101], s[16:17], 0, v[106:107]
	s_waitcnt vmcnt(16)
	s_nop 0
	v_mov_b32_e32 v108, v205
	s_nop 0
	v_mov_b64_e32 v[96:97], v[216:217]
	v_mov_b64_e32 v[98:99], v[218:219]
	v_lshl_add_u64 v[100:101], v[100:101], 0, v[146:147]
	v_mov_b64_e32 v[100:101], v[220:221]
	v_mov_b64_e32 v[102:103], v[222:223]
	s_nop 1
	v_sub_u32_e32 v198, v150, v152
	v_add_u32_e32 v201, v198, v154
	v_add_u32_e32 v190, 0xb0, v201
	v_ashrrev_i32_e32 v191, 31, v190
	v_lshlrev_b64 v[194:195], 12, v[190:191]
	v_lshl_add_u64 v[196:197], v[194:195], 0, s[36:37]
	global_load_dword v205, v[148:149], off offset:704
	v_lshl_add_u64 v[190:191], s[16:17], 0, v[194:195]
	v_lshl_add_u64 v[192:193], s[16:17], 0, v[196:197]
	v_lshl_add_u64 v[190:191], v[190:191], 0, v[146:147]
	v_lshl_add_u64 v[192:193], v[192:193], 0, v[146:147]
	global_load_dwordx4 v[216:219], v[190:191], off
	global_load_dwordx4 v[220:223], v[192:193], off
	v_fmamk_f32 v108, v108, 0x3a000000, v159
	v_rcp_f32_e32 v108, v108
	v_mov_b32_dpp v109, v96 row_ror:8 row_mask:0xf bank_mask:0xf
	v_mov_b32_dpp v113, v100 row_ror:8 row_mask:0xf bank_mask:0xf
	v_mov_b32_dpp v114, v101 row_ror:8 row_mask:0xf bank_mask:0xf
	v_mov_b32_dpp v115, v102 row_ror:8 row_mask:0xf bank_mask:0xf
	v_mov_b32_dpp v116, v103 row_ror:8 row_mask:0xf bank_mask:0xf
	v_mov_b32_dpp v110, v97 row_ror:8 row_mask:0xf bank_mask:0xf
	v_mov_b32_dpp v111, v98 row_ror:8 row_mask:0xf bank_mask:0xf
	v_mov_b32_dpp v112, v99 row_ror:8 row_mask:0xf bank_mask:0xf
	v_cndmask_b32_e64 v116, v116, v99, s[6:7]
	v_cndmask_b32_e64 v115, v115, v98, s[6:7]
	v_cndmask_b32_e64 v99, v114, v97, s[6:7]
	v_cndmask_b32_e64 v97, v113, v96, s[6:7]
	v_cndmask_b32_e64 v114, v103, v112, s[6:7]
	v_cndmask_b32_e64 v117, v102, v111, s[6:7]
	v_cndmask_b32_e64 v113, v101, v110, s[6:7]
	v_cndmask_b32_e64 v109, v100, v109, s[6:7]
	v_lshlrev_b32_e32 v96, 16, v97
	v_and_b32_e32 v97, 0xffff0000, v97
	v_lshlrev_b32_e32 v98, 16, v99
	v_and_b32_e32 v99, 0xffff0000, v99
	v_lshlrev_b32_e32 v100, 16, v115
	v_and_b32_e32 v101, 0xffff0000, v115
	v_lshlrev_b32_e32 v102, 16, v116
	v_and_b32_e32 v103, 0xffff0000, v116
	v_pk_fma_f32 v[94:95], v[94:95], v[108:109], v[98:99] op_sel_hi:[1,0,1]
	v_pk_fma_f32 v[92:93], v[92:93], v[108:109], v[96:97] op_sel_hi:[1,0,1]
	v_pk_fma_f32 v[90:91], v[90:91], v[108:109], v[102:103] op_sel_hi:[1,0,1]
	v_pk_fma_f32 v[88:89], v[88:89], v[108:109], v[100:101] op_sel_hi:[1,0,1]
; __device__ __forceinline__ unsigned cvt_pk_bf16(float lo, float hi) { unsigned r; asm volatile("v_cvt_pk_bf16_f32 %0, %1, %2" : "=v"(r) : "v"(lo), "v"(hi)); return r; }
; __device__ __forceinline__ float bflo(unsigned w) { return __uint_as_float(w << 16); }
; __device__ __forceinline__ float bfhi(unsigned w) { return __uint_as_float(w & 0xffff0000u); }
; __device__ __forceinline__ unsigned dpp_ror8(unsigned x) { return (unsigned)__builtin_amdgcn_update_dpp(0, (int)x, 0x128, 0xf, 0xf, false); }
;     const bool lo = fr < 8;
;     const int r1 = row - fr + (fr & 7), cb = col0 + (lo ? 0 : boff);
;     const u32x4 l1 = *(const u32x4*)(P + (size_t)r1 * ld + cb), l2 = *(const u32x4*)(P + (size_t)(r1 + 8) * ld + cb);
;     const u32x4 s1 = {dpp_ror8(l1.x), dpp_ror8(l1.y), dpp_ror8(l1.z), dpp_ror8(l1.w)}, s2 = {dpp_ror8(l2.x), dpp_ror8(l2.y), dpp_ror8(l2.z), dpp_ror8(l2.w)};
;     wA = lo ? l1 : s2; wB = lo ? s1 : l2;
; }
;     __device__ __forceinline__ void operator()(const f32x4 (&acc)[2][2][4][2], const Unit& u, int wr, int wc, int fr, int fq) const {
;     ...
;                 const float sc = rsin ? __builtin_amdgcn_rcpf(rsin[row] * (1.f / D) + EPS) : 1.0f;
;                 u32x4 rr[2]; if (R) load_pair_lines(R, D, row, fr, col0, rr[0], rr[1]);
; #pragma unroll
;                 for (int bj = 0; bj < 2; ++bj) { f32x4 r0, r1;
;                     if (R) { const u32x4 rw = rr[bj]; r0 = (f32x4){bflo(rw.x), bfhi(rw.x), bflo(rw.y), bfhi(rw.y)}; r1 = (f32x4){bflo(rw.z), bfhi(rw.z), bflo(rw.w), bfhi(rw.w)}; }
;                     else { const float* rp = (row < 8192 ? src_p + off : src_s + (off - (size_t)8192 * D)) + 8 * bj; r0 = *(const f32x4*)rp; r1 = *(const f32x4*)(rp + 4); }
;                     const f32x4 o0 = r0 + acc[ai][bj][m][0] * sc, o1 = r1 + acc[ai][bj][m][1] * sc;
;                     sq += (o0[0] * o0[0] + o0[1] * o0[1]) + (o0[2] * o0[2] + o0[3] * o0[3]) + (o1[0] * o1[0] + o1[1] * o1[1]) + (o1[2] * o1[2] + o1[3] * o1[3]);
;                     w[bj].x = cvt_pk_bf16(o0[0], o0[1]); w[bj].y = cvt_pk_bf16(o0[2], o0[3]); w[bj].z = cvt_pk_bf16(o1[0], o1[1]); w[bj].w = cvt_pk_bf16(o1[2], o1[3]); }
;                 store_pair_lines(O, D, row, fr, col0, w[0], w[1]);
	v_lshlrev_b32_e32 v110, 16, v109
	v_and_b32_e32 v111, 0xffff0000, v109
	v_lshlrev_b32_e32 v112, 16, v113
	v_and_b32_e32 v113, 0xffff0000, v113
	v_cvt_pk_bf16_f32 v92, v92, v93
	v_cvt_pk_bf16_f32 v93, v94, v95
	v_cvt_pk_bf16_f32 v94, v88, v89
	v_cvt_pk_bf16_f32 v95, v90, v91
	v_lshlrev_b32_e32 v88, 16, v117
	v_and_b32_e32 v89, 0xffff0000, v117
	v_lshlrev_b32_e32 v90, 16, v114
	v_and_b32_e32 v91, 0xffff0000, v114
	v_pk_fma_f32 v[86:87], v[86:87], v[108:109], v[112:113] op_sel_hi:[1,0,1]
	v_pk_fma_f32 v[84:85], v[84:85], v[108:109], v[110:111] op_sel_hi:[1,0,1]
	v_pk_fma_f32 v[82:83], v[82:83], v[108:109], v[90:91] op_sel_hi:[1,0,1]
	v_pk_fma_f32 v[80:81], v[80:81], v[108:109], v[88:89] op_sel_hi:[1,0,1]
	v_cvt_pk_bf16_f32 v84, v84, v85
	v_cvt_pk_bf16_f32 v85, v86, v87
	v_cvt_pk_bf16_f32 v86, v80, v81
	v_cvt_pk_bf16_f32 v87, v82, v83
	s_nop 0
	v_mov_b32_dpp v88, v92 row_ror:8 row_mask:0xf bank_mask:0xf
	v_mov_b32_dpp v89, v93 row_ror:8 row_mask:0xf bank_mask:0xf
	v_mov_b32_dpp v80, v84 row_ror:8 row_mask:0xf bank_mask:0xf
	v_mov_b32_dpp v81, v85 row_ror:8 row_mask:0xf bank_mask:0xf
	v_mov_b32_dpp v82, v86 row_ror:8 row_mask:0xf bank_mask:0xf
	v_mov_b32_dpp v83, v87 row_ror:8 row_mask:0xf bank_mask:0xf
	v_cndmask_b32_e64 v84, v84, v88, s[6:7]
	v_cndmask_b32_e64 v85, v85, v89, s[6:7]
	v_lshl_add_u64 v[88:89], s[8:9], 0, v[104:105]
	v_cndmask_b32_e64 v80, v80, v92, s[6:7]
	v_cndmask_b32_e64 v81, v81, v93, s[6:7]
	v_cndmask_b32_e64 v82, v82, v94, s[6:7]
	v_cndmask_b32_e64 v83, v83, v95, s[6:7]
	v_lshl_add_u64 v[88:89], v[88:89], 0, v[146:147]
	v_mov_b32_dpp v90, v94 row_ror:8 row_mask:0xf bank_mask:0xf
	v_mov_b32_dpp v91, v95 row_ror:8 row_mask:0xf bank_mask:0xf
	global_store_dwordx4 v[88:89], v[80:83], off
	v_cndmask_b32_e64 v86, v86, v90, s[6:7]
	v_cndmask_b32_e64 v87, v87, v91, s[6:7]
	v_lshl_add_u64 v[80:81], s[8:9], 0, v[106:107]
	v_lshl_add_u64 v[80:81], v[80:81], 0, v[146:147]
	global_store_dwordx4 v[80:81], v[84:87], off
	v_or_b32_e32 v80, 48, v150
	v_ashrrev_i32_e32 v81, 31, v80
	v_lshl_add_u64 v[82:83], v[80:81], 2, s[10:11]
	v_sub_u32_e32 v80, v80, v152
	v_add_u32_e32 v80, v80, v154
	v_ashrrev_i32_e32 v81, 31, v80
	v_lshlrev_b64 v[88:89], 12, v[80:81]
	v_lshl_add_u64 v[80:81], s[16:17], 0, v[88:89]
	v_lshl_add_u64 v[90:91], v[88:89], 0, s[36:37]
	v_lshl_add_u64 v[80:81], v[80:81], 0, v[146:147]
	v_lshl_add_u64 v[84:85], s[16:17], 0, v[90:91]
	s_waitcnt vmcnt(18)
	s_nop 0
	v_mov_b32_e32 v92, v206
	s_nop 0
	v_mov_b64_e32 v[80:81], v[224:225]
	v_mov_b64_e32 v[82:83], v[226:227]
	v_lshl_add_u64 v[84:85], v[84:85], 0, v[146:147]
	v_mov_b64_e32 v[84:85], v[228:229]
	v_mov_b64_e32 v[86:87], v[230:231]
	s_nop 1
	v_fmamk_f32 v92, v92, 0x3a000000, v159
	v_rcp_f32_e32 v92, v92
	v_mov_b32_dpp v93, v80 row_ror:8 row_mask:0xf bank_mask:0xf
	v_mov_b32_dpp v97, v84 row_ror:8 row_mask:0xf bank_mask:0xf
	v_mov_b32_dpp v98, v85 row_ror:8 row_mask:0xf bank_mask:0xf
	v_mov_b32_dpp v99, v86 row_ror:8 row_mask:0xf bank_mask:0xf
	v_mov_b32_dpp v100, v87 row_ror:8 row_mask:0xf bank_mask:0xf
	v_mov_b32_dpp v94, v81 row_ror:8 row_mask:0xf bank_mask:0xf
	v_mov_b32_dpp v95, v82 row_ror:8 row_mask:0xf bank_mask:0xf
	v_mov_b32_dpp v96, v83 row_ror:8 row_mask:0xf bank_mask:0xf
	v_cndmask_b32_e64 v100, v100, v83, s[6:7]
	v_cndmask_b32_e64 v99, v99, v82, s[6:7]
	v_cndmask_b32_e64 v83, v98, v81, s[6:7]
	v_cndmask_b32_e64 v81, v97, v80, s[6:7]
	v_cndmask_b32_e64 v96, v87, v96, s[6:7]
	v_cndmask_b32_e64 v95, v86, v95, s[6:7]
	v_cndmask_b32_e64 v94, v85, v94, s[6:7]
	v_cndmask_b32_e64 v93, v84, v93, s[6:7]
	v_lshlrev_b32_e32 v80, 16, v81
	v_and_b32_e32 v81, 0xffff0000, v81
	v_lshlrev_b32_e32 v82, 16, v83
	v_and_b32_e32 v83, 0xffff0000, v83
	v_lshlrev_b32_e32 v84, 16, v99
	v_and_b32_e32 v85, 0xffff0000, v99
	v_lshlrev_b32_e32 v86, 16, v100
	v_and_b32_e32 v87, 0xffff0000, v100
	v_pk_fma_f32 v[78:79], v[78:79], v[92:93], v[82:83] op_sel_hi:[1,0,1]
	v_pk_fma_f32 v[76:77], v[76:77], v[92:93], v[80:81] op_sel_hi:[1,0,1]
	v_pk_fma_f32 v[74:75], v[74:75], v[92:93], v[86:87] op_sel_hi:[1,0,1]
	v_pk_fma_f32 v[72:73], v[72:73], v[92:93], v[84:85] op_sel_hi:[1,0,1]
	v_cvt_pk_bf16_f32 v80, v76, v77
	v_cvt_pk_bf16_f32 v81, v78, v79
	v_lshlrev_b32_e32 v76, 16, v95
	v_cvt_pk_bf16_f32 v82, v72, v73
	v_cvt_pk_bf16_f32 v83, v74, v75
	v_lshlrev_b32_e32 v72, 16, v93
	v_and_b32_e32 v73, 0xffff0000, v93
	v_lshlrev_b32_e32 v74, 16, v94
	v_and_b32_e32 v75, 0xffff0000, v94
	v_and_b32_e32 v77, 0xffff0000, v95
	v_lshlrev_b32_e32 v78, 16, v96
	v_and_b32_e32 v79, 0xffff0000, v96
	v_pk_fma_f32 v[70:71], v[70:71], v[92:93], v[74:75] op_sel_hi:[1,0,1]
	v_pk_fma_f32 v[68:69], v[68:69], v[92:93], v[72:73] op_sel_hi:[1,0,1]
	v_pk_fma_f32 v[66:67], v[66:67], v[92:93], v[78:79] op_sel_hi:[1,0,1]
	v_pk_fma_f32 v[64:65], v[64:65], v[92:93], v[76:77] op_sel_hi:[1,0,1]
	v_cvt_pk_bf16_f32 v68, v68, v69
	v_cvt_pk_bf16_f32 v69, v70, v71
	v_cvt_pk_bf16_f32 v70, v64, v65
	v_cvt_pk_bf16_f32 v71, v66, v67
	s_nop 0
	v_mov_b32_dpp v72, v80 row_ror:8 row_mask:0xf bank_mask:0xf
	v_mov_b32_dpp v73, v81 row_ror:8 row_mask:0xf bank_mask:0xf
	v_mov_b32_dpp v64, v68 row_ror:8 row_mask:0xf bank_mask:0xf
	v_mov_b32_dpp v65, v69 row_ror:8 row_mask:0xf bank_mask:0xf
	v_mov_b32_dpp v66, v70 row_ror:8 row_mask:0xf bank_mask:0xf
	v_mov_b32_dpp v67, v71 row_ror:8 row_mask:0xf bank_mask:0xf
	v_cndmask_b32_e64 v68, v68, v72, s[6:7]
	v_cndmask_b32_e64 v69, v69, v73, s[6:7]
	v_lshl_add_u64 v[72:73], s[8:9], 0, v[88:89]
	v_cndmask_b32_e64 v64, v64, v80, s[6:7]
	v_cndmask_b32_e64 v65, v65, v81, s[6:7]
	v_cndmask_b32_e64 v66, v66, v82, s[6:7]
	v_cndmask_b32_e64 v67, v67, v83, s[6:7]
	v_lshl_add_u64 v[72:73], v[72:73], 0, v[146:147]
	v_mov_b32_dpp v74, v82 row_ror:8 row_mask:0xf bank_mask:0xf
	v_mov_b32_dpp v75, v83 row_ror:8 row_mask:0xf bank_mask:0xf
	global_store_dwordx4 v[72:73], v[64:67], off
	v_cndmask_b32_e64 v70, v70, v74, s[6:7]
	v_cndmask_b32_e64 v71, v71, v75, s[6:7]
	v_lshl_add_u64 v[64:65], s[8:9], 0, v[90:91]
	v_lshl_add_u64 v[64:65], v[64:65], 0, v[146:147]
	global_store_dwordx4 v[64:65], v[68:71], off
	v_sub_u32_e32 v64, v150, v152
	v_add_u32_e32 v77, v64, v154
	v_add_u32_e32 v64, 0x80, v77
	v_ashrrev_i32_e32 v65, 31, v64
	v_lshlrev_b64 v[72:73], 12, v[64:65]
	v_lshl_add_u64 v[64:65], s[16:17], 0, v[72:73]
	v_lshl_add_u64 v[74:75], v[72:73], 0, s[36:37]
	v_lshl_add_u64 v[64:65], v[64:65], 0, v[146:147]
	v_lshl_add_u64 v[68:69], s[16:17], 0, v[74:75]
	s_waitcnt vmcnt(17)
; __device__ __forceinline__ void store_pair_lines(bf16_t* O, int ldc, int row, int fr, int col0, u32x4 wA, u32x4 wB) {
;     const u32x4 sA = {dpp_ror8(wA.x), dpp_ror8(wA.y), dpp_ror8(wA.z), dpp_ror8(wA.w)}, sB = {dpp_ror8(wB.x), dpp_ror8(wB.y), dpp_ror8(wB.z), dpp_ror8(wB.w)};
;     const bool lo = fr < 8;
;     const u32x4 o1 = lo ? wA : sB, o2 = lo ? sA : wB;
;     const int r1 = row - fr + (fr & 7), cb = col0 + (lo ? 0 : 8);
;     *(u32x4*)(O + (size_t)r1 * ldc + cb) = o1;
;     *(u32x4*)(O + (size_t)(r1 + 8) * ldc + cb) = o2;
; }
;     const bool lo = fr < 8;
;     const int r1 = row - fr + (fr & 7), cb = col0 + (lo ? 0 : boff);
;     const u32x4 l1 = *(const u32x4*)(P + (size_t)r1 * ld + cb), l2 = *(const u32x4*)(P + (size_t)(r1 + 8) * ld + cb);
;     __device__ __forceinline__ void operator()(const f32x4 (&acc)[2][2][4][2], const Unit& u, int wr, int wc, int fr, int fq) const {
;     ...
;             for (int m = 0; m < 4; ++m) { const int row = row0 + ai * HALF + m * 16; const size_t off = (size_t)row * D + col0; float sq = 0.f; u32x4 w[2];
;                 const float sc = rsin ? __builtin_amdgcn_rcpf(rsin[row] * (1.f / D) + EPS) : 1.0f;
;                 u32x4 rr[2]; if (R) load_pair_lines(R, D, row, fr, col0, rr[0], rr[1]);
; #pragma unroll
;                 for (int bj = 0; bj < 2; ++bj) { f32x4 r0, r1;
;                     if (R) { const u32x4 rw = rr[bj]; r0 = (f32x4){bflo(rw.x), bfhi(rw.x), bflo(rw.y), bfhi(rw.y)}; r1 = (f32x4){bflo(rw.z), bfhi(rw.z), bflo(rw.w), bfhi(rw.w)}; }
;                     else { const float* rp = (row < 8192 ? src_p + off : src_s + (off - (size_t)8192 * D)) + 8 * bj; r0 = *(const f32x4*)rp; r1 = *(const f32x4*)(rp + 4); }
;                     const f32x4 o0 = r0 + acc[ai][bj][m][0] * sc, o1 = r1 + acc[ai][bj][m][1] * sc;
;                     sq += (o0[0] * o0[0] + o0[1] * o0[1]) + (o0[2] * o0[2] + o0[3] * o0[3]) + (o1[0] * o1[0] + o1[1] * o1[1]) + (o1[2] * o1[2] + o1[3] * o1[3]);
;                     w[bj].x = cvt_pk_bf16(o0[0], o0[1]); w[bj].y = cvt_pk_bf16(o0[2], o0[3]); w[bj].z = cvt_pk_bf16(o1[0], o1[1]); w[bj].w = cvt_pk_bf16(o1[2], o1[3]); }
;                 store_pair_lines(O, D, row, fr, col0, w[0], w[1]);
;                 if (ssout) { sq += __shfl_xor(sq, 16); sq += __shfl_xor(sq, 32); if (fq == 0) unsafeAtomicAdd(ssout + row, sq); } }
	s_nop 0
	v_mov_b32_e32 v76, v207
	s_nop 0
	v_mov_b64_e32 v[64:65], v[232:233]
	v_mov_b64_e32 v[66:67], v[234:235]
	v_lshl_add_u64 v[68:69], v[68:69], 0, v[146:147]
	v_mov_b64_e32 v[68:69], v[236:237]
	v_mov_b64_e32 v[70:71], v[238:239]
	s_nop 1
	v_fmamk_f32 v76, v76, 0x3a000000, v159
	v_rcp_f32_e32 v76, v76
	v_mov_b32_dpp v78, v64 row_ror:8 row_mask:0xf bank_mask:0xf
	v_mov_b32_dpp v82, v68 row_ror:8 row_mask:0xf bank_mask:0xf
	v_mov_b32_dpp v83, v69 row_ror:8 row_mask:0xf bank_mask:0xf
	v_mov_b32_dpp v84, v70 row_ror:8 row_mask:0xf bank_mask:0xf
	v_mov_b32_dpp v85, v71 row_ror:8 row_mask:0xf bank_mask:0xf
	v_mov_b32_dpp v79, v65 row_ror:8 row_mask:0xf bank_mask:0xf
	v_mov_b32_dpp v80, v66 row_ror:8 row_mask:0xf bank_mask:0xf
	v_mov_b32_dpp v81, v67 row_ror:8 row_mask:0xf bank_mask:0xf
	v_cndmask_b32_e64 v85, v85, v67, s[6:7]
	v_cndmask_b32_e64 v84, v84, v66, s[6:7]
	v_cndmask_b32_e64 v67, v83, v65, s[6:7]
	v_cndmask_b32_e64 v65, v82, v64, s[6:7]
	v_cndmask_b32_e64 v81, v71, v81, s[6:7]
	v_cndmask_b32_e64 v80, v70, v80, s[6:7]
	v_cndmask_b32_e64 v79, v69, v79, s[6:7]
	v_cndmask_b32_e64 v78, v68, v78, s[6:7]
	v_lshlrev_b32_e32 v64, 16, v65
	v_and_b32_e32 v65, 0xffff0000, v65
	v_lshlrev_b32_e32 v66, 16, v67
	v_and_b32_e32 v67, 0xffff0000, v67
	v_lshlrev_b32_e32 v68, 16, v84
	v_and_b32_e32 v69, 0xffff0000, v84
	v_lshlrev_b32_e32 v70, 16, v85
	v_and_b32_e32 v71, 0xffff0000, v85
	v_pk_fma_f32 v[62:63], v[62:63], v[76:77], v[66:67] op_sel_hi:[1,0,1]
	v_pk_fma_f32 v[60:61], v[60:61], v[76:77], v[64:65] op_sel_hi:[1,0,1]
	v_pk_fma_f32 v[58:59], v[58:59], v[76:77], v[70:71] op_sel_hi:[1,0,1]
	v_pk_fma_f32 v[56:57], v[56:57], v[76:77], v[68:69] op_sel_hi:[1,0,1]
	v_cvt_pk_bf16_f32 v64, v60, v61
	v_cvt_pk_bf16_f32 v65, v62, v63
	v_lshlrev_b32_e32 v60, 16, v80
	v_cvt_pk_bf16_f32 v66, v56, v57
	v_cvt_pk_bf16_f32 v67, v58, v59
	v_lshlrev_b32_e32 v56, 16, v78
	v_and_b32_e32 v57, 0xffff0000, v78
	v_lshlrev_b32_e32 v58, 16, v79
	v_and_b32_e32 v59, 0xffff0000, v79
	v_and_b32_e32 v61, 0xffff0000, v80
	v_lshlrev_b32_e32 v62, 16, v81
	v_and_b32_e32 v63, 0xffff0000, v81
	v_pk_fma_f32 v[54:55], v[54:55], v[76:77], v[58:59] op_sel_hi:[1,0,1]
	v_pk_fma_f32 v[52:53], v[52:53], v[76:77], v[56:57] op_sel_hi:[1,0,1]
	v_pk_fma_f32 v[50:51], v[50:51], v[76:77], v[62:63] op_sel_hi:[1,0,1]
	v_pk_fma_f32 v[48:49], v[48:49], v[76:77], v[60:61] op_sel_hi:[1,0,1]
	v_cvt_pk_bf16_f32 v52, v52, v53
	v_cvt_pk_bf16_f32 v53, v54, v55
	v_cvt_pk_bf16_f32 v54, v48, v49
	v_cvt_pk_bf16_f32 v55, v50, v51
	s_nop 0
	v_mov_b32_dpp v56, v64 row_ror:8 row_mask:0xf bank_mask:0xf
	v_mov_b32_dpp v57, v65 row_ror:8 row_mask:0xf bank_mask:0xf
	v_mov_b32_dpp v48, v52 row_ror:8 row_mask:0xf bank_mask:0xf
	v_mov_b32_dpp v49, v53 row_ror:8 row_mask:0xf bank_mask:0xf
	v_mov_b32_dpp v50, v54 row_ror:8 row_mask:0xf bank_mask:0xf
	v_mov_b32_dpp v51, v55 row_ror:8 row_mask:0xf bank_mask:0xf
	v_cndmask_b32_e64 v52, v52, v56, s[6:7]
	v_cndmask_b32_e64 v53, v53, v57, s[6:7]
	v_lshl_add_u64 v[56:57], s[8:9], 0, v[72:73]
	v_cndmask_b32_e64 v48, v48, v64, s[6:7]
	v_cndmask_b32_e64 v49, v49, v65, s[6:7]
	v_cndmask_b32_e64 v50, v50, v66, s[6:7]
	v_cndmask_b32_e64 v51, v51, v67, s[6:7]
	v_lshl_add_u64 v[56:57], v[56:57], 0, v[146:147]
	v_mov_b32_dpp v58, v66 row_ror:8 row_mask:0xf bank_mask:0xf
	v_mov_b32_dpp v59, v67 row_ror:8 row_mask:0xf bank_mask:0xf
	global_store_dwordx4 v[56:57], v[48:51], off
	v_cndmask_b32_e64 v54, v54, v58, s[6:7]
	v_cndmask_b32_e64 v55, v55, v59, s[6:7]
	v_lshl_add_u64 v[48:49], s[8:9], 0, v[74:75]
	v_lshl_add_u64 v[48:49], v[48:49], 0, v[146:147]
	global_store_dwordx4 v[48:49], v[52:55], off
	v_add_u32_e32 v48, 0x90, v77
	v_ashrrev_i32_e32 v49, 31, v48
	v_lshlrev_b64 v[56:57], 12, v[48:49]
	v_lshl_add_u64 v[48:49], s[16:17], 0, v[56:57]
	v_lshl_add_u64 v[58:59], v[56:57], 0, s[36:37]
	v_lshl_add_u64 v[48:49], v[48:49], 0, v[146:147]
	v_lshl_add_u64 v[52:53], s[16:17], 0, v[58:59]
	s_waitcnt vmcnt(16)
	s_nop 0
	v_mov_b32_e32 v60, v240
	s_nop 0
	v_mov_b64_e32 v[48:49], v[244:245]
	v_mov_b64_e32 v[50:51], v[246:247]
	v_lshl_add_u64 v[52:53], v[52:53], 0, v[146:147]
	v_mov_b64_e32 v[52:53], v[248:249]
	v_mov_b64_e32 v[54:55], v[250:251]
	s_nop 1
	v_fmamk_f32 v60, v60, 0x3a000000, v159
	v_rcp_f32_e32 v60, v60
	v_mov_b32_dpp v61, v48 row_ror:8 row_mask:0xf bank_mask:0xf
	v_mov_b32_dpp v65, v52 row_ror:8 row_mask:0xf bank_mask:0xf
	v_mov_b32_dpp v66, v53 row_ror:8 row_mask:0xf bank_mask:0xf
	v_mov_b32_dpp v67, v54 row_ror:8 row_mask:0xf bank_mask:0xf
	v_mov_b32_dpp v68, v55 row_ror:8 row_mask:0xf bank_mask:0xf
	v_mov_b32_dpp v62, v49 row_ror:8 row_mask:0xf bank_mask:0xf
	v_mov_b32_dpp v63, v50 row_ror:8 row_mask:0xf bank_mask:0xf
	v_mov_b32_dpp v64, v51 row_ror:8 row_mask:0xf bank_mask:0xf
	v_cndmask_b32_e64 v68, v68, v51, s[6:7]
	v_cndmask_b32_e64 v67, v67, v50, s[6:7]
	v_cndmask_b32_e64 v51, v66, v49, s[6:7]
	v_cndmask_b32_e64 v49, v65, v48, s[6:7]
	v_cndmask_b32_e64 v64, v55, v64, s[6:7]
	v_cndmask_b32_e64 v63, v54, v63, s[6:7]
	v_cndmask_b32_e64 v62, v53, v62, s[6:7]
	v_cndmask_b32_e64 v61, v52, v61, s[6:7]
	v_lshlrev_b32_e32 v48, 16, v49
	v_and_b32_e32 v49, 0xffff0000, v49
	v_lshlrev_b32_e32 v50, 16, v51
	v_and_b32_e32 v51, 0xffff0000, v51
	v_lshlrev_b32_e32 v52, 16, v67
	v_and_b32_e32 v53, 0xffff0000, v67
	v_lshlrev_b32_e32 v54, 16, v68
	v_and_b32_e32 v55, 0xffff0000, v68
	v_pk_fma_f32 v[46:47], v[46:47], v[60:61], v[50:51] op_sel_hi:[1,0,1]
	v_pk_fma_f32 v[44:45], v[44:45], v[60:61], v[48:49] op_sel_hi:[1,0,1]
	v_pk_fma_f32 v[42:43], v[42:43], v[60:61], v[54:55] op_sel_hi:[1,0,1]
	v_pk_fma_f32 v[40:41], v[40:41], v[60:61], v[52:53] op_sel_hi:[1,0,1]
	v_cvt_pk_bf16_f32 v48, v44, v45
; __device__ __forceinline__ void store_pair_lines(bf16_t* O, int ldc, int row, int fr, int col0, u32x4 wA, u32x4 wB) {
;     const u32x4 sA = {dpp_ror8(wA.x), dpp_ror8(wA.y), dpp_ror8(wA.z), dpp_ror8(wA.w)}, sB = {dpp_ror8(wB.x), dpp_ror8(wB.y), dpp_ror8(wB.z), dpp_ror8(wB.w)};
;     const bool lo = fr < 8;
;     const u32x4 o1 = lo ? wA : sB, o2 = lo ? sA : wB;
;     const int r1 = row - fr + (fr & 7), cb = col0 + (lo ? 0 : 8);
;     *(u32x4*)(O + (size_t)r1 * ldc + cb) = o1;
;     *(u32x4*)(O + (size_t)(r1 + 8) * ldc + cb) = o2;
; }
;     const bool lo = fr < 8;
;     const int r1 = row - fr + (fr & 7), cb = col0 + (lo ? 0 : boff);
;     const u32x4 l1 = *(const u32x4*)(P + (size_t)r1 * ld + cb), l2 = *(const u32x4*)(P + (size_t)(r1 + 8) * ld + cb);
;     __device__ __forceinline__ void operator()(const f32x4 (&acc)[2][2][4][2], const Unit& u, int wr, int wc, int fr, int fq) const {
;     ...
;             for (int m = 0; m < 4; ++m) { const int row = row0 + ai * HALF + m * 16; const size_t off = (size_t)row * D + col0; float sq = 0.f; u32x4 w[2];
;                 const float sc = rsin ? __builtin_amdgcn_rcpf(rsin[row] * (1.f / D) + EPS) : 1.0f;
;                 u32x4 rr[2]; if (R) load_pair_lines(R, D, row, fr, col0, rr[0], rr[1]);
; #pragma unroll
;                 for (int bj = 0; bj < 2; ++bj) { f32x4 r0, r1;
;                     if (R) { const u32x4 rw = rr[bj]; r0 = (f32x4){bflo(rw.x), bfhi(rw.x), bflo(rw.y), bfhi(rw.y)}; r1 = (f32x4){bflo(rw.z), bfhi(rw.z), bflo(rw.w), bfhi(rw.w)}; }
;                     else { const float* rp = (row < 8192 ? src_p + off : src_s + (off - (size_t)8192 * D)) + 8 * bj; r0 = *(const f32x4*)rp; r1 = *(const f32x4*)(rp + 4); }
;                     const f32x4 o0 = r0 + acc[ai][bj][m][0] * sc, o1 = r1 + acc[ai][bj][m][1] * sc;
;                     sq += (o0[0] * o0[0] + o0[1] * o0[1]) + (o0[2] * o0[2] + o0[3] * o0[3]) + (o1[0] * o1[0] + o1[1] * o1[1]) + (o1[2] * o1[2] + o1[3] * o1[3]);
;                     w[bj].x = cvt_pk_bf16(o0[0], o0[1]); w[bj].y = cvt_pk_bf16(o0[2], o0[3]); w[bj].z = cvt_pk_bf16(o1[0], o1[1]); w[bj].w = cvt_pk_bf16(o1[2], o1[3]); }
;                 store_pair_lines(O, D, row, fr, col0, w[0], w[1]);
;                 if (ssout) { sq += __shfl_xor(sq, 16); sq += __shfl_xor(sq, 32); if (fq == 0) unsafeAtomicAdd(ssout + row, sq); } }
	v_cvt_pk_bf16_f32 v49, v46, v47
	v_lshlrev_b32_e32 v44, 16, v63
	v_cvt_pk_bf16_f32 v50, v40, v41
	v_cvt_pk_bf16_f32 v51, v42, v43
	v_lshlrev_b32_e32 v40, 16, v61
	v_and_b32_e32 v41, 0xffff0000, v61
	v_lshlrev_b32_e32 v42, 16, v62
	v_and_b32_e32 v43, 0xffff0000, v62
	v_and_b32_e32 v45, 0xffff0000, v63
	v_lshlrev_b32_e32 v46, 16, v64
	v_and_b32_e32 v47, 0xffff0000, v64
	v_pk_fma_f32 v[38:39], v[38:39], v[60:61], v[42:43] op_sel_hi:[1,0,1]
	v_pk_fma_f32 v[36:37], v[36:37], v[60:61], v[40:41] op_sel_hi:[1,0,1]
	v_pk_fma_f32 v[34:35], v[34:35], v[60:61], v[46:47] op_sel_hi:[1,0,1]
	v_pk_fma_f32 v[32:33], v[32:33], v[60:61], v[44:45] op_sel_hi:[1,0,1]
	v_cvt_pk_bf16_f32 v36, v36, v37
	v_cvt_pk_bf16_f32 v37, v38, v39
	v_cvt_pk_bf16_f32 v38, v32, v33
	v_cvt_pk_bf16_f32 v39, v34, v35
	s_nop 0
	v_mov_b32_dpp v40, v48 row_ror:8 row_mask:0xf bank_mask:0xf
	v_mov_b32_dpp v41, v49 row_ror:8 row_mask:0xf bank_mask:0xf
	v_mov_b32_dpp v32, v36 row_ror:8 row_mask:0xf bank_mask:0xf
	v_mov_b32_dpp v33, v37 row_ror:8 row_mask:0xf bank_mask:0xf
	v_mov_b32_dpp v34, v38 row_ror:8 row_mask:0xf bank_mask:0xf
	v_mov_b32_dpp v35, v39 row_ror:8 row_mask:0xf bank_mask:0xf
	v_cndmask_b32_e64 v36, v36, v40, s[6:7]
	v_cndmask_b32_e64 v37, v37, v41, s[6:7]
	v_lshl_add_u64 v[40:41], s[8:9], 0, v[56:57]
	v_cndmask_b32_e64 v32, v32, v48, s[6:7]
	v_cndmask_b32_e64 v33, v33, v49, s[6:7]
	v_cndmask_b32_e64 v34, v34, v50, s[6:7]
	v_cndmask_b32_e64 v35, v35, v51, s[6:7]
	v_lshl_add_u64 v[40:41], v[40:41], 0, v[146:147]
	v_mov_b32_dpp v42, v50 row_ror:8 row_mask:0xf bank_mask:0xf
	v_mov_b32_dpp v43, v51 row_ror:8 row_mask:0xf bank_mask:0xf
	global_store_dwordx4 v[40:41], v[32:35], off
	v_cndmask_b32_e64 v38, v38, v42, s[6:7]
	v_cndmask_b32_e64 v39, v39, v43, s[6:7]
	v_lshl_add_u64 v[32:33], s[8:9], 0, v[58:59]
	v_lshl_add_u64 v[32:33], v[32:33], 0, v[146:147]
	global_store_dwordx4 v[32:33], v[36:39], off
	v_add_u32_e32 v32, 0xa0, v77
	v_ashrrev_i32_e32 v33, 31, v32
	v_lshlrev_b64 v[40:41], 12, v[32:33]
	v_lshl_add_u64 v[42:43], v[40:41], 0, s[36:37]
	s_waitcnt vmcnt(13)
	s_nop 0
	v_mov_b32_e32 v44, v204
	v_lshl_add_u64 v[32:33], s[16:17], 0, v[40:41]
	v_lshl_add_u64 v[36:37], s[16:17], 0, v[42:43]
	v_lshl_add_u64 v[32:33], v[32:33], 0, v[146:147]
	v_lshl_add_u64 v[36:37], v[36:37], 0, v[146:147]
	v_mov_b64_e32 v[32:33], v[208:209]
	v_mov_b64_e32 v[34:35], v[210:211]
	v_mov_b64_e32 v[36:37], v[212:213]
	v_mov_b64_e32 v[38:39], v[214:215]
	s_nop 1
	v_fmamk_f32 v44, v44, 0x3a000000, v159
	v_rcp_f32_e32 v44, v44
	v_mov_b32_dpp v45, v32 row_ror:8 row_mask:0xf bank_mask:0xf
	v_mov_b32_dpp v46, v33 row_ror:8 row_mask:0xf bank_mask:0xf
	v_mov_b32_dpp v49, v36 row_ror:8 row_mask:0xf bank_mask:0xf
	v_mov_b32_dpp v50, v37 row_ror:8 row_mask:0xf bank_mask:0xf
	v_mov_b32_dpp v51, v38 row_ror:8 row_mask:0xf bank_mask:0xf
	v_mov_b32_dpp v52, v39 row_ror:8 row_mask:0xf bank_mask:0xf
	v_mov_b32_dpp v47, v34 row_ror:8 row_mask:0xf bank_mask:0xf
	v_mov_b32_dpp v48, v35 row_ror:8 row_mask:0xf bank_mask:0xf
	v_cndmask_b32_e64 v52, v52, v35, s[6:7]
	v_cndmask_b32_e64 v51, v51, v34, s[6:7]
	v_cndmask_b32_e64 v35, v50, v33, s[6:7]
	v_cndmask_b32_e64 v33, v49, v32, s[6:7]
	v_cndmask_b32_e64 v48, v39, v48, s[6:7]
	v_cndmask_b32_e64 v47, v38, v47, s[6:7]
	v_cndmask_b32_e64 v46, v37, v46, s[6:7]
	v_cndmask_b32_e64 v45, v36, v45, s[6:7]
	v_lshlrev_b32_e32 v32, 16, v33
	v_and_b32_e32 v33, 0xffff0000, v33
	v_lshlrev_b32_e32 v34, 16, v35
	v_and_b32_e32 v35, 0xffff0000, v35
	v_lshlrev_b32_e32 v36, 16, v51
	v_and_b32_e32 v37, 0xffff0000, v51
	v_lshlrev_b32_e32 v38, 16, v52
	v_and_b32_e32 v39, 0xffff0000, v52
	v_pk_fma_f32 v[30:31], v[30:31], v[44:45], v[34:35] op_sel_hi:[1,0,1]
	v_pk_fma_f32 v[28:29], v[28:29], v[44:45], v[32:33] op_sel_hi:[1,0,1]
	v_pk_fma_f32 v[26:27], v[26:27], v[44:45], v[38:39] op_sel_hi:[1,0,1]
	v_pk_fma_f32 v[24:25], v[24:25], v[44:45], v[36:37] op_sel_hi:[1,0,1]
	v_cvt_pk_bf16_f32 v32, v28, v29
	v_cvt_pk_bf16_f32 v33, v30, v31
	v_lshlrev_b32_e32 v28, 16, v47
	v_cvt_pk_bf16_f32 v34, v24, v25
	v_cvt_pk_bf16_f32 v35, v26, v27
	v_lshlrev_b32_e32 v24, 16, v45
	v_and_b32_e32 v25, 0xffff0000, v45
	v_lshlrev_b32_e32 v26, 16, v46
	v_and_b32_e32 v27, 0xffff0000, v46
	v_and_b32_e32 v29, 0xffff0000, v47
	v_lshlrev_b32_e32 v30, 16, v48
	v_and_b32_e32 v31, 0xffff0000, v48
	v_pk_fma_f32 v[22:23], v[22:23], v[44:45], v[26:27] op_sel_hi:[1,0,1]
	v_pk_fma_f32 v[20:21], v[20:21], v[44:45], v[24:25] op_sel_hi:[1,0,1]
	v_pk_fma_f32 v[18:19], v[18:19], v[44:45], v[30:31] op_sel_hi:[1,0,1]
	v_pk_fma_f32 v[16:17], v[16:17], v[44:45], v[28:29] op_sel_hi:[1,0,1]
	v_cvt_pk_bf16_f32 v20, v20, v21
	v_cvt_pk_bf16_f32 v21, v22, v23
	v_cvt_pk_bf16_f32 v22, v16, v17
	v_cvt_pk_bf16_f32 v23, v18, v19
	s_nop 0
	v_mov_b32_dpp v24, v32 row_ror:8 row_mask:0xf bank_mask:0xf
	v_mov_b32_dpp v25, v33 row_ror:8 row_mask:0xf bank_mask:0xf
	v_mov_b32_dpp v16, v20 row_ror:8 row_mask:0xf bank_mask:0xf
	v_mov_b32_dpp v17, v21 row_ror:8 row_mask:0xf bank_mask:0xf
	v_mov_b32_dpp v18, v22 row_ror:8 row_mask:0xf bank_mask:0xf
	v_mov_b32_dpp v19, v23 row_ror:8 row_mask:0xf bank_mask:0xf
	v_cndmask_b32_e64 v20, v20, v24, s[6:7]
	v_cndmask_b32_e64 v21, v21, v25, s[6:7]
	v_lshl_add_u64 v[24:25], s[8:9], 0, v[40:41]
	v_cndmask_b32_e64 v16, v16, v32, s[6:7]
	v_cndmask_b32_e64 v17, v17, v33, s[6:7]
	v_cndmask_b32_e64 v18, v18, v34, s[6:7]
	v_cndmask_b32_e64 v19, v19, v35, s[6:7]
	v_lshl_add_u64 v[24:25], v[24:25], 0, v[146:147]
	v_mov_b32_dpp v26, v34 row_ror:8 row_mask:0xf bank_mask:0xf
	v_mov_b32_dpp v27, v35 row_ror:8 row_mask:0xf bank_mask:0xf
	global_store_dwordx4 v[24:25], v[16:19], off
	v_cndmask_b32_e64 v22, v22, v26, s[6:7]
	v_cndmask_b32_e64 v23, v23, v27, s[6:7]
	v_lshl_add_u64 v[16:17], s[8:9], 0, v[42:43]
	v_lshl_add_u64 v[16:17], v[16:17], 0, v[146:147]
	global_store_dwordx4 v[16:17], v[20:23], off
	v_add_u32_e32 v16, 0xb0, v77
	v_ashrrev_i32_e32 v17, 31, v16
	v_lshlrev_b64 v[24:25], 12, v[16:17]
	v_lshl_add_u64 v[26:27], v[24:25], 0, s[36:37]
	s_waitcnt vmcnt(10)
; __device__ __forceinline__ unsigned cvt_pk_bf16(float lo, float hi) { unsigned r; asm volatile("v_cvt_pk_bf16_f32 %0, %1, %2" : "=v"(r) : "v"(lo), "v"(hi)); return r; }
; __device__ __forceinline__ float bflo(unsigned w) { return __uint_as_float(w << 16); }
; __device__ __forceinline__ float bfhi(unsigned w) { return __uint_as_float(w & 0xffff0000u); }
; #define PG8_WAIT_V(n) asm volatile("s_waitcnt vmcnt(" #n ")" ::: "memory")
; #define PG8_BAR __builtin_amdgcn_s_barrier()
;     __device__ __forceinline__ void operator()(const f32x4 (&acc)[2][2][4][2], const Unit& u, int wr, int wc, int fr, int fq) const {
;     ...
;             for (int m = 0; m < 4; ++m) { const int row = row0 + ai * HALF + m * 16; const size_t off = (size_t)row * D + col0; float sq = 0.f; u32x4 w[2];
;                 const float sc = rsin ? __builtin_amdgcn_rcpf(rsin[row] * (1.f / D) + EPS) : 1.0f;
;                 u32x4 rr[2]; if (R) load_pair_lines(R, D, row, fr, col0, rr[0], rr[1]);
; #pragma unroll
;                 for (int bj = 0; bj < 2; ++bj) { f32x4 r0, r1;
;                     if (R) { const u32x4 rw = rr[bj]; r0 = (f32x4){bflo(rw.x), bfhi(rw.x), bflo(rw.y), bfhi(rw.y)}; r1 = (f32x4){bflo(rw.z), bfhi(rw.z), bflo(rw.w), bfhi(rw.w)}; }
;                     else { const float* rp = (row < 8192 ? src_p + off : src_s + (off - (size_t)8192 * D)) + 8 * bj; r0 = *(const f32x4*)rp; r1 = *(const f32x4*)(rp + 4); }
;                     const f32x4 o0 = r0 + acc[ai][bj][m][0] * sc, o1 = r1 + acc[ai][bj][m][1] * sc;
;                     sq += (o0[0] * o0[0] + o0[1] * o0[1]) + (o0[2] * o0[2] + o0[3] * o0[3]) + (o1[0] * o1[0] + o1[1] * o1[1]) + (o1[2] * o1[2] + o1[3] * o1[3]);
;                     w[bj].x = cvt_pk_bf16(o0[0], o0[1]); w[bj].y = cvt_pk_bf16(o0[2], o0[3]); w[bj].z = cvt_pk_bf16(o1[0], o1[1]); w[bj].w = cvt_pk_bf16(o1[2], o1[3]); }
;                 store_pair_lines(O, D, row, fr, col0, w[0], w[1]);
;                 if (ssout) { sq += __shfl_xor(sq, 16); sq += __shfl_xor(sq, 32); if (fq == 0) unsafeAtomicAdd(ssout + row, sq); } }
; template <class Epi>
; __device__ __forceinline__ void gemm_phase(LAS unsigned char* lds, const Gemm g, const StaticOrder& S, const Epi& E) {
;     ...
;     PG8_WAIT_V(0);
;     if (wr == 0) PG8_BAR;
;     PG8_BAR;
	s_nop 0
	v_mov_b32_e32 v28, v205
	v_lshl_add_u64 v[16:17], s[16:17], 0, v[24:25]
	v_lshl_add_u64 v[20:21], s[16:17], 0, v[26:27]
	v_lshl_add_u64 v[16:17], v[16:17], 0, v[146:147]
	v_lshl_add_u64 v[20:21], v[20:21], 0, v[146:147]
	v_mov_b64_e32 v[16:17], v[216:217]
	v_mov_b64_e32 v[18:19], v[218:219]
	v_mov_b64_e32 v[20:21], v[220:221]
	v_mov_b64_e32 v[22:23], v[222:223]
	s_nop 1
	v_fmamk_f32 v28, v28, 0x3a000000, v159
	v_rcp_f32_e32 v28, v28
	v_mov_b32_dpp v29, v16 row_ror:8 row_mask:0xf bank_mask:0xf
	v_mov_b32_dpp v30, v17 row_ror:8 row_mask:0xf bank_mask:0xf
	v_mov_b32_dpp v33, v20 row_ror:8 row_mask:0xf bank_mask:0xf
	v_mov_b32_dpp v34, v21 row_ror:8 row_mask:0xf bank_mask:0xf
	v_mov_b32_dpp v35, v22 row_ror:8 row_mask:0xf bank_mask:0xf
	v_mov_b32_dpp v36, v23 row_ror:8 row_mask:0xf bank_mask:0xf
	v_mov_b32_dpp v31, v18 row_ror:8 row_mask:0xf bank_mask:0xf
	v_mov_b32_dpp v32, v19 row_ror:8 row_mask:0xf bank_mask:0xf
	v_cndmask_b32_e64 v36, v36, v19, s[6:7]
	v_cndmask_b32_e64 v35, v35, v18, s[6:7]
	v_cndmask_b32_e64 v19, v34, v17, s[6:7]
	v_cndmask_b32_e64 v17, v33, v16, s[6:7]
	v_cndmask_b32_e64 v32, v23, v32, s[6:7]
	v_cndmask_b32_e64 v31, v22, v31, s[6:7]
	v_cndmask_b32_e64 v30, v21, v30, s[6:7]
	v_cndmask_b32_e64 v29, v20, v29, s[6:7]
	v_lshlrev_b32_e32 v16, 16, v17
	v_and_b32_e32 v17, 0xffff0000, v17
	v_lshlrev_b32_e32 v18, 16, v19
	v_and_b32_e32 v19, 0xffff0000, v19
	v_lshlrev_b32_e32 v20, 16, v35
	v_and_b32_e32 v21, 0xffff0000, v35
	v_lshlrev_b32_e32 v22, 16, v36
	v_and_b32_e32 v23, 0xffff0000, v36
	v_pk_fma_f32 v[14:15], v[14:15], v[28:29], v[18:19] op_sel_hi:[1,0,1]
	v_pk_fma_f32 v[12:13], v[12:13], v[28:29], v[16:17] op_sel_hi:[1,0,1]
	v_pk_fma_f32 v[10:11], v[10:11], v[28:29], v[22:23] op_sel_hi:[1,0,1]
	v_pk_fma_f32 v[8:9], v[8:9], v[28:29], v[20:21] op_sel_hi:[1,0,1]
	v_cvt_pk_bf16_f32 v16, v12, v13
	v_cvt_pk_bf16_f32 v17, v14, v15
	v_lshlrev_b32_e32 v12, 16, v31
	v_cvt_pk_bf16_f32 v18, v8, v9
	v_cvt_pk_bf16_f32 v19, v10, v11
	v_lshlrev_b32_e32 v8, 16, v29
	v_and_b32_e32 v9, 0xffff0000, v29
	v_lshlrev_b32_e32 v10, 16, v30
	v_and_b32_e32 v11, 0xffff0000, v30
	v_and_b32_e32 v13, 0xffff0000, v31
	v_lshlrev_b32_e32 v14, 16, v32
	v_and_b32_e32 v15, 0xffff0000, v32
	v_pk_fma_f32 v[6:7], v[6:7], v[28:29], v[10:11] op_sel_hi:[1,0,1]
	v_pk_fma_f32 v[4:5], v[4:5], v[28:29], v[8:9] op_sel_hi:[1,0,1]
	v_pk_fma_f32 v[2:3], v[2:3], v[28:29], v[14:15] op_sel_hi:[1,0,1]
	v_pk_fma_f32 v[0:1], v[0:1], v[28:29], v[12:13] op_sel_hi:[1,0,1]
	v_cvt_pk_bf16_f32 v4, v4, v5
	v_cvt_pk_bf16_f32 v5, v6, v7
	v_cvt_pk_bf16_f32 v6, v0, v1
	v_cvt_pk_bf16_f32 v7, v2, v3
	s_nop 0
	v_mov_b32_dpp v8, v16 row_ror:8 row_mask:0xf bank_mask:0xf
	v_mov_b32_dpp v9, v17 row_ror:8 row_mask:0xf bank_mask:0xf
	v_mov_b32_dpp v0, v4 row_ror:8 row_mask:0xf bank_mask:0xf
	v_mov_b32_dpp v1, v5 row_ror:8 row_mask:0xf bank_mask:0xf
	v_mov_b32_dpp v2, v6 row_ror:8 row_mask:0xf bank_mask:0xf
	v_mov_b32_dpp v3, v7 row_ror:8 row_mask:0xf bank_mask:0xf
	v_cndmask_b32_e64 v4, v4, v8, s[6:7]
	v_cndmask_b32_e64 v5, v5, v9, s[6:7]
	v_lshl_add_u64 v[8:9], s[8:9], 0, v[24:25]
	v_cndmask_b32_e64 v0, v0, v16, s[6:7]
	v_cndmask_b32_e64 v1, v1, v17, s[6:7]
	v_cndmask_b32_e64 v2, v2, v18, s[6:7]
	v_cndmask_b32_e64 v3, v3, v19, s[6:7]
	v_lshl_add_u64 v[8:9], v[8:9], 0, v[146:147]
	v_mov_b32_dpp v10, v18 row_ror:8 row_mask:0xf bank_mask:0xf
	v_mov_b32_dpp v11, v19 row_ror:8 row_mask:0xf bank_mask:0xf
	global_store_dwordx4 v[8:9], v[0:3], off
	v_cndmask_b32_e64 v6, v6, v10, s[6:7]
	v_cndmask_b32_e64 v7, v7, v11, s[6:7]
	v_lshl_add_u64 v[0:1], s[8:9], 0, v[26:27]
	v_lshl_add_u64 v[0:1], v[0:1], 0, v[146:147]
	global_store_dwordx4 v[0:1], v[4:7], off
	s_cbranch_vccz .LBB0_798
	s_waitcnt vmcnt(0)
	s_cmpk_gt_u32 s56, 0xff
	s_cbranch_scc1 .LBB0_810
	s_barrier

; #define PG8_STAGE(bufoff, gbase, voff) do { _Pragma("unroll") for (int _i = 0; _i < 2; ++_i) \
;         __builtin_amdgcn_global_load_lds((const unsigned*)((const char*)(gbase) + (voff)[_i]), (LAS unsigned*)(lds + (bufoff) + ldsw + _i * 8192), 16, 0, 0); } while (0)
; #define PG8_WAIT_V(n) asm volatile("s_waitcnt vmcnt(" #n ")" ::: "memory")
; #define PG8_BAR __builtin_amdgcn_s_barrier()
; template <class Epi>
; __device__ __forceinline__ void gemm_phase(LAS unsigned char* lds, const Gemm g, const StaticOrder& S, const Epi& E) {
;     ...
;     for (int i = 0; i < 2; ++i) { int R, C; stage_rc(tid * 16 + i * 8192, R, C);
;         const int Rw = 64 * (R >> 5) + 16 * ((R >> 2) & 3) + 4 * ((R >> 4) & 1) + (R & 3);
;         const int Rf = 64 * (R >> 5) + 8 * ((R >> 2) & 3) + 4 * ((R >> 4) & 1) + (R & 3);
;         const int Rb0 = Epi::PERM ? (Epi::F32OUT ? Rf : Rw) : R, Rb1 = Epi::PERM ? (Epi::F32OUT ? Rf + 32 : Rw + 8) : R + HALF;
;         voffA[i] = (unsigned)(R * K + C) * 2u; voffB0[i] = (unsigned)(Rb0 * K + C) * 2u; voffB1[i] = (unsigned)(Rb1 * K + C) * 2u; }
;     const size_t kstep = (size_t)(BK * 2);
;     const size_t hstep = (size_t)HALF * K * 2;
;     const size_t tstep = 2 * hstep;
;     const unsigned ldsw = (unsigned)wid * 1024u;
;     const int aoff = lds_byte(wr * 64 + fr, fq * 8), boff = lds_byte(wc * 32 + fr, fq * 8);
;     ...
;     Unit cur, nxt; int ui = 0;
;     if (!S.next(0, cur)) return;
;     f32x4 acc[2][2][4][2];
; #pragma unroll
;     for (int a = 0; a < 2; ++a)
; #pragma unroll
;         for (int b = 0; b < 2; ++b)
; #pragma unroll
;             for (int m = 0; m < 4; ++m)
; #pragma unroll
;                 for (int n = 0; n < 2; ++n) acc[a][b][m][n] = (f32x4){0.f, 0.f, 0.f, 0.f};
;     bf16x8 At[4][2], B0[2][2], B1[2][2];
;     const char* cA = (const char*)g.A + (size_t)cur.pm * tstep; const char* cB = (const char*)g.Bt + (size_t)cur.pn * tstep;
;     PG8_STAGE(PG8_SB(0, 0), cB, voffB0); PG8_STAGE(PG8_SA(0, 0), cA, voffA); PG8_STAGE(PG8_SB(0, 1), cB, voffB1); PG8_STAGE(PG8_SA(0, 1), cA + hstep, voffA);
;     if (wr == 1) PG8_BAR;
;     PG8_WAIT_V(4); PG8_BAR;
;     PG8_STAGE(PG8_SB(1, 0), cB + kstep, voffB0); PG8_STAGE(PG8_SA(1, 0), cA + kstep, voffA); PG8_STAGE(PG8_SB(1, 1), cB + kstep, voffB1);
;     PG8_WAIT_V(6); PG8_BAR;
.LBB0_957:
	s_add_u32 s8, s6, 0xec00000
	s_addc_u32 s9, s7, 0
	s_add_u32 s10, s6, 0x1ec20000
	s_mov_b64 s[16:17], 0x80
	s_addc_u32 s11, s7, 0
	s_add_i32 m0, s45, 0x18000
	v_lshl_add_u64 v[10:11], v[10:11], 0, s[16:17]
	s_waitcnt vmcnt(4)
	s_barrier
	global_load_lds_dwordx4 v[10:11], off
	v_lshl_add_u64 v[8:9], v[8:9], 0, s[16:17]
	s_add_i32 m0, s45, 0x1a000
	s_add_i32 s63, s45, 0x8000
	global_load_lds_dwordx4 v[8:9], off
	v_lshl_add_u64 v[6:7], v[6:7], 0, s[16:17]
	s_mov_b32 m0, s63
	s_add_i32 s64, s45, 0xa000
	global_load_lds_dwordx4 v[6:7], off
	v_lshl_add_u64 v[4:5], v[4:5], 0, s[16:17]
	s_mov_b32 m0, s64
	v_lshl_add_u64 v[0:1], v[0:1], 0, s[16:17]
	global_load_lds_dwordx4 v[4:5], off
	s_add_i32 m0, s45, 0x1c000
	v_and_b32_e32 v154, 15, v12
	global_load_lds_dwordx4 v[0:1], off
	v_lshl_add_u64 v[0:1], v[2:3], 0, s[16:17]
	s_add_i32 m0, s45, 0x1e000
	v_lshlrev_b32_e32 v2, 2, v12
	global_load_lds_dwordx4 v[0:1], off
	v_and_b32_e32 v0, 48, v12
	s_and_b32 s6, s36, 3
	s_lshl_b32 s7, s19, 13
	v_lshl_or_b32 v1, v154, 6, v0
	v_and_b32_e32 v2, 32, v2
	v_bitop3_b32 v3, v1, s7, v2 bitop3:0xde
	s_lshl_b32 s7, s6, 12
	s_sext_i32_i8 s71, s18
	v_bitop3_b32 v155, v1, s7, v2 bitop3:0xde
	s_lshl_b32 s18, s6, 6
	v_and_b32_e32 v1, 8, v12
	v_or3_b32 v157, s18, v1, v0
	v_lshlrev_b32_e32 v0, 15, v17
	v_and_b32_e32 v0, 0xffff0000, v0
	v_lshl_add_u32 v0, v16, 12, v0
	v_and_b32_e32 v1, 1, v17
	v_lshl_or_b32 v0, v1, 6, v0
	v_lshl_add_u32 v140, v18, 1, v0
	v_lshlrev_b32_e32 v0, 15, v13
	v_and_b32_e32 v0, 0xffff0000, v0
	s_waitcnt vmcnt(0)
	v_lshl_add_u32 v0, v14, 12, v0
	v_and_b32_e32 v1, 1, v13
	v_lshl_or_b32 v0, v1, 6, v0
	s_add_i32 s68, 0, 0x10000
	s_add_i32 s69, 0, 0x14000
	s_lshl_b32 s65, s19, 6
	v_cmp_gt_u32_e64 s[6:7], 8, v154
	v_and_b32_e32 v156, 7, v12
	s_ashr_i32 s66, s20, 31
	s_mov_b32 s67, s20
	v_mov_b32_e32 v141, v135
	v_lshl_add_u32 v142, v15, 1, v0
	v_mov_b32_e32 v143, v135
	v_add_u32_e32 v158, s68, v155
	v_add_u32_e32 v159, 0, v3
	v_add_u32_e32 v160, s69, v155
	v_mov_b32_e32 v161, 0x358637bd
	s_movk_i32 s70, 0x1800
	v_mov_b64_e32 v[144:145], 0x2ff
	s_barrier

; #define PG8_STAGE(bufoff, gbase, voff) do { _Pragma("unroll") for (int _i = 0; _i < 2; ++_i) \
;         __builtin_amdgcn_global_load_lds((const unsigned*)((const char*)(gbase) + (voff)[_i]), (LAS unsigned*)(lds + (bufoff) + ldsw + _i * 8192), 16, 0, 0); } while (0)
; #define PG8_LDA(dst, b, h) do { _Pragma("unroll") for (int m = 0; m < 4; ++m) _Pragma("unroll") for (int k = 0; k < 2; ++k) dst[m][k] = *(const LAS bf16x8*)(lds + PG8_SA(b, h) + aoff + m * 2048 + k * 1024); } while (0)
; #define PG8_LDB(dst, b, h) do { _Pragma("unroll") for (int n = 0; n < 2; ++n) _Pragma("unroll") for (int k = 0; k < 2; ++k) dst[n][k] = *(const LAS bf16x8*)(lds + PG8_SB(b, h) + boff + n * 2048 + k * 1024); } while (0)
; #define PG8_MMA(ai, bj, At, Bt) do { __builtin_amdgcn_s_setprio(1); _Pragma("unroll") for (int m = 0; m < 4; ++m) _Pragma("unroll") for (int n = 0; n < 2; ++n) _Pragma("unroll") for (int k = 0; k < 2; ++k) \
;         acc[ai][bj][m][n] = __builtin_amdgcn_mfma_f32_16x16x32_bf16(Bt[n][k], At[m][k], acc[ai][bj][m][n], 0, 0, 0); __builtin_amdgcn_s_setprio(0); } while (0)
; #define PG8_WAIT_L(n) asm volatile("s_waitcnt lgkmcnt(" #n ")" ::: "memory")
; template <class Epi>
; __device__ __forceinline__ void gemm_phase(LAS unsigned char* lds, const Gemm g, const StaticOrder& S, const Epi& E) {
;     ...
;         const bool has_next = S.next(ui + 1, nxt);
;         const char* nA = has_next ? (const char*)g.A + (size_t)nxt.pm * tstep : cA; const char* nB = has_next ? (const char*)g.Bt + (size_t)nxt.pn * tstep : cB;
;         for (int t = 0; t < nt; t += 2) {
;             const bool last = (t == nt - 2);
;             const char* a1 = cA + (size_t)(t + 1) * kstep;
;             const char* a2 = last ? nA : cA + (size_t)(t + 2) * kstep; const char* b2 = last ? nB : cB + (size_t)(t + 2) * kstep;
;             const char* a3 = a2 + kstep; const char* b3 = b2 + kstep;
;             PG8_LDB(B0, 0, 0); PG8_SCHED; PG8_LDA(At, 0, 0); PG8_STAGE(PG8_SA(1, 1), a1 + hstep, voffA);
;             PG8_WAIT_L(8); PG8_BAR; PG8_WAIT_L(0); PG8_MMA(0, 0, At, B0); PG8_BAR; PG8_SCHED;
;             PG8_LDB(B1, 0, 1); PG8_STAGE(PG8_SB(0, 0), b2, voffB0);
;             PG8_BAR; PG8_WAIT_L(0); PG8_MMA(0, 1, At, B1); PG8_BAR;
;             PG8_LDA(At, 0, 1); PG8_STAGE(PG8_SA(0, 0), a2, voffA);
;             PG8_BAR; PG8_WAIT_L(0); PG8_MMA(1, 0, At, B0); PG8_BAR; PG8_SCHED;
.LBB0_962:
	ds_read_b128 v[146:149], v158
	ds_read_b128 v[150:153], v158 offset:1024
	ds_read_b128 v[162:165], v158 offset:2048
	ds_read_b128 v[166:169], v158 offset:3072
	s_add_u32 s33, s46, 0xfff80080
	s_addc_u32 s48, s47, -1
	s_cmp_eq_u32 s77, 28
	s_cselect_b32 s49, s37, s48
	s_cselect_b32 s48, s72, s33
	s_cselect_b32 s51, s19, s75
	s_cselect_b32 s50, s73, s74
	v_lshl_add_u64 v[204:205], s[46:47], 0, v[140:141]
	s_add_i32 m0, s45, 0xc000
	ds_read_b128 v[170:173], v159
	ds_read_b128 v[174:177], v159 offset:1024
	ds_read_b128 v[178:181], v159 offset:2048
	ds_read_b128 v[182:185], v159 offset:3072
	ds_read_b128 v[186:189], v159 offset:4096
	ds_read_b128 v[190:193], v159 offset:5120
	ds_read_b128 v[194:197], v159 offset:6144
	ds_read_b128 v[198:201], v159 offset:7168
	global_load_lds_dwordx4 v[204:205], off
	v_lshl_add_u64 v[204:205], s[46:47], 0, v[142:143]
	s_add_i32 m0, s45, 0xe000
	s_nop 0
	global_load_lds_dwordx4 v[204:205], off
	s_waitcnt lgkmcnt(8)
	s_barrier
	s_waitcnt lgkmcnt(0)
	v_mfma_f32_16x16x32_bf16 v[124:127], v[146:149], v[170:173], v[124:127]
	v_mfma_f32_16x16x32_bf16 v[120:123], v[162:165], v[170:173], v[120:123]
	v_mfma_f32_16x16x32_bf16 v[108:111], v[146:149], v[178:181], v[108:111]
	v_mfma_f32_16x16x32_bf16 v[104:107], v[162:165], v[178:181], v[104:107]
	v_mfma_f32_16x16x32_bf16 v[92:95], v[146:149], v[186:189], v[92:95]
	v_mfma_f32_16x16x32_bf16 v[88:91], v[162:165], v[186:189], v[88:91]
	v_mfma_f32_16x16x32_bf16 v[76:79], v[146:149], v[194:197], v[76:79]
	v_mfma_f32_16x16x32_bf16 v[72:75], v[162:165], v[194:197], v[72:75]
	v_mfma_f32_16x16x32_bf16 v[124:127], v[150:153], v[174:177], v[124:127]
	v_mfma_f32_16x16x32_bf16 v[120:123], v[166:169], v[174:177], v[120:123]
	v_mfma_f32_16x16x32_bf16 v[108:111], v[150:153], v[182:185], v[108:111]
	v_mfma_f32_16x16x32_bf16 v[104:107], v[166:169], v[182:185], v[104:107]
	v_mfma_f32_16x16x32_bf16 v[92:95], v[150:153], v[190:193], v[92:95]
	v_mfma_f32_16x16x32_bf16 v[88:91], v[166:169], v[190:193], v[88:91]
	v_mfma_f32_16x16x32_bf16 v[76:79], v[150:153], v[198:201], v[76:79]
	v_mfma_f32_16x16x32_bf16 v[72:75], v[166:169], v[198:201], v[72:75]
	s_barrier
	s_add_i32 s33, s68, s57
	v_lshl_add_u64 v[220:221], s[50:51], 0, v[134:135]
	s_mov_b32 m0, s33
	ds_read_b128 v[204:207], v160
	ds_read_b128 v[208:211], v160 offset:1024
	ds_read_b128 v[212:215], v160 offset:2048
	ds_read_b128 v[216:219], v160 offset:3072
	global_load_lds_dwordx4 v[220:221], off
	v_lshl_add_u64 v[222:223], s[50:51], 0, v[128:129]
	s_add_i32 m0, s33, 0x2000
	s_nop 0
	global_load_lds_dwordx4 v[222:223], off
	s_barrier
	s_waitcnt lgkmcnt(0)
	v_mfma_f32_16x16x32_bf16 v[116:119], v[204:207], v[170:173], v[116:119]
	v_mfma_f32_16x16x32_bf16 v[112:115], v[212:215], v[170:173], v[112:115]
	v_mfma_f32_16x16x32_bf16 v[100:103], v[204:207], v[178:181], v[100:103]
	v_mfma_f32_16x16x32_bf16 v[96:99], v[212:215], v[178:181], v[96:99]
	v_mfma_f32_16x16x32_bf16 v[84:87], v[204:207], v[186:189], v[84:87]
	v_mfma_f32_16x16x32_bf16 v[80:83], v[212:215], v[186:189], v[80:83]
	v_mfma_f32_16x16x32_bf16 v[68:71], v[204:207], v[194:197], v[68:71]
	v_mfma_f32_16x16x32_bf16 v[64:67], v[212:215], v[194:197], v[64:67]
	v_mfma_f32_16x16x32_bf16 v[116:119], v[208:211], v[174:177], v[116:119]
	v_mfma_f32_16x16x32_bf16 v[112:115], v[216:219], v[174:177], v[112:115]
	v_mfma_f32_16x16x32_bf16 v[100:103], v[208:211], v[182:185], v[100:103]
	v_mfma_f32_16x16x32_bf16 v[96:99], v[216:219], v[182:185], v[96:99]
	v_mfma_f32_16x16x32_bf16 v[84:87], v[208:211], v[190:193], v[84:87]
	v_mfma_f32_16x16x32_bf16 v[80:83], v[216:219], v[190:193], v[80:83]
	v_mfma_f32_16x16x32_bf16 v[68:71], v[208:211], v[198:201], v[68:71]
	v_mfma_f32_16x16x32_bf16 v[64:67], v[216:219], v[198:201], v[64:67]
	s_mov_b32 m0, s45
	v_lshl_add_u64 v[224:225], s[48:49], 0, v[138:139]
	s_barrier
	ds_read_b128 v[170:173], v159 offset:16384
	ds_read_b128 v[174:177], v159 offset:17408
	ds_read_b128 v[178:181], v159 offset:18432
	ds_read_b128 v[182:185], v159 offset:19456
	ds_read_b128 v[186:189], v159 offset:20480
	ds_read_b128 v[190:193], v159 offset:21504
	ds_read_b128 v[194:197], v159 offset:22528
	ds_read_b128 v[198:201], v159 offset:23552
	global_load_lds_dwordx4 v[224:225], off
	v_lshl_add_u64 v[226:227], s[48:49], 0, v[132:133]
	s_mov_b32 m0, s59
	s_nop 0
	global_load_lds_dwordx4 v[226:227], off
	s_barrier
	s_waitcnt lgkmcnt(0)
	v_mfma_f32_16x16x32_bf16 v[60:63], v[146:149], v[170:173], v[60:63]
	v_mfma_f32_16x16x32_bf16 v[56:59], v[162:165], v[170:173], v[56:59]
	v_mfma_f32_16x16x32_bf16 v[44:47], v[146:149], v[178:181], v[44:47]
	v_mfma_f32_16x16x32_bf16 v[40:43], v[162:165], v[178:181], v[40:43]
	v_mfma_f32_16x16x32_bf16 v[28:31], v[146:149], v[186:189], v[28:31]
	v_mfma_f32_16x16x32_bf16 v[24:27], v[162:165], v[186:189], v[24:27]
	v_mfma_f32_16x16x32_bf16 v[12:15], v[146:149], v[194:197], v[12:15]
	v_mfma_f32_16x16x32_bf16 v[8:11], v[162:165], v[194:197], v[8:11]
	v_mfma_f32_16x16x32_bf16 v[60:63], v[150:153], v[174:177], v[60:63]
	v_mfma_f32_16x16x32_bf16 v[56:59], v[166:169], v[174:177], v[56:59]
	v_mfma_f32_16x16x32_bf16 v[44:47], v[150:153], v[182:185], v[44:47]
	v_mfma_f32_16x16x32_bf16 v[40:43], v[166:169], v[182:185], v[40:43]
	v_mfma_f32_16x16x32_bf16 v[28:31], v[150:153], v[190:193], v[28:31]
	v_mfma_f32_16x16x32_bf16 v[24:27], v[166:169], v[190:193], v[24:27]
	v_mfma_f32_16x16x32_bf16 v[12:15], v[150:153], v[198:201], v[12:15]
	v_mfma_f32_16x16x32_bf16 v[8:11], v[166:169], v[198:201], v[8:11]
	s_barrier
; #define PG8_STAGE(bufoff, gbase, voff) do { _Pragma("unroll") for (int _i = 0; _i < 2; ++_i) \
;         __builtin_amdgcn_global_load_lds((const unsigned*)((const char*)(gbase) + (voff)[_i]), (LAS unsigned*)(lds + (bufoff) + ldsw + _i * 8192), 16, 0, 0); } while (0)
; #define PG8_LDA(dst, b, h) do { _Pragma("unroll") for (int m = 0; m < 4; ++m) _Pragma("unroll") for (int k = 0; k < 2; ++k) dst[m][k] = *(const LAS bf16x8*)(lds + PG8_SA(b, h) + aoff + m * 2048 + k * 1024); } while (0)
; #define PG8_LDB(dst, b, h) do { _Pragma("unroll") for (int n = 0; n < 2; ++n) _Pragma("unroll") for (int k = 0; k < 2; ++k) dst[n][k] = *(const LAS bf16x8*)(lds + PG8_SB(b, h) + boff + n * 2048 + k * 1024); } while (0)
; #define PG8_MMA(ai, bj, At, Bt) do { __builtin_amdgcn_s_setprio(1); _Pragma("unroll") for (int m = 0; m < 4; ++m) _Pragma("unroll") for (int n = 0; n < 2; ++n) _Pragma("unroll") for (int k = 0; k < 2; ++k) \
;         acc[ai][bj][m][n] = __builtin_amdgcn_mfma_f32_16x16x32_bf16(Bt[n][k], At[m][k], acc[ai][bj][m][n], 0, 0, 0); __builtin_amdgcn_s_setprio(0); } while (0)
; #define PG8_WAIT_V(n) asm volatile("s_waitcnt vmcnt(" #n ")" ::: "memory")
; #define PG8_WAIT_L(n) asm volatile("s_waitcnt lgkmcnt(" #n ")" ::: "memory")
; #define PG8_BAR __builtin_amdgcn_s_barrier()
; #define PG8_SCHED __builtin_amdgcn_sched_barrier(0)
; template <class Epi>
; __device__ __forceinline__ void gemm_phase(LAS unsigned char* lds, const Gemm g, const StaticOrder& S, const Epi& E) {
;     ...
;             PG8_STAGE(PG8_SB(0, 1), b2, voffB1);
;             PG8_WAIT_V(6); PG8_BAR; PG8_MMA(1, 1, At, B1); PG8_BAR;
;             PG8_LDB(B0, 1, 0); PG8_SCHED; PG8_LDA(At, 1, 0); PG8_STAGE(PG8_SA(0, 1), a2 + hstep, voffA);
;             PG8_WAIT_L(8); PG8_BAR; PG8_WAIT_L(0); PG8_MMA(0, 0, At, B0); PG8_BAR; PG8_SCHED;
;             PG8_LDB(B1, 1, 1); PG8_STAGE(PG8_SB(1, 0), b3, voffB0);
;             PG8_BAR; PG8_WAIT_L(0); PG8_MMA(0, 1, At, B1); PG8_BAR;
;             PG8_LDA(At, 1, 1); PG8_STAGE(PG8_SA(1, 0), a3, voffA);
;             PG8_BAR; PG8_WAIT_L(0); PG8_MMA(1, 0, At, B0); PG8_BAR; PG8_SCHED;
	s_add_i32 s33, s69, s57
	v_lshl_add_u64 v[228:229], s[50:51], 0, v[136:137]
	s_mov_b32 m0, s33
	v_lshl_add_u64 v[230:231], s[50:51], 0, v[130:131]
	global_load_lds_dwordx4 v[228:229], off
	s_add_i32 m0, s33, 0x2000
	s_nop 0
	global_load_lds_dwordx4 v[230:231], off
	s_add_i32 s33, 0, 0x18000
	v_add_u32_e32 v166, s33, v155
	ds_read_b128 v[146:149], v166
	ds_read_b128 v[150:153], v166 offset:1024
	ds_read_b128 v[162:165], v166 offset:2048
	ds_read_b128 v[166:169], v166 offset:3072
	s_waitcnt vmcnt(6)
	s_barrier
	v_mfma_f32_16x16x32_bf16 v[52:55], v[204:207], v[170:173], v[52:55]
	v_mfma_f32_16x16x32_bf16 v[48:51], v[212:215], v[170:173], v[48:51]
	v_mfma_f32_16x16x32_bf16 v[36:39], v[204:207], v[178:181], v[36:39]
	v_mfma_f32_16x16x32_bf16 v[32:35], v[212:215], v[178:181], v[32:35]
	v_mfma_f32_16x16x32_bf16 v[20:23], v[204:207], v[186:189], v[20:23]
	v_mfma_f32_16x16x32_bf16 v[16:19], v[212:215], v[186:189], v[16:19]
	v_mfma_f32_16x16x32_bf16 v[4:7], v[204:207], v[194:197], v[4:7]
	v_mfma_f32_16x16x32_bf16 v[0:3], v[212:215], v[194:197], v[0:3]
	v_mfma_f32_16x16x32_bf16 v[52:55], v[208:211], v[174:177], v[52:55]
	v_mfma_f32_16x16x32_bf16 v[48:51], v[216:219], v[174:177], v[48:51]
	v_mfma_f32_16x16x32_bf16 v[36:39], v[208:211], v[182:185], v[36:39]
	v_mfma_f32_16x16x32_bf16 v[32:35], v[216:219], v[182:185], v[32:35]
	v_mfma_f32_16x16x32_bf16 v[20:23], v[208:211], v[190:193], v[20:23]
	v_mfma_f32_16x16x32_bf16 v[16:19], v[216:219], v[190:193], v[16:19]
	v_mfma_f32_16x16x32_bf16 v[4:7], v[208:211], v[198:201], v[4:7]
	v_mfma_f32_16x16x32_bf16 v[0:3], v[216:219], v[198:201], v[0:3]
	s_barrier
	s_add_u32 s48, s48, 0x80000
	s_addc_u32 s49, s49, 0
	s_mov_b32 m0, s60
	v_lshl_add_u64 v[204:205], s[48:49], 0, v[138:139]
	ds_read_b128 v[170:173], v159 offset:32768
	ds_read_b128 v[174:177], v159 offset:33792
	ds_read_b128 v[178:181], v159 offset:34816
	ds_read_b128 v[182:185], v159 offset:35840
	ds_read_b128 v[186:189], v159 offset:36864
	ds_read_b128 v[190:193], v159 offset:37888
	ds_read_b128 v[194:197], v159 offset:38912
	ds_read_b128 v[198:201], v159 offset:39936
	global_load_lds_dwordx4 v[204:205], off
	v_lshl_add_u64 v[204:205], s[48:49], 0, v[132:133]
	s_mov_b32 m0, s61
	s_nop 0
	global_load_lds_dwordx4 v[204:205], off
	s_waitcnt lgkmcnt(8)
	s_barrier
	s_waitcnt lgkmcnt(0)
	v_mfma_f32_16x16x32_bf16 v[124:127], v[146:149], v[170:173], v[124:127]
	v_mfma_f32_16x16x32_bf16 v[120:123], v[162:165], v[170:173], v[120:123]
	v_mfma_f32_16x16x32_bf16 v[108:111], v[146:149], v[178:181], v[108:111]
	v_mfma_f32_16x16x32_bf16 v[104:107], v[162:165], v[178:181], v[104:107]
	v_mfma_f32_16x16x32_bf16 v[92:95], v[146:149], v[186:189], v[92:95]
	v_mfma_f32_16x16x32_bf16 v[88:91], v[162:165], v[186:189], v[88:91]
	v_mfma_f32_16x16x32_bf16 v[76:79], v[146:149], v[194:197], v[76:79]
	v_mfma_f32_16x16x32_bf16 v[72:75], v[162:165], v[194:197], v[72:75]
	v_mfma_f32_16x16x32_bf16 v[124:127], v[150:153], v[174:177], v[124:127]
	v_mfma_f32_16x16x32_bf16 v[120:123], v[166:169], v[174:177], v[120:123]
	v_mfma_f32_16x16x32_bf16 v[108:111], v[150:153], v[182:185], v[108:111]
	v_mfma_f32_16x16x32_bf16 v[104:107], v[166:169], v[182:185], v[104:107]
	v_mfma_f32_16x16x32_bf16 v[92:95], v[150:153], v[190:193], v[92:95]
	v_mfma_f32_16x16x32_bf16 v[88:91], v[166:169], v[190:193], v[88:91]
	v_mfma_f32_16x16x32_bf16 v[76:79], v[150:153], v[198:201], v[76:79]
	v_mfma_f32_16x16x32_bf16 v[72:75], v[166:169], v[198:201], v[72:75]
	s_barrier
	s_add_i32 s48, 0, 0x1c000
	s_add_i32 s33, s33, s57
	v_add_u32_e32 v216, s48, v155
	v_lshl_add_u64 v[220:221], v[220:221], 0, s[16:17]
	s_mov_b32 m0, s33
	ds_read_b128 v[204:207], v216
	ds_read_b128 v[208:211], v216 offset:1024
	ds_read_b128 v[212:215], v216 offset:2048
	ds_read_b128 v[216:219], v216 offset:3072
	global_load_lds_dwordx4 v[220:221], off
	v_lshl_add_u64 v[220:221], v[222:223], 0, s[16:17]
	s_add_i32 m0, s33, 0x2000
	s_nop 0
	global_load_lds_dwordx4 v[220:221], off
	s_barrier
	s_waitcnt lgkmcnt(0)
	v_mfma_f32_16x16x32_bf16 v[116:119], v[204:207], v[170:173], v[116:119]
	v_mfma_f32_16x16x32_bf16 v[112:115], v[212:215], v[170:173], v[112:115]
	v_mfma_f32_16x16x32_bf16 v[100:103], v[204:207], v[178:181], v[100:103]
	v_mfma_f32_16x16x32_bf16 v[96:99], v[212:215], v[178:181], v[96:99]
	v_mfma_f32_16x16x32_bf16 v[84:87], v[204:207], v[186:189], v[84:87]
	v_mfma_f32_16x16x32_bf16 v[80:83], v[212:215], v[186:189], v[80:83]
	v_mfma_f32_16x16x32_bf16 v[68:71], v[204:207], v[194:197], v[68:71]
	v_mfma_f32_16x16x32_bf16 v[64:67], v[212:215], v[194:197], v[64:67]
	v_mfma_f32_16x16x32_bf16 v[116:119], v[208:211], v[174:177], v[116:119]
	v_mfma_f32_16x16x32_bf16 v[112:115], v[216:219], v[174:177], v[112:115]
	v_mfma_f32_16x16x32_bf16 v[100:103], v[208:211], v[182:185], v[100:103]
	v_mfma_f32_16x16x32_bf16 v[96:99], v[216:219], v[182:185], v[96:99]
	v_mfma_f32_16x16x32_bf16 v[84:87], v[208:211], v[190:193], v[84:87]
	v_mfma_f32_16x16x32_bf16 v[80:83], v[216:219], v[190:193], v[80:83]
	v_mfma_f32_16x16x32_bf16 v[68:71], v[208:211], v[198:201], v[68:71]
	v_mfma_f32_16x16x32_bf16 v[64:67], v[216:219], v[198:201], v[64:67]
	s_mov_b32 m0, s63
	v_lshl_add_u64 v[220:221], v[224:225], 0, s[16:17]
	s_barrier
	ds_read_b128 v[170:173], v159 offset:49152
	ds_read_b128 v[174:177], v159 offset:50176
	ds_read_b128 v[178:181], v159 offset:51200
	ds_read_b128 v[182:185], v159 offset:52224
	ds_read_b128 v[186:189], v159 offset:53248
	ds_read_b128 v[190:193], v159 offset:54272
	ds_read_b128 v[194:197], v159 offset:55296
	ds_read_b128 v[198:201], v159 offset:56320
	global_load_lds_dwordx4 v[220:221], off
	v_lshl_add_u64 v[220:221], v[226:227], 0, s[16:17]
	s_mov_b32 m0, s64
	s_nop 0
	global_load_lds_dwordx4 v[220:221], off
	s_barrier
; __device__ __forceinline__ unsigned cvt_pk_bf16(float lo, float hi) { unsigned r; asm volatile("v_cvt_pk_bf16_f32 %0, %1, %2" : "=v"(r) : "v"(lo), "v"(hi)); return r; }
; #define PG8_STAGE(bufoff, gbase, voff) do { _Pragma("unroll") for (int _i = 0; _i < 2; ++_i) \
;         __builtin_amdgcn_global_load_lds((const unsigned*)((const char*)(gbase) + (voff)[_i]), (LAS unsigned*)(lds + (bufoff) + ldsw + _i * 8192), 16, 0, 0); } while (0)
; #define PG8_WAIT_V(n) asm volatile("s_waitcnt vmcnt(" #n ")" ::: "memory")
; #define PG8_BAR __builtin_amdgcn_s_barrier()
;     __device__ __forceinline__ void operator()(const f32x4 (&acc)[2][2][4][2], const Unit& u, int wr, int wc, int fr, int fq) const {
;         const int row0 = u.pm * BM + wr * 64 + fr; const int col0 = u.pn * BM + wc * 64 + 16 * fq;
; #pragma unroll
;         for (int ai = 0; ai < 2; ++ai)
; #pragma unroll
;             for (int m = 0; m < 4; ++m) { const int row = row0 + ai * HALF + m * 16;
;                 const float rs = ssin ? __builtin_amdgcn_rsqf(ssin[row] * (1.f / D) + EPS) : 1.0f; float sq = 0.f; u32x4 w[2];
; #pragma unroll
;                 for (int bj = 0; bj < 2; ++bj) { f32x4 v0 = acc[ai][bj][m][0] * rs, v1 = acc[ai][bj][m][1] * rs;
;                     if (ACT == 1) {
; #pragma unroll
;                         for (int j = 0; j < 4; ++j) { const float a = fmaxf(v0[j], 0.f), b = fmaxf(v1[j], 0.f); v0[j] = a * a; v1[j] = b * b; } }
;                     sq += (v0[0] * v0[0] + v0[1] * v0[1]) + (v0[2] * v0[2] + v0[3] * v0[3]) + (v1[0] * v1[0] + v1[1] * v1[1]) + (v1[2] * v1[2] + v1[3] * v1[3]);
;                     w[bj].x = cvt_pk_bf16(v0[0], v0[1]); w[bj].y = cvt_pk_bf16(v0[2], v0[3]); w[bj].z = cvt_pk_bf16(v1[0], v1[1]); w[bj].w = cvt_pk_bf16(v1[2], v1[3]); }
;                 store_pair_lines(O, ldc, row, fr, col0, w[0], w[1]);
;                 if (ssout) { sq += __shfl_xor(sq, 16); sq += __shfl_xor(sq, 32); if (fq == 0) unsafeAtomicAdd(ssout + row, sq); } }
; template <class Epi>
; __device__ __forceinline__ void gemm_phase(LAS unsigned char* lds, const Gemm g, const StaticOrder& S, const Epi& E) {
;     ...
;             PG8_BAR; PG8_WAIT_L(0); PG8_MMA(1, 0, At, B0); PG8_BAR; PG8_SCHED;
;             PG8_STAGE(PG8_SB(1, 1), b3, voffB1);
;             PG8_WAIT_V(6); PG8_BAR; PG8_MMA(1, 1, At, B1); PG8_BAR;
;         }
;         E(acc, cur, wr, wc, fr, fq);
;         if (!has_next) break;
	s_waitcnt lgkmcnt(0)
	v_mfma_f32_16x16x32_bf16 v[60:63], v[146:149], v[170:173], v[60:63]
	v_mfma_f32_16x16x32_bf16 v[56:59], v[162:165], v[170:173], v[56:59]
	v_mfma_f32_16x16x32_bf16 v[44:47], v[146:149], v[178:181], v[44:47]
	v_mfma_f32_16x16x32_bf16 v[40:43], v[162:165], v[178:181], v[40:43]
	v_mfma_f32_16x16x32_bf16 v[28:31], v[146:149], v[186:189], v[28:31]
	v_mfma_f32_16x16x32_bf16 v[24:27], v[162:165], v[186:189], v[24:27]
	v_mfma_f32_16x16x32_bf16 v[12:15], v[146:149], v[194:197], v[12:15]
	v_mfma_f32_16x16x32_bf16 v[8:11], v[162:165], v[194:197], v[8:11]
	v_mfma_f32_16x16x32_bf16 v[60:63], v[150:153], v[174:177], v[60:63]
	v_mfma_f32_16x16x32_bf16 v[56:59], v[166:169], v[174:177], v[56:59]
	v_mfma_f32_16x16x32_bf16 v[44:47], v[150:153], v[182:185], v[44:47]
	v_mfma_f32_16x16x32_bf16 v[40:43], v[166:169], v[182:185], v[40:43]
	v_mfma_f32_16x16x32_bf16 v[28:31], v[150:153], v[190:193], v[28:31]
	v_mfma_f32_16x16x32_bf16 v[24:27], v[166:169], v[190:193], v[24:27]
	v_mfma_f32_16x16x32_bf16 v[12:15], v[150:153], v[198:201], v[12:15]
	v_mfma_f32_16x16x32_bf16 v[8:11], v[166:169], v[198:201], v[8:11]
	s_barrier
	s_add_i32 s33, s48, s57
	v_lshl_add_u64 v[146:147], v[228:229], 0, s[16:17]
	s_mov_b32 m0, s33
	s_nop 0
	global_load_lds_dwordx4 v[146:147], off
	v_lshl_add_u64 v[146:147], v[230:231], 0, s[16:17]
	s_add_i32 m0, s33, 0x2000
	s_nop 0
	global_load_lds_dwordx4 v[146:147], off
	s_waitcnt vmcnt(6)
	s_barrier
	v_mfma_f32_16x16x32_bf16 v[52:55], v[204:207], v[170:173], v[52:55]
	v_mfma_f32_16x16x32_bf16 v[48:51], v[212:215], v[170:173], v[48:51]
	v_mfma_f32_16x16x32_bf16 v[36:39], v[204:207], v[178:181], v[36:39]
	v_mfma_f32_16x16x32_bf16 v[32:35], v[212:215], v[178:181], v[32:35]
	v_mfma_f32_16x16x32_bf16 v[20:23], v[204:207], v[186:189], v[20:23]
	v_mfma_f32_16x16x32_bf16 v[16:19], v[212:215], v[186:189], v[16:19]
	v_mfma_f32_16x16x32_bf16 v[4:7], v[204:207], v[194:197], v[4:7]
	v_mfma_f32_16x16x32_bf16 v[0:3], v[212:215], v[194:197], v[0:3]
	v_mfma_f32_16x16x32_bf16 v[52:55], v[208:211], v[174:177], v[52:55]
	v_mfma_f32_16x16x32_bf16 v[48:51], v[216:219], v[174:177], v[48:51]
	v_mfma_f32_16x16x32_bf16 v[36:39], v[208:211], v[182:185], v[36:39]
	v_mfma_f32_16x16x32_bf16 v[32:35], v[216:219], v[182:185], v[32:35]
	v_mfma_f32_16x16x32_bf16 v[20:23], v[208:211], v[190:193], v[20:23]
	v_mfma_f32_16x16x32_bf16 v[16:19], v[216:219], v[190:193], v[16:19]
	v_mfma_f32_16x16x32_bf16 v[4:7], v[208:211], v[198:201], v[4:7]
	v_mfma_f32_16x16x32_bf16 v[0:3], v[216:219], v[198:201], v[0:3]
	s_add_i32 s77, s77, 2
	s_add_u32 s46, s46, 0x100
	s_addc_u32 s47, s47, 0
	s_add_u32 s74, s74, 0x100
	s_addc_u32 s75, s75, 0
	s_cmp_gt_u32 s77, 29
	s_barrier
	s_cbranch_scc0 .LBB0_962
	s_lshl_b32 s19, s44, 8
	s_add_i32 s19, s19, s65
	v_or_b32_e32 v152, s19, v154
	v_ashrrev_i32_e32 v153, 31, v152
	v_lshl_add_u64 v[150:151], v[152:153], 2, s[10:11]
	global_load_dword v153, v[150:151], off
	v_or_b32_e32 v180, 16, v152
	v_ashrrev_i32_e32 v181, 31, v180
	v_lshl_add_u64 v[182:183], v[180:181], 2, s[10:11]
	global_load_dword v179, v[182:183], off
	v_or_b32_e32 v180, 32, v152
	v_ashrrev_i32_e32 v181, 31, v180
	v_lshl_add_u64 v[182:183], v[180:181], 2, s[10:11]
	global_load_dword v184, v[182:183], off
	v_or_b32_e32 v180, 48, v152
	v_ashrrev_i32_e32 v181, 31, v180
	v_lshl_add_u64 v[182:183], v[180:181], 2, s[10:11]
	global_load_dword v185, v[182:183], off
	global_load_dword v186, v[150:151], off offset:512
	global_load_dword v187, v[150:151], off offset:576
	global_load_dword v188, v[150:151], off offset:640
	global_load_dword v189, v[150:151], off offset:704
	v_lshl_or_b32 v148, s71, 8, v157
	v_mov_b32_e32 v169, 0
	v_mov_b64_e32 v[146:147], s[8:9]
	v_ashrrev_i32_e32 v149, 31, v148
	v_or_b32_e32 v164, s19, v156
	v_lshlrev_b64 v[148:149], 1, v[148:149]
	v_mad_i64_i32 v[162:163], s[46:47], v164, s70, v[146:147]
	v_or_b32_e32 v165, 8, v164
	v_or_b32_e32 v164, 16, v152
	v_lshl_add_u64 v[162:163], v[162:163], 0, v[148:149]
	v_mad_i64_i32 v[166:167], s[46:47], v165, s70, v[146:147]
	v_ashrrev_i32_e32 v165, 31, v164
	v_lshl_add_u64 v[166:167], v[166:167], 0, v[148:149]
	v_lshl_add_u64 v[170:171], v[164:165], 2, s[10:11]
	s_and_b64 vcc, exec, s[40:41]
	s_mov_b32 s71, s18
	s_mov_b32 s44, s36
	s_mov_b64 s[48:49], s[42:43]
	s_waitcnt vmcnt(7)
	v_fmamk_f32 v153, v153, 0x3a000000, v161
	v_rsq_f32_e32 v168, v153
	v_mov_b32_e32 v153, 0
	v_pk_mul_f32 v[124:125], v[124:125], v[168:169] op_sel_hi:[1,0]
	v_pk_mul_f32 v[120:121], v[120:121], v[168:169] op_sel_hi:[1,0]
	v_pk_mul_f32 v[118:119], v[118:119], v[168:169] op_sel_hi:[1,0]
	v_pk_mul_f32 v[116:117], v[116:117], v[168:169] op_sel_hi:[1,0]
	v_pk_mul_f32 v[126:127], v[126:127], v[168:169] op_sel_hi:[1,0]
	v_pk_mul_f32 v[122:123], v[122:123], v[168:169] op_sel_hi:[1,0]
	v_pk_mul_f32 v[114:115], v[114:115], v[168:169] op_sel_hi:[1,0]
	v_pk_mul_f32 v[112:113], v[112:113], v[168:169] op_sel_hi:[1,0]
	v_cvt_pk_bf16_f32 v124, v124, v125
	v_cvt_pk_bf16_f32 v125, v126, v127
	v_cvt_pk_bf16_f32 v120, v120, v121
	v_cvt_pk_bf16_f32 v121, v122, v123
	v_cvt_pk_bf16_f32 v116, v116, v117
	v_cvt_pk_bf16_f32 v117, v118, v119
	s_nop 0
	v_cvt_pk_bf16_f32 v118, v112, v113
	v_cvt_pk_bf16_f32 v119, v114, v115
	s_nop 0
	v_mov_b32_dpp v169, v124 row_ror:8 row_mask:0xf bank_mask:0xf
	v_mov_b32_dpp v172, v125 row_ror:8 row_mask:0xf bank_mask:0xf
	v_mov_b32_dpp v175, v116 row_ror:8 row_mask:0xf bank_mask:0xf
	v_mov_b32_dpp v176, v117 row_ror:8 row_mask:0xf bank_mask:0xf
	v_mov_b32_dpp v177, v118 row_ror:8 row_mask:0xf bank_mask:0xf
	v_mov_b32_dpp v178, v119 row_ror:8 row_mask:0xf bank_mask:0xf
	v_mov_b32_dpp v173, v120 row_ror:8 row_mask:0xf bank_mask:0xf
	v_mov_b32_dpp v174, v121 row_ror:8 row_mask:0xf bank_mask:0xf
	v_cndmask_b32_e64 v112, v175, v124, s[6:7]
	v_cndmask_b32_e64 v113, v176, v125, s[6:7]
	v_cndmask_b32_e64 v114, v177, v120, s[6:7]
	v_cndmask_b32_e64 v115, v178, v121, s[6:7]
	v_cndmask_b32_e64 v116, v116, v169, s[6:7]
	v_cndmask_b32_e64 v117, v117, v172, s[6:7]
	v_cndmask_b32_e64 v118, v118, v173, s[6:7]
	v_cndmask_b32_e64 v119, v119, v174, s[6:7]
	global_store_dwordx4 v[162:163], v[112:115], off
	global_store_dwordx4 v[166:167], v[116:119], off
	s_waitcnt vmcnt(8)
; __device__ __forceinline__ unsigned cvt_pk_bf16(float lo, float hi) { unsigned r; asm volatile("v_cvt_pk_bf16_f32 %0, %1, %2" : "=v"(r) : "v"(lo), "v"(hi)); return r; }
; __device__ __forceinline__ unsigned dpp_ror8(unsigned x) { return (unsigned)__builtin_amdgcn_update_dpp(0, (int)x, 0x128, 0xf, 0xf, false); }
; __device__ __forceinline__ void store_pair_lines(bf16_t* O, int ldc, int row, int fr, int col0, u32x4 wA, u32x4 wB) {
;     const u32x4 sA = {dpp_ror8(wA.x), dpp_ror8(wA.y), dpp_ror8(wA.z), dpp_ror8(wA.w)}, sB = {dpp_ror8(wB.x), dpp_ror8(wB.y), dpp_ror8(wB.z), dpp_ror8(wB.w)};
;     const bool lo = fr < 8;
;     const u32x4 o1 = lo ? wA : sB, o2 = lo ? sA : wB;
;     const int r1 = row - fr + (fr & 7), cb = col0 + (lo ? 0 : 8);
;     *(u32x4*)(O + (size_t)r1 * ldc + cb) = o1;
;     *(u32x4*)(O + (size_t)(r1 + 8) * ldc + cb) = o2;
; }
;     __device__ __forceinline__ void operator()(const f32x4 (&acc)[2][2][4][2], const Unit& u, int wr, int wc, int fr, int fq) const {
;     ...
;             for (int m = 0; m < 4; ++m) { const int row = row0 + ai * HALF + m * 16;
;                 const float rs = ssin ? __builtin_amdgcn_rsqf(ssin[row] * (1.f / D) + EPS) : 1.0f; float sq = 0.f; u32x4 w[2];
; #pragma unroll
;                 for (int bj = 0; bj < 2; ++bj) { f32x4 v0 = acc[ai][bj][m][0] * rs, v1 = acc[ai][bj][m][1] * rs;
;                     if (ACT == 1) {
; #pragma unroll
;                         for (int j = 0; j < 4; ++j) { const float a = fmaxf(v0[j], 0.f), b = fmaxf(v1[j], 0.f); v0[j] = a * a; v1[j] = b * b; } }
;                     sq += (v0[0] * v0[0] + v0[1] * v0[1]) + (v0[2] * v0[2] + v0[3] * v0[3]) + (v1[0] * v1[0] + v1[1] * v1[1]) + (v1[2] * v1[2] + v1[3] * v1[3]);
;                     w[bj].x = cvt_pk_bf16(v0[0], v0[1]); w[bj].y = cvt_pk_bf16(v0[2], v0[3]); w[bj].z = cvt_pk_bf16(v1[0], v1[1]); w[bj].w = cvt_pk_bf16(v1[2], v1[3]); }
;                 store_pair_lines(O, ldc, row, fr, col0, w[0], w[1]);
;                 if (ssout) { sq += __shfl_xor(sq, 16); sq += __shfl_xor(sq, 32); if (fq == 0) unsafeAtomicAdd(ssout + row, sq); } }
	s_nop 0
	v_mov_b32_e32 v118, v179
	s_nop 1
	v_or_b32_e32 v112, 32, v152
	v_mov_b32_e32 v119, 0
	v_sub_u32_e32 v114, v164, v154
	v_ashrrev_i32_e32 v113, 31, v112
	v_add_u32_e32 v120, v114, v156
	v_lshl_add_u64 v[114:115], v[112:113], 2, s[10:11]
	v_mad_i64_i32 v[116:117], s[46:47], v120, s70, v[146:147]
	v_add_u32_e32 v113, 8, v120
	v_lshl_add_u64 v[116:117], v[116:117], 0, v[148:149]
	v_mad_i64_i32 v[120:121], s[46:47], v113, s70, v[146:147]
	v_lshl_add_u64 v[120:121], v[120:121], 0, v[148:149]
	v_fmamk_f32 v118, v118, 0x3a000000, v161
	v_rsq_f32_e32 v118, v118
	s_nop 0
	v_pk_mul_f32 v[108:109], v[108:109], v[118:119] op_sel_hi:[1,0]
	v_pk_mul_f32 v[104:105], v[104:105], v[118:119] op_sel_hi:[1,0]
	v_pk_mul_f32 v[102:103], v[102:103], v[118:119] op_sel_hi:[1,0]
	v_pk_mul_f32 v[100:101], v[100:101], v[118:119] op_sel_hi:[1,0]
	v_pk_mul_f32 v[110:111], v[110:111], v[118:119] op_sel_hi:[1,0]
	v_pk_mul_f32 v[106:107], v[106:107], v[118:119] op_sel_hi:[1,0]
	v_pk_mul_f32 v[98:99], v[98:99], v[118:119] op_sel_hi:[1,0]
	v_pk_mul_f32 v[96:97], v[96:97], v[118:119] op_sel_hi:[1,0]
	v_cvt_pk_bf16_f32 v108, v108, v109
	v_cvt_pk_bf16_f32 v109, v110, v111
	v_cvt_pk_bf16_f32 v104, v104, v105
	v_cvt_pk_bf16_f32 v105, v106, v107
	v_cvt_pk_bf16_f32 v100, v100, v101
	v_cvt_pk_bf16_f32 v101, v102, v103
	s_nop 0
	v_cvt_pk_bf16_f32 v102, v96, v97
	v_cvt_pk_bf16_f32 v103, v98, v99
	s_nop 0
	v_mov_b32_dpp v119, v108 row_ror:8 row_mask:0xf bank_mask:0xf
	v_mov_b32_dpp v122, v109 row_ror:8 row_mask:0xf bank_mask:0xf
	v_mov_b32_dpp v125, v100 row_ror:8 row_mask:0xf bank_mask:0xf
	v_mov_b32_dpp v126, v101 row_ror:8 row_mask:0xf bank_mask:0xf
	v_mov_b32_dpp v127, v102 row_ror:8 row_mask:0xf bank_mask:0xf
	v_mov_b32_dpp v153, v103 row_ror:8 row_mask:0xf bank_mask:0xf
	v_mov_b32_dpp v123, v104 row_ror:8 row_mask:0xf bank_mask:0xf
	v_mov_b32_dpp v124, v105 row_ror:8 row_mask:0xf bank_mask:0xf
	v_cndmask_b32_e64 v96, v125, v108, s[6:7]
	v_cndmask_b32_e64 v97, v126, v109, s[6:7]
	v_cndmask_b32_e64 v98, v127, v104, s[6:7]
	v_cndmask_b32_e64 v99, v153, v105, s[6:7]
	v_cndmask_b32_e64 v100, v100, v119, s[6:7]
	v_cndmask_b32_e64 v101, v101, v122, s[6:7]
	v_cndmask_b32_e64 v102, v102, v123, s[6:7]
	v_cndmask_b32_e64 v103, v103, v124, s[6:7]
	global_store_dwordx4 v[116:117], v[96:99], off
	global_store_dwordx4 v[120:121], v[100:103], off
	s_waitcnt vmcnt(9)
	s_nop 0
	v_mov_b32_e32 v102, v184
	s_nop 1
	v_or_b32_e32 v96, 48, v152
	v_mov_b32_e32 v103, 0
	v_sub_u32_e32 v98, v112, v154
	v_ashrrev_i32_e32 v97, 31, v96
	v_add_u32_e32 v104, v98, v156
	v_lshl_add_u64 v[98:99], v[96:97], 2, s[10:11]
	v_mad_i64_i32 v[100:101], s[46:47], v104, s70, v[146:147]
	v_add_u32_e32 v97, 8, v104
	v_lshl_add_u64 v[100:101], v[100:101], 0, v[148:149]
	v_mad_i64_i32 v[104:105], s[46:47], v97, s70, v[146:147]
	v_lshl_add_u64 v[104:105], v[104:105], 0, v[148:149]
	v_fmamk_f32 v102, v102, 0x3a000000, v161
	v_rsq_f32_e32 v102, v102
	s_nop 0
	v_pk_mul_f32 v[92:93], v[92:93], v[102:103] op_sel_hi:[1,0]
	v_pk_mul_f32 v[88:89], v[88:89], v[102:103] op_sel_hi:[1,0]
	v_pk_mul_f32 v[86:87], v[86:87], v[102:103] op_sel_hi:[1,0]
	v_pk_mul_f32 v[84:85], v[84:85], v[102:103] op_sel_hi:[1,0]
	v_pk_mul_f32 v[94:95], v[94:95], v[102:103] op_sel_hi:[1,0]
	v_pk_mul_f32 v[90:91], v[90:91], v[102:103] op_sel_hi:[1,0]
	v_pk_mul_f32 v[82:83], v[82:83], v[102:103] op_sel_hi:[1,0]
	v_pk_mul_f32 v[80:81], v[80:81], v[102:103] op_sel_hi:[1,0]
	v_cvt_pk_bf16_f32 v92, v92, v93
	v_cvt_pk_bf16_f32 v93, v94, v95
	v_cvt_pk_bf16_f32 v88, v88, v89
	v_cvt_pk_bf16_f32 v89, v90, v91
	v_cvt_pk_bf16_f32 v84, v84, v85
	v_cvt_pk_bf16_f32 v85, v86, v87
	s_nop 0
	v_cvt_pk_bf16_f32 v86, v80, v81
	v_cvt_pk_bf16_f32 v87, v82, v83
	s_nop 0
	v_mov_b32_dpp v103, v92 row_ror:8 row_mask:0xf bank_mask:0xf
	v_mov_b32_dpp v106, v93 row_ror:8 row_mask:0xf bank_mask:0xf
	v_mov_b32_dpp v109, v84 row_ror:8 row_mask:0xf bank_mask:0xf
	v_mov_b32_dpp v110, v85 row_ror:8 row_mask:0xf bank_mask:0xf
	v_mov_b32_dpp v111, v86 row_ror:8 row_mask:0xf bank_mask:0xf
	v_mov_b32_dpp v113, v87 row_ror:8 row_mask:0xf bank_mask:0xf
	v_mov_b32_dpp v107, v88 row_ror:8 row_mask:0xf bank_mask:0xf
	v_mov_b32_dpp v108, v89 row_ror:8 row_mask:0xf bank_mask:0xf
	v_cndmask_b32_e64 v80, v109, v92, s[6:7]
	v_cndmask_b32_e64 v81, v110, v93, s[6:7]
	v_cndmask_b32_e64 v82, v111, v88, s[6:7]
	v_cndmask_b32_e64 v83, v113, v89, s[6:7]
	v_cndmask_b32_e64 v84, v84, v103, s[6:7]
	v_cndmask_b32_e64 v85, v85, v106, s[6:7]
	v_cndmask_b32_e64 v86, v86, v107, s[6:7]
	v_cndmask_b32_e64 v87, v87, v108, s[6:7]
	global_store_dwordx4 v[100:101], v[80:83], off
	global_store_dwordx4 v[104:105], v[84:87], off
	s_waitcnt vmcnt(10)
; __device__ __forceinline__ unsigned cvt_pk_bf16(float lo, float hi) { unsigned r; asm volatile("v_cvt_pk_bf16_f32 %0, %1, %2" : "=v"(r) : "v"(lo), "v"(hi)); return r; }
; __device__ __forceinline__ unsigned dpp_ror8(unsigned x) { return (unsigned)__builtin_amdgcn_update_dpp(0, (int)x, 0x128, 0xf, 0xf, false); }
; __device__ __forceinline__ void store_pair_lines(bf16_t* O, int ldc, int row, int fr, int col0, u32x4 wA, u32x4 wB) {
;     const u32x4 sA = {dpp_ror8(wA.x), dpp_ror8(wA.y), dpp_ror8(wA.z), dpp_ror8(wA.w)}, sB = {dpp_ror8(wB.x), dpp_ror8(wB.y), dpp_ror8(wB.z), dpp_ror8(wB.w)};
;     const bool lo = fr < 8;
;     const u32x4 o1 = lo ? wA : sB, o2 = lo ? sA : wB;
;     const int r1 = row - fr + (fr & 7), cb = col0 + (lo ? 0 : 8);
;     *(u32x4*)(O + (size_t)r1 * ldc + cb) = o1;
;     *(u32x4*)(O + (size_t)(r1 + 8) * ldc + cb) = o2;
; }
;     __device__ __forceinline__ void operator()(const f32x4 (&acc)[2][2][4][2], const Unit& u, int wr, int wc, int fr, int fq) const {
;     ...
;             for (int m = 0; m < 4; ++m) { const int row = row0 + ai * HALF + m * 16;
;                 const float rs = ssin ? __builtin_amdgcn_rsqf(ssin[row] * (1.f / D) + EPS) : 1.0f; float sq = 0.f; u32x4 w[2];
; #pragma unroll
;                 for (int bj = 0; bj < 2; ++bj) { f32x4 v0 = acc[ai][bj][m][0] * rs, v1 = acc[ai][bj][m][1] * rs;
;                     if (ACT == 1) {
; #pragma unroll
;                         for (int j = 0; j < 4; ++j) { const float a = fmaxf(v0[j], 0.f), b = fmaxf(v1[j], 0.f); v0[j] = a * a; v1[j] = b * b; } }
;                     sq += (v0[0] * v0[0] + v0[1] * v0[1]) + (v0[2] * v0[2] + v0[3] * v0[3]) + (v1[0] * v1[0] + v1[1] * v1[1]) + (v1[2] * v1[2] + v1[3] * v1[3]);
;                     w[bj].x = cvt_pk_bf16(v0[0], v0[1]); w[bj].y = cvt_pk_bf16(v0[2], v0[3]); w[bj].z = cvt_pk_bf16(v1[0], v1[1]); w[bj].w = cvt_pk_bf16(v1[2], v1[3]); }
;                 store_pair_lines(O, ldc, row, fr, col0, w[0], w[1]);
;                 if (ssout) { sq += __shfl_xor(sq, 16); sq += __shfl_xor(sq, 32); if (fq == 0) unsafeAtomicAdd(ssout + row, sq); } }
	s_nop 0
	v_mov_b32_e32 v82, v185
	s_nop 1
	v_mov_b32_e32 v83, 0
	v_sub_u32_e32 v80, v96, v154
	v_add_u32_e32 v84, v80, v156
	v_mad_i64_i32 v[80:81], s[46:47], v84, s70, v[146:147]
	v_add_u32_e32 v84, 8, v84
	v_lshl_add_u64 v[80:81], v[80:81], 0, v[148:149]
	v_mad_i64_i32 v[84:85], s[46:47], v84, s70, v[146:147]
	v_lshl_add_u64 v[84:85], v[84:85], 0, v[148:149]
	v_fmamk_f32 v82, v82, 0x3a000000, v161
	v_rsq_f32_e32 v82, v82
	s_nop 0
	v_pk_mul_f32 v[76:77], v[76:77], v[82:83] op_sel_hi:[1,0]
	v_pk_mul_f32 v[72:73], v[72:73], v[82:83] op_sel_hi:[1,0]
	v_pk_mul_f32 v[70:71], v[70:71], v[82:83] op_sel_hi:[1,0]
	v_pk_mul_f32 v[68:69], v[68:69], v[82:83] op_sel_hi:[1,0]
	v_pk_mul_f32 v[78:79], v[78:79], v[82:83] op_sel_hi:[1,0]
	v_pk_mul_f32 v[74:75], v[74:75], v[82:83] op_sel_hi:[1,0]
	v_pk_mul_f32 v[66:67], v[66:67], v[82:83] op_sel_hi:[1,0]
	v_pk_mul_f32 v[64:65], v[64:65], v[82:83] op_sel_hi:[1,0]
	v_cvt_pk_bf16_f32 v76, v76, v77
	v_cvt_pk_bf16_f32 v77, v78, v79
	v_cvt_pk_bf16_f32 v72, v72, v73
	v_cvt_pk_bf16_f32 v73, v74, v75
	v_cvt_pk_bf16_f32 v68, v68, v69
	v_cvt_pk_bf16_f32 v69, v70, v71
	s_nop 0
	v_cvt_pk_bf16_f32 v70, v64, v65
	v_cvt_pk_bf16_f32 v71, v66, v67
	s_nop 0
	v_mov_b32_dpp v83, v76 row_ror:8 row_mask:0xf bank_mask:0xf
	v_mov_b32_dpp v86, v77 row_ror:8 row_mask:0xf bank_mask:0xf
	v_mov_b32_dpp v89, v68 row_ror:8 row_mask:0xf bank_mask:0xf
	v_mov_b32_dpp v90, v69 row_ror:8 row_mask:0xf bank_mask:0xf
	v_mov_b32_dpp v91, v70 row_ror:8 row_mask:0xf bank_mask:0xf
	v_mov_b32_dpp v92, v71 row_ror:8 row_mask:0xf bank_mask:0xf
	v_mov_b32_dpp v87, v72 row_ror:8 row_mask:0xf bank_mask:0xf
	v_mov_b32_dpp v88, v73 row_ror:8 row_mask:0xf bank_mask:0xf
	v_cndmask_b32_e64 v64, v89, v76, s[6:7]
	v_cndmask_b32_e64 v65, v90, v77, s[6:7]
	v_cndmask_b32_e64 v66, v91, v72, s[6:7]
	v_cndmask_b32_e64 v67, v92, v73, s[6:7]
	v_cndmask_b32_e64 v68, v68, v83, s[6:7]
	v_cndmask_b32_e64 v69, v69, v86, s[6:7]
	v_cndmask_b32_e64 v70, v70, v87, s[6:7]
	v_cndmask_b32_e64 v71, v71, v88, s[6:7]
	global_store_dwordx4 v[80:81], v[64:67], off
	global_store_dwordx4 v[84:85], v[68:71], off
	s_waitcnt vmcnt(11)
	s_nop 0
	v_mov_b32_e32 v66, v186
	s_nop 1
	v_sub_u32_e32 v64, v152, v154
	v_mov_b32_e32 v67, 0
	v_add_u32_e32 v77, v64, v156
	v_add_u32_e32 v64, 0x80, v77
	v_add_u32_e32 v68, 0x88, v77
	v_mad_i64_i32 v[64:65], s[46:47], v64, s70, v[146:147]
	v_mad_i64_i32 v[68:69], s[46:47], v68, s70, v[146:147]
	v_lshl_add_u64 v[64:65], v[64:65], 0, v[148:149]
	v_lshl_add_u64 v[68:69], v[68:69], 0, v[148:149]
	v_fmamk_f32 v66, v66, 0x3a000000, v161
	v_rsq_f32_e32 v66, v66
	s_nop 0
	v_pk_mul_f32 v[60:61], v[60:61], v[66:67] op_sel_hi:[1,0]
	v_pk_mul_f32 v[56:57], v[56:57], v[66:67] op_sel_hi:[1,0]
	v_pk_mul_f32 v[54:55], v[54:55], v[66:67] op_sel_hi:[1,0]
	v_pk_mul_f32 v[52:53], v[52:53], v[66:67] op_sel_hi:[1,0]
	v_pk_mul_f32 v[62:63], v[62:63], v[66:67] op_sel_hi:[1,0]
	v_pk_mul_f32 v[58:59], v[58:59], v[66:67] op_sel_hi:[1,0]
	v_pk_mul_f32 v[50:51], v[50:51], v[66:67] op_sel_hi:[1,0]
	v_pk_mul_f32 v[48:49], v[48:49], v[66:67] op_sel_hi:[1,0]
	v_cvt_pk_bf16_f32 v60, v60, v61
	v_cvt_pk_bf16_f32 v61, v62, v63
	v_cvt_pk_bf16_f32 v56, v56, v57
	v_cvt_pk_bf16_f32 v57, v58, v59
	v_cvt_pk_bf16_f32 v52, v52, v53
	v_cvt_pk_bf16_f32 v53, v54, v55
	s_nop 0
	v_cvt_pk_bf16_f32 v54, v48, v49
	v_cvt_pk_bf16_f32 v55, v50, v51
	s_nop 0
	v_mov_b32_dpp v67, v60 row_ror:8 row_mask:0xf bank_mask:0xf
	v_mov_b32_dpp v70, v61 row_ror:8 row_mask:0xf bank_mask:0xf
	v_mov_b32_dpp v73, v52 row_ror:8 row_mask:0xf bank_mask:0xf
	v_mov_b32_dpp v74, v53 row_ror:8 row_mask:0xf bank_mask:0xf
	v_mov_b32_dpp v75, v54 row_ror:8 row_mask:0xf bank_mask:0xf
	v_mov_b32_dpp v76, v55 row_ror:8 row_mask:0xf bank_mask:0xf
	v_mov_b32_dpp v71, v56 row_ror:8 row_mask:0xf bank_mask:0xf
	v_mov_b32_dpp v72, v57 row_ror:8 row_mask:0xf bank_mask:0xf
	v_cndmask_b32_e64 v48, v73, v60, s[6:7]
	v_cndmask_b32_e64 v49, v74, v61, s[6:7]
	v_cndmask_b32_e64 v50, v75, v56, s[6:7]
	v_cndmask_b32_e64 v51, v76, v57, s[6:7]
	v_cndmask_b32_e64 v52, v52, v67, s[6:7]
	v_cndmask_b32_e64 v53, v53, v70, s[6:7]
	v_cndmask_b32_e64 v54, v54, v71, s[6:7]
	v_cndmask_b32_e64 v55, v55, v72, s[6:7]
	global_store_dwordx4 v[64:65], v[48:51], off
	global_store_dwordx4 v[68:69], v[52:55], off
	s_waitcnt vmcnt(12)
; __device__ __forceinline__ unsigned cvt_pk_bf16(float lo, float hi) { unsigned r; asm volatile("v_cvt_pk_bf16_f32 %0, %1, %2" : "=v"(r) : "v"(lo), "v"(hi)); return r; }
; #define PG8_WAIT_V(n) asm volatile("s_waitcnt vmcnt(" #n ")" ::: "memory")
; #define PG8_BAR __builtin_amdgcn_s_barrier()
;     __device__ __forceinline__ void operator()(const f32x4 (&acc)[2][2][4][2], const Unit& u, int wr, int wc, int fr, int fq) const {
;     ...
;             for (int m = 0; m < 4; ++m) { const int row = row0 + ai * HALF + m * 16;
;                 const float rs = ssin ? __builtin_amdgcn_rsqf(ssin[row] * (1.f / D) + EPS) : 1.0f; float sq = 0.f; u32x4 w[2];
; #pragma unroll
;                 for (int bj = 0; bj < 2; ++bj) { f32x4 v0 = acc[ai][bj][m][0] * rs, v1 = acc[ai][bj][m][1] * rs;
;                     if (ACT == 1) {
; #pragma unroll
;                         for (int j = 0; j < 4; ++j) { const float a = fmaxf(v0[j], 0.f), b = fmaxf(v1[j], 0.f); v0[j] = a * a; v1[j] = b * b; } }
;                     sq += (v0[0] * v0[0] + v0[1] * v0[1]) + (v0[2] * v0[2] + v0[3] * v0[3]) + (v1[0] * v1[0] + v1[1] * v1[1]) + (v1[2] * v1[2] + v1[3] * v1[3]);
;                     w[bj].x = cvt_pk_bf16(v0[0], v0[1]); w[bj].y = cvt_pk_bf16(v0[2], v0[3]); w[bj].z = cvt_pk_bf16(v1[0], v1[1]); w[bj].w = cvt_pk_bf16(v1[2], v1[3]); }
;                 store_pair_lines(O, ldc, row, fr, col0, w[0], w[1]);
;                 if (ssout) { sq += __shfl_xor(sq, 16); sq += __shfl_xor(sq, 32); if (fq == 0) unsafeAtomicAdd(ssout + row, sq); } }
; template <class Epi>
; __device__ __forceinline__ void gemm_phase(LAS unsigned char* lds, const Gemm g, const StaticOrder& S, const Epi& E) {
;     ...
;         E(acc, cur, wr, wc, fr, fq);
;         if (!has_next) break;
; #pragma unroll
;         for (int a = 0; a < 2; ++a)
; #pragma unroll
;             for (int b = 0; b < 2; ++b)
; #pragma unroll
;                 for (int m = 0; m < 4; ++m)
; #pragma unroll
;                     for (int n = 0; n < 2; ++n) acc[a][b][m][n] = (f32x4){0.f, 0.f, 0.f, 0.f};
;         cur = nxt; cA = nA; cB = nB; ++ui;
;     }
;     PG8_WAIT_V(0);
;     if (wr == 0) PG8_BAR;
;     PG8_BAR;
	s_nop 0
	v_mov_b32_e32 v50, v187
	s_nop 1
	v_mov_b32_e32 v51, 0
	v_add_u32_e32 v48, 0x90, v77
	v_add_u32_e32 v52, 0x98, v77
	v_mad_i64_i32 v[48:49], s[46:47], v48, s70, v[146:147]
	v_mad_i64_i32 v[52:53], s[46:47], v52, s70, v[146:147]
	v_lshl_add_u64 v[48:49], v[48:49], 0, v[148:149]
	v_lshl_add_u64 v[52:53], v[52:53], 0, v[148:149]
	v_fmamk_f32 v50, v50, 0x3a000000, v161
	v_rsq_f32_e32 v50, v50
	s_nop 0
	v_pk_mul_f32 v[44:45], v[44:45], v[50:51] op_sel_hi:[1,0]
	v_pk_mul_f32 v[40:41], v[40:41], v[50:51] op_sel_hi:[1,0]
	v_pk_mul_f32 v[38:39], v[38:39], v[50:51] op_sel_hi:[1,0]
	v_pk_mul_f32 v[36:37], v[36:37], v[50:51] op_sel_hi:[1,0]
	v_pk_mul_f32 v[46:47], v[46:47], v[50:51] op_sel_hi:[1,0]
	v_pk_mul_f32 v[42:43], v[42:43], v[50:51] op_sel_hi:[1,0]
	v_pk_mul_f32 v[34:35], v[34:35], v[50:51] op_sel_hi:[1,0]
	v_pk_mul_f32 v[32:33], v[32:33], v[50:51] op_sel_hi:[1,0]
	v_cvt_pk_bf16_f32 v44, v44, v45
	v_cvt_pk_bf16_f32 v45, v46, v47
	v_cvt_pk_bf16_f32 v40, v40, v41
	v_cvt_pk_bf16_f32 v41, v42, v43
	v_cvt_pk_bf16_f32 v36, v36, v37
	v_cvt_pk_bf16_f32 v37, v38, v39
	s_nop 0
	v_cvt_pk_bf16_f32 v38, v32, v33
	v_cvt_pk_bf16_f32 v39, v34, v35
	s_nop 0
	v_mov_b32_dpp v51, v44 row_ror:8 row_mask:0xf bank_mask:0xf
	v_mov_b32_dpp v54, v45 row_ror:8 row_mask:0xf bank_mask:0xf
	v_mov_b32_dpp v57, v36 row_ror:8 row_mask:0xf bank_mask:0xf
	v_mov_b32_dpp v58, v37 row_ror:8 row_mask:0xf bank_mask:0xf
	v_mov_b32_dpp v59, v38 row_ror:8 row_mask:0xf bank_mask:0xf
	v_mov_b32_dpp v60, v39 row_ror:8 row_mask:0xf bank_mask:0xf
	v_mov_b32_dpp v55, v40 row_ror:8 row_mask:0xf bank_mask:0xf
	v_mov_b32_dpp v56, v41 row_ror:8 row_mask:0xf bank_mask:0xf
	v_cndmask_b32_e64 v32, v57, v44, s[6:7]
	v_cndmask_b32_e64 v33, v58, v45, s[6:7]
	v_cndmask_b32_e64 v34, v59, v40, s[6:7]
	v_cndmask_b32_e64 v35, v60, v41, s[6:7]
	v_cndmask_b32_e64 v36, v36, v51, s[6:7]
	v_cndmask_b32_e64 v37, v37, v54, s[6:7]
	v_cndmask_b32_e64 v38, v38, v55, s[6:7]
	v_cndmask_b32_e64 v39, v39, v56, s[6:7]
	global_store_dwordx4 v[48:49], v[32:35], off
	global_store_dwordx4 v[52:53], v[36:39], off
	s_waitcnt vmcnt(13)
	s_nop 0
	v_mov_b32_e32 v34, v188
	s_nop 1
	v_mov_b32_e32 v35, 0
	v_add_u32_e32 v32, 0xa0, v77
	v_add_u32_e32 v36, 0xa8, v77
	v_mad_i64_i32 v[32:33], s[46:47], v32, s70, v[146:147]
	v_mad_i64_i32 v[36:37], s[46:47], v36, s70, v[146:147]
	v_lshl_add_u64 v[32:33], v[32:33], 0, v[148:149]
	v_lshl_add_u64 v[36:37], v[36:37], 0, v[148:149]
	s_mov_b64 s[46:47], s[38:39]
	v_fmamk_f32 v34, v34, 0x3a000000, v161
	v_rsq_f32_e32 v34, v34
	s_nop 0
	v_pk_mul_f32 v[28:29], v[28:29], v[34:35] op_sel_hi:[1,0]
	v_pk_mul_f32 v[24:25], v[24:25], v[34:35] op_sel_hi:[1,0]
	v_pk_mul_f32 v[22:23], v[22:23], v[34:35] op_sel_hi:[1,0]
	v_pk_mul_f32 v[20:21], v[20:21], v[34:35] op_sel_hi:[1,0]
	v_pk_mul_f32 v[30:31], v[30:31], v[34:35] op_sel_hi:[1,0]
	v_pk_mul_f32 v[26:27], v[26:27], v[34:35] op_sel_hi:[1,0]
	v_pk_mul_f32 v[18:19], v[18:19], v[34:35] op_sel_hi:[1,0]
	v_pk_mul_f32 v[16:17], v[16:17], v[34:35] op_sel_hi:[1,0]
	v_cvt_pk_bf16_f32 v28, v28, v29
	v_cvt_pk_bf16_f32 v29, v30, v31
	v_cvt_pk_bf16_f32 v24, v24, v25
	v_cvt_pk_bf16_f32 v25, v26, v27
	v_cvt_pk_bf16_f32 v20, v20, v21
	v_cvt_pk_bf16_f32 v21, v22, v23
	s_nop 0
	v_cvt_pk_bf16_f32 v22, v16, v17
	v_cvt_pk_bf16_f32 v23, v18, v19
	s_nop 0
	v_mov_b32_dpp v35, v28 row_ror:8 row_mask:0xf bank_mask:0xf
	v_mov_b32_dpp v38, v29 row_ror:8 row_mask:0xf bank_mask:0xf
	v_mov_b32_dpp v41, v20 row_ror:8 row_mask:0xf bank_mask:0xf
	v_mov_b32_dpp v42, v21 row_ror:8 row_mask:0xf bank_mask:0xf
	v_mov_b32_dpp v43, v22 row_ror:8 row_mask:0xf bank_mask:0xf
	v_mov_b32_dpp v44, v23 row_ror:8 row_mask:0xf bank_mask:0xf
	v_mov_b32_dpp v39, v24 row_ror:8 row_mask:0xf bank_mask:0xf
	v_mov_b32_dpp v40, v25 row_ror:8 row_mask:0xf bank_mask:0xf
	v_cndmask_b32_e64 v16, v41, v28, s[6:7]
	v_cndmask_b32_e64 v17, v42, v29, s[6:7]
	v_cndmask_b32_e64 v18, v43, v24, s[6:7]
	v_cndmask_b32_e64 v19, v44, v25, s[6:7]
	v_cndmask_b32_e64 v20, v20, v35, s[6:7]
	v_cndmask_b32_e64 v21, v21, v38, s[6:7]
	v_cndmask_b32_e64 v22, v22, v39, s[6:7]
	v_cndmask_b32_e64 v23, v23, v40, s[6:7]
	global_store_dwordx4 v[32:33], v[16:19], off
	global_store_dwordx4 v[36:37], v[20:23], off
	s_waitcnt vmcnt(14)
	s_nop 0
	v_mov_b32_e32 v18, v189
	s_nop 1
	v_mov_b32_e32 v19, 0
	v_add_u32_e32 v16, 0xb0, v77
	v_add_u32_e32 v20, 0xb8, v77
	v_mad_i64_i32 v[16:17], s[38:39], v16, s70, v[146:147]
	v_mad_i64_i32 v[20:21], s[38:39], v20, s70, v[146:147]
	v_lshl_add_u64 v[16:17], v[16:17], 0, v[148:149]
	v_lshl_add_u64 v[20:21], v[20:21], 0, v[148:149]
	v_fmamk_f32 v18, v18, 0x3a000000, v161
	v_rsq_f32_e32 v18, v18
	s_nop 0
	v_pk_mul_f32 v[12:13], v[12:13], v[18:19] op_sel_hi:[1,0]
	v_pk_mul_f32 v[8:9], v[8:9], v[18:19] op_sel_hi:[1,0]
	v_pk_mul_f32 v[6:7], v[6:7], v[18:19] op_sel_hi:[1,0]
	v_pk_mul_f32 v[4:5], v[4:5], v[18:19] op_sel_hi:[1,0]
	v_pk_mul_f32 v[14:15], v[14:15], v[18:19] op_sel_hi:[1,0]
	v_pk_mul_f32 v[10:11], v[10:11], v[18:19] op_sel_hi:[1,0]
	v_pk_mul_f32 v[2:3], v[2:3], v[18:19] op_sel_hi:[1,0]
	v_pk_mul_f32 v[0:1], v[0:1], v[18:19] op_sel_hi:[1,0]
	v_cvt_pk_bf16_f32 v12, v12, v13
	v_cvt_pk_bf16_f32 v13, v14, v15
	v_cvt_pk_bf16_f32 v8, v8, v9
	v_cvt_pk_bf16_f32 v9, v10, v11
	v_cvt_pk_bf16_f32 v4, v4, v5
	v_cvt_pk_bf16_f32 v5, v6, v7
	s_nop 0
	v_cvt_pk_bf16_f32 v6, v0, v1
	v_cvt_pk_bf16_f32 v7, v2, v3
	s_nop 0
	v_mov_b32_dpp v19, v12 row_ror:8 row_mask:0xf bank_mask:0xf
	v_mov_b32_dpp v22, v13 row_ror:8 row_mask:0xf bank_mask:0xf
	v_mov_b32_dpp v25, v4 row_ror:8 row_mask:0xf bank_mask:0xf
	v_mov_b32_dpp v26, v5 row_ror:8 row_mask:0xf bank_mask:0xf
	v_mov_b32_dpp v27, v6 row_ror:8 row_mask:0xf bank_mask:0xf
	v_mov_b32_dpp v28, v7 row_ror:8 row_mask:0xf bank_mask:0xf
	v_mov_b32_dpp v23, v8 row_ror:8 row_mask:0xf bank_mask:0xf
	v_mov_b32_dpp v24, v9 row_ror:8 row_mask:0xf bank_mask:0xf
	v_cndmask_b32_e64 v0, v25, v12, s[6:7]
	v_cndmask_b32_e64 v1, v26, v13, s[6:7]
	v_cndmask_b32_e64 v2, v27, v8, s[6:7]
	v_cndmask_b32_e64 v3, v28, v9, s[6:7]
	v_cndmask_b32_e64 v4, v4, v19, s[6:7]
	v_cndmask_b32_e64 v5, v5, v22, s[6:7]
	v_cndmask_b32_e64 v6, v6, v23, s[6:7]
	v_cndmask_b32_e64 v7, v7, v24, s[6:7]
	global_store_dwordx4 v[16:17], v[0:3], off
	global_store_dwordx4 v[20:21], v[4:7], off
	s_cbranch_vccz .LBB0_958
	s_waitcnt vmcnt(0)
	s_cmpk_gt_u32 s52, 0xff
	s_cbranch_scc1 .LBB0_966
	s_barrier

; #define LAS __attribute__((address_space(3)))
; __device__ __forceinline__ void vt_item(LAS unsigned char* lds, const bf16_t* src, int sstride, bf16_t* vt_rows, int tok0) {
;     int tid = threadIdx.x; asm volatile("" : "+v"(tid));
;     constexpr int TROW = 272;
; #pragma unroll
;     for (int i = 0; i < 2; ++i) { const int cid = tid + i * 512, row = cid >> 4, cc = cid & 15;
;         const u32x4 v = *(const u32x4*)(src + (size_t)row * sstride + cc * 8);
;         *(LAS u32x4*)(lds + row * TROW + cc * 16) = v; }
;     __syncthreads();
; #pragma unroll
;     for (int i = 0; i < 2; ++i) { const int wid2 = tid + i * 512, d = wid2 >> 3, ck = wid2 & 7;
;         unsigned short e[8];
; #pragma unroll
;         for (int j = 0; j < 8; ++j) { const int quad = (ck & 1) * 2 + (j >> 2); const int q2 = (quad == 1) ? 2 : (quad == 2 ? 1 : quad); const int t = (ck >> 1) * 16 + q2 * 4 + (j & 3);
;             e[j] = *(const LAS unsigned short*)(lds + t * TROW + d * 2); }
;         u32x4 o; o.x = e[0] | ((unsigned)e[1] << 16); o.y = e[2] | ((unsigned)e[3] << 16); o.z = e[4] | ((unsigned)e[5] << 16); o.w = e[6] | ((unsigned)e[7] << 16);
;         *(u32x4*)(vt_rows + (size_t)d * M + tok0 + ck * 8) = o; }
;     __syncthreads();
; __global__ void __launch_bounds__(NTHREADS, 2) fwd_megakernel(Params P) {
;     ...
;                 _Pragma("unroll 1") for (int rp_ = 0; rp_ < REP_PREP; ++rp_) for (int it = bid; it < 256 * 4; it += G) { const int tt = it >> 2, h = it & 3;
;                     vt_item(lds, Z3 + (size_t)(tt * 64) * OD_IN + 2560 + h * 128, OD_IN, SVT + (size_t)(h * 128) * M, tt * 64); }
.LBB0_1021:
	s_cmp_lg_u32 s8, s50
	s_mov_b64 s[8:9], -1
	s_cbranch_scc0 .LBB0_1025
	s_andn2_b64 vcc, exec, s[38:39]
	s_mov_b32 s16, s53
	s_mov_b32 s59, s51
	s_mov_b32 s60, s44
	s_cbranch_vccnz .LBB0_1024
	v_mov_b32_e32 v111, v41
	s_and_b32 s8, s59, 0xffffffc0
	s_mul_i32 s61, s8, 0x1800
	s_mul_hi_i32 s33, s8, 0x1800
	s_add_u32 s61, s46, s61
	s_addc_u32 s33, s47, s33
	s_and_b32 s64, s16, 0x180
	v_mov_b32_e32 v104, v202
	s_lshl_b32 s62, s64, 1
	s_add_u32 s62, s61, s62
	v_lshlrev_b32_e32 v112, 4, v104
	v_and_b32_e32 v110, 0xf0, v112
	s_addc_u32 s63, s33, 0
	v_add_u32_e32 v106, 0x200, v104
	v_lshl_add_u64 v[70:71], s[62:63], 0, v[110:111]
	v_ashrrev_i32_e32 v109, 4, v104
	v_ashrrev_i32_e32 v113, 4, v106
	v_lshl_add_u64 v[70:71], v[70:71], 0, s[40:41]
	v_mad_i64_i32 v[100:101], s[62:63], v109, s45, v[70:71]
	s_nop 1
	v_mad_i64_i32 v[102:103], s[62:63], v113, s45, v[70:71]
	s_nop 1
	global_load_dwordx4 v[116:119], v[100:101], off
	global_load_dwordx4 v[120:123], v[102:103], off
	global_load_dword v72, v[100:101], off
	global_load_dword v74, v[102:103], off
.LBB0_1023:
	s_and_b32 s8, s59, 0xffffffc0
	s_ashr_i32 s9, s8, 31
	s_mul_i32 s61, s8, 0x1800
	s_mul_hi_i32 s33, s8, 0x1800
	s_add_u32 s61, s46, s61
	s_addc_u32 s33, s47, s33
	s_and_b32 s64, s16, 0x180
	v_mov_b32_e32 v32, v202
	s_lshl_b32 s62, s64, 1
	s_add_u32 s62, s61, s62
	v_lshlrev_b32_e32 v64, 4, v32
	v_and_b32_e32 v40, 0xf0, v64
	s_addc_u32 s63, s33, 0
	v_add_u32_e32 v34, 0x200, v32
	v_lshl_add_u64 v[24:25], s[62:63], 0, v[40:41]
	v_ashrrev_i32_e32 v37, 4, v32
	v_ashrrev_i32_e32 v65, 4, v34
	v_lshl_add_u64 v[24:25], v[24:25], 0, s[40:41]
	v_mad_i64_i32 v[26:27], s[62:63], v37, s45, v[24:25]
	v_mad_i64_i32 v[28:29], s[62:63], v65, s45, v[24:25]
	s_nop 0
	s_nop 0
	s_nop 0
	v_lshlrev_b32_e32 v33, 1, v32
	s_lshl_b32 s33, s64, 15
	v_lshlrev_b32_e32 v35, 3, v32
	v_and_b32_e32 v38, 2, v33
	s_add_u32 s33, s48, s33
	v_ashrrev_i32_e32 v32, 3, v32
	v_and_b32_e32 v66, 48, v35
	v_ashrrev_i32_e32 v34, 3, v34
	v_add_u32_e32 v36, 0, v40
	v_cmp_eq_u32_e32 vcc, 0, v38
	s_addc_u32 s61, s49, 0
	s_lshl_b64 s[8:9], s[8:9], 1
	v_lshl_add_u32 v67, v32, 1, 0
	v_lshl_or_b32 v40, v38, 1, v66
	v_cndmask_b32_e64 v68, 12, 8, vcc
	v_lshl_add_u32 v69, v34, 1, 0
	v_mad_u64_u32 v[38:39], s[62:63], v37, s19, v[36:37]
	v_mad_u64_u32 v[36:37], s[62:63], v65, s19, v[36:37]
	s_add_u32 s8, s33, s8
	v_ashrrev_i32_e32 v33, 31, v32
	v_ashrrev_i32_e32 v35, 31, v34
	v_mad_u32_u24 v37, v40, s19, v67
	v_or_b32_e32 v39, v68, v66
	v_mad_u32_u24 v66, v40, s19, v69
	v_and_b32_e32 v40, 0x70, v64
	s_addc_u32 s9, s61, s9
	v_lshlrev_b64 v[32:33], 15, v[32:33]
	v_lshlrev_b64 v[34:35], 15, v[34:35]
	v_mad_u32_u24 v67, v39, s19, v67
	v_mad_u32_u24 v39, v39, s19, v69
	v_lshl_add_u64 v[64:65], s[8:9], 0, v[40:41]
	v_lshl_add_u64 v[32:33], v[64:65], 0, v[32:33]
	v_lshl_add_u64 v[34:35], v[64:65], 0, v[34:35]
	s_add_i32 s60, s60, s20
	s_add_i32 s59, s59, s52
	s_add_i32 s16, s16, s76
	s_cmpk_lt_i32 s60, 0x400
	s_waitcnt vmcnt(3)
	ds_write_b128 v38, v[116:119]
	s_waitcnt vmcnt(2)
	ds_write_b128 v36, v[120:123]
	s_waitcnt lgkmcnt(0)
	v_mov_b32_e32 v111, v41
	s_and_b32 s8, s59, 0xffffffc0
	s_mul_i32 s61, s8, 0x1800
	s_mul_hi_i32 s33, s8, 0x1800
	s_add_u32 s61, s46, s61
	s_addc_u32 s33, s47, s33
	s_and_b32 s64, s16, 0x180
	v_mov_b32_e32 v104, v202
	s_lshl_b32 s62, s64, 1
	s_add_u32 s62, s61, s62
	v_lshlrev_b32_e32 v112, 4, v104
	v_and_b32_e32 v110, 0xf0, v112
	s_addc_u32 s63, s33, 0
	v_add_u32_e32 v106, 0x200, v104
	v_lshl_add_u64 v[70:71], s[62:63], 0, v[110:111]
	v_ashrrev_i32_e32 v109, 4, v104
	v_ashrrev_i32_e32 v113, 4, v106
	v_lshl_add_u64 v[70:71], v[70:71], 0, s[40:41]
	v_mad_i64_i32 v[100:101], s[62:63], v109, s45, v[70:71]
	s_nop 1
	v_mad_i64_i32 v[102:103], s[62:63], v113, s45, v[70:71]
	s_nop 1
	global_load_dwordx4 v[116:119], v[100:101], off
	global_load_dwordx4 v[120:123], v[102:103], off
	s_cmpk_lt_i32 s60, 0x400
	s_barrier
	ds_read_u16 v24, v37
	ds_read_u16 v28, v37 offset:272
	ds_read_u16 v25, v37 offset:544
	ds_read_u16 v29, v37 offset:816
	ds_read_u16 v26, v67
	ds_read_u16 v30, v67 offset:272
	ds_read_u16 v27, v67 offset:544
	ds_read_u16 v31, v67 offset:816
	ds_read_u16 v36, v66
	ds_read_u16 v37, v66 offset:272
	ds_read_u16 v38, v66 offset:544
	ds_read_u16 v40, v66 offset:816
	ds_read_u16 v64, v39
	ds_read_u16 v65, v39 offset:272
	ds_read_u16 v66, v39 offset:544
	ds_read_u16 v39, v39 offset:816
	s_waitcnt lgkmcnt(8)
	v_perm_b32 v27, v31, v27, s54
	v_perm_b32 v26, v30, v26, s54
	v_perm_b32 v25, v29, v25, s54
	v_perm_b32 v24, v28, v24, s54
	s_waitcnt lgkmcnt(0)
	v_perm_b32 v31, v39, v66, s54
	v_perm_b32 v30, v65, v64, s54
	v_perm_b32 v29, v40, v38, s54
	v_perm_b32 v28, v37, v36, s54
	global_store_dwordx4 v[32:33], v[24:27], off
	global_store_dwordx4 v[34:35], v[28:31], off
	s_barrier
	s_cbranch_scc1 .LBB0_1023
	s_waitcnt vmcnt(0)

; #define LAS __attribute__((address_space(3)))
; __device__ __forceinline__ unsigned cvt_pk_bf16(float lo, float hi) { unsigned r; asm volatile("v_cvt_pk_bf16_f32 %0, %1, %2" : "=v"(r) : "v"(lo), "v"(hi)); return r; }
; __device__ __forceinline__ void transpose_item(const float* W, int K, int N, bf16_t* WT, LAS float* scr, int item, int lane, const float* gk) {
;     ...
;     for (int i = 0; i < 16; ++i) { LAS float* d = scr + (4 * i + (lane >> 4)) * 65 + 4 * (lane & 15); d[0] = v[i][0]; d[1] = v[i][1]; d[2] = v[i][2]; d[3] = v[i][3]; }
;     asm volatile("s_waitcnt lgkmcnt(0)" ::: "memory");
;     const int c = lane & 7;
; #pragma unroll
;     for (int j = 0; j < 8; ++j) { const int n = (lane >> 3) + 8 * j; const LAS float* s = scr + (8 * c) * 65 + n;
;         u32x4 o; o.x = cvt_pk_bf16(s[0 * 65], s[1 * 65]); o.y = cvt_pk_bf16(s[2 * 65], s[3 * 65]); o.z = cvt_pk_bf16(s[4 * 65], s[5 * 65]); o.w = cvt_pk_bf16(s[6 * 65], s[7 * 65]);
;         *(u32x4*)(WT + (size_t)(n0 + n) * K + k0 + 8 * c) = o; }
.LBB0_1108:
	v_add_u32_e32 v0, v180, v181
	s_waitcnt vmcnt(15)
	ds_write2_b32 v0, v6, v7 offset1:1
	ds_write2_b32 v0, v8, v9 offset0:2 offset1:3
	v_add_u32_e32 v6, 0x410, v0
	s_waitcnt vmcnt(14)
	ds_write2_b32 v6, v2, v3 offset1:1
	v_add_u32_e32 v2, 0x418, v0
	ds_write2_b32 v2, v4, v5 offset1:1
	v_add_u32_e32 v2, 0x820, v0
	s_waitcnt vmcnt(13)
	ds_write2_b32 v2, v14, v15 offset1:1
	v_add_u32_e32 v2, 0x828, v0
	ds_write2_b32 v2, v16, v17 offset1:1
	v_add_u32_e32 v2, 0xc30, v0
	s_waitcnt vmcnt(12)
	ds_write2_b32 v2, v10, v11 offset1:1
	v_add_u32_e32 v2, 0xc38, v0
	ds_write2_b32 v2, v12, v13 offset1:1
	v_add_u32_e32 v2, 0x1040, v0
	s_waitcnt vmcnt(11)
	ds_write2_b32 v2, v22, v23 offset1:1
	v_add_u32_e32 v2, 0x1048, v0
	ds_write2_b32 v2, v24, v25 offset1:1
	v_add_u32_e32 v2, 0x1450, v0
	s_waitcnt vmcnt(10)
	ds_write2_b32 v2, v18, v19 offset1:1
	v_add_u32_e32 v2, 0x1458, v0
	ds_write2_b32 v2, v20, v21 offset1:1
	v_add_u32_e32 v2, 0x1860, v0
	s_waitcnt vmcnt(9)
	ds_write2_b32 v2, v30, v31 offset1:1
	v_add_u32_e32 v2, 0x1868, v0
	ds_write2_b32 v2, v32, v33 offset1:1
	v_add_u32_e32 v2, 0x1c70, v0
	s_waitcnt vmcnt(8)
	ds_write2_b32 v2, v26, v27 offset1:1
	v_add_u32_e32 v2, 0x1c78, v0
	ds_write2_b32 v2, v28, v29 offset1:1
	v_add_u32_e32 v2, 0x2080, v0
	s_waitcnt vmcnt(7)
	ds_write2_b32 v2, v38, v39 offset1:1
	v_add_u32_e32 v2, 0x2088, v0
	ds_write2_b32 v2, v40, v41 offset1:1
	v_add_u32_e32 v2, 0x2490, v0
	s_waitcnt vmcnt(6)
	ds_write2_b32 v2, v34, v35 offset1:1
	v_add_u32_e32 v2, 0x2498, v0
	ds_write2_b32 v2, v36, v37 offset1:1
	v_add_u32_e32 v2, 0x28a0, v0
	s_waitcnt vmcnt(5)
	ds_write2_b32 v2, v46, v47 offset1:1
	v_add_u32_e32 v2, 0x28a8, v0
	ds_write2_b32 v2, v48, v49 offset1:1
	v_add_u32_e32 v2, 0x2cb0, v0
	s_waitcnt vmcnt(4)
	ds_write2_b32 v2, v42, v43 offset1:1
	v_add_u32_e32 v2, 0x2cb8, v0
	ds_write2_b32 v2, v44, v45 offset1:1
	v_add_u32_e32 v2, 0x30c0, v0
	s_waitcnt vmcnt(3)
	ds_write2_b32 v2, v54, v55 offset1:1
	v_add_u32_e32 v2, 0x30c8, v0
	ds_write2_b32 v2, v56, v57 offset1:1
	v_add_u32_e32 v2, 0x34d0, v0
	s_waitcnt vmcnt(2)
	ds_write2_b32 v2, v50, v51 offset1:1
	v_add_u32_e32 v2, 0x34d8, v0
	ds_write2_b32 v2, v52, v53 offset1:1
	v_add_u32_e32 v2, 0x38e0, v0
	s_waitcnt vmcnt(1)
	ds_write2_b32 v2, v62, v63 offset1:1
	v_add_u32_e32 v2, 0x38e8, v0
	ds_write2_b32 v2, v64, v65 offset1:1
	v_add_u32_e32 v2, 0x3cf0, v0
	v_add_u32_e32 v0, 0x3cf8, v0
	s_waitcnt vmcnt(0)
	ds_write2_b32 v2, v58, v59 offset1:1
	ds_write2_b32 v0, v60, v61 offset1:1
	s_waitcnt lgkmcnt(0)
	v_add_u32_e32 v14, 0x400, v183
	ds_read2_b32 v[16:17], v183 offset1:65
	ds_read2_b32 v[18:19], v183 offset0:130 offset1:195
	ds_read2_b32 v[20:21], v14 offset0:4 offset1:69
	ds_read2_b32 v[22:23], v14 offset0:134 offset1:199
	ds_read2_b32 v[24:25], v183 offset0:8 offset1:73
	ds_read2_b32 v[26:27], v183 offset0:138 offset1:203
	ds_read2_b32 v[28:29], v14 offset0:12 offset1:77
	ds_read2_b32 v[30:31], v14 offset0:142 offset1:207
	ds_read2_b32 v[32:33], v183 offset0:16 offset1:81
	ds_read2_b32 v[34:35], v183 offset0:146 offset1:211
	ds_read2_b32 v[36:37], v14 offset0:20 offset1:85
	ds_read2_b32 v[38:39], v14 offset0:150 offset1:215
	ds_read2_b32 v[40:41], v183 offset0:24 offset1:89
	ds_read2_b32 v[42:43], v183 offset0:154 offset1:219
	ds_read2_b32 v[44:45], v14 offset0:28 offset1:93
	ds_read2_b32 v[46:47], v14 offset0:158 offset1:223
	ds_read2_b32 v[48:49], v183 offset0:32 offset1:97
	ds_read2_b32 v[50:51], v183 offset0:162 offset1:227
	ds_read2_b32 v[52:53], v14 offset0:36 offset1:101
	ds_read2_b32 v[54:55], v14 offset0:166 offset1:231
	ds_read2_b32 v[56:57], v183 offset0:40 offset1:105
	ds_read2_b32 v[58:59], v183 offset0:170 offset1:235
	ds_read2_b32 v[60:61], v14 offset0:44 offset1:109
	ds_read2_b32 v[62:63], v14 offset0:174 offset1:239
	ds_read2_b32 v[64:65], v183 offset0:48 offset1:113
	ds_read2_b32 v[70:71], v183 offset0:178 offset1:243
	ds_read2_b32 v[100:101], v14 offset0:52 offset1:117
	ds_read2_b32 v[102:103], v14 offset0:182 offset1:247
	ds_read2_b32 v[104:105], v183 offset0:56 offset1:121
	ds_read2_b32 v[106:107], v183 offset0:186 offset1:251
	ds_read2_b32 v[108:109], v14 offset0:60 offset1:125
	ds_read2_b32 v[110:111], v14 offset0:190 offset1:255
	s_waitcnt lgkmcnt(15)
; #define LAS __attribute__((address_space(3)))
; __device__ __forceinline__ unsigned cvt_pk_bf16(float lo, float hi) { unsigned r; asm volatile("v_cvt_pk_bf16_f32 %0, %1, %2" : "=v"(r) : "v"(lo), "v"(hi)); return r; }
; __device__ __forceinline__ void transpose_item(const float* W, int K, int N, bf16_t* WT, LAS float* scr, int item, int lane, const float* gk) {
;     ...
;     const int c = lane & 7;
; #pragma unroll
;     for (int j = 0; j < 8; ++j) { const int n = (lane >> 3) + 8 * j; const LAS float* s = scr + (8 * c) * 65 + n;
;         u32x4 o; o.x = cvt_pk_bf16(s[0 * 65], s[1 * 65]); o.y = cvt_pk_bf16(s[2 * 65], s[3 * 65]); o.z = cvt_pk_bf16(s[4 * 65], s[5 * 65]); o.w = cvt_pk_bf16(s[6 * 65], s[7 * 65]);
;         *(u32x4*)(WT + (size_t)(n0 + n) * K + k0 + 8 * c) = o; }
;     asm volatile("s_waitcnt lgkmcnt(0)" ::: "memory");
	v_cvt_pk_bf16_f32 v4, v16, v17
	s_waitcnt lgkmcnt(15)
	v_cvt_pk_bf16_f32 v5, v18, v19
	s_waitcnt lgkmcnt(15)
	v_cvt_pk_bf16_f32 v6, v20, v21
	v_add_u32_e32 v15, s50, v182
	s_waitcnt lgkmcnt(15)
	v_cvt_pk_bf16_f32 v7, v22, v23
	v_mad_u64_u32 v[8:9], s[50:51], v15, s54, 0
	v_ashrrev_i32_e32 v12, 31, v15
	v_mov_b32_e32 v0, v9
	s_ashr_i32 s53, s52, 31
	v_mad_u64_u32 v[12:13], s[50:51], v12, s54, v[0:1]
	v_lshl_add_u64 v[2:3], s[52:53], 1, v[66:67]
	v_mov_b32_e32 v9, v12
	v_lshl_add_u64 v[8:9], v[8:9], 1, v[2:3]
	global_store_dwordx4 v[8:9], v[4:7], off
	v_add_u32_e32 v0, 8, v15
	v_ashrrev_i32_e32 v12, 31, v0
	s_waitcnt lgkmcnt(15)
	v_cvt_pk_bf16_f32 v4, v24, v25
	s_waitcnt lgkmcnt(15)
	v_cvt_pk_bf16_f32 v5, v26, v27
	s_waitcnt lgkmcnt(15)
	v_cvt_pk_bf16_f32 v6, v28, v29
	s_waitcnt lgkmcnt(15)
	v_cvt_pk_bf16_f32 v7, v30, v31
	v_mad_u64_u32 v[8:9], s[50:51], v0, s54, 0
	v_mov_b32_e32 v0, v9
	v_mad_u64_u32 v[12:13], s[50:51], v12, s54, v[0:1]
	v_mov_b32_e32 v9, v12
	v_lshl_add_u64 v[8:9], v[8:9], 1, v[2:3]
	global_store_dwordx4 v[8:9], v[4:7], off
	v_add_u32_e32 v0, 16, v15
	v_ashrrev_i32_e32 v12, 31, v0
	s_waitcnt lgkmcnt(15)
	v_cvt_pk_bf16_f32 v4, v32, v33
	s_waitcnt lgkmcnt(15)
	v_cvt_pk_bf16_f32 v5, v34, v35
	s_waitcnt lgkmcnt(15)
	v_cvt_pk_bf16_f32 v6, v36, v37
	s_waitcnt lgkmcnt(15)
	v_cvt_pk_bf16_f32 v7, v38, v39
	v_mad_u64_u32 v[8:9], s[50:51], v0, s54, 0
	v_mov_b32_e32 v0, v9
	v_mad_u64_u32 v[12:13], s[50:51], v12, s54, v[0:1]
	v_mov_b32_e32 v9, v12
	v_lshl_add_u64 v[8:9], v[8:9], 1, v[2:3]
	global_store_dwordx4 v[8:9], v[4:7], off
	v_add_u32_e32 v0, 24, v15
	v_ashrrev_i32_e32 v12, 31, v0
	s_waitcnt lgkmcnt(15)
	v_cvt_pk_bf16_f32 v4, v40, v41
	s_waitcnt lgkmcnt(15)
	v_cvt_pk_bf16_f32 v5, v42, v43
	s_waitcnt lgkmcnt(15)
	v_cvt_pk_bf16_f32 v6, v44, v45
	s_waitcnt lgkmcnt(15)
	v_cvt_pk_bf16_f32 v7, v46, v47
	v_mad_u64_u32 v[8:9], s[50:51], v0, s54, 0
	v_mov_b32_e32 v0, v9
	v_mad_u64_u32 v[12:13], s[50:51], v12, s54, v[0:1]
	v_mov_b32_e32 v9, v12
	v_lshl_add_u64 v[8:9], v[8:9], 1, v[2:3]
	global_store_dwordx4 v[8:9], v[4:7], off
	v_add_u32_e32 v0, 32, v15
	v_ashrrev_i32_e32 v12, 31, v0
	s_waitcnt lgkmcnt(15)
	v_cvt_pk_bf16_f32 v4, v48, v49
	s_waitcnt lgkmcnt(14)
	v_cvt_pk_bf16_f32 v5, v50, v51
	s_waitcnt lgkmcnt(13)
	v_cvt_pk_bf16_f32 v6, v52, v53
	s_waitcnt lgkmcnt(12)
	v_cvt_pk_bf16_f32 v7, v54, v55
	v_mad_u64_u32 v[8:9], s[50:51], v0, s54, 0
	v_mov_b32_e32 v0, v9
	v_mad_u64_u32 v[12:13], s[50:51], v12, s54, v[0:1]
	v_mov_b32_e32 v9, v12
	v_lshl_add_u64 v[8:9], v[8:9], 1, v[2:3]
	global_store_dwordx4 v[8:9], v[4:7], off
	v_add_u32_e32 v0, 40, v15
	v_ashrrev_i32_e32 v12, 31, v0
	s_waitcnt lgkmcnt(11)
	v_cvt_pk_bf16_f32 v4, v56, v57
	s_waitcnt lgkmcnt(10)
	v_cvt_pk_bf16_f32 v5, v58, v59
	s_waitcnt lgkmcnt(9)
	v_cvt_pk_bf16_f32 v6, v60, v61
	s_waitcnt lgkmcnt(8)
	v_cvt_pk_bf16_f32 v7, v62, v63
	v_mad_u64_u32 v[8:9], s[50:51], v0, s54, 0
	v_mov_b32_e32 v0, v9
	v_mad_u64_u32 v[12:13], s[50:51], v12, s54, v[0:1]
	v_mov_b32_e32 v9, v12
	v_lshl_add_u64 v[8:9], v[8:9], 1, v[2:3]
	global_store_dwordx4 v[8:9], v[4:7], off
	v_add_u32_e32 v0, 48, v15
	v_ashrrev_i32_e32 v12, 31, v0
	s_waitcnt lgkmcnt(7)
	v_cvt_pk_bf16_f32 v4, v64, v65
	s_waitcnt lgkmcnt(6)
	v_cvt_pk_bf16_f32 v5, v70, v71
	s_waitcnt lgkmcnt(5)
	v_cvt_pk_bf16_f32 v6, v100, v101
	s_waitcnt lgkmcnt(4)
	v_cvt_pk_bf16_f32 v7, v102, v103
	v_mad_u64_u32 v[8:9], s[50:51], v0, s54, 0
	v_mov_b32_e32 v0, v9
	v_mad_u64_u32 v[12:13], s[50:51], v12, s54, v[0:1]
	v_mov_b32_e32 v9, v12
	v_lshl_add_u64 v[8:9], v[8:9], 1, v[2:3]
	global_store_dwordx4 v[8:9], v[4:7], off
	v_add_u32_e32 v0, 56, v15
	s_add_i32 s76, s76, s26
	s_waitcnt lgkmcnt(3)
	v_cvt_pk_bf16_f32 v4, v104, v105
	s_waitcnt lgkmcnt(2)
	v_cvt_pk_bf16_f32 v5, v106, v107
	s_waitcnt lgkmcnt(1)
	v_cvt_pk_bf16_f32 v6, v108, v109
	s_waitcnt lgkmcnt(0)
	v_cvt_pk_bf16_f32 v7, v110, v111
	v_mad_u64_u32 v[8:9], s[50:51], v0, s54, 0
	v_ashrrev_i32_e32 v10, 31, v0
	v_mov_b32_e32 v0, v9
	v_mad_u64_u32 v[10:11], s[50:51], v10, s54, v[0:1]
	v_mov_b32_e32 v9, v10
	v_lshl_add_u64 v[2:3], v[8:9], 1, v[2:3]
	global_store_dwordx4 v[2:3], v[4:7], off
	s_waitcnt lgkmcnt(0)
	s_add_i32 s74, s74, s75
	s_cmp_lt_i32 s76, s57
	s_cbranch_scc0 .LBB0_1088

; #define LAS __attribute__((address_space(3)))
; __device__ __forceinline__ unsigned cvt_pk_bf16(float lo, float hi) { unsigned r; asm volatile("v_cvt_pk_bf16_f32 %0, %1, %2" : "=v"(r) : "v"(lo), "v"(hi)); return r; }
; __device__ __forceinline__ void transpose_item(const float* W, int K, int N, bf16_t* WT, LAS float* scr, int item, int lane, const float* gk) {
;     ...
;     for (int i = 0; i < 16; ++i) { LAS float* d = scr + (4 * i + (lane >> 4)) * 65 + 4 * (lane & 15); d[0] = v[i][0]; d[1] = v[i][1]; d[2] = v[i][2]; d[3] = v[i][3]; }
;     asm volatile("s_waitcnt lgkmcnt(0)" ::: "memory");
;     const int c = lane & 7;
; #pragma unroll
;     for (int j = 0; j < 8; ++j) { const int n = (lane >> 3) + 8 * j; const LAS float* s = scr + (8 * c) * 65 + n;
;         u32x4 o; o.x = cvt_pk_bf16(s[0 * 65], s[1 * 65]); o.y = cvt_pk_bf16(s[2 * 65], s[3 * 65]); o.z = cvt_pk_bf16(s[4 * 65], s[5 * 65]); o.w = cvt_pk_bf16(s[6 * 65], s[7 * 65]);
;         *(u32x4*)(WT + (size_t)(n0 + n) * K + k0 + 8 * c) = o; }
.LBB0_1162:
	v_add_u32_e32 v68, v180, v181
	s_waitcnt vmcnt(15)
	ds_write2_b32 v68, v4, v5 offset1:1
	ds_write2_b32 v68, v6, v7 offset0:2 offset1:3
	v_add_u32_e32 v4, 0x410, v68
	s_waitcnt vmcnt(14)
	ds_write2_b32 v4, v0, v1 offset1:1
	v_add_u32_e32 v0, 0x418, v68
	ds_write2_b32 v0, v2, v3 offset1:1
	v_add_u32_e32 v0, 0x820, v68
	s_waitcnt vmcnt(13)
	ds_write2_b32 v0, v12, v13 offset1:1
	v_add_u32_e32 v0, 0x828, v68
	ds_write2_b32 v0, v14, v15 offset1:1
	v_add_u32_e32 v0, 0xc30, v68
	s_waitcnt vmcnt(12)
	ds_write2_b32 v0, v8, v9 offset1:1
	v_add_u32_e32 v0, 0xc38, v68
	ds_write2_b32 v0, v10, v11 offset1:1
	v_add_u32_e32 v0, 0x1040, v68
	s_waitcnt vmcnt(11)
	ds_write2_b32 v0, v20, v21 offset1:1
	v_add_u32_e32 v0, 0x1048, v68
	ds_write2_b32 v0, v22, v23 offset1:1
	v_add_u32_e32 v0, 0x1450, v68
	s_waitcnt vmcnt(10)
	ds_write2_b32 v0, v16, v17 offset1:1
	v_add_u32_e32 v0, 0x1458, v68
	ds_write2_b32 v0, v18, v19 offset1:1
	v_add_u32_e32 v0, 0x1860, v68
	s_waitcnt vmcnt(9)
	ds_write2_b32 v0, v28, v29 offset1:1
	v_add_u32_e32 v0, 0x1868, v68
	ds_write2_b32 v0, v30, v31 offset1:1
	v_add_u32_e32 v0, 0x1c70, v68
	s_waitcnt vmcnt(8)
	ds_write2_b32 v0, v24, v25 offset1:1
	v_add_u32_e32 v0, 0x1c78, v68
	ds_write2_b32 v0, v26, v27 offset1:1
	v_add_u32_e32 v0, 0x2080, v68
	s_waitcnt vmcnt(7)
	ds_write2_b32 v0, v36, v37 offset1:1
	v_add_u32_e32 v0, 0x2088, v68
	ds_write2_b32 v0, v38, v39 offset1:1
	v_add_u32_e32 v0, 0x2490, v68
	s_waitcnt vmcnt(6)
	ds_write2_b32 v0, v32, v33 offset1:1
	v_add_u32_e32 v0, 0x2498, v68
	ds_write2_b32 v0, v34, v35 offset1:1
	v_add_u32_e32 v0, 0x28a0, v68
	s_waitcnt vmcnt(5)
	ds_write2_b32 v0, v44, v45 offset1:1
	v_add_u32_e32 v0, 0x28a8, v68
	ds_write2_b32 v0, v46, v47 offset1:1
	v_add_u32_e32 v0, 0x2cb0, v68
	s_waitcnt vmcnt(4)
	ds_write2_b32 v0, v40, v41 offset1:1
	v_add_u32_e32 v0, 0x2cb8, v68
	ds_write2_b32 v0, v42, v43 offset1:1
	v_add_u32_e32 v0, 0x30c0, v68
	s_waitcnt vmcnt(3)
	ds_write2_b32 v0, v52, v53 offset1:1
	v_add_u32_e32 v0, 0x30c8, v68
	ds_write2_b32 v0, v54, v55 offset1:1
	v_add_u32_e32 v0, 0x34d0, v68
	s_waitcnt vmcnt(2)
	ds_write2_b32 v0, v48, v49 offset1:1
	v_add_u32_e32 v0, 0x34d8, v68
	ds_write2_b32 v0, v50, v51 offset1:1
	v_add_u32_e32 v0, 0x38e0, v68
	s_waitcnt vmcnt(1)
	ds_write2_b32 v0, v60, v61 offset1:1
	v_add_u32_e32 v0, 0x38e8, v68
	ds_write2_b32 v0, v62, v63 offset1:1
	v_add_u32_e32 v0, 0x3cf0, v68
	s_waitcnt vmcnt(0)
	ds_write2_b32 v0, v56, v57 offset1:1
	v_add_u32_e32 v0, 0x3cf8, v68
	ds_write2_b32 v0, v58, v59 offset1:1
	s_waitcnt lgkmcnt(0)
	v_add_u32_e32 v12, 0x400, v183
	ds_read2_b32 v[14:15], v183 offset1:65
	ds_read2_b32 v[16:17], v183 offset0:130 offset1:195
	ds_read2_b32 v[18:19], v12 offset0:4 offset1:69
	ds_read2_b32 v[20:21], v12 offset0:134 offset1:199
	ds_read2_b32 v[22:23], v183 offset0:8 offset1:73
	ds_read2_b32 v[24:25], v183 offset0:138 offset1:203
	ds_read2_b32 v[26:27], v12 offset0:12 offset1:77
	ds_read2_b32 v[28:29], v12 offset0:142 offset1:207
	ds_read2_b32 v[30:31], v183 offset0:16 offset1:81
	ds_read2_b32 v[32:33], v183 offset0:146 offset1:211
	ds_read2_b32 v[34:35], v12 offset0:20 offset1:85
	ds_read2_b32 v[36:37], v12 offset0:150 offset1:215
	ds_read2_b32 v[38:39], v183 offset0:24 offset1:89
	ds_read2_b32 v[40:41], v183 offset0:154 offset1:219
	ds_read2_b32 v[42:43], v12 offset0:28 offset1:93
	ds_read2_b32 v[44:45], v12 offset0:158 offset1:223
	ds_read2_b32 v[46:47], v183 offset0:32 offset1:97
	ds_read2_b32 v[48:49], v183 offset0:162 offset1:227
	ds_read2_b32 v[50:51], v12 offset0:36 offset1:101
	ds_read2_b32 v[52:53], v12 offset0:166 offset1:231
	ds_read2_b32 v[54:55], v183 offset0:40 offset1:105
	ds_read2_b32 v[56:57], v183 offset0:170 offset1:235
	ds_read2_b32 v[58:59], v12 offset0:44 offset1:109
	ds_read2_b32 v[60:61], v12 offset0:174 offset1:239
	ds_read2_b32 v[62:63], v183 offset0:48 offset1:113
	ds_read2_b32 v[68:69], v183 offset0:178 offset1:243
	ds_read2_b32 v[70:71], v12 offset0:52 offset1:117
	ds_read2_b32 v[72:73], v12 offset0:182 offset1:247
	ds_read2_b32 v[100:101], v183 offset0:56 offset1:121
	ds_read2_b32 v[102:103], v183 offset0:186 offset1:251
	ds_read2_b32 v[104:105], v12 offset0:60 offset1:125
	ds_read2_b32 v[106:107], v12 offset0:190 offset1:255
	s_waitcnt lgkmcnt(15)
; #define LAS __attribute__((address_space(3)))
; __device__ __forceinline__ unsigned cvt_pk_bf16(float lo, float hi) { unsigned r; asm volatile("v_cvt_pk_bf16_f32 %0, %1, %2" : "=v"(r) : "v"(lo), "v"(hi)); return r; }
; __device__ __forceinline__ void transpose_item(const float* W, int K, int N, bf16_t* WT, LAS float* scr, int item, int lane, const float* gk) {
;     ...
;     const int c = lane & 7;
; #pragma unroll
;     for (int j = 0; j < 8; ++j) { const int n = (lane >> 3) + 8 * j; const LAS float* s = scr + (8 * c) * 65 + n;
;         u32x4 o; o.x = cvt_pk_bf16(s[0 * 65], s[1 * 65]); o.y = cvt_pk_bf16(s[2 * 65], s[3 * 65]); o.z = cvt_pk_bf16(s[4 * 65], s[5 * 65]); o.w = cvt_pk_bf16(s[6 * 65], s[7 * 65]);
;         *(u32x4*)(WT + (size_t)(n0 + n) * K + k0 + 8 * c) = o; }
;     asm volatile("s_waitcnt lgkmcnt(0)" ::: "memory");
	v_cvt_pk_bf16_f32 v2, v14, v15
	s_waitcnt lgkmcnt(15)
	v_cvt_pk_bf16_f32 v3, v16, v17
	s_waitcnt lgkmcnt(15)
	v_cvt_pk_bf16_f32 v4, v18, v19
	v_add_u32_e32 v13, s30, v182
	s_waitcnt lgkmcnt(15)
	v_cvt_pk_bf16_f32 v5, v20, v21
	v_mad_u64_u32 v[6:7], s[30:31], v13, s36, 0
	v_ashrrev_i32_e32 v9, 31, v13
	v_mov_b32_e32 v8, v7
	s_ashr_i32 s35, s34, 31
	v_mad_u64_u32 v[8:9], s[30:31], v9, s36, v[8:9]
	v_lshl_add_u64 v[0:1], s[34:35], 1, v[66:67]
	v_mov_b32_e32 v7, v8
	v_lshl_add_u64 v[6:7], v[6:7], 1, v[0:1]
	global_store_dwordx4 v[6:7], v[2:5], off
	s_add_i32 s44, s44, s26
	s_add_i32 s42, s42, s43
	s_waitcnt lgkmcnt(15)
	v_cvt_pk_bf16_f32 v2, v22, v23
	s_waitcnt lgkmcnt(15)
	v_cvt_pk_bf16_f32 v3, v24, v25
	s_waitcnt lgkmcnt(15)
	v_cvt_pk_bf16_f32 v4, v26, v27
	s_waitcnt lgkmcnt(15)
	v_cvt_pk_bf16_f32 v5, v28, v29
	v_add_u32_e32 v6, 8, v13
	v_ashrrev_i32_e32 v9, 31, v6
	v_mad_u64_u32 v[6:7], s[30:31], v6, s36, 0
	v_mov_b32_e32 v8, v7
	v_mad_u64_u32 v[8:9], s[30:31], v9, s36, v[8:9]
	v_mov_b32_e32 v7, v8
	v_lshl_add_u64 v[6:7], v[6:7], 1, v[0:1]
	global_store_dwordx4 v[6:7], v[2:5], off
	s_cmp_lt_i32 s44, s39
	s_waitcnt lgkmcnt(15)
	v_cvt_pk_bf16_f32 v2, v30, v31
	s_waitcnt lgkmcnt(15)
	v_cvt_pk_bf16_f32 v3, v32, v33
	s_waitcnt lgkmcnt(15)
	v_cvt_pk_bf16_f32 v4, v34, v35
	s_waitcnt lgkmcnt(15)
	v_cvt_pk_bf16_f32 v5, v36, v37
	v_add_u32_e32 v6, 16, v13
	v_ashrrev_i32_e32 v9, 31, v6
	v_mad_u64_u32 v[6:7], s[30:31], v6, s36, 0
	v_mov_b32_e32 v8, v7
	v_mad_u64_u32 v[8:9], s[30:31], v9, s36, v[8:9]
	v_mov_b32_e32 v7, v8
	v_lshl_add_u64 v[6:7], v[6:7], 1, v[0:1]
	global_store_dwordx4 v[6:7], v[2:5], off
	s_waitcnt lgkmcnt(15)
	s_nop 0
	v_cvt_pk_bf16_f32 v2, v38, v39
	s_waitcnt lgkmcnt(15)
	v_cvt_pk_bf16_f32 v3, v40, v41
	s_waitcnt lgkmcnt(15)
	v_cvt_pk_bf16_f32 v4, v42, v43
	s_waitcnt lgkmcnt(15)
	v_cvt_pk_bf16_f32 v5, v44, v45
	v_add_u32_e32 v6, 24, v13
	v_ashrrev_i32_e32 v9, 31, v6
	v_mad_u64_u32 v[6:7], s[30:31], v6, s36, 0
	v_mov_b32_e32 v8, v7
	v_mad_u64_u32 v[8:9], s[30:31], v9, s36, v[8:9]
	v_mov_b32_e32 v7, v8
	v_lshl_add_u64 v[6:7], v[6:7], 1, v[0:1]
	global_store_dwordx4 v[6:7], v[2:5], off
	s_waitcnt lgkmcnt(15)
	s_nop 0
	v_cvt_pk_bf16_f32 v2, v46, v47
	s_waitcnt lgkmcnt(14)
	v_cvt_pk_bf16_f32 v3, v48, v49
	s_waitcnt lgkmcnt(13)
	v_cvt_pk_bf16_f32 v4, v50, v51
	s_waitcnt lgkmcnt(12)
	v_cvt_pk_bf16_f32 v5, v52, v53
	v_add_u32_e32 v6, 32, v13
	v_ashrrev_i32_e32 v9, 31, v6
	v_mad_u64_u32 v[6:7], s[30:31], v6, s36, 0
	v_mov_b32_e32 v8, v7
	v_mad_u64_u32 v[8:9], s[30:31], v9, s36, v[8:9]
	v_mov_b32_e32 v7, v8
	v_lshl_add_u64 v[6:7], v[6:7], 1, v[0:1]
	global_store_dwordx4 v[6:7], v[2:5], off
	s_waitcnt lgkmcnt(11)
	s_nop 0
	v_cvt_pk_bf16_f32 v2, v54, v55
	s_waitcnt lgkmcnt(10)
	v_cvt_pk_bf16_f32 v3, v56, v57
	s_waitcnt lgkmcnt(9)
	v_cvt_pk_bf16_f32 v4, v58, v59
	s_waitcnt lgkmcnt(8)
	v_cvt_pk_bf16_f32 v5, v60, v61
	v_add_u32_e32 v6, 40, v13
	v_ashrrev_i32_e32 v9, 31, v6
	v_mad_u64_u32 v[6:7], s[30:31], v6, s36, 0
	v_mov_b32_e32 v8, v7
	v_mad_u64_u32 v[8:9], s[30:31], v9, s36, v[8:9]
	v_mov_b32_e32 v7, v8
	v_lshl_add_u64 v[6:7], v[6:7], 1, v[0:1]
	global_store_dwordx4 v[6:7], v[2:5], off
	s_waitcnt lgkmcnt(7)
	s_nop 0
	v_cvt_pk_bf16_f32 v2, v62, v63
	s_waitcnt lgkmcnt(6)
	v_cvt_pk_bf16_f32 v3, v68, v69
	s_waitcnt lgkmcnt(5)
	v_cvt_pk_bf16_f32 v4, v70, v71
	s_waitcnt lgkmcnt(4)
	v_cvt_pk_bf16_f32 v5, v72, v73
	v_add_u32_e32 v6, 48, v13
	v_ashrrev_i32_e32 v9, 31, v6
	v_mad_u64_u32 v[6:7], s[30:31], v6, s36, 0
	v_mov_b32_e32 v8, v7
	v_mad_u64_u32 v[8:9], s[30:31], v9, s36, v[8:9]
	v_mov_b32_e32 v7, v8
	v_lshl_add_u64 v[6:7], v[6:7], 1, v[0:1]
	global_store_dwordx4 v[6:7], v[2:5], off
	s_waitcnt lgkmcnt(3)
	s_nop 0
	v_cvt_pk_bf16_f32 v2, v100, v101
	s_waitcnt lgkmcnt(2)
	v_cvt_pk_bf16_f32 v3, v102, v103
	s_waitcnt lgkmcnt(1)
	v_cvt_pk_bf16_f32 v4, v104, v105
	s_waitcnt lgkmcnt(0)
	v_cvt_pk_bf16_f32 v5, v106, v107
	v_add_u32_e32 v6, 56, v13
	v_ashrrev_i32_e32 v9, 31, v6
	v_mad_u64_u32 v[6:7], s[30:31], v6, s36, 0
	v_mov_b32_e32 v8, v7
	v_mad_u64_u32 v[8:9], s[30:31], v9, s36, v[8:9]
	v_mov_b32_e32 v7, v8
	v_lshl_add_u64 v[0:1], v[6:7], 1, v[0:1]
	global_store_dwordx4 v[0:1], v[2:5], off
	s_waitcnt lgkmcnt(0)
	s_cbranch_scc0 .LBB0_1142

; #define PG8_STAGE(bufoff, gbase, voff) do { _Pragma("unroll") for (int _i = 0; _i < 2; ++_i) \
;         __builtin_amdgcn_global_load_lds((const unsigned*)((const char*)(gbase) + (voff)[_i]), (LAS unsigned*)(lds + (bufoff) + ldsw + _i * 8192), 16, 0, 0); } while (0)
; #define PG8_WAIT_V(n) asm volatile("s_waitcnt vmcnt(" #n ")" ::: "memory")
; #define PG8_BAR __builtin_amdgcn_s_barrier()
; template <class Epi>
; __device__ __forceinline__ void gemm_phase(LAS unsigned char* lds, const Gemm g, const StaticOrder& S, const Epi& E) {
;     ...
;     for (int i = 0; i < 2; ++i) { int R, C; stage_rc(tid * 16 + i * 8192, R, C);
;         const int Rw = 64 * (R >> 5) + 16 * ((R >> 2) & 3) + 4 * ((R >> 4) & 1) + (R & 3);
;         const int Rf = 64 * (R >> 5) + 8 * ((R >> 2) & 3) + 4 * ((R >> 4) & 1) + (R & 3);
;         const int Rb0 = Epi::PERM ? (Epi::F32OUT ? Rf : Rw) : R, Rb1 = Epi::PERM ? (Epi::F32OUT ? Rf + 32 : Rw + 8) : R + HALF;
;         voffA[i] = (unsigned)(R * K + C) * 2u; voffB0[i] = (unsigned)(Rb0 * K + C) * 2u; voffB1[i] = (unsigned)(Rb1 * K + C) * 2u; }
;     const size_t kstep = (size_t)(BK * 2);
;     const size_t hstep = (size_t)HALF * K * 2;
;     const size_t tstep = 2 * hstep;
;     const unsigned ldsw = (unsigned)wid * 1024u;
;     const int aoff = lds_byte(wr * 64 + fr, fq * 8), boff = lds_byte(wc * 32 + fr, fq * 8);
;     ...
;     Unit cur, nxt; int ui = 0;
;     if (!S.next(0, cur)) return;
;     f32x4 acc[2][2][4][2];
; #pragma unroll
;     for (int a = 0; a < 2; ++a)
; #pragma unroll
;         for (int b = 0; b < 2; ++b)
; #pragma unroll
;             for (int m = 0; m < 4; ++m)
; #pragma unroll
;                 for (int n = 0; n < 2; ++n) acc[a][b][m][n] = (f32x4){0.f, 0.f, 0.f, 0.f};
;     bf16x8 At[4][2], B0[2][2], B1[2][2];
;     const char* cA = (const char*)g.A + (size_t)cur.pm * tstep; const char* cB = (const char*)g.Bt + (size_t)cur.pn * tstep;
;     PG8_STAGE(PG8_SB(0, 0), cB, voffB0); PG8_STAGE(PG8_SA(0, 0), cA, voffA); PG8_STAGE(PG8_SB(0, 1), cB, voffB1); PG8_STAGE(PG8_SA(0, 1), cA + hstep, voffA);
;     if (wr == 1) PG8_BAR;
;     PG8_WAIT_V(4); PG8_BAR;
;     PG8_STAGE(PG8_SB(1, 0), cB + kstep, voffB0); PG8_STAGE(PG8_SA(1, 0), cA + kstep, voffA); PG8_STAGE(PG8_SB(1, 1), cB + kstep, voffB1);
;     PG8_WAIT_V(6); PG8_BAR;
.LBB0_1235:
	s_add_u32 s10, s18, 0x6400000
	s_addc_u32 s11, s19, 0
	s_add_u32 s18, s18, 0x1ec10000
	s_mov_b64 s[26:27], 0x80
	s_addc_u32 s19, s19, 0
	s_add_i32 m0, s45, 0x18000
	v_lshl_add_u64 v[10:11], v[10:11], 0, s[26:27]
	s_waitcnt vmcnt(4)
	s_barrier
	global_load_lds_dwordx4 v[10:11], off
	v_lshl_add_u64 v[8:9], v[8:9], 0, s[26:27]
	s_add_i32 m0, s45, 0x1a000
	s_add_i32 s62, s45, 0x8000
	global_load_lds_dwordx4 v[8:9], off
	v_lshl_add_u64 v[6:7], v[6:7], 0, s[26:27]
	s_mov_b32 m0, s62
	s_add_i32 s63, s45, 0xa000
	global_load_lds_dwordx4 v[6:7], off
	v_lshl_add_u64 v[4:5], v[4:5], 0, s[26:27]
	s_mov_b32 m0, s63
	v_lshl_add_u64 v[0:1], v[0:1], 0, s[26:27]
	global_load_lds_dwordx4 v[4:5], off
	s_add_i32 m0, s45, 0x1c000
	v_and_b32_e32 v150, 15, v12
	global_load_lds_dwordx4 v[0:1], off
	v_lshl_add_u64 v[0:1], v[2:3], 0, s[26:27]
	s_add_i32 m0, s45, 0x1e000
	v_lshlrev_b32_e32 v3, 2, v12
	global_load_lds_dwordx4 v[0:1], off
	v_bfe_u32 v0, v12, 4, 2
	v_lshlrev_b32_e32 v1, 4, v0
	s_and_b32 s6, s6, 3
	s_lshl_b32 s64, s7, 6
	v_lshl_or_b32 v2, v150, 6, v1
	s_lshl_b32 s7, s7, 13
	v_and_b32_e32 v3, 32, v3
	v_bitop3_b32 v4, v2, s7, v3 bitop3:0xde
	s_lshl_b32 s7, s6, 12
	v_cmp_eq_u32_e64 s[8:9], 0, v0
	v_lshlrev_b32_e32 v0, 15, v13
	v_bitop3_b32 v151, v2, s7, v3 bitop3:0xde
	s_lshl_b32 s28, s6, 6
	v_and_b32_e32 v2, 8, v12
	v_and_b32_e32 v0, 0xffff0000, v0
	v_or3_b32 v153, s28, v2, v1
	v_lshl_add_u32 v0, v14, 12, v0
	v_and_b32_e32 v1, 1, v13
	v_lshl_or_b32 v0, v1, 6, v0
	v_lshl_add_u32 v140, v15, 1, v0
	v_lshlrev_b32_e32 v0, 15, v16
	v_and_b32_e32 v0, 0xffff0000, v0
	s_waitcnt vmcnt(0)
	v_lshl_add_u32 v0, v17, 12, v0
	v_and_b32_e32 v1, 1, v16
	v_lshl_or_b32 v0, v1, 6, v0
	s_add_i32 s68, 0, 0x10000
	s_add_i32 s69, 0, 0x14000
	v_cmp_gt_u32_e64 s[6:7], 8, v150
	v_and_b32_e32 v152, 7, v12
	s_ashr_i32 s65, s20, 31
	s_mov_b32 s66, s20
	s_ashr_i32 s67, s2, 31
	v_mov_b32_e32 v141, v131
	v_lshl_add_u32 v142, v18, 1, v0
	v_mov_b32_e32 v143, v131
	v_add_u32_e32 v154, s68, v151
	v_add_u32_e32 v155, 0, v4
	v_add_u32_e32 v156, s69, v151
	s_mov_b64 s[28:29], 0x8000
	v_mov_b64_e32 v[144:145], 0x1ff
	s_barrier
	s_branch .LBB0_1237

; #define PG8_STAGE(bufoff, gbase, voff) do { _Pragma("unroll") for (int _i = 0; _i < 2; ++_i) \
;         __builtin_amdgcn_global_load_lds((const unsigned*)((const char*)(gbase) + (voff)[_i]), (LAS unsigned*)(lds + (bufoff) + ldsw + _i * 8192), 16, 0, 0); } while (0)
; #define PG8_LDA(dst, b, h) do { _Pragma("unroll") for (int m = 0; m < 4; ++m) _Pragma("unroll") for (int k = 0; k < 2; ++k) dst[m][k] = *(const LAS bf16x8*)(lds + PG8_SA(b, h) + aoff + m * 2048 + k * 1024); } while (0)
; #define PG8_LDB(dst, b, h) do { _Pragma("unroll") for (int n = 0; n < 2; ++n) _Pragma("unroll") for (int k = 0; k < 2; ++k) dst[n][k] = *(const LAS bf16x8*)(lds + PG8_SB(b, h) + boff + n * 2048 + k * 1024); } while (0)
; #define PG8_MMA(ai, bj, At, Bt) do { __builtin_amdgcn_s_setprio(1); _Pragma("unroll") for (int m = 0; m < 4; ++m) _Pragma("unroll") for (int n = 0; n < 2; ++n) _Pragma("unroll") for (int k = 0; k < 2; ++k) \
;         acc[ai][bj][m][n] = __builtin_amdgcn_mfma_f32_16x16x32_bf16(Bt[n][k], At[m][k], acc[ai][bj][m][n], 0, 0, 0); __builtin_amdgcn_s_setprio(0); } while (0)
; #define PG8_WAIT_L(n) asm volatile("s_waitcnt lgkmcnt(" #n ")" ::: "memory")
; template <class Epi>
; __device__ __forceinline__ void gemm_phase(LAS unsigned char* lds, const Gemm g, const StaticOrder& S, const Epi& E) {
;     ...
;         const bool has_next = S.next(ui + 1, nxt);
;         const char* nA = has_next ? (const char*)g.A + (size_t)nxt.pm * tstep : cA; const char* nB = has_next ? (const char*)g.Bt + (size_t)nxt.pn * tstep : cB;
;         for (int t = 0; t < nt; t += 2) {
;             const bool last = (t == nt - 2);
;             const char* a1 = cA + (size_t)(t + 1) * kstep;
;             const char* a2 = last ? nA : cA + (size_t)(t + 2) * kstep; const char* b2 = last ? nB : cB + (size_t)(t + 2) * kstep;
;             const char* a3 = a2 + kstep; const char* b3 = b2 + kstep;
;             PG8_LDB(B0, 0, 0); PG8_SCHED; PG8_LDA(At, 0, 0); PG8_STAGE(PG8_SA(1, 1), a1 + hstep, voffA);
;             PG8_WAIT_L(8); PG8_BAR; PG8_WAIT_L(0); PG8_MMA(0, 0, At, B0); PG8_BAR; PG8_SCHED;
;             PG8_LDB(B1, 0, 1); PG8_STAGE(PG8_SB(0, 0), b2, voffB0);
;             PG8_BAR; PG8_WAIT_L(0); PG8_MMA(0, 1, At, B1); PG8_BAR;
;             PG8_LDA(At, 0, 1); PG8_STAGE(PG8_SA(0, 0), a2, voffA);
;             PG8_BAR; PG8_WAIT_L(0); PG8_MMA(1, 0, At, B0); PG8_BAR; PG8_SCHED;
.LBB0_1245:
	ds_read_b128 v[146:149], v154
	ds_read_b128 v[158:161], v154 offset:1024
	ds_read_b128 v[162:165], v154 offset:2048
	ds_read_b128 v[166:169], v154 offset:3072
	s_add_u32 s33, s46, 0xfff80080
	s_addc_u32 s48, s47, -1
	s_cmp_eq_u32 s73, 28
	s_cselect_b32 s49, s35, s48
	s_cselect_b32 s48, s43, s33
	s_cselect_b32 s51, s31, s72
	s_cselect_b32 s50, s70, s71
	v_lshl_add_u64 v[204:205], s[46:47], 0, v[140:141]
	s_add_i32 m0, s45, 0xc000
	ds_read_b128 v[170:173], v155
	ds_read_b128 v[174:177], v155 offset:1024
	ds_read_b128 v[178:181], v155 offset:2048
	ds_read_b128 v[182:185], v155 offset:3072
	ds_read_b128 v[186:189], v155 offset:4096
	ds_read_b128 v[190:193], v155 offset:5120
	ds_read_b128 v[194:197], v155 offset:6144
	ds_read_b128 v[198:201], v155 offset:7168
	global_load_lds_dwordx4 v[204:205], off
	v_lshl_add_u64 v[204:205], s[46:47], 0, v[142:143]
	s_add_i32 m0, s45, 0xe000
	s_nop 0
	global_load_lds_dwordx4 v[204:205], off
	s_waitcnt lgkmcnt(8)
	s_barrier
	s_waitcnt lgkmcnt(0)
	v_mfma_f32_16x16x32_bf16 v[124:127], v[146:149], v[170:173], v[124:127]
	v_mfma_f32_16x16x32_bf16 v[120:123], v[162:165], v[170:173], v[120:123]
	v_mfma_f32_16x16x32_bf16 v[108:111], v[146:149], v[178:181], v[108:111]
	v_mfma_f32_16x16x32_bf16 v[104:107], v[162:165], v[178:181], v[104:107]
	v_mfma_f32_16x16x32_bf16 v[92:95], v[146:149], v[186:189], v[92:95]
	v_mfma_f32_16x16x32_bf16 v[88:91], v[162:165], v[186:189], v[88:91]
	v_mfma_f32_16x16x32_bf16 v[76:79], v[146:149], v[194:197], v[76:79]
	v_mfma_f32_16x16x32_bf16 v[72:75], v[162:165], v[194:197], v[72:75]
	v_mfma_f32_16x16x32_bf16 v[124:127], v[158:161], v[174:177], v[124:127]
	v_mfma_f32_16x16x32_bf16 v[120:123], v[166:169], v[174:177], v[120:123]
	v_mfma_f32_16x16x32_bf16 v[108:111], v[158:161], v[182:185], v[108:111]
	v_mfma_f32_16x16x32_bf16 v[104:107], v[166:169], v[182:185], v[104:107]
	v_mfma_f32_16x16x32_bf16 v[92:95], v[158:161], v[190:193], v[92:95]
	v_mfma_f32_16x16x32_bf16 v[88:91], v[166:169], v[190:193], v[88:91]
	v_mfma_f32_16x16x32_bf16 v[76:79], v[158:161], v[198:201], v[76:79]
	v_mfma_f32_16x16x32_bf16 v[72:75], v[166:169], v[198:201], v[72:75]
	s_barrier
	s_add_i32 s33, s68, s57
	v_lshl_add_u64 v[220:221], s[50:51], 0, v[130:131]
	s_mov_b32 m0, s33
	ds_read_b128 v[204:207], v156
	ds_read_b128 v[208:211], v156 offset:1024
	ds_read_b128 v[212:215], v156 offset:2048
	ds_read_b128 v[216:219], v156 offset:3072
	global_load_lds_dwordx4 v[220:221], off
	v_lshl_add_u64 v[222:223], s[50:51], 0, v[136:137]
	s_add_i32 m0, s33, 0x2000
	s_nop 0
	global_load_lds_dwordx4 v[222:223], off
	s_barrier
	s_waitcnt lgkmcnt(0)
	v_mfma_f32_16x16x32_bf16 v[116:119], v[204:207], v[170:173], v[116:119]
	v_mfma_f32_16x16x32_bf16 v[112:115], v[212:215], v[170:173], v[112:115]
	v_mfma_f32_16x16x32_bf16 v[100:103], v[204:207], v[178:181], v[100:103]
	v_mfma_f32_16x16x32_bf16 v[96:99], v[212:215], v[178:181], v[96:99]
	v_mfma_f32_16x16x32_bf16 v[84:87], v[204:207], v[186:189], v[84:87]
	v_mfma_f32_16x16x32_bf16 v[80:83], v[212:215], v[186:189], v[80:83]
	v_mfma_f32_16x16x32_bf16 v[68:71], v[204:207], v[194:197], v[68:71]
	v_mfma_f32_16x16x32_bf16 v[64:67], v[212:215], v[194:197], v[64:67]
	v_mfma_f32_16x16x32_bf16 v[116:119], v[208:211], v[174:177], v[116:119]
	v_mfma_f32_16x16x32_bf16 v[112:115], v[216:219], v[174:177], v[112:115]
	v_mfma_f32_16x16x32_bf16 v[100:103], v[208:211], v[182:185], v[100:103]
	v_mfma_f32_16x16x32_bf16 v[96:99], v[216:219], v[182:185], v[96:99]
	v_mfma_f32_16x16x32_bf16 v[84:87], v[208:211], v[190:193], v[84:87]
	v_mfma_f32_16x16x32_bf16 v[80:83], v[216:219], v[190:193], v[80:83]
	v_mfma_f32_16x16x32_bf16 v[68:71], v[208:211], v[198:201], v[68:71]
	v_mfma_f32_16x16x32_bf16 v[64:67], v[216:219], v[198:201], v[64:67]
	s_mov_b32 m0, s45
	v_lshl_add_u64 v[224:225], s[48:49], 0, v[128:129]
	s_barrier
	ds_read_b128 v[170:173], v155 offset:16384
	ds_read_b128 v[174:177], v155 offset:17408
	ds_read_b128 v[178:181], v155 offset:18432
	ds_read_b128 v[182:185], v155 offset:19456
	ds_read_b128 v[186:189], v155 offset:20480
	ds_read_b128 v[190:193], v155 offset:21504
	ds_read_b128 v[194:197], v155 offset:22528
	ds_read_b128 v[198:201], v155 offset:23552
	global_load_lds_dwordx4 v[224:225], off
	v_lshl_add_u64 v[226:227], s[48:49], 0, v[134:135]
	s_mov_b32 m0, s58
	s_nop 0
	global_load_lds_dwordx4 v[226:227], off
	s_barrier
	s_waitcnt lgkmcnt(0)
	v_mfma_f32_16x16x32_bf16 v[60:63], v[146:149], v[170:173], v[60:63]
	v_mfma_f32_16x16x32_bf16 v[56:59], v[162:165], v[170:173], v[56:59]
	v_mfma_f32_16x16x32_bf16 v[44:47], v[146:149], v[178:181], v[44:47]
	v_mfma_f32_16x16x32_bf16 v[40:43], v[162:165], v[178:181], v[40:43]
	v_mfma_f32_16x16x32_bf16 v[28:31], v[146:149], v[186:189], v[28:31]
	v_mfma_f32_16x16x32_bf16 v[24:27], v[162:165], v[186:189], v[24:27]
	v_mfma_f32_16x16x32_bf16 v[12:15], v[146:149], v[194:197], v[12:15]
	v_mfma_f32_16x16x32_bf16 v[8:11], v[162:165], v[194:197], v[8:11]
	v_mfma_f32_16x16x32_bf16 v[60:63], v[158:161], v[174:177], v[60:63]
	v_mfma_f32_16x16x32_bf16 v[56:59], v[166:169], v[174:177], v[56:59]
	v_mfma_f32_16x16x32_bf16 v[44:47], v[158:161], v[182:185], v[44:47]
	v_mfma_f32_16x16x32_bf16 v[40:43], v[166:169], v[182:185], v[40:43]
	v_mfma_f32_16x16x32_bf16 v[28:31], v[158:161], v[190:193], v[28:31]
	v_mfma_f32_16x16x32_bf16 v[24:27], v[166:169], v[190:193], v[24:27]
	v_mfma_f32_16x16x32_bf16 v[12:15], v[158:161], v[198:201], v[12:15]
	v_mfma_f32_16x16x32_bf16 v[8:11], v[166:169], v[198:201], v[8:11]
	s_barrier
; #define PG8_STAGE(bufoff, gbase, voff) do { _Pragma("unroll") for (int _i = 0; _i < 2; ++_i) \
;         __builtin_amdgcn_global_load_lds((const unsigned*)((const char*)(gbase) + (voff)[_i]), (LAS unsigned*)(lds + (bufoff) + ldsw + _i * 8192), 16, 0, 0); } while (0)
; #define PG8_LDA(dst, b, h) do { _Pragma("unroll") for (int m = 0; m < 4; ++m) _Pragma("unroll") for (int k = 0; k < 2; ++k) dst[m][k] = *(const LAS bf16x8*)(lds + PG8_SA(b, h) + aoff + m * 2048 + k * 1024); } while (0)
; #define PG8_LDB(dst, b, h) do { _Pragma("unroll") for (int n = 0; n < 2; ++n) _Pragma("unroll") for (int k = 0; k < 2; ++k) dst[n][k] = *(const LAS bf16x8*)(lds + PG8_SB(b, h) + boff + n * 2048 + k * 1024); } while (0)
; #define PG8_MMA(ai, bj, At, Bt) do { __builtin_amdgcn_s_setprio(1); _Pragma("unroll") for (int m = 0; m < 4; ++m) _Pragma("unroll") for (int n = 0; n < 2; ++n) _Pragma("unroll") for (int k = 0; k < 2; ++k) \
;         acc[ai][bj][m][n] = __builtin_amdgcn_mfma_f32_16x16x32_bf16(Bt[n][k], At[m][k], acc[ai][bj][m][n], 0, 0, 0); __builtin_amdgcn_s_setprio(0); } while (0)
; #define PG8_WAIT_V(n) asm volatile("s_waitcnt vmcnt(" #n ")" ::: "memory")
; #define PG8_WAIT_L(n) asm volatile("s_waitcnt lgkmcnt(" #n ")" ::: "memory")
; #define PG8_BAR __builtin_amdgcn_s_barrier()
; #define PG8_SCHED __builtin_amdgcn_sched_barrier(0)
; template <class Epi>
; __device__ __forceinline__ void gemm_phase(LAS unsigned char* lds, const Gemm g, const StaticOrder& S, const Epi& E) {
;     ...
;             PG8_STAGE(PG8_SB(0, 1), b2, voffB1);
;             PG8_WAIT_V(6); PG8_BAR; PG8_MMA(1, 1, At, B1); PG8_BAR;
;             PG8_LDB(B0, 1, 0); PG8_SCHED; PG8_LDA(At, 1, 0); PG8_STAGE(PG8_SA(0, 1), a2 + hstep, voffA);
;             PG8_WAIT_L(8); PG8_BAR; PG8_WAIT_L(0); PG8_MMA(0, 0, At, B0); PG8_BAR; PG8_SCHED;
;             PG8_LDB(B1, 1, 1); PG8_STAGE(PG8_SB(1, 0), b3, voffB0);
;             PG8_BAR; PG8_WAIT_L(0); PG8_MMA(0, 1, At, B1); PG8_BAR;
;             PG8_LDA(At, 1, 1); PG8_STAGE(PG8_SA(1, 0), a3, voffA);
;             PG8_BAR; PG8_WAIT_L(0); PG8_MMA(1, 0, At, B0); PG8_BAR; PG8_SCHED;
	s_add_i32 s33, s69, s57
	v_lshl_add_u64 v[228:229], s[50:51], 0, v[132:133]
	s_mov_b32 m0, s33
	v_lshl_add_u64 v[230:231], s[50:51], 0, v[138:139]
	global_load_lds_dwordx4 v[228:229], off
	s_add_i32 m0, s33, 0x2000
	s_nop 0
	global_load_lds_dwordx4 v[230:231], off
	s_add_i32 s33, 0, 0x18000
	v_add_u32_e32 v157, s33, v151
	ds_read_b128 v[146:149], v157
	ds_read_b128 v[158:161], v157 offset:1024
	ds_read_b128 v[162:165], v157 offset:2048
	ds_read_b128 v[166:169], v157 offset:3072
	s_waitcnt vmcnt(6)
	s_barrier
	v_mfma_f32_16x16x32_bf16 v[52:55], v[204:207], v[170:173], v[52:55]
	v_mfma_f32_16x16x32_bf16 v[48:51], v[212:215], v[170:173], v[48:51]
	v_mfma_f32_16x16x32_bf16 v[36:39], v[204:207], v[178:181], v[36:39]
	v_mfma_f32_16x16x32_bf16 v[32:35], v[212:215], v[178:181], v[32:35]
	v_mfma_f32_16x16x32_bf16 v[20:23], v[204:207], v[186:189], v[20:23]
	v_mfma_f32_16x16x32_bf16 v[16:19], v[212:215], v[186:189], v[16:19]
	v_mfma_f32_16x16x32_bf16 v[4:7], v[204:207], v[194:197], v[4:7]
	v_mfma_f32_16x16x32_bf16 v[0:3], v[212:215], v[194:197], v[0:3]
	v_mfma_f32_16x16x32_bf16 v[52:55], v[208:211], v[174:177], v[52:55]
	v_mfma_f32_16x16x32_bf16 v[48:51], v[216:219], v[174:177], v[48:51]
	v_mfma_f32_16x16x32_bf16 v[36:39], v[208:211], v[182:185], v[36:39]
	v_mfma_f32_16x16x32_bf16 v[32:35], v[216:219], v[182:185], v[32:35]
	v_mfma_f32_16x16x32_bf16 v[20:23], v[208:211], v[190:193], v[20:23]
	v_mfma_f32_16x16x32_bf16 v[16:19], v[216:219], v[190:193], v[16:19]
	v_mfma_f32_16x16x32_bf16 v[4:7], v[208:211], v[198:201], v[4:7]
	v_mfma_f32_16x16x32_bf16 v[0:3], v[216:219], v[198:201], v[0:3]
	s_barrier
	s_add_u32 s48, s48, 0x80000
	s_addc_u32 s49, s49, 0
	s_mov_b32 m0, s59
	v_lshl_add_u64 v[204:205], s[48:49], 0, v[128:129]
	ds_read_b128 v[170:173], v155 offset:32768
	ds_read_b128 v[174:177], v155 offset:33792
	ds_read_b128 v[178:181], v155 offset:34816
	ds_read_b128 v[182:185], v155 offset:35840
	ds_read_b128 v[186:189], v155 offset:36864
	ds_read_b128 v[190:193], v155 offset:37888
	ds_read_b128 v[194:197], v155 offset:38912
	ds_read_b128 v[198:201], v155 offset:39936
	global_load_lds_dwordx4 v[204:205], off
	v_lshl_add_u64 v[204:205], s[48:49], 0, v[134:135]
	s_mov_b32 m0, s60
	s_nop 0
	global_load_lds_dwordx4 v[204:205], off
	s_waitcnt lgkmcnt(8)
	s_barrier
	s_waitcnt lgkmcnt(0)
	v_mfma_f32_16x16x32_bf16 v[124:127], v[146:149], v[170:173], v[124:127]
	v_mfma_f32_16x16x32_bf16 v[120:123], v[162:165], v[170:173], v[120:123]
	v_mfma_f32_16x16x32_bf16 v[108:111], v[146:149], v[178:181], v[108:111]
	v_mfma_f32_16x16x32_bf16 v[104:107], v[162:165], v[178:181], v[104:107]
	v_mfma_f32_16x16x32_bf16 v[92:95], v[146:149], v[186:189], v[92:95]
	v_mfma_f32_16x16x32_bf16 v[88:91], v[162:165], v[186:189], v[88:91]
	v_mfma_f32_16x16x32_bf16 v[76:79], v[146:149], v[194:197], v[76:79]
	v_mfma_f32_16x16x32_bf16 v[72:75], v[162:165], v[194:197], v[72:75]
	v_mfma_f32_16x16x32_bf16 v[124:127], v[158:161], v[174:177], v[124:127]
	v_mfma_f32_16x16x32_bf16 v[120:123], v[166:169], v[174:177], v[120:123]
	v_mfma_f32_16x16x32_bf16 v[108:111], v[158:161], v[182:185], v[108:111]
	v_mfma_f32_16x16x32_bf16 v[104:107], v[166:169], v[182:185], v[104:107]
	v_mfma_f32_16x16x32_bf16 v[92:95], v[158:161], v[190:193], v[92:95]
	v_mfma_f32_16x16x32_bf16 v[88:91], v[166:169], v[190:193], v[88:91]
	v_mfma_f32_16x16x32_bf16 v[76:79], v[158:161], v[198:201], v[76:79]
	v_mfma_f32_16x16x32_bf16 v[72:75], v[166:169], v[198:201], v[72:75]
	s_barrier
	s_add_i32 s48, 0, 0x1c000
	s_add_i32 s33, s33, s57
	v_add_u32_e32 v157, s48, v151
	v_lshl_add_u64 v[220:221], v[220:221], 0, s[26:27]
	s_mov_b32 m0, s33
	ds_read_b128 v[204:207], v157
	ds_read_b128 v[208:211], v157 offset:1024
	ds_read_b128 v[212:215], v157 offset:2048
	ds_read_b128 v[216:219], v157 offset:3072
	global_load_lds_dwordx4 v[220:221], off
	v_lshl_add_u64 v[220:221], v[222:223], 0, s[26:27]
	s_add_i32 m0, s33, 0x2000
	s_nop 0
	global_load_lds_dwordx4 v[220:221], off
	s_barrier
	s_waitcnt lgkmcnt(0)
	v_mfma_f32_16x16x32_bf16 v[116:119], v[204:207], v[170:173], v[116:119]
	v_mfma_f32_16x16x32_bf16 v[112:115], v[212:215], v[170:173], v[112:115]
	v_mfma_f32_16x16x32_bf16 v[100:103], v[204:207], v[178:181], v[100:103]
	v_mfma_f32_16x16x32_bf16 v[96:99], v[212:215], v[178:181], v[96:99]
	v_mfma_f32_16x16x32_bf16 v[84:87], v[204:207], v[186:189], v[84:87]
	v_mfma_f32_16x16x32_bf16 v[80:83], v[212:215], v[186:189], v[80:83]
	v_mfma_f32_16x16x32_bf16 v[68:71], v[204:207], v[194:197], v[68:71]
	v_mfma_f32_16x16x32_bf16 v[64:67], v[212:215], v[194:197], v[64:67]
	v_mfma_f32_16x16x32_bf16 v[116:119], v[208:211], v[174:177], v[116:119]
	v_mfma_f32_16x16x32_bf16 v[112:115], v[216:219], v[174:177], v[112:115]
	v_mfma_f32_16x16x32_bf16 v[100:103], v[208:211], v[182:185], v[100:103]
	v_mfma_f32_16x16x32_bf16 v[96:99], v[216:219], v[182:185], v[96:99]
	v_mfma_f32_16x16x32_bf16 v[84:87], v[208:211], v[190:193], v[84:87]
	v_mfma_f32_16x16x32_bf16 v[80:83], v[216:219], v[190:193], v[80:83]
	v_mfma_f32_16x16x32_bf16 v[68:71], v[208:211], v[198:201], v[68:71]
	v_mfma_f32_16x16x32_bf16 v[64:67], v[216:219], v[198:201], v[64:67]
	s_mov_b32 m0, s62
	v_lshl_add_u64 v[220:221], v[224:225], 0, s[26:27]
	s_barrier
	ds_read_b128 v[170:173], v155 offset:49152
	ds_read_b128 v[174:177], v155 offset:50176
	ds_read_b128 v[178:181], v155 offset:51200
	ds_read_b128 v[182:185], v155 offset:52224
	ds_read_b128 v[186:189], v155 offset:53248
	ds_read_b128 v[190:193], v155 offset:54272
	ds_read_b128 v[194:197], v155 offset:55296
	ds_read_b128 v[198:201], v155 offset:56320
	global_load_lds_dwordx4 v[220:221], off
	v_lshl_add_u64 v[220:221], v[226:227], 0, s[26:27]
	s_mov_b32 m0, s63
	s_nop 0
	global_load_lds_dwordx4 v[220:221], off
	s_barrier
; #define PG8_STAGE(bufoff, gbase, voff) do { _Pragma("unroll") for (int _i = 0; _i < 2; ++_i) \
;         __builtin_amdgcn_global_load_lds((const unsigned*)((const char*)(gbase) + (voff)[_i]), (LAS unsigned*)(lds + (bufoff) + ldsw + _i * 8192), 16, 0, 0); } while (0)
; #define PG8_MMA(ai, bj, At, Bt) do { __builtin_amdgcn_s_setprio(1); _Pragma("unroll") for (int m = 0; m < 4; ++m) _Pragma("unroll") for (int n = 0; n < 2; ++n) _Pragma("unroll") for (int k = 0; k < 2; ++k) \
;         acc[ai][bj][m][n] = __builtin_amdgcn_mfma_f32_16x16x32_bf16(Bt[n][k], At[m][k], acc[ai][bj][m][n], 0, 0, 0); __builtin_amdgcn_s_setprio(0); } while (0)
; #define PG8_WAIT_V(n) asm volatile("s_waitcnt vmcnt(" #n ")" ::: "memory")
; #define PG8_WAIT_L(n) asm volatile("s_waitcnt lgkmcnt(" #n ")" ::: "memory")
; #define PG8_BAR __builtin_amdgcn_s_barrier()
; #define PG8_SCHED __builtin_amdgcn_sched_barrier(0)
;     const bool lo = fr < 8;
;     const int r1 = row - fr + (fr & 7), cb = col0 + (lo ? 0 : boff);
;     const u32x4 l1 = *(const u32x4*)(P + (size_t)r1 * ld + cb), l2 = *(const u32x4*)(P + (size_t)(r1 + 8) * ld + cb);
; template <class Epi>
; __device__ __forceinline__ void gemm_phase(LAS unsigned char* lds, const Gemm g, const StaticOrder& S, const Epi& E) {
;     ...
;             PG8_BAR; PG8_WAIT_L(0); PG8_MMA(1, 0, At, B0); PG8_BAR; PG8_SCHED;
;             PG8_STAGE(PG8_SB(1, 1), b3, voffB1);
;             PG8_WAIT_V(6); PG8_BAR; PG8_MMA(1, 1, At, B1); PG8_BAR;
;         }
	s_waitcnt lgkmcnt(0)
	v_mfma_f32_16x16x32_bf16 v[60:63], v[146:149], v[170:173], v[60:63]
	v_mfma_f32_16x16x32_bf16 v[56:59], v[162:165], v[170:173], v[56:59]
	v_mfma_f32_16x16x32_bf16 v[44:47], v[146:149], v[178:181], v[44:47]
	v_mfma_f32_16x16x32_bf16 v[40:43], v[162:165], v[178:181], v[40:43]
	v_mfma_f32_16x16x32_bf16 v[28:31], v[146:149], v[186:189], v[28:31]
	v_mfma_f32_16x16x32_bf16 v[24:27], v[162:165], v[186:189], v[24:27]
	v_mfma_f32_16x16x32_bf16 v[12:15], v[146:149], v[194:197], v[12:15]
	v_mfma_f32_16x16x32_bf16 v[8:11], v[162:165], v[194:197], v[8:11]
	v_mfma_f32_16x16x32_bf16 v[60:63], v[158:161], v[174:177], v[60:63]
	v_mfma_f32_16x16x32_bf16 v[56:59], v[166:169], v[174:177], v[56:59]
	v_mfma_f32_16x16x32_bf16 v[44:47], v[158:161], v[182:185], v[44:47]
	v_mfma_f32_16x16x32_bf16 v[40:43], v[166:169], v[182:185], v[40:43]
	v_mfma_f32_16x16x32_bf16 v[28:31], v[158:161], v[190:193], v[28:31]
	v_mfma_f32_16x16x32_bf16 v[24:27], v[166:169], v[190:193], v[24:27]
	v_mfma_f32_16x16x32_bf16 v[12:15], v[158:161], v[198:201], v[12:15]
	v_mfma_f32_16x16x32_bf16 v[8:11], v[166:169], v[198:201], v[8:11]
	s_barrier
	s_add_i32 s33, s48, s57
	v_lshl_add_u64 v[146:147], v[228:229], 0, s[26:27]
	s_mov_b32 m0, s33
	s_nop 0
	global_load_lds_dwordx4 v[146:147], off
	v_lshl_add_u64 v[146:147], v[230:231], 0, s[26:27]
	s_add_i32 m0, s33, 0x2000
	s_nop 0
	global_load_lds_dwordx4 v[146:147], off
	s_waitcnt vmcnt(6)
	s_barrier
	v_mfma_f32_16x16x32_bf16 v[52:55], v[204:207], v[170:173], v[52:55]
	v_mfma_f32_16x16x32_bf16 v[48:51], v[212:215], v[170:173], v[48:51]
	v_mfma_f32_16x16x32_bf16 v[36:39], v[204:207], v[178:181], v[36:39]
	v_mfma_f32_16x16x32_bf16 v[32:35], v[212:215], v[178:181], v[32:35]
	v_mfma_f32_16x16x32_bf16 v[20:23], v[204:207], v[186:189], v[20:23]
	v_mfma_f32_16x16x32_bf16 v[16:19], v[212:215], v[186:189], v[16:19]
	v_mfma_f32_16x16x32_bf16 v[4:7], v[204:207], v[194:197], v[4:7]
	v_mfma_f32_16x16x32_bf16 v[0:3], v[212:215], v[194:197], v[0:3]
	v_mfma_f32_16x16x32_bf16 v[52:55], v[208:211], v[174:177], v[52:55]
	v_mfma_f32_16x16x32_bf16 v[48:51], v[216:219], v[174:177], v[48:51]
	v_mfma_f32_16x16x32_bf16 v[36:39], v[208:211], v[182:185], v[36:39]
	v_mfma_f32_16x16x32_bf16 v[32:35], v[216:219], v[182:185], v[32:35]
	v_mfma_f32_16x16x32_bf16 v[20:23], v[208:211], v[190:193], v[20:23]
	v_mfma_f32_16x16x32_bf16 v[16:19], v[216:219], v[190:193], v[16:19]
	v_mfma_f32_16x16x32_bf16 v[4:7], v[208:211], v[198:201], v[4:7]
	v_mfma_f32_16x16x32_bf16 v[0:3], v[216:219], v[198:201], v[0:3]
	s_add_i32 s73, s73, 2
	s_add_u32 s46, s46, 0x100
	s_addc_u32 s47, s47, 0
	s_add_u32 s71, s71, 0x100
	s_addc_u32 s72, s72, 0
	s_cmp_gt_u32 s73, 29
	s_barrier
	s_cbranch_scc0 .LBB0_1245
	s_lshl_b32 s31, s44, 8
	s_add_i32 s31, s31, s64
	v_or_b32_e32 v148, s31, v152
	v_ashrrev_i32_e32 v149, 31, v148
	v_lshlrev_b64 v[166:167], 12, v[148:149]
	v_or_b32_e32 v148, 8, v148
	v_lshl_or_b32 v146, s42, 8, v153
	v_ashrrev_i32_e32 v149, 31, v148
	v_ashrrev_i32_e32 v147, 31, v146
	v_lshlrev_b64 v[168:169], 12, v[148:149]
	v_lshl_add_u64 v[158:159], s[10:11], 0, v[166:167]
	v_lshlrev_b64 v[146:147], 1, v[146:147]
	v_lshl_add_u64 v[148:149], s[10:11], 0, v[168:169]
	v_lshl_add_u64 v[158:159], v[158:159], 0, v[146:147]
	v_lshl_add_u64 v[148:149], v[148:149], 0, v[146:147]
	global_load_dwordx4 v[158:161], v[158:159], off
	global_load_dwordx4 v[162:165], v[148:149], off
	v_or_b32_e32 v194, s31, v150
	v_or_b32_e32 v184, 16, v194
	v_sub_u32_e32 v185, v184, v150
	v_add_u32_e32 v186, v185, v152
	v_ashrrev_i32_e32 v187, 31, v186
	v_lshlrev_b64 v[190:191], 12, v[186:187]
	v_lshl_add_u64 v[192:193], v[190:191], 0, s[28:29]
	v_lshl_add_u64 v[186:187], s[10:11], 0, v[190:191]
	v_lshl_add_u64 v[188:189], s[10:11], 0, v[192:193]
	v_lshl_add_u64 v[186:187], v[186:187], 0, v[146:147]
	v_lshl_add_u64 v[188:189], v[188:189], 0, v[146:147]
	global_load_dwordx4 v[196:199], v[186:187], off
	global_load_dwordx4 v[204:207], v[188:189], off
	v_or_b32_e32 v194, s31, v150
	v_or_b32_e32 v184, 32, v194
	v_sub_u32_e32 v185, v184, v150
	v_add_u32_e32 v186, v185, v152
	v_ashrrev_i32_e32 v187, 31, v186
	v_lshlrev_b64 v[190:191], 12, v[186:187]
	v_lshl_add_u64 v[192:193], v[190:191], 0, s[28:29]
	v_lshl_add_u64 v[186:187], s[10:11], 0, v[190:191]
	v_lshl_add_u64 v[188:189], s[10:11], 0, v[192:193]
	v_lshl_add_u64 v[186:187], v[186:187], 0, v[146:147]
	v_lshl_add_u64 v[188:189], v[188:189], 0, v[146:147]
	global_load_dwordx4 v[208:211], v[186:187], off
	global_load_dwordx4 v[212:215], v[188:189], off
	v_or_b32_e32 v194, s31, v150
	v_or_b32_e32 v184, 48, v194
	v_sub_u32_e32 v185, v184, v150
	v_add_u32_e32 v186, v185, v152
	v_ashrrev_i32_e32 v187, 31, v186
	v_lshlrev_b64 v[190:191], 12, v[186:187]
	v_lshl_add_u64 v[192:193], v[190:191], 0, s[28:29]
	v_lshl_add_u64 v[186:187], s[10:11], 0, v[190:191]
	v_lshl_add_u64 v[188:189], s[10:11], 0, v[192:193]
	v_lshl_add_u64 v[186:187], v[186:187], 0, v[146:147]
	v_lshl_add_u64 v[188:189], v[188:189], 0, v[146:147]
	global_load_dwordx4 v[216:219], v[186:187], off
	global_load_dwordx4 v[220:223], v[188:189], off
	v_or_b32_e32 v194, s31, v150
	v_add_u32_e32 v184, 0x80, v194
	v_sub_u32_e32 v185, v184, v150
	v_add_u32_e32 v186, v185, v152
	v_ashrrev_i32_e32 v187, 31, v186
	v_lshlrev_b64 v[190:191], 12, v[186:187]
	v_lshl_add_u64 v[192:193], v[190:191], 0, s[28:29]
	v_lshl_add_u64 v[186:187], s[10:11], 0, v[190:191]
	v_lshl_add_u64 v[188:189], s[10:11], 0, v[192:193]
	v_lshl_add_u64 v[186:187], v[186:187], 0, v[146:147]
	v_lshl_add_u64 v[188:189], v[188:189], 0, v[146:147]
	global_load_dwordx4 v[224:227], v[186:187], off
	global_load_dwordx4 v[228:231], v[188:189], off
	v_or_b32_e32 v194, s31, v150
	v_add_u32_e32 v184, 0x90, v194
	v_sub_u32_e32 v185, v184, v150
	v_add_u32_e32 v186, v185, v152
	v_ashrrev_i32_e32 v187, 31, v186
	v_lshlrev_b64 v[190:191], 12, v[186:187]
	v_lshl_add_u64 v[192:193], v[190:191], 0, s[28:29]
	v_lshl_add_u64 v[186:187], s[10:11], 0, v[190:191]
	v_lshl_add_u64 v[188:189], s[10:11], 0, v[192:193]
	v_lshl_add_u64 v[186:187], v[186:187], 0, v[146:147]
	v_lshl_add_u64 v[188:189], v[188:189], 0, v[146:147]
	global_load_dwordx4 v[232:235], v[186:187], off
	global_load_dwordx4 v[236:239], v[188:189], off
	v_or_b32_e32 v194, s31, v150
	v_add_u32_e32 v184, 0xa0, v194
	v_sub_u32_e32 v185, v184, v150
	v_add_u32_e32 v186, v185, v152
	v_ashrrev_i32_e32 v187, 31, v186
	v_lshlrev_b64 v[190:191], 12, v[186:187]
	v_lshl_add_u64 v[192:193], v[190:191], 0, s[28:29]
	v_lshl_add_u64 v[186:187], s[10:11], 0, v[190:191]
	v_lshl_add_u64 v[188:189], s[10:11], 0, v[192:193]
	v_lshl_add_u64 v[186:187], v[186:187], 0, v[146:147]
	v_lshl_add_u64 v[188:189], v[188:189], 0, v[146:147]
	global_load_dwordx4 v[240:243], v[186:187], off
	global_load_dwordx4 v[244:247], v[188:189], off
	v_or_b32_e32 v148, s31, v150
	s_waitcnt vmcnt(12)
; __device__ __forceinline__ void store_pair_lines(bf16_t* O, int ldc, int row, int fr, int col0, u32x4 wA, u32x4 wB) {
;     const u32x4 sA = {dpp_ror8(wA.x), dpp_ror8(wA.y), dpp_ror8(wA.z), dpp_ror8(wA.w)}, sB = {dpp_ror8(wB.x), dpp_ror8(wB.y), dpp_ror8(wB.z), dpp_ror8(wB.w)};
;     const bool lo = fr < 8;
;     const u32x4 o1 = lo ? wA : sB, o2 = lo ? sA : wB;
;     const int r1 = row - fr + (fr & 7), cb = col0 + (lo ? 0 : 8);
;     *(u32x4*)(O + (size_t)r1 * ldc + cb) = o1;
;     *(u32x4*)(O + (size_t)(r1 + 8) * ldc + cb) = o2;
; }
;     const bool lo = fr < 8;
;     const int r1 = row - fr + (fr & 7), cb = col0 + (lo ? 0 : boff);
;     const u32x4 l1 = *(const u32x4*)(P + (size_t)r1 * ld + cb), l2 = *(const u32x4*)(P + (size_t)(r1 + 8) * ld + cb);
;     __device__ __forceinline__ void operator()(const f32x4 (&acc)[2][2][4][2], const Unit& u, int wr, int wc, int fr, int fq) const {
;     ...
;             for (int m = 0; m < 4; ++m) { const int row = row0 + ai * HALF + m * 16; const size_t off = (size_t)row * D + col0; float sq = 0.f; u32x4 w[2];
;                 const float sc = rsin ? __builtin_amdgcn_rcpf(rsin[row] * (1.f / D) + EPS) : 1.0f;
;                 u32x4 rr[2]; if (R) load_pair_lines(R, D, row, fr, col0, rr[0], rr[1]);
; #pragma unroll
;                 for (int bj = 0; bj < 2; ++bj) { f32x4 r0, r1;
;                     if (R) { const u32x4 rw = rr[bj]; r0 = (f32x4){bflo(rw.x), bfhi(rw.x), bflo(rw.y), bfhi(rw.y)}; r1 = (f32x4){bflo(rw.z), bfhi(rw.z), bflo(rw.w), bfhi(rw.w)}; }
;                     else { const float* rp = (row < 8192 ? src_p + off : src_s + (off - (size_t)8192 * D)) + 8 * bj; r0 = *(const f32x4*)rp; r1 = *(const f32x4*)(rp + 4); }
;                     const f32x4 o0 = r0 + acc[ai][bj][m][0] * sc, o1 = r1 + acc[ai][bj][m][1] * sc;
;                     sq += (o0[0] * o0[0] + o0[1] * o0[1]) + (o0[2] * o0[2] + o0[3] * o0[3]) + (o1[0] * o1[0] + o1[1] * o1[1]) + (o1[2] * o1[2] + o1[3] * o1[3]);
;                     w[bj].x = cvt_pk_bf16(o0[0], o0[1]); w[bj].y = cvt_pk_bf16(o0[2], o0[3]); w[bj].z = cvt_pk_bf16(o1[0], o1[1]); w[bj].w = cvt_pk_bf16(o1[2], o1[3]); }
;                 store_pair_lines(O, D, row, fr, col0, w[0], w[1]);
;                 if (ssout) { sq += __shfl_xor(sq, 16); sq += __shfl_xor(sq, 32); if (fq == 0) unsafeAtomicAdd(ssout + row, sq); } }
	v_mov_b32_dpp v149, v158 row_ror:8 row_mask:0xf bank_mask:0xf
	v_mov_b32_dpp v157, v159 row_ror:8 row_mask:0xf bank_mask:0xf
	v_mov_b32_dpp v171, v161 row_ror:8 row_mask:0xf bank_mask:0xf
	v_mov_b32_dpp v172, v162 row_ror:8 row_mask:0xf bank_mask:0xf
	v_mov_b32_dpp v173, v163 row_ror:8 row_mask:0xf bank_mask:0xf
	v_mov_b32_dpp v170, v160 row_ror:8 row_mask:0xf bank_mask:0xf
	v_mov_b32_dpp v174, v164 row_ror:8 row_mask:0xf bank_mask:0xf
	v_mov_b32_dpp v175, v165 row_ror:8 row_mask:0xf bank_mask:0xf
	v_cndmask_b32_e64 v165, v165, v171, s[6:7]
	v_cndmask_b32_e64 v157, v163, v157, s[6:7]
	v_cndmask_b32_e64 v149, v162, v149, s[6:7]
	v_cndmask_b32_e64 v173, v173, v159, s[6:7]
	v_cndmask_b32_e64 v171, v172, v158, s[6:7]
	v_cndmask_b32_e64 v164, v164, v170, s[6:7]
	v_cndmask_b32_e64 v177, v175, v161, s[6:7]
	v_cndmask_b32_e64 v175, v174, v160, s[6:7]
	v_lshlrev_b32_e32 v158, 16, v149
	v_and_b32_e32 v159, 0xffff0000, v149
	v_lshlrev_b32_e32 v160, 16, v157
	v_and_b32_e32 v161, 0xffff0000, v157
	v_lshlrev_b32_e32 v170, 16, v171
	v_and_b32_e32 v171, 0xffff0000, v171
	v_lshlrev_b32_e32 v172, 16, v173
	v_and_b32_e32 v173, 0xffff0000, v173
	v_lshlrev_b32_e32 v174, 16, v175
	v_and_b32_e32 v175, 0xffff0000, v175
	v_pk_add_f32 v[160:161], v[118:119], v[160:161]
	v_pk_add_f32 v[158:159], v[116:117], v[158:159]
	v_pk_add_f32 v[116:117], v[126:127], v[172:173]
	v_pk_add_f32 v[118:119], v[124:125], v[170:171]
	v_lshlrev_b32_e32 v176, 16, v177
	v_and_b32_e32 v177, 0xffff0000, v177
	v_pk_add_f32 v[120:121], v[120:121], v[174:175]
	v_mul_f32_e32 v124, v119, v119
	v_mul_f32_e32 v125, v117, v117
	v_lshlrev_b32_e32 v162, 16, v164
	v_and_b32_e32 v163, 0xffff0000, v164
	v_lshlrev_b32_e32 v164, 16, v165
	v_and_b32_e32 v165, 0xffff0000, v165
	v_pk_add_f32 v[122:123], v[122:123], v[176:177]
	v_mul_f32_e32 v126, v121, v121
	v_fmac_f32_e32 v124, v118, v118
	v_fmac_f32_e32 v125, v116, v116
	v_pk_add_f32 v[114:115], v[114:115], v[164:165]
	v_mul_f32_e32 v127, v123, v123
	v_cvt_pk_bf16_f32 v119, v118, v119
	v_cvt_pk_bf16_f32 v117, v116, v117
	v_cvt_pk_bf16_f32 v121, v120, v121
	v_fmac_f32_e32 v126, v120, v120
	v_add_f32_e32 v116, v124, v125
	v_pk_add_f32 v[112:113], v[112:113], v[162:163]
	v_cvt_pk_bf16_f32 v123, v122, v123
	v_cvt_pk_bf16_f32 v149, v158, v159
	v_cvt_pk_bf16_f32 v157, v160, v161
	v_fmac_f32_e32 v127, v122, v122
	v_cvt_pk_bf16_f32 v162, v112, v113
	v_cvt_pk_bf16_f32 v163, v114, v115
	v_add_f32_e32 v116, v126, v116
	v_mov_b32_dpp v182, v149 row_ror:8 row_mask:0xf bank_mask:0xf
	v_mov_b32_dpp v120, v163 row_ror:8 row_mask:0xf bank_mask:0xf
	v_mul_f32_e32 v115, v115, v115
	v_mov_b32_dpp v178, v119 row_ror:8 row_mask:0xf bank_mask:0xf
	v_mov_b32_dpp v181, v123 row_ror:8 row_mask:0xf bank_mask:0xf
	v_add_f32_e32 v122, v127, v116
	v_cndmask_b32_e64 v116, v182, v119, s[6:7]
	v_cndmask_b32_e64 v119, v120, v123, s[6:7]
	v_fmac_f32_e32 v115, v114, v114
	v_mul_f32_e32 v114, v159, v159
	v_mul_f32_e32 v123, v161, v161
	v_fmac_f32_e32 v114, v158, v158
	v_fmac_f32_e32 v123, v160, v160
	v_mul_f32_e32 v113, v113, v113
	v_add_f32_e32 v114, v114, v123
	v_fmac_f32_e32 v113, v112, v112
	v_add_f32_e32 v112, v113, v114
	v_add_f32_e32 v112, v115, v112
	v_and_b32_e32 v113, 64, v203
	v_add_f32_e32 v115, v112, v122
	v_xor_b32_e32 v112, 16, v203
	v_add_u32_e32 v126, 64, v113
	v_cmp_lt_i32_e32 vcc, v112, v126
	v_mov_b32_e32 v118, 0
	v_mov_b32_dpp v183, v157 row_ror:8 row_mask:0xf bank_mask:0xf
	v_cndmask_b32_e32 v112, v203, v112, vcc
	v_lshlrev_b32_e32 v114, 2, v112
	v_mov_b32_e32 v127, v115
	s_nop 1
	v_permlane16_swap_b32_e32 v127, v115
	v_lshl_add_u64 v[112:113], s[16:17], 0, v[166:167]
	v_lshl_add_u64 v[124:125], v[112:113], 0, v[146:147]
	v_xor_b32_e32 v113, 32, v203
	v_cmp_lt_i32_e32 vcc, v113, v126
	s_waitcnt lgkmcnt(0)
	v_add_f32_e32 v112, v115, v127
	v_mov_b32_dpp v118, v162 row_ror:8 row_mask:0xf bank_mask:0xf
	v_cndmask_b32_e32 v113, v203, v113, vcc
	v_lshlrev_b32_e32 v115, 2, v113
	v_mov_b32_e32 v113, v112
	s_nop 1
	v_permlane32_swap_b32_e32 v113, v112
	v_mov_b32_dpp v179, v117 row_ror:8 row_mask:0xf bank_mask:0xf
	v_cndmask_b32_e64 v117, v183, v117, s[6:7]
	v_cndmask_b32_e64 v118, v118, v121, s[6:7]
	v_mov_b32_dpp v180, v121 row_ror:8 row_mask:0xf bank_mask:0xf
	global_store_dwordx4 v[124:125], v[116:119], off
	v_cndmask_b32_e64 v120, v149, v178, s[6:7]
	v_cndmask_b32_e64 v121, v157, v179, s[6:7]
	v_lshl_add_u64 v[116:117], s[16:17], 0, v[168:169]
	v_cndmask_b32_e64 v122, v162, v180, s[6:7]
	v_cndmask_b32_e64 v123, v163, v181, s[6:7]
	v_lshl_add_u64 v[116:117], v[116:117], 0, v[146:147]
	global_store_dwordx4 v[116:117], v[120:123], off
	s_and_saveexec_b64 s[42:43], s[8:9]
	s_cbranch_execz .LBB0_1248
	v_ashrrev_i32_e32 v149, 31, v148
	s_waitcnt lgkmcnt(0)
	v_add_f32_e32 v116, v112, v113
	v_lshl_add_u64 v[112:113], v[148:149], 2, s[18:19]
	global_atomic_add_f32 v[112:113], v116, off

; #define PG8_STAGE(bufoff, gbase, voff) do { _Pragma("unroll") for (int _i = 0; _i < 2; ++_i) \
;         __builtin_amdgcn_global_load_lds((const unsigned*)((const char*)(gbase) + (voff)[_i]), (LAS unsigned*)(lds + (bufoff) + ldsw + _i * 8192), 16, 0, 0); } while (0)
; #define PG8_WAIT_V(n) asm volatile("s_waitcnt vmcnt(" #n ")" ::: "memory")
; #define PG8_BAR __builtin_amdgcn_s_barrier()
; template <class Epi>
; __device__ __forceinline__ void gemm_phase(LAS unsigned char* lds, const Gemm g, const StaticOrder& S, const Epi& E) {
;     ...
;     for (int i = 0; i < 2; ++i) { int R, C; stage_rc(tid * 16 + i * 8192, R, C);
;         const int Rw = 64 * (R >> 5) + 16 * ((R >> 2) & 3) + 4 * ((R >> 4) & 1) + (R & 3);
;         const int Rf = 64 * (R >> 5) + 8 * ((R >> 2) & 3) + 4 * ((R >> 4) & 1) + (R & 3);
;         const int Rb0 = Epi::PERM ? (Epi::F32OUT ? Rf : Rw) : R, Rb1 = Epi::PERM ? (Epi::F32OUT ? Rf + 32 : Rw + 8) : R + HALF;
;         voffA[i] = (unsigned)(R * K + C) * 2u; voffB0[i] = (unsigned)(Rb0 * K + C) * 2u; voffB1[i] = (unsigned)(Rb1 * K + C) * 2u; }
;     const size_t kstep = (size_t)(BK * 2);
;     const size_t hstep = (size_t)HALF * K * 2;
;     const size_t tstep = 2 * hstep;
;     const unsigned ldsw = (unsigned)wid * 1024u;
;     const int aoff = lds_byte(wr * 64 + fr, fq * 8), boff = lds_byte(wc * 32 + fr, fq * 8);
;     ...
;     Unit cur, nxt; int ui = 0;
;     if (!S.next(0, cur)) return;
;     f32x4 acc[2][2][4][2];
; #pragma unroll
;     for (int a = 0; a < 2; ++a)
; #pragma unroll
;         for (int b = 0; b < 2; ++b)
; #pragma unroll
;             for (int m = 0; m < 4; ++m)
; #pragma unroll
;                 for (int n = 0; n < 2; ++n) acc[a][b][m][n] = (f32x4){0.f, 0.f, 0.f, 0.f};
;     bf16x8 At[4][2], B0[2][2], B1[2][2];
;     const char* cA = (const char*)g.A + (size_t)cur.pm * tstep; const char* cB = (const char*)g.Bt + (size_t)cur.pn * tstep;
;     PG8_STAGE(PG8_SB(0, 0), cB, voffB0); PG8_STAGE(PG8_SA(0, 0), cA, voffA); PG8_STAGE(PG8_SB(0, 1), cB, voffB1); PG8_STAGE(PG8_SA(0, 1), cA + hstep, voffA);
;     if (wr == 1) PG8_BAR;
;     PG8_WAIT_V(4); PG8_BAR;
;     PG8_STAGE(PG8_SB(1, 0), cB + kstep, voffB0); PG8_STAGE(PG8_SA(1, 0), cA + kstep, voffA); PG8_STAGE(PG8_SB(1, 1), cB + kstep, voffB1);
;     PG8_WAIT_V(6); PG8_BAR;
.LBB0_1356:
	s_add_u32 s12, s10, 0xec00000
	s_mov_b64 s[16:17], 0x80
	s_addc_u32 s13, s11, 0
	s_add_i32 m0, s37, 0x18000
	v_lshl_add_u64 v[10:11], v[10:11], 0, s[16:17]
	s_waitcnt vmcnt(4)
	s_barrier
	global_load_lds_dwordx4 v[10:11], off
	v_lshl_add_u64 v[8:9], v[8:9], 0, s[16:17]
	s_add_i32 m0, s37, 0x1a000
	s_add_i32 s51, s37, 0x8000
	global_load_lds_dwordx4 v[8:9], off
	v_lshl_add_u64 v[6:7], v[6:7], 0, s[16:17]
	s_mov_b32 m0, s51
	s_add_i32 s52, s37, 0xa000
	global_load_lds_dwordx4 v[6:7], off
	v_lshl_add_u64 v[4:5], v[4:5], 0, s[16:17]
	s_mov_b32 m0, s52
	v_lshl_add_u64 v[0:1], v[0:1], 0, s[16:17]
	global_load_lds_dwordx4 v[4:5], off
	s_add_i32 m0, s37, 0x1c000
	v_and_b32_e32 v146, 15, v12
	global_load_lds_dwordx4 v[0:1], off
	v_lshl_add_u64 v[0:1], v[2:3], 0, s[16:17]
	s_add_i32 m0, s37, 0x1e000
	v_lshlrev_b32_e32 v2, 2, v12
	global_load_lds_dwordx4 v[0:1], off
	v_and_b32_e32 v0, 48, v12
	s_sext_i32_i16 s59, s6
	s_and_b32 s6, s7, 3
	s_lshl_b32 s7, s18, 13
	v_lshl_or_b32 v1, v146, 6, v0
	v_and_b32_e32 v2, 32, v2
	v_bitop3_b32 v3, v1, s7, v2 bitop3:0xde
	s_lshl_b32 s7, s6, 12
	s_lshl_b32 s53, s18, 6
	v_bitop3_b32 v147, v1, s7, v2 bitop3:0xde
	s_lshl_b32 s18, s6, 6
	v_and_b32_e32 v1, 8, v12
	v_or3_b32 v156, s18, v1, v0
	v_lshlrev_b32_e32 v0, 15, v13
	v_and_b32_e32 v0, 0xffff0000, v0
	v_lshl_add_u32 v0, v14, 12, v0
	v_and_b32_e32 v1, 1, v13
	v_lshl_or_b32 v0, v1, 6, v0
	v_lshl_add_u32 v140, v15, 1, v0
	v_lshlrev_b32_e32 v0, 15, v16
	v_and_b32_e32 v0, 0xffff0000, v0
	s_waitcnt vmcnt(0)
	v_and_b32_e32 v148, 7, v12
	v_lshl_add_u32 v0, v17, 12, v0
	v_and_b32_e32 v1, 1, v16
	v_sub_u32_e32 v2, v148, v146
	v_lshl_or_b32 v0, v1, 6, v0
	s_add_i32 s56, 0, 0x10000
	s_add_i32 s57, 0, 0x14000
	v_cmp_gt_u32_e64 s[6:7], 8, v146
	s_ashr_i32 s54, s20, 31
	s_mov_b32 s55, s20
	v_add_u32_e32 v149, 16, v2
	v_add_u32_e32 v150, 32, v2
	v_add_u32_e32 v151, 48, v2
	v_add_u32_e32 v152, 0x80, v2
	v_add_u32_e32 v153, 0x90, v2
	v_add_u32_e32 v154, 0xa0, v2
	v_add_u32_e32 v155, 0xb0, v2
	v_mov_b32_e32 v141, v131
	v_lshl_add_u32 v142, v18, 1, v0
	v_mov_b32_e32 v143, v131
	v_add_u32_e32 v157, s56, v147
	v_add_u32_e32 v158, 0, v3
	v_add_u32_e32 v159, s57, v147
	s_mov_b32 s58, 0x20000
	v_mov_b64_e32 v[144:145], 0x7ff
	s_barrier

; #define PG8_STAGE(bufoff, gbase, voff) do { _Pragma("unroll") for (int _i = 0; _i < 2; ++_i) \
;         __builtin_amdgcn_global_load_lds((const unsigned*)((const char*)(gbase) + (voff)[_i]), (LAS unsigned*)(lds + (bufoff) + ldsw + _i * 8192), 16, 0, 0); } while (0)
; #define PG8_LDA(dst, b, h) do { _Pragma("unroll") for (int m = 0; m < 4; ++m) _Pragma("unroll") for (int k = 0; k < 2; ++k) dst[m][k] = *(const LAS bf16x8*)(lds + PG8_SA(b, h) + aoff + m * 2048 + k * 1024); } while (0)
; #define PG8_LDB(dst, b, h) do { _Pragma("unroll") for (int n = 0; n < 2; ++n) _Pragma("unroll") for (int k = 0; k < 2; ++k) dst[n][k] = *(const LAS bf16x8*)(lds + PG8_SB(b, h) + boff + n * 2048 + k * 1024); } while (0)
; #define PG8_MMA(ai, bj, At, Bt) do { __builtin_amdgcn_s_setprio(1); _Pragma("unroll") for (int m = 0; m < 4; ++m) _Pragma("unroll") for (int n = 0; n < 2; ++n) _Pragma("unroll") for (int k = 0; k < 2; ++k) \
;         acc[ai][bj][m][n] = __builtin_amdgcn_mfma_f32_16x16x32_bf16(Bt[n][k], At[m][k], acc[ai][bj][m][n], 0, 0, 0); __builtin_amdgcn_s_setprio(0); } while (0)
; #define PG8_WAIT_L(n) asm volatile("s_waitcnt lgkmcnt(" #n ")" ::: "memory")
; template <class Epi>
; __device__ __forceinline__ void gemm_phase(LAS unsigned char* lds, const Gemm g, const StaticOrder& S, const Epi& E) {
;     ...
;         const bool has_next = S.next(ui + 1, nxt);
;         const char* nA = has_next ? (const char*)g.A + (size_t)nxt.pm * tstep : cA; const char* nB = has_next ? (const char*)g.Bt + (size_t)nxt.pn * tstep : cB;
;         for (int t = 0; t < nt; t += 2) {
;             const bool last = (t == nt - 2);
;             const char* a1 = cA + (size_t)(t + 1) * kstep;
;             const char* a2 = last ? nA : cA + (size_t)(t + 2) * kstep; const char* b2 = last ? nB : cB + (size_t)(t + 2) * kstep;
;             const char* a3 = a2 + kstep; const char* b3 = b2 + kstep;
;             PG8_LDB(B0, 0, 0); PG8_SCHED; PG8_LDA(At, 0, 0); PG8_STAGE(PG8_SA(1, 1), a1 + hstep, voffA);
;             PG8_WAIT_L(8); PG8_BAR; PG8_WAIT_L(0); PG8_MMA(0, 0, At, B0); PG8_BAR; PG8_SCHED;
;             PG8_LDB(B1, 0, 1); PG8_STAGE(PG8_SB(0, 0), b2, voffB0);
;             PG8_BAR; PG8_WAIT_L(0); PG8_MMA(0, 1, At, B1); PG8_BAR;
;             PG8_LDA(At, 0, 1); PG8_STAGE(PG8_SA(0, 0), a2, voffA);
;             PG8_BAR; PG8_WAIT_L(0); PG8_MMA(1, 0, At, B0); PG8_BAR; PG8_SCHED;
.LBB0_1365:
	ds_read_b128 v[160:163], v157
	ds_read_b128 v[164:167], v157 offset:1024
	ds_read_b128 v[168:171], v157 offset:2048
	ds_read_b128 v[172:175], v157 offset:3072
	s_add_u32 s33, s38, 0xfff80080
	s_addc_u32 s40, s39, -1
	s_cmp_eq_u32 s64, 28
	s_cselect_b32 s41, s27, s40
	s_cselect_b32 s40, s60, s33
	s_cselect_b32 s43, s19, s63
	s_cselect_b32 s42, s61, s62
	v_lshl_add_u64 v[200:201], s[38:39], 0, v[140:141]
	s_add_i32 m0, s37, 0xc000
	ds_read_b128 v[176:179], v158
	ds_read_b128 v[180:183], v158 offset:1024
	ds_read_b128 v[184:187], v158 offset:2048
	ds_read_b128 v[188:191], v158 offset:3072
	ds_read_b128 v[192:195], v158 offset:4096
	ds_read_b128 v[196:199], v158 offset:5120
	ds_read_b128 v[204:207], v158 offset:6144
	ds_read_b128 v[208:211], v158 offset:7168
	global_load_lds_dwordx4 v[200:201], off
	v_lshl_add_u64 v[200:201], s[38:39], 0, v[142:143]
	s_add_i32 m0, s37, 0xe000
	s_nop 0
	global_load_lds_dwordx4 v[200:201], off
	s_waitcnt lgkmcnt(8)
	s_barrier
	s_waitcnt lgkmcnt(0)
	v_mfma_f32_16x16x32_bf16 v[124:127], v[160:163], v[176:179], v[124:127]
	v_mfma_f32_16x16x32_bf16 v[120:123], v[168:171], v[176:179], v[120:123]
	v_mfma_f32_16x16x32_bf16 v[108:111], v[160:163], v[184:187], v[108:111]
	v_mfma_f32_16x16x32_bf16 v[104:107], v[168:171], v[184:187], v[104:107]
	v_mfma_f32_16x16x32_bf16 v[92:95], v[160:163], v[192:195], v[92:95]
	v_mfma_f32_16x16x32_bf16 v[88:91], v[168:171], v[192:195], v[88:91]
	v_mfma_f32_16x16x32_bf16 v[76:79], v[160:163], v[204:207], v[76:79]
	v_mfma_f32_16x16x32_bf16 v[72:75], v[168:171], v[204:207], v[72:75]
	v_mfma_f32_16x16x32_bf16 v[124:127], v[164:167], v[180:183], v[124:127]
	v_mfma_f32_16x16x32_bf16 v[120:123], v[172:175], v[180:183], v[120:123]
	v_mfma_f32_16x16x32_bf16 v[108:111], v[164:167], v[188:191], v[108:111]
	v_mfma_f32_16x16x32_bf16 v[104:107], v[172:175], v[188:191], v[104:107]
	v_mfma_f32_16x16x32_bf16 v[92:95], v[164:167], v[196:199], v[92:95]
	v_mfma_f32_16x16x32_bf16 v[88:91], v[172:175], v[196:199], v[88:91]
	v_mfma_f32_16x16x32_bf16 v[76:79], v[164:167], v[208:211], v[76:79]
	v_mfma_f32_16x16x32_bf16 v[72:75], v[172:175], v[208:211], v[72:75]
	s_barrier
	s_add_i32 s33, s56, s46
	v_lshl_add_u64 v[200:201], s[42:43], 0, v[130:131]
	s_mov_b32 m0, s33
	ds_read_b128 v[212:215], v159
	ds_read_b128 v[216:219], v159 offset:1024
	ds_read_b128 v[220:223], v159 offset:2048
	ds_read_b128 v[224:227], v159 offset:3072
	global_load_lds_dwordx4 v[200:201], off
	v_lshl_add_u64 v[228:229], s[42:43], 0, v[136:137]
	s_add_i32 m0, s33, 0x2000
	s_nop 0
	global_load_lds_dwordx4 v[228:229], off
	s_barrier
	s_waitcnt lgkmcnt(0)
	v_mfma_f32_16x16x32_bf16 v[116:119], v[212:215], v[176:179], v[116:119]
	v_mfma_f32_16x16x32_bf16 v[112:115], v[220:223], v[176:179], v[112:115]
	v_mfma_f32_16x16x32_bf16 v[100:103], v[212:215], v[184:187], v[100:103]
	v_mfma_f32_16x16x32_bf16 v[96:99], v[220:223], v[184:187], v[96:99]
	v_mfma_f32_16x16x32_bf16 v[84:87], v[212:215], v[192:195], v[84:87]
	v_mfma_f32_16x16x32_bf16 v[80:83], v[220:223], v[192:195], v[80:83]
	v_mfma_f32_16x16x32_bf16 v[68:71], v[212:215], v[204:207], v[68:71]
	v_mfma_f32_16x16x32_bf16 v[64:67], v[220:223], v[204:207], v[64:67]
	v_mfma_f32_16x16x32_bf16 v[116:119], v[216:219], v[180:183], v[116:119]
	v_mfma_f32_16x16x32_bf16 v[112:115], v[224:227], v[180:183], v[112:115]
	v_mfma_f32_16x16x32_bf16 v[100:103], v[216:219], v[188:191], v[100:103]
	v_mfma_f32_16x16x32_bf16 v[96:99], v[224:227], v[188:191], v[96:99]
	v_mfma_f32_16x16x32_bf16 v[84:87], v[216:219], v[196:199], v[84:87]
	v_mfma_f32_16x16x32_bf16 v[80:83], v[224:227], v[196:199], v[80:83]
	v_mfma_f32_16x16x32_bf16 v[68:71], v[216:219], v[208:211], v[68:71]
	v_mfma_f32_16x16x32_bf16 v[64:67], v[224:227], v[208:211], v[64:67]
	s_mov_b32 m0, s37
	v_lshl_add_u64 v[230:231], s[40:41], 0, v[128:129]
	s_barrier
	ds_read_b128 v[176:179], v158 offset:16384
	ds_read_b128 v[180:183], v158 offset:17408
	ds_read_b128 v[184:187], v158 offset:18432
	ds_read_b128 v[188:191], v158 offset:19456
	ds_read_b128 v[192:195], v158 offset:20480
	ds_read_b128 v[196:199], v158 offset:21504
	ds_read_b128 v[204:207], v158 offset:22528
	ds_read_b128 v[208:211], v158 offset:23552
	global_load_lds_dwordx4 v[230:231], off
	v_lshl_add_u64 v[232:233], s[40:41], 0, v[134:135]
	s_mov_b32 m0, s47
	s_nop 0
	global_load_lds_dwordx4 v[232:233], off
	s_barrier
	s_waitcnt lgkmcnt(0)
	v_mfma_f32_16x16x32_bf16 v[60:63], v[160:163], v[176:179], v[60:63]
	v_mfma_f32_16x16x32_bf16 v[56:59], v[168:171], v[176:179], v[56:59]
	v_mfma_f32_16x16x32_bf16 v[44:47], v[160:163], v[184:187], v[44:47]
	v_mfma_f32_16x16x32_bf16 v[40:43], v[168:171], v[184:187], v[40:43]
	v_mfma_f32_16x16x32_bf16 v[28:31], v[160:163], v[192:195], v[28:31]
	v_mfma_f32_16x16x32_bf16 v[24:27], v[168:171], v[192:195], v[24:27]
	v_mfma_f32_16x16x32_bf16 v[12:15], v[160:163], v[204:207], v[12:15]
	v_mfma_f32_16x16x32_bf16 v[8:11], v[168:171], v[204:207], v[8:11]
	v_mfma_f32_16x16x32_bf16 v[60:63], v[164:167], v[180:183], v[60:63]
	v_mfma_f32_16x16x32_bf16 v[56:59], v[172:175], v[180:183], v[56:59]
	v_mfma_f32_16x16x32_bf16 v[44:47], v[164:167], v[188:191], v[44:47]
	v_mfma_f32_16x16x32_bf16 v[40:43], v[172:175], v[188:191], v[40:43]
	v_mfma_f32_16x16x32_bf16 v[28:31], v[164:167], v[196:199], v[28:31]
	v_mfma_f32_16x16x32_bf16 v[24:27], v[172:175], v[196:199], v[24:27]
	v_mfma_f32_16x16x32_bf16 v[12:15], v[164:167], v[208:211], v[12:15]
	v_mfma_f32_16x16x32_bf16 v[8:11], v[172:175], v[208:211], v[8:11]
	s_barrier
; #define PG8_STAGE(bufoff, gbase, voff) do { _Pragma("unroll") for (int _i = 0; _i < 2; ++_i) \
;         __builtin_amdgcn_global_load_lds((const unsigned*)((const char*)(gbase) + (voff)[_i]), (LAS unsigned*)(lds + (bufoff) + ldsw + _i * 8192), 16, 0, 0); } while (0)
; #define PG8_LDA(dst, b, h) do { _Pragma("unroll") for (int m = 0; m < 4; ++m) _Pragma("unroll") for (int k = 0; k < 2; ++k) dst[m][k] = *(const LAS bf16x8*)(lds + PG8_SA(b, h) + aoff + m * 2048 + k * 1024); } while (0)
; #define PG8_LDB(dst, b, h) do { _Pragma("unroll") for (int n = 0; n < 2; ++n) _Pragma("unroll") for (int k = 0; k < 2; ++k) dst[n][k] = *(const LAS bf16x8*)(lds + PG8_SB(b, h) + boff + n * 2048 + k * 1024); } while (0)
; #define PG8_MMA(ai, bj, At, Bt) do { __builtin_amdgcn_s_setprio(1); _Pragma("unroll") for (int m = 0; m < 4; ++m) _Pragma("unroll") for (int n = 0; n < 2; ++n) _Pragma("unroll") for (int k = 0; k < 2; ++k) \
;         acc[ai][bj][m][n] = __builtin_amdgcn_mfma_f32_16x16x32_bf16(Bt[n][k], At[m][k], acc[ai][bj][m][n], 0, 0, 0); __builtin_amdgcn_s_setprio(0); } while (0)
; #define PG8_WAIT_V(n) asm volatile("s_waitcnt vmcnt(" #n ")" ::: "memory")
; #define PG8_WAIT_L(n) asm volatile("s_waitcnt lgkmcnt(" #n ")" ::: "memory")
; #define PG8_BAR __builtin_amdgcn_s_barrier()
; #define PG8_SCHED __builtin_amdgcn_sched_barrier(0)
; template <class Epi>
; __device__ __forceinline__ void gemm_phase(LAS unsigned char* lds, const Gemm g, const StaticOrder& S, const Epi& E) {
;     ...
;             PG8_STAGE(PG8_SB(0, 1), b2, voffB1);
;             PG8_WAIT_V(6); PG8_BAR; PG8_MMA(1, 1, At, B1); PG8_BAR;
;             PG8_LDB(B0, 1, 0); PG8_SCHED; PG8_LDA(At, 1, 0); PG8_STAGE(PG8_SA(0, 1), a2 + hstep, voffA);
;             PG8_WAIT_L(8); PG8_BAR; PG8_WAIT_L(0); PG8_MMA(0, 0, At, B0); PG8_BAR; PG8_SCHED;
;             PG8_LDB(B1, 1, 1); PG8_STAGE(PG8_SB(1, 0), b3, voffB0);
;             PG8_BAR; PG8_WAIT_L(0); PG8_MMA(0, 1, At, B1); PG8_BAR;
;             PG8_LDA(At, 1, 1); PG8_STAGE(PG8_SA(1, 0), a3, voffA);
;             PG8_BAR; PG8_WAIT_L(0); PG8_MMA(1, 0, At, B0); PG8_BAR; PG8_SCHED;
	s_add_i32 s33, s57, s46
	v_lshl_add_u64 v[234:235], s[42:43], 0, v[132:133]
	s_mov_b32 m0, s33
	v_lshl_add_u64 v[236:237], s[42:43], 0, v[138:139]
	global_load_lds_dwordx4 v[234:235], off
	s_add_i32 m0, s33, 0x2000
	s_nop 0
	global_load_lds_dwordx4 v[236:237], off
	s_add_i32 s33, 0, 0x18000
	v_add_u32_e32 v172, s33, v147
	ds_read_b128 v[160:163], v172
	ds_read_b128 v[164:167], v172 offset:1024
	ds_read_b128 v[168:171], v172 offset:2048
	ds_read_b128 v[172:175], v172 offset:3072
	s_waitcnt vmcnt(6)
	s_barrier
	v_mfma_f32_16x16x32_bf16 v[52:55], v[212:215], v[176:179], v[52:55]
	v_mfma_f32_16x16x32_bf16 v[48:51], v[220:223], v[176:179], v[48:51]
	v_mfma_f32_16x16x32_bf16 v[36:39], v[212:215], v[184:187], v[36:39]
	v_mfma_f32_16x16x32_bf16 v[32:35], v[220:223], v[184:187], v[32:35]
	v_mfma_f32_16x16x32_bf16 v[20:23], v[212:215], v[192:195], v[20:23]
	v_mfma_f32_16x16x32_bf16 v[16:19], v[220:223], v[192:195], v[16:19]
	v_mfma_f32_16x16x32_bf16 v[4:7], v[212:215], v[204:207], v[4:7]
	v_mfma_f32_16x16x32_bf16 v[0:3], v[220:223], v[204:207], v[0:3]
	v_mfma_f32_16x16x32_bf16 v[52:55], v[216:219], v[180:183], v[52:55]
	v_mfma_f32_16x16x32_bf16 v[48:51], v[224:227], v[180:183], v[48:51]
	v_mfma_f32_16x16x32_bf16 v[36:39], v[216:219], v[188:191], v[36:39]
	v_mfma_f32_16x16x32_bf16 v[32:35], v[224:227], v[188:191], v[32:35]
	v_mfma_f32_16x16x32_bf16 v[20:23], v[216:219], v[196:199], v[20:23]
	v_mfma_f32_16x16x32_bf16 v[16:19], v[224:227], v[196:199], v[16:19]
	v_mfma_f32_16x16x32_bf16 v[4:7], v[216:219], v[208:211], v[4:7]
	v_mfma_f32_16x16x32_bf16 v[0:3], v[224:227], v[208:211], v[0:3]
	s_barrier
	s_add_u32 s40, s40, 0x80000
	s_addc_u32 s41, s41, 0
	s_mov_b32 m0, s48
	v_lshl_add_u64 v[212:213], s[40:41], 0, v[128:129]
	ds_read_b128 v[176:179], v158 offset:32768
	ds_read_b128 v[180:183], v158 offset:33792
	ds_read_b128 v[184:187], v158 offset:34816
	ds_read_b128 v[188:191], v158 offset:35840
	ds_read_b128 v[192:195], v158 offset:36864
	ds_read_b128 v[196:199], v158 offset:37888
	ds_read_b128 v[204:207], v158 offset:38912
	ds_read_b128 v[208:211], v158 offset:39936
	global_load_lds_dwordx4 v[212:213], off
	v_lshl_add_u64 v[212:213], s[40:41], 0, v[134:135]
	s_mov_b32 m0, s49
	s_nop 0
	global_load_lds_dwordx4 v[212:213], off
	s_waitcnt lgkmcnt(8)
	s_barrier
	s_waitcnt lgkmcnt(0)
	v_mfma_f32_16x16x32_bf16 v[124:127], v[160:163], v[176:179], v[124:127]
	v_mfma_f32_16x16x32_bf16 v[120:123], v[168:171], v[176:179], v[120:123]
	v_mfma_f32_16x16x32_bf16 v[108:111], v[160:163], v[184:187], v[108:111]
	v_mfma_f32_16x16x32_bf16 v[104:107], v[168:171], v[184:187], v[104:107]
	v_mfma_f32_16x16x32_bf16 v[92:95], v[160:163], v[192:195], v[92:95]
	v_mfma_f32_16x16x32_bf16 v[88:91], v[168:171], v[192:195], v[88:91]
	v_mfma_f32_16x16x32_bf16 v[76:79], v[160:163], v[204:207], v[76:79]
	v_mfma_f32_16x16x32_bf16 v[72:75], v[168:171], v[204:207], v[72:75]
	v_mfma_f32_16x16x32_bf16 v[124:127], v[164:167], v[180:183], v[124:127]
	v_mfma_f32_16x16x32_bf16 v[120:123], v[172:175], v[180:183], v[120:123]
	v_mfma_f32_16x16x32_bf16 v[108:111], v[164:167], v[188:191], v[108:111]
	v_mfma_f32_16x16x32_bf16 v[104:107], v[172:175], v[188:191], v[104:107]
	v_mfma_f32_16x16x32_bf16 v[92:95], v[164:167], v[196:199], v[92:95]
	v_mfma_f32_16x16x32_bf16 v[88:91], v[172:175], v[196:199], v[88:91]
	v_mfma_f32_16x16x32_bf16 v[76:79], v[164:167], v[208:211], v[76:79]
	v_mfma_f32_16x16x32_bf16 v[72:75], v[172:175], v[208:211], v[72:75]
	s_barrier
	s_add_i32 s40, 0, 0x1c000
	s_add_i32 s33, s33, s46
	v_add_u32_e32 v203, s40, v147
	v_lshl_add_u64 v[200:201], v[200:201], 0, s[16:17]
	s_mov_b32 m0, s33
	ds_read_b128 v[212:215], v203
	ds_read_b128 v[216:219], v203 offset:1024
	ds_read_b128 v[220:223], v203 offset:2048
	ds_read_b128 v[224:227], v203 offset:3072
	global_load_lds_dwordx4 v[200:201], off
	v_lshl_add_u64 v[200:201], v[228:229], 0, s[16:17]
	s_add_i32 m0, s33, 0x2000
	s_nop 0
	global_load_lds_dwordx4 v[200:201], off
	s_barrier
	s_waitcnt lgkmcnt(0)
	v_mfma_f32_16x16x32_bf16 v[116:119], v[212:215], v[176:179], v[116:119]
	v_mfma_f32_16x16x32_bf16 v[112:115], v[220:223], v[176:179], v[112:115]
	v_mfma_f32_16x16x32_bf16 v[100:103], v[212:215], v[184:187], v[100:103]
	v_mfma_f32_16x16x32_bf16 v[96:99], v[220:223], v[184:187], v[96:99]
	v_mfma_f32_16x16x32_bf16 v[84:87], v[212:215], v[192:195], v[84:87]
	v_mfma_f32_16x16x32_bf16 v[80:83], v[220:223], v[192:195], v[80:83]
	v_mfma_f32_16x16x32_bf16 v[68:71], v[212:215], v[204:207], v[68:71]
	v_mfma_f32_16x16x32_bf16 v[64:67], v[220:223], v[204:207], v[64:67]
	v_mfma_f32_16x16x32_bf16 v[116:119], v[216:219], v[180:183], v[116:119]
	v_mfma_f32_16x16x32_bf16 v[112:115], v[224:227], v[180:183], v[112:115]
	v_mfma_f32_16x16x32_bf16 v[100:103], v[216:219], v[188:191], v[100:103]
	v_mfma_f32_16x16x32_bf16 v[96:99], v[224:227], v[188:191], v[96:99]
	v_mfma_f32_16x16x32_bf16 v[84:87], v[216:219], v[196:199], v[84:87]
	v_mfma_f32_16x16x32_bf16 v[80:83], v[224:227], v[196:199], v[80:83]
	v_mfma_f32_16x16x32_bf16 v[68:71], v[216:219], v[208:211], v[68:71]
	v_mfma_f32_16x16x32_bf16 v[64:67], v[224:227], v[208:211], v[64:67]
	s_mov_b32 m0, s51
	v_lshl_add_u64 v[200:201], v[230:231], 0, s[16:17]
	s_barrier
	ds_read_b128 v[176:179], v158 offset:49152
	ds_read_b128 v[180:183], v158 offset:50176
	ds_read_b128 v[184:187], v158 offset:51200
	ds_read_b128 v[188:191], v158 offset:52224
	ds_read_b128 v[192:195], v158 offset:53248
	ds_read_b128 v[196:199], v158 offset:54272
	ds_read_b128 v[204:207], v158 offset:55296
	ds_read_b128 v[208:211], v158 offset:56320
	global_load_lds_dwordx4 v[200:201], off
	v_lshl_add_u64 v[200:201], v[232:233], 0, s[16:17]
	s_mov_b32 m0, s52
	s_nop 0
	global_load_lds_dwordx4 v[200:201], off
	s_barrier
; __device__ __forceinline__ unsigned cvt_pk_bf16(float lo, float hi) { unsigned r; asm volatile("v_cvt_pk_bf16_f32 %0, %1, %2" : "=v"(r) : "v"(lo), "v"(hi)); return r; }
; #define PG8_STAGE(bufoff, gbase, voff) do { _Pragma("unroll") for (int _i = 0; _i < 2; ++_i) \
;         __builtin_amdgcn_global_load_lds((const unsigned*)((const char*)(gbase) + (voff)[_i]), (LAS unsigned*)(lds + (bufoff) + ldsw + _i * 8192), 16, 0, 0); } while (0)
; #define PG8_MMA(ai, bj, At, Bt) do { __builtin_amdgcn_s_setprio(1); _Pragma("unroll") for (int m = 0; m < 4; ++m) _Pragma("unroll") for (int n = 0; n < 2; ++n) _Pragma("unroll") for (int k = 0; k < 2; ++k) \
;         acc[ai][bj][m][n] = __builtin_amdgcn_mfma_f32_16x16x32_bf16(Bt[n][k], At[m][k], acc[ai][bj][m][n], 0, 0, 0); __builtin_amdgcn_s_setprio(0); } while (0)
; #define PG8_WAIT_V(n) asm volatile("s_waitcnt vmcnt(" #n ")" ::: "memory")
; #define PG8_BAR __builtin_amdgcn_s_barrier()
;     __device__ __forceinline__ void operator()(const f32x4 (&acc)[2][2][4][2], const Unit& u, int wr, int wc, int fr, int fq) const {
;     ...
;             for (int m = 0; m < 4; ++m) { const int row = row0 + ai * HALF + m * 16;
;                 const float rs = ssin ? __builtin_amdgcn_rsqf(ssin[row] * (1.f / D) + EPS) : 1.0f; float sq = 0.f; u32x4 w[2];
; #pragma unroll
;                 for (int bj = 0; bj < 2; ++bj) { f32x4 v0 = acc[ai][bj][m][0] * rs, v1 = acc[ai][bj][m][1] * rs;
;                     if (ACT == 1) {
; #pragma unroll
;                         for (int j = 0; j < 4; ++j) { const float a = fmaxf(v0[j], 0.f), b = fmaxf(v1[j], 0.f); v0[j] = a * a; v1[j] = b * b; } }
;                     sq += (v0[0] * v0[0] + v0[1] * v0[1]) + (v0[2] * v0[2] + v0[3] * v0[3]) + (v1[0] * v1[0] + v1[1] * v1[1]) + (v1[2] * v1[2] + v1[3] * v1[3]);
;                     w[bj].x = cvt_pk_bf16(v0[0], v0[1]); w[bj].y = cvt_pk_bf16(v0[2], v0[3]); w[bj].z = cvt_pk_bf16(v1[0], v1[1]); w[bj].w = cvt_pk_bf16(v1[2], v1[3]); }
;                 store_pair_lines(O, ldc, row, fr, col0, w[0], w[1]);
; template <class Epi>
; __device__ __forceinline__ void gemm_phase(LAS unsigned char* lds, const Gemm g, const StaticOrder& S, const Epi& E) {
;     ...
;             PG8_BAR; PG8_WAIT_L(0); PG8_MMA(1, 0, At, B0); PG8_BAR; PG8_SCHED;
;             PG8_STAGE(PG8_SB(1, 1), b3, voffB1);
;             PG8_WAIT_V(6); PG8_BAR; PG8_MMA(1, 1, At, B1); PG8_BAR;
;         }
	s_waitcnt lgkmcnt(0)
	v_mfma_f32_16x16x32_bf16 v[60:63], v[160:163], v[176:179], v[60:63]
	v_mfma_f32_16x16x32_bf16 v[56:59], v[168:171], v[176:179], v[56:59]
	v_mfma_f32_16x16x32_bf16 v[44:47], v[160:163], v[184:187], v[44:47]
	v_mfma_f32_16x16x32_bf16 v[40:43], v[168:171], v[184:187], v[40:43]
	v_mfma_f32_16x16x32_bf16 v[28:31], v[160:163], v[192:195], v[28:31]
	v_mfma_f32_16x16x32_bf16 v[24:27], v[168:171], v[192:195], v[24:27]
	v_mfma_f32_16x16x32_bf16 v[12:15], v[160:163], v[204:207], v[12:15]
	v_mfma_f32_16x16x32_bf16 v[8:11], v[168:171], v[204:207], v[8:11]
	v_mfma_f32_16x16x32_bf16 v[60:63], v[164:167], v[180:183], v[60:63]
	v_mfma_f32_16x16x32_bf16 v[56:59], v[172:175], v[180:183], v[56:59]
	v_mfma_f32_16x16x32_bf16 v[44:47], v[164:167], v[188:191], v[44:47]
	v_mfma_f32_16x16x32_bf16 v[40:43], v[172:175], v[188:191], v[40:43]
	v_mfma_f32_16x16x32_bf16 v[28:31], v[164:167], v[196:199], v[28:31]
	v_mfma_f32_16x16x32_bf16 v[24:27], v[172:175], v[196:199], v[24:27]
	v_mfma_f32_16x16x32_bf16 v[12:15], v[164:167], v[208:211], v[12:15]
	v_mfma_f32_16x16x32_bf16 v[8:11], v[172:175], v[208:211], v[8:11]
	s_barrier
	s_add_i32 s33, s40, s46
	v_lshl_add_u64 v[160:161], v[234:235], 0, s[16:17]
	s_mov_b32 m0, s33
	s_nop 0
	global_load_lds_dwordx4 v[160:161], off
	v_lshl_add_u64 v[160:161], v[236:237], 0, s[16:17]
	s_add_i32 m0, s33, 0x2000
	s_nop 0
	global_load_lds_dwordx4 v[160:161], off
	s_waitcnt vmcnt(6)
	s_barrier
	v_mfma_f32_16x16x32_bf16 v[52:55], v[212:215], v[176:179], v[52:55]
	v_mfma_f32_16x16x32_bf16 v[48:51], v[220:223], v[176:179], v[48:51]
	v_mfma_f32_16x16x32_bf16 v[36:39], v[212:215], v[184:187], v[36:39]
	v_mfma_f32_16x16x32_bf16 v[32:35], v[220:223], v[184:187], v[32:35]
	v_mfma_f32_16x16x32_bf16 v[20:23], v[212:215], v[192:195], v[20:23]
	v_mfma_f32_16x16x32_bf16 v[16:19], v[220:223], v[192:195], v[16:19]
	v_mfma_f32_16x16x32_bf16 v[4:7], v[212:215], v[204:207], v[4:7]
	v_mfma_f32_16x16x32_bf16 v[0:3], v[220:223], v[204:207], v[0:3]
	v_mfma_f32_16x16x32_bf16 v[52:55], v[216:219], v[180:183], v[52:55]
	v_mfma_f32_16x16x32_bf16 v[48:51], v[224:227], v[180:183], v[48:51]
	v_mfma_f32_16x16x32_bf16 v[36:39], v[216:219], v[188:191], v[36:39]
	v_mfma_f32_16x16x32_bf16 v[32:35], v[224:227], v[188:191], v[32:35]
	v_mfma_f32_16x16x32_bf16 v[20:23], v[216:219], v[196:199], v[20:23]
	v_mfma_f32_16x16x32_bf16 v[16:19], v[224:227], v[196:199], v[16:19]
	v_mfma_f32_16x16x32_bf16 v[4:7], v[216:219], v[208:211], v[4:7]
	v_mfma_f32_16x16x32_bf16 v[0:3], v[224:227], v[208:211], v[0:3]
	s_add_i32 s64, s64, 2
	s_add_u32 s38, s38, 0x100
	s_addc_u32 s39, s39, 0
	s_add_u32 s62, s62, 0x100
	s_addc_u32 s63, s63, 0
	s_cmp_gt_u32 s64, 29
	s_barrier
	s_cbranch_scc0 .LBB0_1365
	v_max_f32_e32 v124, 0, v124
	v_max_f32_e32 v120, 0, v120
	v_max_f32_e32 v125, 0, v125
	v_max_f32_e32 v121, 0, v121
	v_max_f32_e32 v122, 0, v122
	v_max_f32_e32 v118, 0, v118
	v_max_f32_e32 v119, 0, v119
	v_mul_f32_e32 v124, v124, v124
	v_mul_f32_e32 v120, v120, v120
	v_mul_f32_e32 v125, v125, v125
	v_mul_f32_e32 v121, v121, v121
	v_max_f32_e32 v126, 0, v126
	v_mul_f32_e32 v122, v122, v122
	v_max_f32_e32 v127, 0, v127
	v_max_f32_e32 v123, 0, v123
	v_max_f32_e32 v116, 0, v116
	v_max_f32_e32 v112, 0, v112
	v_max_f32_e32 v117, 0, v117
	v_max_f32_e32 v113, 0, v113
	v_max_f32_e32 v114, 0, v114
	v_mul_f32_e32 v118, v118, v118
	v_mul_f32_e32 v119, v119, v119
	s_lshl_b32 s19, s36, 8
	v_mul_f32_e32 v126, v126, v126
	v_mul_f32_e32 v127, v127, v127
	v_mul_f32_e32 v123, v123, v123
	v_cvt_pk_bf16_f32 v124, v124, v125
	v_cvt_pk_bf16_f32 v125, v126, v127
	v_cvt_pk_bf16_f32 v120, v120, v121
	v_cvt_pk_bf16_f32 v121, v122, v123
	v_mul_f32_e32 v116, v116, v116
	v_mul_f32_e32 v112, v112, v112
	v_mul_f32_e32 v117, v117, v117
	v_mul_f32_e32 v113, v113, v113
	v_mul_f32_e32 v114, v114, v114
	v_max_f32_e32 v115, 0, v115
	v_cvt_pk_bf16_f32 v122, v116, v117
	v_cvt_pk_bf16_f32 v119, v118, v119
	s_add_i32 s19, s19, s53
	v_mul_f32_e32 v115, v115, v115
	v_cvt_pk_bf16_f32 v112, v112, v113
	v_cvt_pk_bf16_f32 v113, v114, v115
	v_mov_b32_dpp v118, v124 row_ror:8 row_mask:0xf bank_mask:0xf
	v_mov_b32_dpp v123, v125 row_ror:8 row_mask:0xf bank_mask:0xf
	v_mov_b32_dpp v114, v122 row_ror:8 row_mask:0xf bank_mask:0xf
	v_cndmask_b32_e64 v118, v122, v118, s[6:7]
	v_or_b32_e32 v122, s19, v148
	v_lshl_or_b32 v162, s59, 8, v156
	v_mov_b32_dpp v126, v120 row_ror:8 row_mask:0xf bank_mask:0xf
	v_mov_b32_dpp v127, v121 row_ror:8 row_mask:0xf bank_mask:0xf
	v_mov_b32_dpp v115, v119 row_ror:8 row_mask:0xf bank_mask:0xf
	v_mov_b32_dpp v116, v112 row_ror:8 row_mask:0xf bank_mask:0xf
	v_mov_b32_dpp v117, v113 row_ror:8 row_mask:0xf bank_mask:0xf
	v_cndmask_b32_e64 v119, v119, v123, s[6:7]
	v_ashrrev_i32_e32 v123, 31, v122
	v_ashrrev_i32_e32 v163, 31, v162
	v_cndmask_b32_e64 v116, v116, v120, s[6:7]
	v_cndmask_b32_e64 v117, v117, v121, s[6:7]
	v_cndmask_b32_e64 v120, v112, v126, s[6:7]
	v_cndmask_b32_e64 v121, v113, v127, s[6:7]
	v_lshlrev_b64 v[112:113], 14, v[122:123]
	v_cndmask_b32_e64 v114, v114, v124, s[6:7]
	v_cndmask_b32_e64 v115, v115, v125, s[6:7]
	v_lshl_add_u64 v[124:125], s[12:13], 0, v[112:113]
	v_lshlrev_b64 v[112:113], 1, v[162:163]
	v_lshl_add_u64 v[124:125], v[124:125], 0, v[112:113]
	global_store_dwordx4 v[124:125], v[114:117], off
	v_max_f32_e32 v108, v108, v108
	v_max_f32_e32 v104, v104, v104
	v_or_b32_e32 v114, 8, v122
	v_ashrrev_i32_e32 v115, 31, v114
	v_lshlrev_b64 v[114:115], 14, v[114:115]
	v_lshl_add_u64 v[114:115], s[12:13], 0, v[114:115]
	v_max_f32_e32 v108, 0, v108
	v_max_f32_e32 v104, 0, v104
	v_max_f32_e32 v109, 0, v109
	v_max_f32_e32 v105, 0, v105
	v_max_f32_e32 v100, 0, v100
	v_max_f32_e32 v101, 0, v101
; __device__ __forceinline__ unsigned cvt_pk_bf16(float lo, float hi) { unsigned r; asm volatile("v_cvt_pk_bf16_f32 %0, %1, %2" : "=v"(r) : "v"(lo), "v"(hi)); return r; }
;     __device__ __forceinline__ void operator()(const f32x4 (&acc)[2][2][4][2], const Unit& u, int wr, int wc, int fr, int fq) const {
;     ...
;             for (int m = 0; m < 4; ++m) { const int row = row0 + ai * HALF + m * 16;
;                 const float rs = ssin ? __builtin_amdgcn_rsqf(ssin[row] * (1.f / D) + EPS) : 1.0f; float sq = 0.f; u32x4 w[2];
; #pragma unroll
;                 for (int bj = 0; bj < 2; ++bj) { f32x4 v0 = acc[ai][bj][m][0] * rs, v1 = acc[ai][bj][m][1] * rs;
;                     if (ACT == 1) {
; #pragma unroll
;                         for (int j = 0; j < 4; ++j) { const float a = fmaxf(v0[j], 0.f), b = fmaxf(v1[j], 0.f); v0[j] = a * a; v1[j] = b * b; } }
;                     sq += (v0[0] * v0[0] + v0[1] * v0[1]) + (v0[2] * v0[2] + v0[3] * v0[3]) + (v1[0] * v1[0] + v1[1] * v1[1]) + (v1[2] * v1[2] + v1[3] * v1[3]);
;                     w[bj].x = cvt_pk_bf16(v0[0], v0[1]); w[bj].y = cvt_pk_bf16(v0[2], v0[3]); w[bj].z = cvt_pk_bf16(v1[0], v1[1]); w[bj].w = cvt_pk_bf16(v1[2], v1[3]); }
;                 store_pair_lines(O, ldc, row, fr, col0, w[0], w[1]);
	v_max_f32_e32 v102, 0, v102
	v_max_f32_e32 v98, 0, v98
	v_max_f32_e32 v103, 0, v103
	v_lshl_add_u64 v[114:115], v[114:115], 0, v[112:113]
	v_mul_f32_e32 v108, v108, v108
	v_mul_f32_e32 v104, v104, v104
	v_mul_f32_e32 v109, v109, v109
	v_mul_f32_e32 v105, v105, v105
	v_max_f32_e32 v110, 0, v110
	v_max_f32_e32 v106, 0, v106
	v_max_f32_e32 v111, 0, v111
	v_max_f32_e32 v107, 0, v107
	v_max_f32_e32 v96, 0, v96
	v_mul_f32_e32 v100, v100, v100
	v_max_f32_e32 v97, 0, v97
	v_mul_f32_e32 v101, v101, v101
	v_mul_f32_e32 v102, v102, v102
	v_mul_f32_e32 v98, v98, v98
	v_max_f32_e32 v99, 0, v99
	v_mul_f32_e32 v103, v103, v103
	global_store_dwordx4 v[114:115], v[118:121], off
	v_mul_f32_e32 v110, v110, v110
	v_mul_f32_e32 v106, v106, v106
	v_mul_f32_e32 v111, v111, v111
	v_mul_f32_e32 v107, v107, v107
	v_cvt_pk_bf16_f32 v108, v108, v109
	v_cvt_pk_bf16_f32 v109, v110, v111
	v_cvt_pk_bf16_f32 v104, v104, v105
	v_cvt_pk_bf16_f32 v105, v106, v107
	v_mul_f32_e32 v96, v96, v96
	v_mul_f32_e32 v97, v97, v97
	v_mul_f32_e32 v99, v99, v99
	v_cvt_pk_bf16_f32 v100, v100, v101
	v_cvt_pk_bf16_f32 v101, v102, v103
	v_cvt_pk_bf16_f32 v102, v96, v97
	v_cvt_pk_bf16_f32 v103, v98, v99
	v_or_b32_e32 v160, s19, v146
	v_mov_b32_dpp v98, v102 row_ror:8 row_mask:0xf bank_mask:0xf
	v_mov_b32_dpp v110, v104 row_ror:8 row_mask:0xf bank_mask:0xf
	v_mov_b32_dpp v99, v103 row_ror:8 row_mask:0xf bank_mask:0xf
	v_cndmask_b32_e64 v98, v98, v104, s[6:7]
	v_add_u32_e32 v104, v149, v160
	v_mov_b32_dpp v111, v105 row_ror:8 row_mask:0xf bank_mask:0xf
	v_cndmask_b32_e64 v99, v99, v105, s[6:7]
	v_ashrrev_i32_e32 v105, 31, v104
	v_lshlrev_b64 v[104:105], 14, v[104:105]
	v_mov_b32_dpp v96, v100 row_ror:8 row_mask:0xf bank_mask:0xf
	v_mov_b32_dpp v97, v101 row_ror:8 row_mask:0xf bank_mask:0xf
	v_lshl_add_u64 v[104:105], s[12:13], 0, v[104:105]
	v_cndmask_b32_e64 v96, v96, v108, s[6:7]
	v_cndmask_b32_e64 v97, v97, v109, s[6:7]
	v_lshl_add_u64 v[104:105], v[104:105], 0, v[112:113]
	v_mov_b32_dpp v106, v108 row_ror:8 row_mask:0xf bank_mask:0xf
	v_mov_b32_dpp v107, v109 row_ror:8 row_mask:0xf bank_mask:0xf
	global_store_dwordx4 v[104:105], v[96:99], off
	v_max_f32_e32 v92, 0, v92
	v_max_f32_e32 v88, 0, v88
	v_add_co_u32_e32 v96, vcc, s58, v104
	v_max_f32_e32 v93, 0, v93
	v_max_f32_e32 v89, 0, v89
	v_max_f32_e32 v84, 0, v84
	v_max_f32_e32 v85, 0, v85
	v_max_f32_e32 v86, 0, v86
	v_max_f32_e32 v82, 0, v82
	v_max_f32_e32 v87, 0, v87
	v_cndmask_b32_e64 v100, v100, v106, s[6:7]
	v_cndmask_b32_e64 v101, v101, v107, s[6:7]
	v_cndmask_b32_e64 v102, v102, v110, s[6:7]
	v_cndmask_b32_e64 v103, v103, v111, s[6:7]
	v_addc_co_u32_e32 v97, vcc, 0, v105, vcc
	v_mul_f32_e32 v92, v92, v92
	v_mul_f32_e32 v88, v88, v88
	v_mul_f32_e32 v93, v93, v93
	v_mul_f32_e32 v89, v89, v89
	v_max_f32_e32 v94, 0, v94
	v_max_f32_e32 v90, 0, v90
	v_max_f32_e32 v95, 0, v95
	v_max_f32_e32 v91, 0, v91
	v_max_f32_e32 v80, 0, v80
	v_mul_f32_e32 v84, v84, v84
	v_max_f32_e32 v81, 0, v81
	v_mul_f32_e32 v85, v85, v85
	v_mul_f32_e32 v86, v86, v86
	v_mul_f32_e32 v82, v82, v82
	v_max_f32_e32 v83, 0, v83
	v_mul_f32_e32 v87, v87, v87
	global_store_dwordx4 v[96:97], v[100:103], off
	v_mul_f32_e32 v94, v94, v94
	v_mul_f32_e32 v90, v90, v90
	v_mul_f32_e32 v95, v95, v95
	v_mul_f32_e32 v91, v91, v91
	v_cvt_pk_bf16_f32 v92, v92, v93
	v_cvt_pk_bf16_f32 v93, v94, v95
	v_cvt_pk_bf16_f32 v88, v88, v89
	v_cvt_pk_bf16_f32 v89, v90, v91
	v_mul_f32_e32 v80, v80, v80
	v_mul_f32_e32 v81, v81, v81
	v_mul_f32_e32 v83, v83, v83
	v_cvt_pk_bf16_f32 v84, v84, v85
	v_cvt_pk_bf16_f32 v85, v86, v87
	v_cvt_pk_bf16_f32 v86, v80, v81
	v_cvt_pk_bf16_f32 v87, v82, v83
	v_mov_b32_e32 v82, 0
	v_mov_b32_dpp v82, v86 row_ror:8 row_mask:0xf bank_mask:0xf
	v_mov_b32_dpp v94, v88 row_ror:8 row_mask:0xf bank_mask:0xf
	v_mov_b32_dpp v83, v87 row_ror:8 row_mask:0xf bank_mask:0xf
	v_cndmask_b32_e64 v82, v82, v88, s[6:7]
	v_add_u32_e32 v88, v150, v160
	v_mov_b32_dpp v95, v89 row_ror:8 row_mask:0xf bank_mask:0xf
	v_cndmask_b32_e64 v83, v83, v89, s[6:7]
	v_ashrrev_i32_e32 v89, 31, v88
	v_lshlrev_b64 v[88:89], 14, v[88:89]
	v_mov_b32_dpp v80, v84 row_ror:8 row_mask:0xf bank_mask:0xf
	v_mov_b32_dpp v81, v85 row_ror:8 row_mask:0xf bank_mask:0xf
	v_lshl_add_u64 v[88:89], s[12:13], 0, v[88:89]
	v_cndmask_b32_e64 v80, v80, v92, s[6:7]
	v_cndmask_b32_e64 v81, v81, v93, s[6:7]
	v_lshl_add_u64 v[88:89], v[88:89], 0, v[112:113]
	v_mov_b32_dpp v90, v92 row_ror:8 row_mask:0xf bank_mask:0xf
	v_mov_b32_dpp v91, v93 row_ror:8 row_mask:0xf bank_mask:0xf
	global_store_dwordx4 v[88:89], v[80:83], off
	v_max_f32_e32 v76, 0, v76
	v_max_f32_e32 v72, 0, v72
	v_add_co_u32_e32 v80, vcc, s58, v88
	v_max_f32_e32 v77, 0, v77
	v_max_f32_e32 v73, 0, v73
	v_max_f32_e32 v68, 0, v68
	v_max_f32_e32 v69, 0, v69
	v_max_f32_e32 v70, 0, v70
	v_max_f32_e32 v66, 0, v66
	v_max_f32_e32 v71, 0, v71
	v_cndmask_b32_e64 v84, v84, v90, s[6:7]
	v_cndmask_b32_e64 v85, v85, v91, s[6:7]
	v_cndmask_b32_e64 v86, v86, v94, s[6:7]
	v_cndmask_b32_e64 v87, v87, v95, s[6:7]
	v_addc_co_u32_e32 v81, vcc, 0, v89, vcc
	v_mul_f32_e32 v76, v76, v76
	v_mul_f32_e32 v72, v72, v72
	v_mul_f32_e32 v77, v77, v77
	v_mul_f32_e32 v73, v73, v73
	v_max_f32_e32 v78, 0, v78
	v_max_f32_e32 v74, 0, v74
	v_max_f32_e32 v79, 0, v79
	v_max_f32_e32 v75, 0, v75
	v_max_f32_e32 v64, 0, v64
	v_mul_f32_e32 v68, v68, v68
	v_max_f32_e32 v65, 0, v65
	v_mul_f32_e32 v69, v69, v69
	v_mul_f32_e32 v70, v70, v70
	v_mul_f32_e32 v66, v66, v66
	v_max_f32_e32 v67, 0, v67
	v_mul_f32_e32 v71, v71, v71
	global_store_dwordx4 v[80:81], v[84:87], off
	v_mul_f32_e32 v78, v78, v78
	v_mul_f32_e32 v74, v74, v74
	v_mul_f32_e32 v79, v79, v79
	v_mul_f32_e32 v75, v75, v75
	v_cvt_pk_bf16_f32 v76, v76, v77
; __device__ __forceinline__ unsigned cvt_pk_bf16(float lo, float hi) { unsigned r; asm volatile("v_cvt_pk_bf16_f32 %0, %1, %2" : "=v"(r) : "v"(lo), "v"(hi)); return r; }
;     __device__ __forceinline__ void operator()(const f32x4 (&acc)[2][2][4][2], const Unit& u, int wr, int wc, int fr, int fq) const {
;     ...
;             for (int m = 0; m < 4; ++m) { const int row = row0 + ai * HALF + m * 16;
;                 const float rs = ssin ? __builtin_amdgcn_rsqf(ssin[row] * (1.f / D) + EPS) : 1.0f; float sq = 0.f; u32x4 w[2];
; #pragma unroll
;                 for (int bj = 0; bj < 2; ++bj) { f32x4 v0 = acc[ai][bj][m][0] * rs, v1 = acc[ai][bj][m][1] * rs;
;                     if (ACT == 1) {
; #pragma unroll
;                         for (int j = 0; j < 4; ++j) { const float a = fmaxf(v0[j], 0.f), b = fmaxf(v1[j], 0.f); v0[j] = a * a; v1[j] = b * b; } }
;                     sq += (v0[0] * v0[0] + v0[1] * v0[1]) + (v0[2] * v0[2] + v0[3] * v0[3]) + (v1[0] * v1[0] + v1[1] * v1[1]) + (v1[2] * v1[2] + v1[3] * v1[3]);
;                     w[bj].x = cvt_pk_bf16(v0[0], v0[1]); w[bj].y = cvt_pk_bf16(v0[2], v0[3]); w[bj].z = cvt_pk_bf16(v1[0], v1[1]); w[bj].w = cvt_pk_bf16(v1[2], v1[3]); }
;                 store_pair_lines(O, ldc, row, fr, col0, w[0], w[1]);
	v_cvt_pk_bf16_f32 v77, v78, v79
	v_cvt_pk_bf16_f32 v72, v72, v73
	v_cvt_pk_bf16_f32 v73, v74, v75
	v_mul_f32_e32 v64, v64, v64
	v_mul_f32_e32 v65, v65, v65
	v_mul_f32_e32 v67, v67, v67
	v_cvt_pk_bf16_f32 v68, v68, v69
	v_cvt_pk_bf16_f32 v69, v70, v71
	v_cvt_pk_bf16_f32 v70, v64, v65
	v_cvt_pk_bf16_f32 v71, v66, v67
	v_mov_b32_e32 v66, 0
	v_mov_b32_dpp v66, v70 row_ror:8 row_mask:0xf bank_mask:0xf
	v_mov_b32_dpp v78, v72 row_ror:8 row_mask:0xf bank_mask:0xf
	v_mov_b32_dpp v67, v71 row_ror:8 row_mask:0xf bank_mask:0xf
	v_cndmask_b32_e64 v66, v66, v72, s[6:7]
	v_add_u32_e32 v72, v151, v160
	v_mov_b32_dpp v79, v73 row_ror:8 row_mask:0xf bank_mask:0xf
	v_cndmask_b32_e64 v67, v67, v73, s[6:7]
	v_ashrrev_i32_e32 v73, 31, v72
	v_lshlrev_b64 v[72:73], 14, v[72:73]
	v_mov_b32_dpp v64, v68 row_ror:8 row_mask:0xf bank_mask:0xf
	v_mov_b32_dpp v65, v69 row_ror:8 row_mask:0xf bank_mask:0xf
	v_lshl_add_u64 v[72:73], s[12:13], 0, v[72:73]
	v_cndmask_b32_e64 v64, v64, v76, s[6:7]
	v_cndmask_b32_e64 v65, v65, v77, s[6:7]
	v_lshl_add_u64 v[72:73], v[72:73], 0, v[112:113]
	v_mov_b32_dpp v74, v76 row_ror:8 row_mask:0xf bank_mask:0xf
	v_mov_b32_dpp v75, v77 row_ror:8 row_mask:0xf bank_mask:0xf
	global_store_dwordx4 v[72:73], v[64:67], off
	v_max_f32_e32 v60, 0, v60
	v_max_f32_e32 v56, 0, v56
	v_add_co_u32_e32 v64, vcc, s58, v72
	v_max_f32_e32 v61, 0, v61
	v_max_f32_e32 v57, 0, v57
	v_max_f32_e32 v52, 0, v52
	v_max_f32_e32 v53, 0, v53
	v_max_f32_e32 v54, 0, v54
	v_max_f32_e32 v50, 0, v50
	v_max_f32_e32 v55, 0, v55
	v_cndmask_b32_e64 v68, v68, v74, s[6:7]
	v_cndmask_b32_e64 v69, v69, v75, s[6:7]
	v_cndmask_b32_e64 v70, v70, v78, s[6:7]
	v_cndmask_b32_e64 v71, v71, v79, s[6:7]
	v_addc_co_u32_e32 v65, vcc, 0, v73, vcc
	v_mul_f32_e32 v60, v60, v60
	v_mul_f32_e32 v56, v56, v56
	v_mul_f32_e32 v61, v61, v61
	v_mul_f32_e32 v57, v57, v57
	v_max_f32_e32 v62, 0, v62
	v_max_f32_e32 v58, 0, v58
	v_max_f32_e32 v63, 0, v63
	v_max_f32_e32 v59, 0, v59
	v_max_f32_e32 v48, 0, v48
	v_mul_f32_e32 v52, v52, v52
	v_max_f32_e32 v49, 0, v49
	v_mul_f32_e32 v53, v53, v53
	v_mul_f32_e32 v54, v54, v54
	v_mul_f32_e32 v50, v50, v50
	v_max_f32_e32 v51, 0, v51
	v_mul_f32_e32 v55, v55, v55
	global_store_dwordx4 v[64:65], v[68:71], off
	v_mul_f32_e32 v62, v62, v62
	v_mul_f32_e32 v58, v58, v58
	v_mul_f32_e32 v63, v63, v63
	v_mul_f32_e32 v59, v59, v59
	v_cvt_pk_bf16_f32 v60, v60, v61
	v_cvt_pk_bf16_f32 v61, v62, v63
	v_cvt_pk_bf16_f32 v56, v56, v57
	v_cvt_pk_bf16_f32 v57, v58, v59
	v_mul_f32_e32 v48, v48, v48
	v_mul_f32_e32 v49, v49, v49
	v_mul_f32_e32 v51, v51, v51
	v_cvt_pk_bf16_f32 v52, v52, v53
	v_cvt_pk_bf16_f32 v53, v54, v55
	v_cvt_pk_bf16_f32 v54, v48, v49
	v_cvt_pk_bf16_f32 v55, v50, v51
	v_mov_b32_e32 v50, 0
	v_mov_b32_dpp v50, v54 row_ror:8 row_mask:0xf bank_mask:0xf
	v_mov_b32_dpp v62, v56 row_ror:8 row_mask:0xf bank_mask:0xf
	v_mov_b32_dpp v51, v55 row_ror:8 row_mask:0xf bank_mask:0xf
	v_cndmask_b32_e64 v50, v50, v56, s[6:7]
	v_add_u32_e32 v56, v152, v160
	v_mov_b32_dpp v63, v57 row_ror:8 row_mask:0xf bank_mask:0xf
	v_cndmask_b32_e64 v51, v51, v57, s[6:7]
	v_ashrrev_i32_e32 v57, 31, v56
	v_lshlrev_b64 v[56:57], 14, v[56:57]
	v_mov_b32_dpp v48, v52 row_ror:8 row_mask:0xf bank_mask:0xf
	v_mov_b32_dpp v49, v53 row_ror:8 row_mask:0xf bank_mask:0xf
	v_lshl_add_u64 v[56:57], s[12:13], 0, v[56:57]
	v_cndmask_b32_e64 v48, v48, v60, s[6:7]
	v_cndmask_b32_e64 v49, v49, v61, s[6:7]
	v_lshl_add_u64 v[56:57], v[56:57], 0, v[112:113]
	v_mov_b32_dpp v58, v60 row_ror:8 row_mask:0xf bank_mask:0xf
	v_mov_b32_dpp v59, v61 row_ror:8 row_mask:0xf bank_mask:0xf
	global_store_dwordx4 v[56:57], v[48:51], off
	v_max_f32_e32 v44, 0, v44
	v_max_f32_e32 v40, 0, v40
	v_add_co_u32_e32 v48, vcc, s58, v56
	v_max_f32_e32 v45, 0, v45
	v_max_f32_e32 v41, 0, v41
	v_max_f32_e32 v36, 0, v36
	v_max_f32_e32 v37, 0, v37
	v_max_f32_e32 v38, 0, v38
	v_max_f32_e32 v34, 0, v34
	v_max_f32_e32 v39, 0, v39
	v_cndmask_b32_e64 v52, v52, v58, s[6:7]
	v_cndmask_b32_e64 v53, v53, v59, s[6:7]
	v_cndmask_b32_e64 v54, v54, v62, s[6:7]
	v_cndmask_b32_e64 v55, v55, v63, s[6:7]
	v_addc_co_u32_e32 v49, vcc, 0, v57, vcc
	v_mul_f32_e32 v44, v44, v44
	v_mul_f32_e32 v40, v40, v40
	v_mul_f32_e32 v45, v45, v45
	v_mul_f32_e32 v41, v41, v41
	v_max_f32_e32 v46, 0, v46
	v_max_f32_e32 v42, 0, v42
	v_max_f32_e32 v47, 0, v47
	v_max_f32_e32 v43, 0, v43
	v_max_f32_e32 v32, 0, v32
	v_mul_f32_e32 v36, v36, v36
	v_max_f32_e32 v33, 0, v33
	v_mul_f32_e32 v37, v37, v37
	v_mul_f32_e32 v38, v38, v38
	v_mul_f32_e32 v34, v34, v34
	v_max_f32_e32 v35, 0, v35
	v_mul_f32_e32 v39, v39, v39
	global_store_dwordx4 v[48:49], v[52:55], off
	v_mul_f32_e32 v46, v46, v46
	v_mul_f32_e32 v42, v42, v42
	v_mul_f32_e32 v47, v47, v47
	v_mul_f32_e32 v43, v43, v43
	v_cvt_pk_bf16_f32 v44, v44, v45
	v_cvt_pk_bf16_f32 v45, v46, v47
	v_cvt_pk_bf16_f32 v40, v40, v41
	v_cvt_pk_bf16_f32 v41, v42, v43
	v_mul_f32_e32 v32, v32, v32
	v_mul_f32_e32 v33, v33, v33
	v_mul_f32_e32 v35, v35, v35
	v_cvt_pk_bf16_f32 v36, v36, v37
	v_cvt_pk_bf16_f32 v37, v38, v39
	v_cvt_pk_bf16_f32 v38, v32, v33
	v_cvt_pk_bf16_f32 v39, v34, v35
	v_mov_b32_e32 v34, 0
	v_mov_b32_dpp v34, v38 row_ror:8 row_mask:0xf bank_mask:0xf
	v_mov_b32_dpp v46, v40 row_ror:8 row_mask:0xf bank_mask:0xf
	v_mov_b32_dpp v35, v39 row_ror:8 row_mask:0xf bank_mask:0xf
	v_cndmask_b32_e64 v34, v34, v40, s[6:7]
	v_add_u32_e32 v40, v153, v160
	v_mov_b32_dpp v47, v41 row_ror:8 row_mask:0xf bank_mask:0xf
	v_cndmask_b32_e64 v35, v35, v41, s[6:7]
	v_ashrrev_i32_e32 v41, 31, v40
	v_lshlrev_b64 v[40:41], 14, v[40:41]
	v_mov_b32_dpp v32, v36 row_ror:8 row_mask:0xf bank_mask:0xf
; __device__ __forceinline__ unsigned cvt_pk_bf16(float lo, float hi) { unsigned r; asm volatile("v_cvt_pk_bf16_f32 %0, %1, %2" : "=v"(r) : "v"(lo), "v"(hi)); return r; }
; #define PG8_WAIT_V(n) asm volatile("s_waitcnt vmcnt(" #n ")" ::: "memory")
; #define PG8_BAR __builtin_amdgcn_s_barrier()
;     __device__ __forceinline__ void operator()(const f32x4 (&acc)[2][2][4][2], const Unit& u, int wr, int wc, int fr, int fq) const {
;     ...
;                 for (int bj = 0; bj < 2; ++bj) { f32x4 v0 = acc[ai][bj][m][0] * rs, v1 = acc[ai][bj][m][1] * rs;
;                     if (ACT == 1) {
; #pragma unroll
;                         for (int j = 0; j < 4; ++j) { const float a = fmaxf(v0[j], 0.f), b = fmaxf(v1[j], 0.f); v0[j] = a * a; v1[j] = b * b; } }
;                     sq += (v0[0] * v0[0] + v0[1] * v0[1]) + (v0[2] * v0[2] + v0[3] * v0[3]) + (v1[0] * v1[0] + v1[1] * v1[1]) + (v1[2] * v1[2] + v1[3] * v1[3]);
;                     w[bj].x = cvt_pk_bf16(v0[0], v0[1]); w[bj].y = cvt_pk_bf16(v0[2], v0[3]); w[bj].z = cvt_pk_bf16(v1[0], v1[1]); w[bj].w = cvt_pk_bf16(v1[2], v1[3]); }
;                 store_pair_lines(O, ldc, row, fr, col0, w[0], w[1]);
; template <class Epi>
; __device__ __forceinline__ void gemm_phase(LAS unsigned char* lds, const Gemm g, const StaticOrder& S, const Epi& E) {
;     ...
;         E(acc, cur, wr, wc, fr, fq);
;         if (!has_next) break;
; #pragma unroll
;         for (int a = 0; a < 2; ++a)
; #pragma unroll
;             for (int b = 0; b < 2; ++b)
; #pragma unroll
;                 for (int m = 0; m < 4; ++m)
; #pragma unroll
;                     for (int n = 0; n < 2; ++n) acc[a][b][m][n] = (f32x4){0.f, 0.f, 0.f, 0.f};
;         cur = nxt; cA = nA; cB = nB; ++ui;
;     }
;     PG8_WAIT_V(0);
;     if (wr == 0) PG8_BAR;
;     PG8_BAR;
	v_mov_b32_dpp v33, v37 row_ror:8 row_mask:0xf bank_mask:0xf
	v_lshl_add_u64 v[40:41], s[12:13], 0, v[40:41]
	v_cndmask_b32_e64 v32, v32, v44, s[6:7]
	v_cndmask_b32_e64 v33, v33, v45, s[6:7]
	v_lshl_add_u64 v[40:41], v[40:41], 0, v[112:113]
	v_mov_b32_dpp v42, v44 row_ror:8 row_mask:0xf bank_mask:0xf
	v_mov_b32_dpp v43, v45 row_ror:8 row_mask:0xf bank_mask:0xf
	global_store_dwordx4 v[40:41], v[32:35], off
	v_max_f32_e32 v28, 0, v28
	v_max_f32_e32 v24, 0, v24
	v_add_co_u32_e32 v32, vcc, s58, v40
	v_max_f32_e32 v29, 0, v29
	v_max_f32_e32 v25, 0, v25
	v_max_f32_e32 v20, 0, v20
	v_max_f32_e32 v21, 0, v21
	v_max_f32_e32 v22, 0, v22
	v_max_f32_e32 v18, 0, v18
	v_max_f32_e32 v23, 0, v23
	v_cndmask_b32_e64 v36, v36, v42, s[6:7]
	v_cndmask_b32_e64 v37, v37, v43, s[6:7]
	v_cndmask_b32_e64 v38, v38, v46, s[6:7]
	v_cndmask_b32_e64 v39, v39, v47, s[6:7]
	v_addc_co_u32_e32 v33, vcc, 0, v41, vcc
	v_mul_f32_e32 v28, v28, v28
	v_mul_f32_e32 v24, v24, v24
	v_mul_f32_e32 v29, v29, v29
	v_mul_f32_e32 v25, v25, v25
	v_max_f32_e32 v30, 0, v30
	v_max_f32_e32 v26, 0, v26
	v_max_f32_e32 v31, 0, v31
	v_max_f32_e32 v27, 0, v27
	v_max_f32_e32 v16, 0, v16
	v_mul_f32_e32 v20, v20, v20
	v_max_f32_e32 v17, 0, v17
	v_mul_f32_e32 v21, v21, v21
	v_mul_f32_e32 v22, v22, v22
	v_mul_f32_e32 v18, v18, v18
	v_max_f32_e32 v19, 0, v19
	v_mul_f32_e32 v23, v23, v23
	global_store_dwordx4 v[32:33], v[36:39], off
	v_mul_f32_e32 v30, v30, v30
	v_mul_f32_e32 v26, v26, v26
	v_mul_f32_e32 v31, v31, v31
	v_mul_f32_e32 v27, v27, v27
	v_cvt_pk_bf16_f32 v28, v28, v29
	v_cvt_pk_bf16_f32 v29, v30, v31
	v_cvt_pk_bf16_f32 v24, v24, v25
	v_cvt_pk_bf16_f32 v25, v26, v27
	v_mul_f32_e32 v16, v16, v16
	v_mul_f32_e32 v17, v17, v17
	v_mul_f32_e32 v19, v19, v19
	v_cvt_pk_bf16_f32 v20, v20, v21
	v_cvt_pk_bf16_f32 v21, v22, v23
	v_cvt_pk_bf16_f32 v22, v16, v17
	v_cvt_pk_bf16_f32 v23, v18, v19
	v_mov_b32_e32 v18, 0
	v_mov_b32_dpp v18, v22 row_ror:8 row_mask:0xf bank_mask:0xf
	v_mov_b32_dpp v30, v24 row_ror:8 row_mask:0xf bank_mask:0xf
	v_mov_b32_dpp v19, v23 row_ror:8 row_mask:0xf bank_mask:0xf
	v_cndmask_b32_e64 v18, v18, v24, s[6:7]
	v_add_u32_e32 v24, v154, v160
	v_mov_b32_dpp v31, v25 row_ror:8 row_mask:0xf bank_mask:0xf
	v_cndmask_b32_e64 v19, v19, v25, s[6:7]
	v_ashrrev_i32_e32 v25, 31, v24
	v_lshlrev_b64 v[24:25], 14, v[24:25]
	v_mov_b32_dpp v16, v20 row_ror:8 row_mask:0xf bank_mask:0xf
	v_mov_b32_dpp v17, v21 row_ror:8 row_mask:0xf bank_mask:0xf
	v_lshl_add_u64 v[24:25], s[12:13], 0, v[24:25]
	v_cndmask_b32_e64 v16, v16, v28, s[6:7]
	v_cndmask_b32_e64 v17, v17, v29, s[6:7]
	v_lshl_add_u64 v[24:25], v[24:25], 0, v[112:113]
	v_mov_b32_dpp v26, v28 row_ror:8 row_mask:0xf bank_mask:0xf
	v_mov_b32_dpp v27, v29 row_ror:8 row_mask:0xf bank_mask:0xf
	global_store_dwordx4 v[24:25], v[16:19], off
	v_max_f32_e32 v12, 0, v12
	v_max_f32_e32 v8, 0, v8
	v_add_co_u32_e32 v16, vcc, s58, v24
	v_max_f32_e32 v13, 0, v13
	v_max_f32_e32 v9, 0, v9
	v_max_f32_e32 v4, 0, v4
	v_max_f32_e32 v5, 0, v5
	v_max_f32_e32 v6, 0, v6
	v_max_f32_e32 v2, 0, v2
	v_max_f32_e32 v7, 0, v7
	v_cndmask_b32_e64 v20, v20, v26, s[6:7]
	v_cndmask_b32_e64 v21, v21, v27, s[6:7]
	v_cndmask_b32_e64 v22, v22, v30, s[6:7]
	v_cndmask_b32_e64 v23, v23, v31, s[6:7]
	v_addc_co_u32_e32 v17, vcc, 0, v25, vcc
	v_mul_f32_e32 v12, v12, v12
	v_mul_f32_e32 v8, v8, v8
	v_mul_f32_e32 v13, v13, v13
	v_mul_f32_e32 v9, v9, v9
	v_max_f32_e32 v14, 0, v14
	v_max_f32_e32 v10, 0, v10
	v_max_f32_e32 v15, 0, v15
	v_max_f32_e32 v11, 0, v11
	v_max_f32_e32 v0, 0, v0
	v_mul_f32_e32 v4, v4, v4
	v_max_f32_e32 v1, 0, v1
	v_mul_f32_e32 v5, v5, v5
	v_mul_f32_e32 v6, v6, v6
	v_mul_f32_e32 v2, v2, v2
	v_max_f32_e32 v3, 0, v3
	v_mul_f32_e32 v7, v7, v7
	global_store_dwordx4 v[16:17], v[20:23], off
	v_mul_f32_e32 v14, v14, v14
	v_mul_f32_e32 v10, v10, v10
	v_mul_f32_e32 v15, v15, v15
	v_mul_f32_e32 v11, v11, v11
	v_cvt_pk_bf16_f32 v12, v12, v13
	v_cvt_pk_bf16_f32 v13, v14, v15
	v_cvt_pk_bf16_f32 v8, v8, v9
	v_cvt_pk_bf16_f32 v9, v10, v11
	v_mul_f32_e32 v0, v0, v0
	v_mul_f32_e32 v1, v1, v1
	v_mul_f32_e32 v3, v3, v3
	v_cvt_pk_bf16_f32 v4, v4, v5
	v_cvt_pk_bf16_f32 v5, v6, v7
	v_cvt_pk_bf16_f32 v6, v0, v1
	v_cvt_pk_bf16_f32 v7, v2, v3
	v_mov_b32_e32 v2, 0
	v_mov_b32_dpp v2, v6 row_ror:8 row_mask:0xf bank_mask:0xf
	v_mov_b32_dpp v14, v8 row_ror:8 row_mask:0xf bank_mask:0xf
	v_mov_b32_dpp v3, v7 row_ror:8 row_mask:0xf bank_mask:0xf
	v_cndmask_b32_e64 v2, v2, v8, s[6:7]
	v_add_u32_e32 v8, v155, v160
	v_mov_b32_dpp v15, v9 row_ror:8 row_mask:0xf bank_mask:0xf
	v_cndmask_b32_e64 v3, v3, v9, s[6:7]
	v_ashrrev_i32_e32 v9, 31, v8
	v_lshlrev_b64 v[8:9], 14, v[8:9]
	v_mov_b32_dpp v0, v4 row_ror:8 row_mask:0xf bank_mask:0xf
	v_mov_b32_dpp v1, v5 row_ror:8 row_mask:0xf bank_mask:0xf
	v_lshl_add_u64 v[8:9], s[12:13], 0, v[8:9]
	v_cndmask_b32_e64 v0, v0, v12, s[6:7]
	v_cndmask_b32_e64 v1, v1, v13, s[6:7]
	v_lshl_add_u64 v[8:9], v[8:9], 0, v[112:113]
	global_store_dwordx4 v[8:9], v[0:3], off
	v_mov_b32_dpp v10, v12 row_ror:8 row_mask:0xf bank_mask:0xf
	v_mov_b32_dpp v11, v13 row_ror:8 row_mask:0xf bank_mask:0xf
	v_add_co_u32_e32 v0, vcc, 0x20000, v8
	v_cndmask_b32_e64 v4, v4, v10, s[6:7]
	s_nop 0
	v_addc_co_u32_e32 v1, vcc, 0, v9, vcc
	v_cndmask_b32_e64 v5, v5, v11, s[6:7]
	v_cndmask_b32_e64 v6, v6, v14, s[6:7]
	v_cndmask_b32_e64 v7, v7, v15, s[6:7]
	s_and_b64 vcc, exec, s[30:31]
	s_mov_b32 s59, s18
	s_mov_b32 s36, s26
	s_mov_b64 s[40:41], s[34:35]
	s_mov_b64 s[38:39], s[28:29]
	global_store_dwordx4 v[0:1], v[4:7], off
	s_cbranch_vccz .LBB0_1357
	s_waitcnt vmcnt(0)
	s_cmpk_gt_u32 s44, 0xff
	s_cbranch_scc1 .LBB0_1369
	s_barrier

; #define PG8_STAGE(bufoff, gbase, voff) do { _Pragma("unroll") for (int _i = 0; _i < 2; ++_i) \
;         __builtin_amdgcn_global_load_lds((const unsigned*)((const char*)(gbase) + (voff)[_i]), (LAS unsigned*)(lds + (bufoff) + ldsw + _i * 8192), 16, 0, 0); } while (0)
; #define PG8_WAIT_V(n) asm volatile("s_waitcnt vmcnt(" #n ")" ::: "memory")
; #define PG8_BAR __builtin_amdgcn_s_barrier()
; template <class Epi>
; __device__ __forceinline__ void gemm_phase(LAS unsigned char* lds, const Gemm g, const StaticOrder& S, const Epi& E) {
;     ...
;     for (int i = 0; i < 2; ++i) { int R, C; stage_rc(tid * 16 + i * 8192, R, C);
;         const int Rw = 64 * (R >> 5) + 16 * ((R >> 2) & 3) + 4 * ((R >> 4) & 1) + (R & 3);
;         const int Rf = 64 * (R >> 5) + 8 * ((R >> 2) & 3) + 4 * ((R >> 4) & 1) + (R & 3);
;         const int Rb0 = Epi::PERM ? (Epi::F32OUT ? Rf : Rw) : R, Rb1 = Epi::PERM ? (Epi::F32OUT ? Rf + 32 : Rw + 8) : R + HALF;
;         voffA[i] = (unsigned)(R * K + C) * 2u; voffB0[i] = (unsigned)(Rb0 * K + C) * 2u; voffB1[i] = (unsigned)(Rb1 * K + C) * 2u; }
;     const size_t kstep = (size_t)(BK * 2);
;     const size_t hstep = (size_t)HALF * K * 2;
;     const size_t tstep = 2 * hstep;
;     const unsigned ldsw = (unsigned)wid * 1024u;
;     const int aoff = lds_byte(wr * 64 + fr, fq * 8), boff = lds_byte(wc * 32 + fr, fq * 8);
;     ...
;     Unit cur, nxt; int ui = 0;
;     if (!S.next(0, cur)) return;
;     f32x4 acc[2][2][4][2];
; #pragma unroll
;     for (int a = 0; a < 2; ++a)
; #pragma unroll
;         for (int b = 0; b < 2; ++b)
; #pragma unroll
;             for (int m = 0; m < 4; ++m)
; #pragma unroll
;                 for (int n = 0; n < 2; ++n) acc[a][b][m][n] = (f32x4){0.f, 0.f, 0.f, 0.f};
;     bf16x8 At[4][2], B0[2][2], B1[2][2];
;     const char* cA = (const char*)g.A + (size_t)cur.pm * tstep; const char* cB = (const char*)g.Bt + (size_t)cur.pn * tstep;
;     PG8_STAGE(PG8_SB(0, 0), cB, voffB0); PG8_STAGE(PG8_SA(0, 0), cA, voffA); PG8_STAGE(PG8_SB(0, 1), cB, voffB1); PG8_STAGE(PG8_SA(0, 1), cA + hstep, voffA);
;     if (wr == 1) PG8_BAR;
;     PG8_WAIT_V(4); PG8_BAR;
;     PG8_STAGE(PG8_SB(1, 0), cB + kstep, voffB0); PG8_STAGE(PG8_SA(1, 0), cA + kstep, voffA); PG8_STAGE(PG8_SB(1, 1), cB + kstep, voffB1);
;     PG8_WAIT_V(6); PG8_BAR;
;     for (;;) {
;         const bool has_next = S.next(ui + 1, nxt);
.LBB0_1431:
	s_add_u32 s12, s18, 0x6400000
	s_addc_u32 s13, s19, 0
	s_add_u32 s18, s18, 0x1ec10000
	s_mov_b64 s[26:27], 0x80
	s_addc_u32 s19, s19, 0
	s_add_i32 m0, s54, 0x18000
	v_lshl_add_u64 v[10:11], v[10:11], 0, s[26:27]
	s_waitcnt vmcnt(4)
	s_barrier
	global_load_lds_dwordx4 v[10:11], off
	v_lshl_add_u64 v[8:9], v[8:9], 0, s[26:27]
	s_add_i32 m0, s54, 0x1a000
	s_add_i32 s60, s54, 0x8000
	global_load_lds_dwordx4 v[8:9], off
	v_lshl_add_u64 v[6:7], v[6:7], 0, s[26:27]
	s_mov_b32 m0, s60
	s_add_i32 s61, s54, 0xa000
	global_load_lds_dwordx4 v[6:7], off
	v_lshl_add_u64 v[4:5], v[4:5], 0, s[26:27]
	s_mov_b32 m0, s61
	v_lshl_add_u64 v[0:1], v[0:1], 0, s[26:27]
	global_load_lds_dwordx4 v[4:5], off
	s_add_i32 m0, s54, 0x1c000
	s_and_b32 s9, s6, 3
	global_load_lds_dwordx4 v[0:1], off
	v_lshl_add_u64 v[0:1], v[2:3], 0, s[26:27]
	s_add_i32 m0, s54, 0x1e000
	v_and_b32_e32 v174, 15, v12
	global_load_lds_dwordx4 v[0:1], off
	v_and_b32_e32 v0, 48, v12
	v_lshlrev_b32_e32 v2, 2, v12
	s_lshl_b32 s6, s7, 13
	v_lshl_or_b32 v1, v174, 6, v0
	v_and_b32_e32 v2, 32, v2
	v_lshl_or_b32 v178, s9, 6, v0
	v_lshlrev_b32_e32 v0, 17, v13
	v_bitop3_b32 v3, v1, s6, v2 bitop3:0xde
	s_lshl_b32 s6, s9, 12
	v_and_b32_e32 v0, 0xfffc0000, v0
	v_bitop3_b32 v175, v1, s6, v2 bitop3:0xde
	v_lshl_add_u32 v0, v14, 14, v0
	v_and_b32_e32 v1, 1, v13
	v_lshl_or_b32 v0, v1, 6, v0
	v_lshl_add_u32 v148, v15, 1, v0
	v_lshlrev_b32_e32 v0, 17, v16
	s_lshl_b32 s62, s7, 6
	s_ashr_i32 s63, s20, 31
	s_ashr_i32 s65, s2, 31
	v_and_b32_e32 v0, 0xfffc0000, v0
	s_waitcnt vmcnt(0)
	s_cmp_lg_u64 s[16:17], 0
	v_lshl_add_u32 v0, v17, 14, v0
	v_and_b32_e32 v1, 1, v16
	s_cselect_b64 s[28:29], -1, 0
	v_lshl_or_b32 v0, v1, 6, v0
	s_add_i32 s66, 0, 0x10000
	s_add_i32 s67, 0, 0x14000
	v_cmp_gt_u32_e64 s[6:7], 8, v174
	v_and_b32_e32 v176, 7, v12
	v_and_b32_e32 v177, 8, v12
	s_mov_b32 s64, s20
	v_mov_b32_e32 v149, v139
	v_lshl_add_u32 v150, v18, 1, v0
	v_mov_b32_e32 v151, v139
	v_add_u32_e32 v179, s66, v175
	v_add_u32_e32 v180, 0, v3
	v_add_u32_e32 v181, s67, v175
	v_mov_b32_e32 v182, 0x358637bd
	s_movk_i32 s68, 0x1f80
	s_movk_i32 s69, 0x1f70
	s_movk_i32 s70, 0x1f60
	s_movk_i32 s71, 0x1f50
	v_mov_b64_e32 v[152:153], 0x1ff
	v_bfrev_b32_e32 v183, 63
	s_barrier
	s_branch .LBB0_1434

; #define PG8_STAGE(bufoff, gbase, voff) do { _Pragma("unroll") for (int _i = 0; _i < 2; ++_i) \
;         __builtin_amdgcn_global_load_lds((const unsigned*)((const char*)(gbase) + (voff)[_i]), (LAS unsigned*)(lds + (bufoff) + ldsw + _i * 8192), 16, 0, 0); } while (0)
; #define PG8_LDA(dst, b, h) do { _Pragma("unroll") for (int m = 0; m < 4; ++m) _Pragma("unroll") for (int k = 0; k < 2; ++k) dst[m][k] = *(const LAS bf16x8*)(lds + PG8_SA(b, h) + aoff + m * 2048 + k * 1024); } while (0)
; #define PG8_LDB(dst, b, h) do { _Pragma("unroll") for (int n = 0; n < 2; ++n) _Pragma("unroll") for (int k = 0; k < 2; ++k) dst[n][k] = *(const LAS bf16x8*)(lds + PG8_SB(b, h) + boff + n * 2048 + k * 1024); } while (0)
; #define PG8_MMA(ai, bj, At, Bt) do { __builtin_amdgcn_s_setprio(1); _Pragma("unroll") for (int m = 0; m < 4; ++m) _Pragma("unroll") for (int n = 0; n < 2; ++n) _Pragma("unroll") for (int k = 0; k < 2; ++k) \
;         acc[ai][bj][m][n] = __builtin_amdgcn_mfma_f32_16x16x32_bf16(Bt[n][k], At[m][k], acc[ai][bj][m][n], 0, 0, 0); __builtin_amdgcn_s_setprio(0); } while (0)
; #define PG8_WAIT_L(n) asm volatile("s_waitcnt lgkmcnt(" #n ")" ::: "memory")
; #define PG8_BAR __builtin_amdgcn_s_barrier()
; #define PG8_SCHED __builtin_amdgcn_sched_barrier(0)
; template <class Epi>
; __device__ __forceinline__ void gemm_phase(LAS unsigned char* lds, const Gemm g, const StaticOrder& S, const Epi& E) {
;     ...
;             PG8_LDB(B0, 0, 0); PG8_SCHED; PG8_LDA(At, 0, 0); PG8_STAGE(PG8_SA(1, 1), a1 + hstep, voffA);
;             PG8_WAIT_L(8); PG8_BAR; PG8_WAIT_L(0); PG8_MMA(0, 0, At, B0); PG8_BAR; PG8_SCHED;
;             PG8_LDB(B1, 0, 1); PG8_STAGE(PG8_SB(0, 0), b2, voffB0);
;             PG8_BAR; PG8_WAIT_L(0); PG8_MMA(0, 1, At, B1); PG8_BAR;
;             PG8_LDA(At, 0, 1); PG8_STAGE(PG8_SA(0, 0), a2, voffA);
;             PG8_BAR; PG8_WAIT_L(0); PG8_MMA(1, 0, At, B0); PG8_BAR; PG8_SCHED;
.LBB0_1443:
	ds_read_b128 v[128:131], v179
	ds_read_b128 v[132:135], v179 offset:1024
	ds_read_b128 v[154:157], v179 offset:2048
	ds_read_b128 v[158:161], v179 offset:3072
	s_add_u32 s33, s42, 0xffe00080
	s_addc_u32 s44, s43, -1
	s_cmpk_eq_i32 s74, 0x7c
	s_cselect_b32 s45, s9, s44
	s_cselect_b32 s44, s11, s33
	s_cselect_b32 s47, s31, s73
	s_cselect_b32 s46, s35, s72
	v_lshl_add_u64 v[200:201], s[42:43], 0, v[148:149]
	s_add_i32 m0, s54, 0xc000
	ds_read_b128 v[162:165], v180
	ds_read_b128 v[166:169], v180 offset:1024
	ds_read_b128 v[170:173], v180 offset:2048
	ds_read_b128 v[184:187], v180 offset:3072
	ds_read_b128 v[188:191], v180 offset:4096
	ds_read_b128 v[192:195], v180 offset:5120
	ds_read_b128 v[196:199], v180 offset:6144
	ds_read_b128 v[204:207], v180 offset:7168
	global_load_lds_dwordx4 v[200:201], off
	v_lshl_add_u64 v[200:201], s[42:43], 0, v[150:151]
	s_add_i32 m0, s54, 0xe000
	s_nop 0
	global_load_lds_dwordx4 v[200:201], off
	s_waitcnt lgkmcnt(8)
	s_barrier
	s_waitcnt lgkmcnt(0)
	v_mfma_f32_16x16x32_bf16 v[124:127], v[128:131], v[162:165], v[124:127]
	v_mfma_f32_16x16x32_bf16 v[120:123], v[154:157], v[162:165], v[120:123]
	v_mfma_f32_16x16x32_bf16 v[108:111], v[128:131], v[170:173], v[108:111]
	v_mfma_f32_16x16x32_bf16 v[104:107], v[154:157], v[170:173], v[104:107]
	v_mfma_f32_16x16x32_bf16 v[92:95], v[128:131], v[188:191], v[92:95]
	v_mfma_f32_16x16x32_bf16 v[88:91], v[154:157], v[188:191], v[88:91]
	v_mfma_f32_16x16x32_bf16 v[76:79], v[128:131], v[196:199], v[76:79]
	v_mfma_f32_16x16x32_bf16 v[72:75], v[154:157], v[196:199], v[72:75]
	v_mfma_f32_16x16x32_bf16 v[124:127], v[132:135], v[166:169], v[124:127]
	v_mfma_f32_16x16x32_bf16 v[120:123], v[158:161], v[166:169], v[120:123]
	v_mfma_f32_16x16x32_bf16 v[108:111], v[132:135], v[184:187], v[108:111]
	v_mfma_f32_16x16x32_bf16 v[104:107], v[158:161], v[184:187], v[104:107]
	v_mfma_f32_16x16x32_bf16 v[92:95], v[132:135], v[192:195], v[92:95]
	v_mfma_f32_16x16x32_bf16 v[88:91], v[158:161], v[192:195], v[88:91]
	v_mfma_f32_16x16x32_bf16 v[76:79], v[132:135], v[204:207], v[76:79]
	v_mfma_f32_16x16x32_bf16 v[72:75], v[158:161], v[204:207], v[72:75]
	s_barrier
	s_add_i32 s33, s66, s53
	v_lshl_add_u64 v[200:201], s[46:47], 0, v[138:139]
	s_mov_b32 m0, s33
	ds_read_b128 v[208:211], v181
	ds_read_b128 v[212:215], v181 offset:1024
	ds_read_b128 v[216:219], v181 offset:2048
	ds_read_b128 v[220:223], v181 offset:3072
	global_load_lds_dwordx4 v[200:201], off
	v_lshl_add_u64 v[224:225], s[46:47], 0, v[144:145]
	s_add_i32 m0, s33, 0x2000
	s_nop 0
	global_load_lds_dwordx4 v[224:225], off
	s_barrier
	s_waitcnt lgkmcnt(0)
	v_mfma_f32_16x16x32_bf16 v[116:119], v[208:211], v[162:165], v[116:119]
	v_mfma_f32_16x16x32_bf16 v[112:115], v[216:219], v[162:165], v[112:115]
	v_mfma_f32_16x16x32_bf16 v[100:103], v[208:211], v[170:173], v[100:103]
	v_mfma_f32_16x16x32_bf16 v[96:99], v[216:219], v[170:173], v[96:99]
	v_mfma_f32_16x16x32_bf16 v[84:87], v[208:211], v[188:191], v[84:87]
	v_mfma_f32_16x16x32_bf16 v[80:83], v[216:219], v[188:191], v[80:83]
	v_mfma_f32_16x16x32_bf16 v[68:71], v[208:211], v[196:199], v[68:71]
	v_mfma_f32_16x16x32_bf16 v[64:67], v[216:219], v[196:199], v[64:67]
	v_mfma_f32_16x16x32_bf16 v[116:119], v[212:215], v[166:169], v[116:119]
	v_mfma_f32_16x16x32_bf16 v[112:115], v[220:223], v[166:169], v[112:115]
	v_mfma_f32_16x16x32_bf16 v[100:103], v[212:215], v[184:187], v[100:103]
	v_mfma_f32_16x16x32_bf16 v[96:99], v[220:223], v[184:187], v[96:99]
	v_mfma_f32_16x16x32_bf16 v[84:87], v[212:215], v[192:195], v[84:87]
	v_mfma_f32_16x16x32_bf16 v[80:83], v[220:223], v[192:195], v[80:83]
	v_mfma_f32_16x16x32_bf16 v[68:71], v[212:215], v[204:207], v[68:71]
	v_mfma_f32_16x16x32_bf16 v[64:67], v[220:223], v[204:207], v[64:67]
	s_mov_b32 m0, s54
	v_lshl_add_u64 v[226:227], s[44:45], 0, v[136:137]
	s_barrier
	ds_read_b128 v[162:165], v180 offset:16384
	ds_read_b128 v[166:169], v180 offset:17408
	ds_read_b128 v[170:173], v180 offset:18432
	ds_read_b128 v[184:187], v180 offset:19456
	ds_read_b128 v[188:191], v180 offset:20480
	ds_read_b128 v[192:195], v180 offset:21504
	ds_read_b128 v[196:199], v180 offset:22528
	ds_read_b128 v[204:207], v180 offset:23552
	global_load_lds_dwordx4 v[226:227], off
	v_lshl_add_u64 v[228:229], s[44:45], 0, v[142:143]
	s_mov_b32 m0, s55
	s_nop 0
	global_load_lds_dwordx4 v[228:229], off
	s_barrier
	s_waitcnt lgkmcnt(0)
	v_mfma_f32_16x16x32_bf16 v[60:63], v[128:131], v[162:165], v[60:63]
	v_mfma_f32_16x16x32_bf16 v[56:59], v[154:157], v[162:165], v[56:59]
	v_mfma_f32_16x16x32_bf16 v[44:47], v[128:131], v[170:173], v[44:47]
	v_mfma_f32_16x16x32_bf16 v[40:43], v[154:157], v[170:173], v[40:43]
	v_mfma_f32_16x16x32_bf16 v[28:31], v[128:131], v[188:191], v[28:31]
	v_mfma_f32_16x16x32_bf16 v[24:27], v[154:157], v[188:191], v[24:27]
	v_mfma_f32_16x16x32_bf16 v[12:15], v[128:131], v[196:199], v[12:15]
	v_mfma_f32_16x16x32_bf16 v[8:11], v[154:157], v[196:199], v[8:11]
	v_mfma_f32_16x16x32_bf16 v[60:63], v[132:135], v[166:169], v[60:63]
	v_mfma_f32_16x16x32_bf16 v[56:59], v[158:161], v[166:169], v[56:59]
	v_mfma_f32_16x16x32_bf16 v[44:47], v[132:135], v[184:187], v[44:47]
	v_mfma_f32_16x16x32_bf16 v[40:43], v[158:161], v[184:187], v[40:43]
	v_mfma_f32_16x16x32_bf16 v[28:31], v[132:135], v[192:195], v[28:31]
	v_mfma_f32_16x16x32_bf16 v[24:27], v[158:161], v[192:195], v[24:27]
	v_mfma_f32_16x16x32_bf16 v[12:15], v[132:135], v[204:207], v[12:15]
	v_mfma_f32_16x16x32_bf16 v[8:11], v[158:161], v[204:207], v[8:11]
	s_barrier
; #define PG8_STAGE(bufoff, gbase, voff) do { _Pragma("unroll") for (int _i = 0; _i < 2; ++_i) \
;         __builtin_amdgcn_global_load_lds((const unsigned*)((const char*)(gbase) + (voff)[_i]), (LAS unsigned*)(lds + (bufoff) + ldsw + _i * 8192), 16, 0, 0); } while (0)
; #define PG8_LDA(dst, b, h) do { _Pragma("unroll") for (int m = 0; m < 4; ++m) _Pragma("unroll") for (int k = 0; k < 2; ++k) dst[m][k] = *(const LAS bf16x8*)(lds + PG8_SA(b, h) + aoff + m * 2048 + k * 1024); } while (0)
; #define PG8_LDB(dst, b, h) do { _Pragma("unroll") for (int n = 0; n < 2; ++n) _Pragma("unroll") for (int k = 0; k < 2; ++k) dst[n][k] = *(const LAS bf16x8*)(lds + PG8_SB(b, h) + boff + n * 2048 + k * 1024); } while (0)
; #define PG8_MMA(ai, bj, At, Bt) do { __builtin_amdgcn_s_setprio(1); _Pragma("unroll") for (int m = 0; m < 4; ++m) _Pragma("unroll") for (int n = 0; n < 2; ++n) _Pragma("unroll") for (int k = 0; k < 2; ++k) \
;         acc[ai][bj][m][n] = __builtin_amdgcn_mfma_f32_16x16x32_bf16(Bt[n][k], At[m][k], acc[ai][bj][m][n], 0, 0, 0); __builtin_amdgcn_s_setprio(0); } while (0)
; #define PG8_WAIT_V(n) asm volatile("s_waitcnt vmcnt(" #n ")" ::: "memory")
; #define PG8_WAIT_L(n) asm volatile("s_waitcnt lgkmcnt(" #n ")" ::: "memory")
; #define PG8_BAR __builtin_amdgcn_s_barrier()
; #define PG8_SCHED __builtin_amdgcn_sched_barrier(0)
; template <class Epi>
; __device__ __forceinline__ void gemm_phase(LAS unsigned char* lds, const Gemm g, const StaticOrder& S, const Epi& E) {
;     ...
;             PG8_STAGE(PG8_SB(0, 1), b2, voffB1);
;             PG8_WAIT_V(6); PG8_BAR; PG8_MMA(1, 1, At, B1); PG8_BAR;
;             PG8_LDB(B0, 1, 0); PG8_SCHED; PG8_LDA(At, 1, 0); PG8_STAGE(PG8_SA(0, 1), a2 + hstep, voffA);
;             PG8_WAIT_L(8); PG8_BAR; PG8_WAIT_L(0); PG8_MMA(0, 0, At, B0); PG8_BAR; PG8_SCHED;
;             PG8_LDB(B1, 1, 1); PG8_STAGE(PG8_SB(1, 0), b3, voffB0);
;             PG8_BAR; PG8_WAIT_L(0); PG8_MMA(0, 1, At, B1); PG8_BAR;
	s_add_i32 s33, s67, s53
	v_lshl_add_u64 v[230:231], s[46:47], 0, v[140:141]
	s_mov_b32 m0, s33
	v_lshl_add_u64 v[232:233], s[46:47], 0, v[146:147]
	global_load_lds_dwordx4 v[230:231], off
	s_add_i32 m0, s33, 0x2000
	s_nop 0
	global_load_lds_dwordx4 v[232:233], off
	s_add_i32 s33, 0, 0x18000
	v_add_u32_e32 v158, s33, v175
	ds_read_b128 v[128:131], v158
	ds_read_b128 v[132:135], v158 offset:1024
	ds_read_b128 v[154:157], v158 offset:2048
	ds_read_b128 v[158:161], v158 offset:3072
	s_waitcnt vmcnt(6)
	s_barrier
	v_mfma_f32_16x16x32_bf16 v[52:55], v[208:211], v[162:165], v[52:55]
	v_mfma_f32_16x16x32_bf16 v[48:51], v[216:219], v[162:165], v[48:51]
	v_mfma_f32_16x16x32_bf16 v[36:39], v[208:211], v[170:173], v[36:39]
	v_mfma_f32_16x16x32_bf16 v[32:35], v[216:219], v[170:173], v[32:35]
	v_mfma_f32_16x16x32_bf16 v[20:23], v[208:211], v[188:191], v[20:23]
	v_mfma_f32_16x16x32_bf16 v[16:19], v[216:219], v[188:191], v[16:19]
	v_mfma_f32_16x16x32_bf16 v[4:7], v[208:211], v[196:199], v[4:7]
	v_mfma_f32_16x16x32_bf16 v[0:3], v[216:219], v[196:199], v[0:3]
	v_mfma_f32_16x16x32_bf16 v[52:55], v[212:215], v[166:169], v[52:55]
	v_mfma_f32_16x16x32_bf16 v[48:51], v[220:223], v[166:169], v[48:51]
	v_mfma_f32_16x16x32_bf16 v[36:39], v[212:215], v[184:187], v[36:39]
	v_mfma_f32_16x16x32_bf16 v[32:35], v[220:223], v[184:187], v[32:35]
	v_mfma_f32_16x16x32_bf16 v[20:23], v[212:215], v[192:195], v[20:23]
	v_mfma_f32_16x16x32_bf16 v[16:19], v[220:223], v[192:195], v[16:19]
	v_mfma_f32_16x16x32_bf16 v[4:7], v[212:215], v[204:207], v[4:7]
	v_mfma_f32_16x16x32_bf16 v[0:3], v[220:223], v[204:207], v[0:3]
	s_barrier
	s_add_u32 s44, s44, 0x200000
	s_addc_u32 s45, s45, 0
	s_mov_b32 m0, s56
	v_lshl_add_u64 v[208:209], s[44:45], 0, v[136:137]
	ds_read_b128 v[162:165], v180 offset:32768
	ds_read_b128 v[166:169], v180 offset:33792
	ds_read_b128 v[170:173], v180 offset:34816
	ds_read_b128 v[184:187], v180 offset:35840
	ds_read_b128 v[188:191], v180 offset:36864
	ds_read_b128 v[192:195], v180 offset:37888
	ds_read_b128 v[196:199], v180 offset:38912
	ds_read_b128 v[204:207], v180 offset:39936
	global_load_lds_dwordx4 v[208:209], off
	v_lshl_add_u64 v[208:209], s[44:45], 0, v[142:143]
	s_mov_b32 m0, s57
	s_nop 0
	global_load_lds_dwordx4 v[208:209], off
	s_waitcnt lgkmcnt(8)
	s_barrier
	s_waitcnt lgkmcnt(0)
	v_mfma_f32_16x16x32_bf16 v[124:127], v[128:131], v[162:165], v[124:127]
	v_mfma_f32_16x16x32_bf16 v[120:123], v[154:157], v[162:165], v[120:123]
	v_mfma_f32_16x16x32_bf16 v[108:111], v[128:131], v[170:173], v[108:111]
	v_mfma_f32_16x16x32_bf16 v[104:107], v[154:157], v[170:173], v[104:107]
	v_mfma_f32_16x16x32_bf16 v[92:95], v[128:131], v[188:191], v[92:95]
	v_mfma_f32_16x16x32_bf16 v[88:91], v[154:157], v[188:191], v[88:91]
	v_mfma_f32_16x16x32_bf16 v[76:79], v[128:131], v[196:199], v[76:79]
	v_mfma_f32_16x16x32_bf16 v[72:75], v[154:157], v[196:199], v[72:75]
	v_mfma_f32_16x16x32_bf16 v[124:127], v[132:135], v[166:169], v[124:127]
	v_mfma_f32_16x16x32_bf16 v[120:123], v[158:161], v[166:169], v[120:123]
	v_mfma_f32_16x16x32_bf16 v[108:111], v[132:135], v[184:187], v[108:111]
	v_mfma_f32_16x16x32_bf16 v[104:107], v[158:161], v[184:187], v[104:107]
	v_mfma_f32_16x16x32_bf16 v[92:95], v[132:135], v[192:195], v[92:95]
	v_mfma_f32_16x16x32_bf16 v[88:91], v[158:161], v[192:195], v[88:91]
	v_mfma_f32_16x16x32_bf16 v[76:79], v[132:135], v[204:207], v[76:79]
	v_mfma_f32_16x16x32_bf16 v[72:75], v[158:161], v[204:207], v[72:75]
	s_barrier
	s_add_i32 s44, 0, 0x1c000
	s_add_i32 s33, s33, s53
	v_add_u32_e32 v203, s44, v175
	v_lshl_add_u64 v[200:201], v[200:201], 0, s[26:27]
	s_mov_b32 m0, s33
	ds_read_b128 v[208:211], v203
	ds_read_b128 v[212:215], v203 offset:1024
	ds_read_b128 v[216:219], v203 offset:2048
	ds_read_b128 v[220:223], v203 offset:3072
	global_load_lds_dwordx4 v[200:201], off
	v_lshl_add_u64 v[200:201], v[224:225], 0, s[26:27]
	s_add_i32 m0, s33, 0x2000
	s_nop 0
	global_load_lds_dwordx4 v[200:201], off
	s_barrier
	s_waitcnt lgkmcnt(0)
	v_mfma_f32_16x16x32_bf16 v[116:119], v[208:211], v[162:165], v[116:119]
	v_mfma_f32_16x16x32_bf16 v[112:115], v[216:219], v[162:165], v[112:115]
	v_mfma_f32_16x16x32_bf16 v[100:103], v[208:211], v[170:173], v[100:103]
	v_mfma_f32_16x16x32_bf16 v[96:99], v[216:219], v[170:173], v[96:99]
	v_mfma_f32_16x16x32_bf16 v[84:87], v[208:211], v[188:191], v[84:87]
	v_mfma_f32_16x16x32_bf16 v[80:83], v[216:219], v[188:191], v[80:83]
	v_mfma_f32_16x16x32_bf16 v[68:71], v[208:211], v[196:199], v[68:71]
	v_mfma_f32_16x16x32_bf16 v[64:67], v[216:219], v[196:199], v[64:67]
	v_mfma_f32_16x16x32_bf16 v[116:119], v[212:215], v[166:169], v[116:119]
	v_mfma_f32_16x16x32_bf16 v[112:115], v[220:223], v[166:169], v[112:115]
	v_mfma_f32_16x16x32_bf16 v[100:103], v[212:215], v[184:187], v[100:103]
	v_mfma_f32_16x16x32_bf16 v[96:99], v[220:223], v[184:187], v[96:99]
	v_mfma_f32_16x16x32_bf16 v[84:87], v[212:215], v[192:195], v[84:87]
	v_mfma_f32_16x16x32_bf16 v[80:83], v[220:223], v[192:195], v[80:83]
	v_mfma_f32_16x16x32_bf16 v[68:71], v[212:215], v[204:207], v[68:71]
	v_mfma_f32_16x16x32_bf16 v[64:67], v[220:223], v[204:207], v[64:67]
	s_mov_b32 m0, s60
	v_lshl_add_u64 v[200:201], v[226:227], 0, s[26:27]
	s_barrier
; __device__ __forceinline__ float bflo(unsigned w) { return __uint_as_float(w << 16); }
; __device__ __forceinline__ float bfhi(unsigned w) { return __uint_as_float(w & 0xffff0000u); }
; #define PG8_STAGE(bufoff, gbase, voff) do { _Pragma("unroll") for (int _i = 0; _i < 2; ++_i) \
;         __builtin_amdgcn_global_load_lds((const unsigned*)((const char*)(gbase) + (voff)[_i]), (LAS unsigned*)(lds + (bufoff) + ldsw + _i * 8192), 16, 0, 0); } while (0)
; #define PG8_LDA(dst, b, h) do { _Pragma("unroll") for (int m = 0; m < 4; ++m) _Pragma("unroll") for (int k = 0; k < 2; ++k) dst[m][k] = *(const LAS bf16x8*)(lds + PG8_SA(b, h) + aoff + m * 2048 + k * 1024); } while (0)
; #define PG8_MMA(ai, bj, At, Bt) do { __builtin_amdgcn_s_setprio(1); _Pragma("unroll") for (int m = 0; m < 4; ++m) _Pragma("unroll") for (int n = 0; n < 2; ++n) _Pragma("unroll") for (int k = 0; k < 2; ++k) \
;         acc[ai][bj][m][n] = __builtin_amdgcn_mfma_f32_16x16x32_bf16(Bt[n][k], At[m][k], acc[ai][bj][m][n], 0, 0, 0); __builtin_amdgcn_s_setprio(0); } while (0)
; #define PG8_WAIT_V(n) asm volatile("s_waitcnt vmcnt(" #n ")" ::: "memory")
; #define PG8_WAIT_L(n) asm volatile("s_waitcnt lgkmcnt(" #n ")" ::: "memory")
;     __device__ __forceinline__ void operator()(const f32x4 (&acc)[2][2][4][2], const Unit& u, int wr, int wc, int fr, int fq) const {
;     ...
;             for (int m = 0; m < 4; ++m) { const int row = row0 + ai * HALF + m * 16; const size_t off = (size_t)row * D + col0; float sq = 0.f; u32x4 w[2];
;                 const float sc = rsin ? __builtin_amdgcn_rcpf(rsin[row] * (1.f / D) + EPS) : 1.0f;
;                 u32x4 rr[2]; if (R) load_pair_lines(R, D, row, fr, col0, rr[0], rr[1]);
; #pragma unroll
;                 for (int bj = 0; bj < 2; ++bj) { f32x4 r0, r1;
;                     if (R) { const u32x4 rw = rr[bj]; r0 = (f32x4){bflo(rw.x), bfhi(rw.x), bflo(rw.y), bfhi(rw.y)}; r1 = (f32x4){bflo(rw.z), bfhi(rw.z), bflo(rw.w), bfhi(rw.w)}; }
; template <class Epi>
; __device__ __forceinline__ void gemm_phase(LAS unsigned char* lds, const Gemm g, const StaticOrder& S, const Epi& E) {
;     ...
;             PG8_LDA(At, 1, 1); PG8_STAGE(PG8_SA(1, 0), a3, voffA);
;             PG8_BAR; PG8_WAIT_L(0); PG8_MMA(1, 0, At, B0); PG8_BAR; PG8_SCHED;
;             PG8_STAGE(PG8_SB(1, 1), b3, voffB1);
;             PG8_WAIT_V(6); PG8_BAR; PG8_MMA(1, 1, At, B1); PG8_BAR;
;         }
	ds_read_b128 v[162:165], v180 offset:49152
	ds_read_b128 v[166:169], v180 offset:50176
	ds_read_b128 v[170:173], v180 offset:51200
	ds_read_b128 v[184:187], v180 offset:52224
	ds_read_b128 v[188:191], v180 offset:53248
	ds_read_b128 v[192:195], v180 offset:54272
	ds_read_b128 v[196:199], v180 offset:55296
	ds_read_b128 v[204:207], v180 offset:56320
	global_load_lds_dwordx4 v[200:201], off
	v_lshl_add_u64 v[200:201], v[228:229], 0, s[26:27]
	s_mov_b32 m0, s61
	s_nop 0
	global_load_lds_dwordx4 v[200:201], off
	s_barrier
	s_waitcnt lgkmcnt(0)
	v_mfma_f32_16x16x32_bf16 v[60:63], v[128:131], v[162:165], v[60:63]
	v_mfma_f32_16x16x32_bf16 v[56:59], v[154:157], v[162:165], v[56:59]
	v_mfma_f32_16x16x32_bf16 v[44:47], v[128:131], v[170:173], v[44:47]
	v_mfma_f32_16x16x32_bf16 v[40:43], v[154:157], v[170:173], v[40:43]
	v_mfma_f32_16x16x32_bf16 v[28:31], v[128:131], v[188:191], v[28:31]
	v_mfma_f32_16x16x32_bf16 v[24:27], v[154:157], v[188:191], v[24:27]
	v_mfma_f32_16x16x32_bf16 v[12:15], v[128:131], v[196:199], v[12:15]
	v_mfma_f32_16x16x32_bf16 v[8:11], v[154:157], v[196:199], v[8:11]
	v_mfma_f32_16x16x32_bf16 v[60:63], v[132:135], v[166:169], v[60:63]
	v_mfma_f32_16x16x32_bf16 v[56:59], v[158:161], v[166:169], v[56:59]
	v_mfma_f32_16x16x32_bf16 v[44:47], v[132:135], v[184:187], v[44:47]
	v_mfma_f32_16x16x32_bf16 v[40:43], v[158:161], v[184:187], v[40:43]
	v_mfma_f32_16x16x32_bf16 v[28:31], v[132:135], v[192:195], v[28:31]
	v_mfma_f32_16x16x32_bf16 v[24:27], v[158:161], v[192:195], v[24:27]
	v_mfma_f32_16x16x32_bf16 v[12:15], v[132:135], v[204:207], v[12:15]
	v_mfma_f32_16x16x32_bf16 v[8:11], v[158:161], v[204:207], v[8:11]
	s_barrier
	s_add_i32 s33, s44, s53
	v_lshl_add_u64 v[128:129], v[230:231], 0, s[26:27]
	s_mov_b32 m0, s33
	s_nop 0
	global_load_lds_dwordx4 v[128:129], off
	v_lshl_add_u64 v[128:129], v[232:233], 0, s[26:27]
	s_add_i32 m0, s33, 0x2000
	s_nop 0
	global_load_lds_dwordx4 v[128:129], off
	s_waitcnt vmcnt(6)
	s_barrier
	v_mfma_f32_16x16x32_bf16 v[52:55], v[208:211], v[162:165], v[52:55]
	v_mfma_f32_16x16x32_bf16 v[48:51], v[216:219], v[162:165], v[48:51]
	v_mfma_f32_16x16x32_bf16 v[36:39], v[208:211], v[170:173], v[36:39]
	v_mfma_f32_16x16x32_bf16 v[32:35], v[216:219], v[170:173], v[32:35]
	v_mfma_f32_16x16x32_bf16 v[20:23], v[208:211], v[188:191], v[20:23]
	v_mfma_f32_16x16x32_bf16 v[16:19], v[216:219], v[188:191], v[16:19]
	v_mfma_f32_16x16x32_bf16 v[4:7], v[208:211], v[196:199], v[4:7]
	v_mfma_f32_16x16x32_bf16 v[0:3], v[216:219], v[196:199], v[0:3]
	v_mfma_f32_16x16x32_bf16 v[52:55], v[212:215], v[166:169], v[52:55]
	v_mfma_f32_16x16x32_bf16 v[48:51], v[220:223], v[166:169], v[48:51]
	v_mfma_f32_16x16x32_bf16 v[36:39], v[212:215], v[184:187], v[36:39]
	v_mfma_f32_16x16x32_bf16 v[32:35], v[220:223], v[184:187], v[32:35]
	v_mfma_f32_16x16x32_bf16 v[20:23], v[212:215], v[192:195], v[20:23]
	v_mfma_f32_16x16x32_bf16 v[16:19], v[220:223], v[192:195], v[16:19]
	v_mfma_f32_16x16x32_bf16 v[4:7], v[212:215], v[204:207], v[4:7]
	v_mfma_f32_16x16x32_bf16 v[0:3], v[220:223], v[204:207], v[0:3]
	s_add_i32 s74, s74, 2
	s_add_u32 s42, s42, 0x100
	s_addc_u32 s43, s43, 0
	s_add_u32 s72, s72, 0x100
	s_addc_u32 s73, s73, 0
	s_cmpk_gt_u32 s74, 0x7d
	s_barrier
	s_cbranch_scc0 .LBB0_1443
	s_lshl_b32 s9, s10, 8
	s_add_i32 s10, s9, s62
	v_or_b32_e32 v158, s10, v174
	v_ashrrev_i32_e32 v159, 31, v158
	v_lshl_add_u64 v[160:161], v[158:159], 2, s[18:19]
	global_load_dword v168, v[160:161], off
	v_lshl_or_b32 v156, s8, 8, v178
	v_or_b32_e32 v154, v156, v177
	v_ashrrev_i32_e32 v155, 31, v154
	v_cndmask_b32_e64 v128, 0, 1, s[28:29]
	v_or_b32_e32 v166, s10, v176
	v_cmp_ne_u32_e64 s[8:9], 1, v128
	s_andn2_b64 vcc, exec, s[28:29]
	v_lshlrev_b64 v[162:163], 1, v[154:155]
	v_ashrrev_i32_e32 v167, 31, v166
	v_or_b32_e32 v164, 8, v166
	s_cbranch_vccnz .LBB0_1447
	v_ashrrev_i32_e32 v165, 31, v164
	v_lshlrev_b64 v[128:129], 12, v[166:167]
	v_lshlrev_b64 v[132:133], 12, v[164:165]
	v_lshl_add_u64 v[128:129], s[16:17], 0, v[128:129]
	v_lshl_add_u64 v[132:133], s[16:17], 0, v[132:133]
	v_lshl_add_u64 v[128:129], v[128:129], 0, v[162:163]
	v_lshl_add_u64 v[132:133], v[132:133], 0, v[162:163]
	global_load_dwordx4 v[128:131], v[128:129], off
	global_load_dwordx4 v[132:135], v[132:133], off
	s_waitcnt vmcnt(0)
	v_mov_b32_dpp v157, v128 row_ror:8 row_mask:0xf bank_mask:0xf
	v_mov_b32_dpp v165, v129 row_ror:8 row_mask:0xf bank_mask:0xf
	v_mov_b32_dpp v169, v130 row_ror:8 row_mask:0xf bank_mask:0xf
	v_mov_b32_dpp v170, v131 row_ror:8 row_mask:0xf bank_mask:0xf
	v_mov_b32_dpp v171, v132 row_ror:8 row_mask:0xf bank_mask:0xf
	v_mov_b32_dpp v172, v133 row_ror:8 row_mask:0xf bank_mask:0xf
	v_mov_b32_dpp v173, v134 row_ror:8 row_mask:0xf bank_mask:0xf
	v_mov_b32_dpp v187, v135 row_ror:8 row_mask:0xf bank_mask:0xf
	v_cndmask_b32_e64 v184, v132, v157, s[6:7]
	v_cndmask_b32_e64 v185, v133, v165, s[6:7]
	v_cndmask_b32_e64 v186, v134, v169, s[6:7]
	v_cndmask_b32_e64 v188, v171, v128, s[6:7]
	v_cndmask_b32_e64 v189, v172, v129, s[6:7]
	v_cndmask_b32_e64 v190, v173, v130, s[6:7]
	v_cndmask_b32_e64 v191, v187, v131, s[6:7]
	v_cndmask_b32_e64 v187, v135, v170, s[6:7]
	s_and_b64 vcc, exec, s[8:9]
	v_cmp_gt_i32_e64 s[10:11], s58, v158
	s_cbranch_vccnz .LBB0_1448
